# GEMM main loops: one B half-tile stage (2 LDS-DMA pieces) moved from the 6-piece load segment to the following 2-piece segment; waits recounted
# baseline (speedup 1.0000x reference)
; #define PG8_STAGE(bufoff, gbase, voff) do { _Pragma("unroll") for (int _i = 0; _i < 2; ++_i) \
;         __builtin_amdgcn_global_load_lds((const unsigned*)((const char*)(gbase) + (voff)[_i]), (PG8_LAS unsigned*)(lds + (bufoff) + ldsw + _i * 8192), 16, 0, 0); } while (0)
; #define PG8_LDA(dst, b, h) do { _Pragma("unroll") for (int m = 0; m < 4; ++m) _Pragma("unroll") for (int k = 0; k < 2; ++k) dst[m][k] = *(const PG8_LAS bf16x8*)(lds + PG8_SA(b, h) + aoff + m * 2048 + k * 1024); } while (0)
; #define PG8_LDB(dst, b, h) do { _Pragma("unroll") for (int n = 0; n < 2; ++n) _Pragma("unroll") for (int k = 0; k < 2; ++k) dst[n][k] = *(const PG8_LAS bf16x8*)(lds + PG8_SB(b, h) + boff + n * 2048 + k * 1024); } while (0)
; #define PG8_MMA(ai, bj, At, Bt) do { __builtin_amdgcn_s_setprio(1); _Pragma("unroll") for (int m = 0; m < 4; ++m) _Pragma("unroll") for (int n = 0; n < 2; ++n) _Pragma("unroll") for (int k = 0; k < 2; ++k) \
;         acc[ai][bj][m][n] = __builtin_amdgcn_mfma_f32_16x16x32_bf16(Bt[n][k], At[m][k], acc[ai][bj][m][n], 0, 0, 0); __builtin_amdgcn_s_setprio(0); } while (0)
; #define PG8_WAIT_V(n) asm volatile("s_waitcnt vmcnt(" #n ")" ::: "memory")
; #define PG8_WAIT_L(n) asm volatile("s_waitcnt lgkmcnt(" #n ")" ::: "memory")
; #define PG8_BAR __builtin_amdgcn_s_barrier()
; #define PG8_SCHED __builtin_amdgcn_sched_barrier(0)
; template <class Epi, class Sched, bool ALIGN_EPI = false, bool SP2 = false>
; __device__ __forceinline__ void gemm_phase(PG8_LAS unsigned char* lds, const Gemm g, const Sched& S, const Epi& E, int tid_in) {
;     ...
;             PG8_LDB(B0, 0, 0); PG8_LDB(B1, 0, 1); PG8_SCHED; PG8_LDA(At, 0, 0); PG8_STAGE(PG8_SA(1, 1), a1 + hsA, voffA);
;             PG8_WAIT_V(8); PG8_WAIT_L(0); PG8_BAR; PG8_MMA(0, 0, At, B0); PG8_MMA(0, 1, At, B1); PG8_BAR; PG8_SCHED;
;             PG8_LDA(At, 0, 1); PG8_STAGE(PG8_SB(0, 0), b2, voffB); PG8_STAGE(PG8_SB(0, 1), b2 + hsB, voffB); PG8_STAGE(PG8_SA(0, 0), a2, voffA);
;             PG8_WAIT_V(8); PG8_WAIT_L(0); PG8_BAR; PG8_MMA(1, 0, At, B0); PG8_MMA(1, 1, At, B1); PG8_BAR; PG8_SCHED;
.LBB0_244:
	s_add_i32 s24, s53, -2
	s_cmp_ge_i32 s24, s28
	s_cselect_b32 s54, s29, 0
	s_cselect_b32 s55, s44, 0
	s_cmp_ge_i32 s53, s28
	s_cselect_b32 s25, s29, 0
	s_cselect_b32 s24, s44, 0
	s_add_u32 s25, s22, s25
	s_addc_u32 s24, s23, s24
	s_add_u32 s58, s25, 0x80
	s_addc_u32 s24, s24, 0
	s_add_i32 s60, 0, 0x10000
	s_cmp_eq_u32 s43, s53
	s_cselect_b32 s25, s5, s24
	s_cselect_b32 s24, s4, s58
	s_cselect_b32 s59, s21, s52
	s_cselect_b32 s58, s20, s51
	s_add_i32 s61, 0, 0x14000
	v_add_u32_e32 v160, s60, v142
	v_add_u32_e32 v176, s61, v142
	ds_read_b128 v[148:151], v160
	ds_read_b128 v[152:155], v160 offset:1024
	ds_read_b128 v[156:159], v160 offset:2048
	ds_read_b128 v[160:163], v160 offset:3072
	ds_read_b128 v[164:167], v176
	ds_read_b128 v[168:171], v176 offset:1024
	ds_read_b128 v[172:175], v176 offset:2048
	ds_read_b128 v[176:179], v176 offset:3072
	v_lshl_add_u64 v[230:231], s[22:23], 0, v[140:141]
	v_lshl_add_u64 v[230:231], v[230:231], 0, s[54:55]
	s_add_i32 m0, s37, 0xc000
	ds_read_b128 v[180:183], v147
	ds_read_b128 v[184:187], v147 offset:1024
	ds_read_b128 v[188:191], v147 offset:2048
	ds_read_b128 v[204:207], v147 offset:3072
	ds_read_b128 v[208:211], v147 offset:4096
	ds_read_b128 v[212:215], v147 offset:5120
	ds_read_b128 v[216:219], v147 offset:6144
	ds_read_b128 v[220:223], v147 offset:7168
	global_load_lds_dwordx4 v[230:231], off
	v_lshl_add_u64 v[230:231], s[22:23], 0, v[138:139]
	v_lshl_add_u64 v[230:231], v[230:231], 0, s[54:55]
	s_add_i32 m0, s37, 0xe000
	s_nop 0
	global_load_lds_dwordx4 v[230:231], off
	s_waitcnt vmcnt(8)
	s_waitcnt lgkmcnt(0)
	s_barrier
	s_setprio 1
	s_waitcnt lgkmcnt(0)
	v_mfma_f32_16x16x32_bf16 v[124:127], v[148:151], v[180:183], v[124:127]
	v_mfma_f32_16x16x32_bf16 v[120:123], v[156:159], v[180:183], v[120:123]
	v_mfma_f32_16x16x32_bf16 v[112:115], v[148:151], v[188:191], v[112:115]
	v_mfma_f32_16x16x32_bf16 v[104:107], v[156:159], v[188:191], v[104:107]
	v_mfma_f32_16x16x32_bf16 v[96:99], v[148:151], v[208:211], v[96:99]
	v_mfma_f32_16x16x32_bf16 v[88:91], v[156:159], v[208:211], v[88:91]
	v_mfma_f32_16x16x32_bf16 v[80:83], v[148:151], v[216:219], v[80:83]
	v_mfma_f32_16x16x32_bf16 v[72:75], v[156:159], v[216:219], v[72:75]
	v_mfma_f32_16x16x32_bf16 v[124:127], v[152:155], v[184:187], v[124:127]
	v_mfma_f32_16x16x32_bf16 v[120:123], v[160:163], v[184:187], v[120:123]
	v_mfma_f32_16x16x32_bf16 v[112:115], v[152:155], v[204:207], v[112:115]
	v_mfma_f32_16x16x32_bf16 v[104:107], v[160:163], v[204:207], v[104:107]
	v_mfma_f32_16x16x32_bf16 v[96:99], v[152:155], v[212:215], v[96:99]
	v_mfma_f32_16x16x32_bf16 v[88:91], v[160:163], v[212:215], v[88:91]
	v_mfma_f32_16x16x32_bf16 v[80:83], v[152:155], v[220:223], v[80:83]
	v_mfma_f32_16x16x32_bf16 v[72:75], v[160:163], v[220:223], v[72:75]
	s_setprio 0
	s_setprio 1
	v_mfma_f32_16x16x32_bf16 v[128:131], v[164:167], v[180:183], v[128:131]
	v_mfma_f32_16x16x32_bf16 v[116:119], v[172:175], v[180:183], v[116:119]
	v_mfma_f32_16x16x32_bf16 v[108:111], v[164:167], v[188:191], v[108:111]
	v_mfma_f32_16x16x32_bf16 v[100:103], v[172:175], v[188:191], v[100:103]
	v_mfma_f32_16x16x32_bf16 v[92:95], v[164:167], v[208:211], v[92:95]
	v_mfma_f32_16x16x32_bf16 v[84:87], v[172:175], v[208:211], v[84:87]
	v_mfma_f32_16x16x32_bf16 v[76:79], v[164:167], v[216:219], v[76:79]
	v_mfma_f32_16x16x32_bf16 v[68:71], v[172:175], v[216:219], v[68:71]
	v_mfma_f32_16x16x32_bf16 v[128:131], v[168:171], v[184:187], v[128:131]
	v_mfma_f32_16x16x32_bf16 v[116:119], v[176:179], v[184:187], v[116:119]
	v_mfma_f32_16x16x32_bf16 v[108:111], v[168:171], v[204:207], v[108:111]
	v_mfma_f32_16x16x32_bf16 v[100:103], v[176:179], v[204:207], v[100:103]
	v_mfma_f32_16x16x32_bf16 v[92:95], v[168:171], v[212:215], v[92:95]
	v_mfma_f32_16x16x32_bf16 v[84:87], v[176:179], v[212:215], v[84:87]
	v_mfma_f32_16x16x32_bf16 v[76:79], v[168:171], v[220:223], v[76:79]
	v_mfma_f32_16x16x32_bf16 v[68:71], v[176:179], v[220:223], v[68:71]
	s_setprio 0
	s_barrier
	s_add_i32 s54, s60, s35
	v_lshl_add_u64 v[230:231], s[58:59], 0, v[134:135]
	s_mov_b32 m0, s54
	ds_read_b128 v[180:183], v147 offset:16384
	ds_read_b128 v[184:187], v147 offset:17408
	ds_read_b128 v[188:191], v147 offset:18432
	ds_read_b128 v[204:207], v147 offset:19456
	ds_read_b128 v[208:211], v147 offset:20480
	ds_read_b128 v[212:215], v147 offset:21504
	ds_read_b128 v[216:219], v147 offset:22528
	ds_read_b128 v[220:223], v147 offset:23552
	global_load_lds_dwordx4 v[230:231], off
	s_add_i32 m0, s54, 0x2000
	s_add_u32 s54, s58, s6
	v_lshl_add_u64 v[232:233], s[58:59], 0, v[0:1]
	s_addc_u32 s55, s59, s7
	s_add_i32 s58, s61, s35
	global_load_lds_dwordx4 v[232:233], off
	v_lshl_add_u64 v[238:239], s[54:55], 0, v[134:135]
	v_lshl_add_u64 v[240:241], s[54:55], 0, v[0:1]
	v_lshl_add_u64 v[242:243], s[24:25], 0, v[136:137]
	s_mov_b32 m0, s37
	v_lshl_add_u64 v[244:245], s[24:25], 0, v[132:133]
	global_load_lds_dwordx4 v[242:243], off
	s_mov_b32 m0, s38
	s_nop 0
	global_load_lds_dwordx4 v[244:245], off
	s_waitcnt vmcnt(6)
	s_waitcnt lgkmcnt(0)
	s_barrier
; #define PG8_STAGE(bufoff, gbase, voff) do { _Pragma("unroll") for (int _i = 0; _i < 2; ++_i) \
;         __builtin_amdgcn_global_load_lds((const unsigned*)((const char*)(gbase) + (voff)[_i]), (PG8_LAS unsigned*)(lds + (bufoff) + ldsw + _i * 8192), 16, 0, 0); } while (0)
; #define PG8_LDA(dst, b, h) do { _Pragma("unroll") for (int m = 0; m < 4; ++m) _Pragma("unroll") for (int k = 0; k < 2; ++k) dst[m][k] = *(const PG8_LAS bf16x8*)(lds + PG8_SA(b, h) + aoff + m * 2048 + k * 1024); } while (0)
; #define PG8_LDB(dst, b, h) do { _Pragma("unroll") for (int n = 0; n < 2; ++n) _Pragma("unroll") for (int k = 0; k < 2; ++k) dst[n][k] = *(const PG8_LAS bf16x8*)(lds + PG8_SB(b, h) + boff + n * 2048 + k * 1024); } while (0)
; #define PG8_MMA(ai, bj, At, Bt) do { __builtin_amdgcn_s_setprio(1); _Pragma("unroll") for (int m = 0; m < 4; ++m) _Pragma("unroll") for (int n = 0; n < 2; ++n) _Pragma("unroll") for (int k = 0; k < 2; ++k) \
;         acc[ai][bj][m][n] = __builtin_amdgcn_mfma_f32_16x16x32_bf16(Bt[n][k], At[m][k], acc[ai][bj][m][n], 0, 0, 0); __builtin_amdgcn_s_setprio(0); } while (0)
; #define PG8_WAIT_V(n) asm volatile("s_waitcnt vmcnt(" #n ")" ::: "memory")
; #define PG8_WAIT_L(n) asm volatile("s_waitcnt lgkmcnt(" #n ")" ::: "memory")
; #define PG8_BAR __builtin_amdgcn_s_barrier()
; #define PG8_SCHED __builtin_amdgcn_sched_barrier(0)
; template <class Epi, class Sched, bool ALIGN_EPI = false, bool SP2 = false>
; __device__ __forceinline__ void gemm_phase(PG8_LAS unsigned char* lds, const Gemm g, const Sched& S, const Epi& E, int tid_in) {
;     ...
;             PG8_WAIT_V(8); PG8_WAIT_L(0); PG8_BAR; PG8_MMA(1, 0, At, B0); PG8_MMA(1, 1, At, B1); PG8_BAR; PG8_SCHED;
;             PG8_LDB(B0, 1, 0); PG8_LDB(B1, 1, 1); PG8_SCHED; PG8_LDA(At, 1, 0); PG8_STAGE(PG8_SA(0, 1), a2 + hsA, voffA);
;             PG8_WAIT_V(8); PG8_WAIT_L(0); PG8_BAR; PG8_MMA(0, 0, At, B0); PG8_MMA(0, 1, At, B1); PG8_BAR; PG8_SCHED;
	s_setprio 1
	s_waitcnt lgkmcnt(0)
	v_mfma_f32_16x16x32_bf16 v[64:67], v[148:151], v[180:183], v[64:67]
	v_mfma_f32_16x16x32_bf16 v[56:59], v[156:159], v[180:183], v[56:59]
	v_mfma_f32_16x16x32_bf16 v[48:51], v[148:151], v[188:191], v[48:51]
	v_mfma_f32_16x16x32_bf16 v[40:43], v[156:159], v[188:191], v[40:43]
	v_mfma_f32_16x16x32_bf16 v[32:35], v[148:151], v[208:211], v[32:35]
	v_mfma_f32_16x16x32_bf16 v[24:27], v[156:159], v[208:211], v[24:27]
	v_mfma_f32_16x16x32_bf16 v[16:19], v[148:151], v[216:219], v[16:19]
	v_mfma_f32_16x16x32_bf16 v[8:11], v[156:159], v[216:219], v[8:11]
	v_mfma_f32_16x16x32_bf16 v[64:67], v[152:155], v[184:187], v[64:67]
	v_mfma_f32_16x16x32_bf16 v[56:59], v[160:163], v[184:187], v[56:59]
	v_mfma_f32_16x16x32_bf16 v[48:51], v[152:155], v[204:207], v[48:51]
	v_mfma_f32_16x16x32_bf16 v[40:43], v[160:163], v[204:207], v[40:43]
	v_mfma_f32_16x16x32_bf16 v[32:35], v[152:155], v[212:215], v[32:35]
	v_mfma_f32_16x16x32_bf16 v[24:27], v[160:163], v[212:215], v[24:27]
	v_mfma_f32_16x16x32_bf16 v[16:19], v[152:155], v[220:223], v[16:19]
	v_mfma_f32_16x16x32_bf16 v[8:11], v[160:163], v[220:223], v[8:11]
	s_setprio 0
	s_setprio 1
	v_mfma_f32_16x16x32_bf16 v[60:63], v[164:167], v[180:183], v[60:63]
	v_mfma_f32_16x16x32_bf16 v[52:55], v[172:175], v[180:183], v[52:55]
	v_mfma_f32_16x16x32_bf16 v[44:47], v[164:167], v[188:191], v[44:47]
	v_mfma_f32_16x16x32_bf16 v[36:39], v[172:175], v[188:191], v[36:39]
	v_mfma_f32_16x16x32_bf16 v[28:31], v[164:167], v[208:211], v[28:31]
	v_mfma_f32_16x16x32_bf16 v[20:23], v[172:175], v[208:211], v[20:23]
	v_mfma_f32_16x16x32_bf16 v[12:15], v[164:167], v[216:219], v[12:15]
	v_mfma_f32_16x16x32_bf16 v[4:7], v[172:175], v[216:219], v[4:7]
	v_mfma_f32_16x16x32_bf16 v[60:63], v[168:171], v[184:187], v[60:63]
	v_mfma_f32_16x16x32_bf16 v[52:55], v[176:179], v[184:187], v[52:55]
	v_mfma_f32_16x16x32_bf16 v[44:47], v[168:171], v[204:207], v[44:47]
	v_mfma_f32_16x16x32_bf16 v[36:39], v[176:179], v[204:207], v[36:39]
	v_mfma_f32_16x16x32_bf16 v[28:31], v[168:171], v[212:215], v[28:31]
	v_mfma_f32_16x16x32_bf16 v[20:23], v[176:179], v[212:215], v[20:23]
	v_mfma_f32_16x16x32_bf16 v[12:15], v[168:171], v[220:223], v[12:15]
	v_mfma_f32_16x16x32_bf16 v[4:7], v[176:179], v[220:223], v[4:7]
	s_setprio 0
	s_barrier
	s_add_i32 s54, 0, 0x18000
	s_add_i32 s55, 0, 0x1c000
	v_add_u32_e32 v160, s54, v142
	v_add_u32_e32 v176, s55, v142
	ds_read_b128 v[148:151], v160
	ds_read_b128 v[152:155], v160 offset:1024
	ds_read_b128 v[156:159], v160 offset:2048
	ds_read_b128 v[160:163], v160 offset:3072
	ds_read_b128 v[164:167], v176
	ds_read_b128 v[168:171], v176 offset:1024
	ds_read_b128 v[172:175], v176 offset:2048
	ds_read_b128 v[176:179], v176 offset:3072
	s_add_u32 s24, s24, s0
	s_addc_u32 s25, s25, s1
	s_mov_b32 m0, s39
	v_lshl_add_u64 v[246:247], s[24:25], 0, v[136:137]
	ds_read_b128 v[180:183], v147 offset:32768
	ds_read_b128 v[184:187], v147 offset:33792
	ds_read_b128 v[188:191], v147 offset:34816
	ds_read_b128 v[204:207], v147 offset:35840
	ds_read_b128 v[208:211], v147 offset:36864
	ds_read_b128 v[212:215], v147 offset:37888
	ds_read_b128 v[216:219], v147 offset:38912
	ds_read_b128 v[220:223], v147 offset:39936
	global_load_lds_dwordx4 v[246:247], off
	v_lshl_add_u64 v[246:247], s[24:25], 0, v[132:133]
	s_mov_b32 m0, s40
	s_nop 0
	global_load_lds_dwordx4 v[246:247], off
	s_add_i32 m0, s35, 0x14000
	s_nop 0
	global_load_lds_dwordx4 v[238:239], off
	s_add_i32 m0, s35, 0x16000
	s_nop 0
	global_load_lds_dwordx4 v[240:241], off
	s_waitcnt vmcnt(8)
	s_waitcnt lgkmcnt(0)
	s_barrier
	s_setprio 1
	s_waitcnt lgkmcnt(0)
	v_mfma_f32_16x16x32_bf16 v[124:127], v[148:151], v[180:183], v[124:127]
	v_mfma_f32_16x16x32_bf16 v[120:123], v[156:159], v[180:183], v[120:123]
	v_mfma_f32_16x16x32_bf16 v[112:115], v[148:151], v[188:191], v[112:115]
	v_mfma_f32_16x16x32_bf16 v[104:107], v[156:159], v[188:191], v[104:107]
	v_mfma_f32_16x16x32_bf16 v[96:99], v[148:151], v[208:211], v[96:99]
	v_mfma_f32_16x16x32_bf16 v[88:91], v[156:159], v[208:211], v[88:91]
	v_mfma_f32_16x16x32_bf16 v[80:83], v[148:151], v[216:219], v[80:83]
	v_mfma_f32_16x16x32_bf16 v[72:75], v[156:159], v[216:219], v[72:75]
	v_mfma_f32_16x16x32_bf16 v[124:127], v[152:155], v[184:187], v[124:127]
	v_mfma_f32_16x16x32_bf16 v[120:123], v[160:163], v[184:187], v[120:123]
	v_mfma_f32_16x16x32_bf16 v[112:115], v[152:155], v[204:207], v[112:115]
	v_mfma_f32_16x16x32_bf16 v[104:107], v[160:163], v[204:207], v[104:107]
	v_mfma_f32_16x16x32_bf16 v[96:99], v[152:155], v[212:215], v[96:99]
	v_mfma_f32_16x16x32_bf16 v[88:91], v[160:163], v[212:215], v[88:91]
	v_mfma_f32_16x16x32_bf16 v[80:83], v[152:155], v[220:223], v[80:83]
	v_mfma_f32_16x16x32_bf16 v[72:75], v[160:163], v[220:223], v[72:75]
	s_setprio 0
	s_setprio 1
	v_mfma_f32_16x16x32_bf16 v[128:131], v[164:167], v[180:183], v[128:131]
	v_mfma_f32_16x16x32_bf16 v[116:119], v[172:175], v[180:183], v[116:119]
	v_mfma_f32_16x16x32_bf16 v[108:111], v[164:167], v[188:191], v[108:111]
	v_mfma_f32_16x16x32_bf16 v[100:103], v[172:175], v[188:191], v[100:103]
	v_mfma_f32_16x16x32_bf16 v[92:95], v[164:167], v[208:211], v[92:95]
	v_mfma_f32_16x16x32_bf16 v[84:87], v[172:175], v[208:211], v[84:87]
	v_mfma_f32_16x16x32_bf16 v[76:79], v[164:167], v[216:219], v[76:79]
	v_mfma_f32_16x16x32_bf16 v[68:71], v[172:175], v[216:219], v[68:71]
	v_mfma_f32_16x16x32_bf16 v[128:131], v[168:171], v[184:187], v[128:131]
	v_mfma_f32_16x16x32_bf16 v[116:119], v[176:179], v[184:187], v[116:119]
	v_mfma_f32_16x16x32_bf16 v[108:111], v[168:171], v[204:207], v[108:111]
	v_mfma_f32_16x16x32_bf16 v[100:103], v[176:179], v[204:207], v[100:103]
	v_mfma_f32_16x16x32_bf16 v[92:95], v[168:171], v[212:215], v[92:95]
	v_mfma_f32_16x16x32_bf16 v[84:87], v[176:179], v[212:215], v[84:87]
	v_mfma_f32_16x16x32_bf16 v[76:79], v[168:171], v[220:223], v[76:79]
	v_mfma_f32_16x16x32_bf16 v[68:71], v[176:179], v[220:223], v[68:71]
	s_setprio 0
	s_barrier
; #define PG8_STAGE(bufoff, gbase, voff) do { _Pragma("unroll") for (int _i = 0; _i < 2; ++_i) \
;         __builtin_amdgcn_global_load_lds((const unsigned*)((const char*)(gbase) + (voff)[_i]), (PG8_LAS unsigned*)(lds + (bufoff) + ldsw + _i * 8192), 16, 0, 0); } while (0)
; #define PG8_LDA(dst, b, h) do { _Pragma("unroll") for (int m = 0; m < 4; ++m) _Pragma("unroll") for (int k = 0; k < 2; ++k) dst[m][k] = *(const PG8_LAS bf16x8*)(lds + PG8_SA(b, h) + aoff + m * 2048 + k * 1024); } while (0)
; #define PG8_MMA(ai, bj, At, Bt) do { __builtin_amdgcn_s_setprio(1); _Pragma("unroll") for (int m = 0; m < 4; ++m) _Pragma("unroll") for (int n = 0; n < 2; ++n) _Pragma("unroll") for (int k = 0; k < 2; ++k) \
;         acc[ai][bj][m][n] = __builtin_amdgcn_mfma_f32_16x16x32_bf16(Bt[n][k], At[m][k], acc[ai][bj][m][n], 0, 0, 0); __builtin_amdgcn_s_setprio(0); } while (0)
; #define PG8_WAIT_V(n) asm volatile("s_waitcnt vmcnt(" #n ")" ::: "memory")
; #define PG8_WAIT_L(n) asm volatile("s_waitcnt lgkmcnt(" #n ")" ::: "memory")
; #define PG8_BAR __builtin_amdgcn_s_barrier()
; #define PG8_SCHED __builtin_amdgcn_sched_barrier(0)
; template <class Epi, class Sched, bool ALIGN_EPI = false, bool SP2 = false>
; __device__ __forceinline__ void gemm_phase(PG8_LAS unsigned char* lds, const Gemm g, const Sched& S, const Epi& E, int tid_in) {
;     ...
;         for (int t = 0; t < nt; t += 2) {
;     ...
;             PG8_LDA(At, 1, 1); PG8_STAGE(PG8_SB(1, 0), b3, voffB); PG8_STAGE(PG8_SB(1, 1), b3 + hsB, voffB); PG8_STAGE(PG8_SA(1, 0), a3, voffA);
;             PG8_WAIT_V(8); PG8_WAIT_L(0); PG8_BAR; PG8_MMA(1, 0, At, B0); PG8_MMA(1, 1, At, B1); PG8_BAR; PG8_SCHED;
	s_add_i32 s24, s54, s35
	v_lshl_add_u64 v[230:231], v[230:231], 0, s[80:81]
	s_mov_b32 m0, s24
	ds_read_b128 v[180:183], v147 offset:49152
	ds_read_b128 v[184:187], v147 offset:50176
	ds_read_b128 v[188:191], v147 offset:51200
	ds_read_b128 v[204:207], v147 offset:52224
	ds_read_b128 v[208:211], v147 offset:53248
	ds_read_b128 v[212:215], v147 offset:54272
	ds_read_b128 v[216:219], v147 offset:55296
	ds_read_b128 v[220:223], v147 offset:56320
	global_load_lds_dwordx4 v[230:231], off
	v_lshl_add_u64 v[230:231], v[232:233], 0, s[80:81]
	s_add_i32 m0, s24, 0x2000
	s_add_i32 s24, s55, s35
	global_load_lds_dwordx4 v[230:231], off
	v_lshl_add_u64 v[230:231], v[238:239], 0, s[80:81]
	s_mov_b32 m0, s24
	s_nop 0
	global_load_lds_dwordx4 v[230:231], off
	v_lshl_add_u64 v[230:231], v[240:241], 0, s[80:81]
	s_add_i32 m0, s24, 0x2000
	s_nop 0
	global_load_lds_dwordx4 v[230:231], off
	v_lshl_add_u64 v[230:231], v[242:243], 0, s[80:81]
	s_mov_b32 m0, s41
	s_nop 0
	global_load_lds_dwordx4 v[230:231], off
	v_lshl_add_u64 v[230:231], v[244:245], 0, s[80:81]
	s_mov_b32 m0, s42
	s_nop 0
	global_load_lds_dwordx4 v[230:231], off
	s_waitcnt vmcnt(6)
	s_waitcnt lgkmcnt(0)
	s_barrier
	s_setprio 1
	s_waitcnt lgkmcnt(0)
	v_mfma_f32_16x16x32_bf16 v[64:67], v[148:151], v[180:183], v[64:67]
	v_mfma_f32_16x16x32_bf16 v[56:59], v[156:159], v[180:183], v[56:59]
	v_mfma_f32_16x16x32_bf16 v[48:51], v[148:151], v[188:191], v[48:51]
	v_mfma_f32_16x16x32_bf16 v[40:43], v[156:159], v[188:191], v[40:43]
	v_mfma_f32_16x16x32_bf16 v[32:35], v[148:151], v[208:211], v[32:35]
	v_mfma_f32_16x16x32_bf16 v[24:27], v[156:159], v[208:211], v[24:27]
	v_mfma_f32_16x16x32_bf16 v[16:19], v[148:151], v[216:219], v[16:19]
	v_mfma_f32_16x16x32_bf16 v[8:11], v[156:159], v[216:219], v[8:11]
	v_mfma_f32_16x16x32_bf16 v[64:67], v[152:155], v[184:187], v[64:67]
	v_mfma_f32_16x16x32_bf16 v[56:59], v[160:163], v[184:187], v[56:59]
	v_mfma_f32_16x16x32_bf16 v[48:51], v[152:155], v[204:207], v[48:51]
	v_mfma_f32_16x16x32_bf16 v[40:43], v[160:163], v[204:207], v[40:43]
	v_mfma_f32_16x16x32_bf16 v[32:35], v[152:155], v[212:215], v[32:35]
	v_mfma_f32_16x16x32_bf16 v[24:27], v[160:163], v[212:215], v[24:27]
	v_mfma_f32_16x16x32_bf16 v[16:19], v[152:155], v[220:223], v[16:19]
	v_mfma_f32_16x16x32_bf16 v[8:11], v[160:163], v[220:223], v[8:11]
	s_setprio 0
	s_setprio 1
	v_mfma_f32_16x16x32_bf16 v[60:63], v[164:167], v[180:183], v[60:63]
	v_mfma_f32_16x16x32_bf16 v[52:55], v[172:175], v[180:183], v[52:55]
	v_mfma_f32_16x16x32_bf16 v[44:47], v[164:167], v[188:191], v[44:47]
	v_mfma_f32_16x16x32_bf16 v[36:39], v[172:175], v[188:191], v[36:39]
	v_mfma_f32_16x16x32_bf16 v[28:31], v[164:167], v[208:211], v[28:31]
	v_mfma_f32_16x16x32_bf16 v[20:23], v[172:175], v[208:211], v[20:23]
	v_mfma_f32_16x16x32_bf16 v[12:15], v[164:167], v[216:219], v[12:15]
	v_mfma_f32_16x16x32_bf16 v[4:7], v[172:175], v[216:219], v[4:7]
	v_mfma_f32_16x16x32_bf16 v[60:63], v[168:171], v[184:187], v[60:63]
	v_mfma_f32_16x16x32_bf16 v[52:55], v[176:179], v[184:187], v[52:55]
	v_mfma_f32_16x16x32_bf16 v[44:47], v[168:171], v[204:207], v[44:47]
	v_mfma_f32_16x16x32_bf16 v[36:39], v[176:179], v[204:207], v[36:39]
	v_mfma_f32_16x16x32_bf16 v[28:31], v[168:171], v[212:215], v[28:31]
	v_mfma_f32_16x16x32_bf16 v[20:23], v[176:179], v[212:215], v[20:23]
	v_mfma_f32_16x16x32_bf16 v[12:15], v[168:171], v[220:223], v[12:15]
	v_mfma_f32_16x16x32_bf16 v[4:7], v[176:179], v[220:223], v[4:7]
	s_setprio 0
	s_barrier
	s_add_i32 s24, s53, 2
	s_add_u32 s51, s51, 0x100
	s_addc_u32 s52, s52, 0
	s_add_u32 s22, s22, 0x100
	s_addc_u32 s23, s23, 0
	s_cmp_ge_i32 s53, s43
	s_mov_b32 s53, s24
	s_cbranch_scc0 .LBB0_244

; #define PG8_STAGE(bufoff, gbase, voff) do { _Pragma("unroll") for (int _i = 0; _i < 2; ++_i) \
;         __builtin_amdgcn_global_load_lds((const unsigned*)((const char*)(gbase) + (voff)[_i]), (PG8_LAS unsigned*)(lds + (bufoff) + ldsw + _i * 8192), 16, 0, 0); } while (0)
; #define PG8_LDA(dst, b, h) do { _Pragma("unroll") for (int m = 0; m < 4; ++m) _Pragma("unroll") for (int k = 0; k < 2; ++k) dst[m][k] = *(const PG8_LAS bf16x8*)(lds + PG8_SA(b, h) + aoff + m * 2048 + k * 1024); } while (0)
; #define PG8_LDB(dst, b, h) do { _Pragma("unroll") for (int n = 0; n < 2; ++n) _Pragma("unroll") for (int k = 0; k < 2; ++k) dst[n][k] = *(const PG8_LAS bf16x8*)(lds + PG8_SB(b, h) + boff + n * 2048 + k * 1024); } while (0)
; #define PG8_MMA(ai, bj, At, Bt) do { __builtin_amdgcn_s_setprio(1); _Pragma("unroll") for (int m = 0; m < 4; ++m) _Pragma("unroll") for (int n = 0; n < 2; ++n) _Pragma("unroll") for (int k = 0; k < 2; ++k) \
;         acc[ai][bj][m][n] = __builtin_amdgcn_mfma_f32_16x16x32_bf16(Bt[n][k], At[m][k], acc[ai][bj][m][n], 0, 0, 0); __builtin_amdgcn_s_setprio(0); } while (0)
; template <class Epi, class Sched, bool ALIGN_EPI = false, bool SP2 = false>
; __device__ __forceinline__ void gemm_phase(PG8_LAS unsigned char* lds, const Gemm g, const Sched& S, const Epi& E, int tid_in) {
;     ...
;             const bool last = (t == nt - 2);
;             if constexpr (mid_hook<Epi>::value) { if (t == Epi::H1 || t == Epi::H2) E.mid(acc, cur, wr, wc, fr, fq, t == Epi::H2); }
;             const char* a1 = cA + (size_t)(t + 1) * kstep + (t >= jt ? jb : 0);
;             const char* a2 = last ? nA : cA + (size_t)(t + 2) * kstep + (t + 2 >= jt ? jb : 0); const char* b2 = last ? nB : cB + (size_t)(t + 2) * kstep;
;             const char* a3 = a2 + kstep; const char* b3 = b2 + kstep;
;             if (last && has_next) S.a_ready(nxt);
;             if constexpr (SP2) {
;             PG8_LDB(B0, 0, 0); PG8_LDB(B1, 0, 1); PG8_SCHED; PG8_LDA(At, 0, 0); PG8_STAGE(PG8_SA(1, 1), a1 + hsA, voffA);
;             PG8_WAIT_V(8); PG8_WAIT_L(0); PG8_BAR; PG8_MMA(0, 0, At, B0); PG8_MMA(0, 1, At, B1); PG8_BAR; PG8_SCHED;
;             PG8_LDA(At, 0, 1); PG8_STAGE(PG8_SB(0, 0), b2, voffB); PG8_STAGE(PG8_SB(0, 1), b2 + hsB, voffB); PG8_STAGE(PG8_SA(0, 0), a2, voffA);
;             PG8_WAIT_V(8); PG8_WAIT_L(0); PG8_BAR; PG8_MMA(1, 0, At, B0); PG8_MMA(1, 1, At, B1); PG8_BAR; PG8_SCHED;
.LBB0_321:
	s_add_i32 s40, s42, -2
	s_cmp_ge_i32 s40, s33
	s_cselect_b32 s78, s49, 0
	s_cselect_b32 s79, s65, 0
	s_cmp_ge_i32 s42, s33
	s_cselect_b32 s41, s49, 0
	s_cselect_b32 s40, s65, 0
	s_add_u32 s41, s4, s41
	s_addc_u32 s40, s5, s40
	s_add_u32 s43, s41, 0x80
	s_addc_u32 s40, s40, 0
	s_add_i32 s84, 0, 0x10000
	s_cmp_eq_u32 s64, s42
	s_cselect_b32 s41, s37, s40
	s_cselect_b32 s40, s36, s43
	s_cselect_b32 s83, s39, s77
	s_cselect_b32 s82, s38, s76
	s_add_i32 s43, 0, 0x14000
	v_add_u32_e32 v144, s84, v219
	v_add_u32_e32 v170, s43, v219
	ds_read_b128 v[132:135], v144
	ds_read_b128 v[136:139], v144 offset:1024
	ds_read_b128 v[140:143], v144 offset:2048
	ds_read_b128 v[144:147], v144 offset:3072
	ds_read_b128 v[148:151], v170
	ds_read_b128 v[162:165], v170 offset:1024
	ds_read_b128 v[166:169], v170 offset:2048
	ds_read_b128 v[170:173], v170 offset:3072
	v_lshl_add_u64 v[190:191], s[4:5], 0, v[160:161]
	v_lshl_add_u64 v[190:191], v[190:191], 0, s[78:79]
	s_add_i32 m0, s53, 0xc000
	ds_read_b128 v[174:177], v221
	ds_read_b128 v[178:181], v221 offset:1024
	ds_read_b128 v[182:185], v221 offset:2048
	ds_read_b128 v[186:189], v221 offset:3072
	ds_read_b128 v[204:207], v221 offset:4096
	ds_read_b128 v[208:211], v221 offset:5120
	ds_read_b128 v[212:215], v221 offset:6144
	ds_read_b128 v[238:241], v221 offset:7168
	global_load_lds_dwordx4 v[190:191], off
	v_lshl_add_u64 v[190:191], s[4:5], 0, v[158:159]
	v_lshl_add_u64 v[190:191], v[190:191], 0, s[78:79]
	s_add_i32 m0, s53, 0xe000
	s_nop 0
	global_load_lds_dwordx4 v[190:191], off
	s_waitcnt vmcnt(8)
	s_waitcnt lgkmcnt(0)
	s_barrier
	s_setprio 1
	s_waitcnt lgkmcnt(0)
	v_mfma_f32_16x16x32_bf16 v[128:131], v[132:135], v[174:177], v[128:131]
	v_mfma_f32_16x16x32_bf16 v[124:127], v[140:143], v[174:177], v[124:127]
	v_mfma_f32_16x16x32_bf16 v[120:123], v[132:135], v[182:185], v[120:123]
	v_mfma_f32_16x16x32_bf16 v[116:119], v[140:143], v[182:185], v[116:119]
	v_mfma_f32_16x16x32_bf16 v[112:115], v[132:135], v[204:207], v[112:115]
	v_mfma_f32_16x16x32_bf16 v[108:111], v[140:143], v[204:207], v[108:111]
	v_mfma_f32_16x16x32_bf16 v[104:107], v[132:135], v[212:215], v[104:107]
	v_mfma_f32_16x16x32_bf16 v[100:103], v[140:143], v[212:215], v[100:103]
	v_mfma_f32_16x16x32_bf16 v[128:131], v[136:139], v[178:181], v[128:131]
	v_mfma_f32_16x16x32_bf16 v[124:127], v[144:147], v[178:181], v[124:127]
	v_mfma_f32_16x16x32_bf16 v[120:123], v[136:139], v[186:189], v[120:123]
	v_mfma_f32_16x16x32_bf16 v[116:119], v[144:147], v[186:189], v[116:119]
	v_mfma_f32_16x16x32_bf16 v[112:115], v[136:139], v[208:211], v[112:115]
	v_mfma_f32_16x16x32_bf16 v[108:111], v[144:147], v[208:211], v[108:111]
	v_mfma_f32_16x16x32_bf16 v[104:107], v[136:139], v[238:241], v[104:107]
	v_mfma_f32_16x16x32_bf16 v[100:103], v[144:147], v[238:241], v[100:103]
	s_setprio 0
	s_setprio 1
	v_mfma_f32_16x16x32_bf16 v[64:67], v[148:151], v[174:177], v[64:67]
	v_mfma_f32_16x16x32_bf16 v[56:59], v[166:169], v[174:177], v[56:59]
	v_mfma_f32_16x16x32_bf16 v[60:63], v[148:151], v[182:185], v[60:63]
	v_mfma_f32_16x16x32_bf16 v[52:55], v[166:169], v[182:185], v[52:55]
	v_mfma_f32_16x16x32_bf16 v[48:51], v[148:151], v[204:207], v[48:51]
	v_mfma_f32_16x16x32_bf16 v[40:43], v[166:169], v[204:207], v[40:43]
	v_mfma_f32_16x16x32_bf16 v[44:47], v[148:151], v[212:215], v[44:47]
	v_mfma_f32_16x16x32_bf16 v[36:39], v[166:169], v[212:215], v[36:39]
	v_mfma_f32_16x16x32_bf16 v[64:67], v[162:165], v[178:181], v[64:67]
	v_mfma_f32_16x16x32_bf16 v[56:59], v[170:173], v[178:181], v[56:59]
	v_mfma_f32_16x16x32_bf16 v[60:63], v[162:165], v[186:189], v[60:63]
	v_mfma_f32_16x16x32_bf16 v[52:55], v[170:173], v[186:189], v[52:55]
	v_mfma_f32_16x16x32_bf16 v[48:51], v[162:165], v[208:211], v[48:51]
	v_mfma_f32_16x16x32_bf16 v[40:43], v[170:173], v[208:211], v[40:43]
	v_mfma_f32_16x16x32_bf16 v[44:47], v[162:165], v[238:241], v[44:47]
	v_mfma_f32_16x16x32_bf16 v[36:39], v[170:173], v[238:241], v[36:39]
	s_setprio 0
	s_barrier
	s_add_i32 s78, s84, s52
	v_lshl_add_u64 v[190:191], s[82:83], 0, v[152:153]
	s_mov_b32 m0, s78
	ds_read_b128 v[174:177], v221 offset:16384
	ds_read_b128 v[178:181], v221 offset:17408
	ds_read_b128 v[182:185], v221 offset:18432
	ds_read_b128 v[186:189], v221 offset:19456
	ds_read_b128 v[204:207], v221 offset:20480
	ds_read_b128 v[208:211], v221 offset:21504
	ds_read_b128 v[212:215], v221 offset:22528
	ds_read_b128 v[238:241], v221 offset:23552
	global_load_lds_dwordx4 v[190:191], off
	s_add_i32 m0, s78, 0x2000
	s_add_u32 s78, s82, s12
	v_lshl_add_u64 v[216:217], s[82:83], 0, v[156:157]
	s_addc_u32 s79, s83, s13
	s_add_i32 s43, s43, s52
	global_load_lds_dwordx4 v[216:217], off
	v_lshl_add_u64 v[222:223], s[78:79], 0, v[152:153]
	v_lshl_add_u64 v[230:231], s[78:79], 0, v[156:157]
	v_lshl_add_u64 v[232:233], s[40:41], 0, v[0:1]
	s_mov_b32 m0, s53
	v_lshl_add_u64 v[242:243], s[40:41], 0, v[154:155]
	global_load_lds_dwordx4 v[232:233], off
	s_mov_b32 m0, s54
	s_nop 0
	global_load_lds_dwordx4 v[242:243], off
	s_waitcnt vmcnt(6)
	s_waitcnt lgkmcnt(0)
	s_barrier
; #define PG8_STAGE(bufoff, gbase, voff) do { _Pragma("unroll") for (int _i = 0; _i < 2; ++_i) \
;         __builtin_amdgcn_global_load_lds((const unsigned*)((const char*)(gbase) + (voff)[_i]), (PG8_LAS unsigned*)(lds + (bufoff) + ldsw + _i * 8192), 16, 0, 0); } while (0)
; #define PG8_LDA(dst, b, h) do { _Pragma("unroll") for (int m = 0; m < 4; ++m) _Pragma("unroll") for (int k = 0; k < 2; ++k) dst[m][k] = *(const PG8_LAS bf16x8*)(lds + PG8_SA(b, h) + aoff + m * 2048 + k * 1024); } while (0)
; #define PG8_LDB(dst, b, h) do { _Pragma("unroll") for (int n = 0; n < 2; ++n) _Pragma("unroll") for (int k = 0; k < 2; ++k) dst[n][k] = *(const PG8_LAS bf16x8*)(lds + PG8_SB(b, h) + boff + n * 2048 + k * 1024); } while (0)
; #define PG8_MMA(ai, bj, At, Bt) do { __builtin_amdgcn_s_setprio(1); _Pragma("unroll") for (int m = 0; m < 4; ++m) _Pragma("unroll") for (int n = 0; n < 2; ++n) _Pragma("unroll") for (int k = 0; k < 2; ++k) \
;         acc[ai][bj][m][n] = __builtin_amdgcn_mfma_f32_16x16x32_bf16(Bt[n][k], At[m][k], acc[ai][bj][m][n], 0, 0, 0); __builtin_amdgcn_s_setprio(0); } while (0)
; #define PG8_WAIT_V(n) asm volatile("s_waitcnt vmcnt(" #n ")" ::: "memory")
; #define PG8_WAIT_L(n) asm volatile("s_waitcnt lgkmcnt(" #n ")" ::: "memory")
; #define PG8_BAR __builtin_amdgcn_s_barrier()
; #define PG8_SCHED __builtin_amdgcn_sched_barrier(0)
; template <class Epi, class Sched, bool ALIGN_EPI = false, bool SP2 = false>
; __device__ __forceinline__ void gemm_phase(PG8_LAS unsigned char* lds, const Gemm g, const Sched& S, const Epi& E, int tid_in) {
;     ...
;             PG8_WAIT_V(8); PG8_WAIT_L(0); PG8_BAR; PG8_MMA(1, 0, At, B0); PG8_MMA(1, 1, At, B1); PG8_BAR; PG8_SCHED;
;             PG8_LDB(B0, 1, 0); PG8_LDB(B1, 1, 1); PG8_SCHED; PG8_LDA(At, 1, 0); PG8_STAGE(PG8_SA(0, 1), a2 + hsA, voffA);
;             PG8_WAIT_V(8); PG8_WAIT_L(0); PG8_BAR; PG8_MMA(0, 0, At, B0); PG8_MMA(0, 1, At, B1); PG8_BAR; PG8_SCHED;
	s_setprio 1
	s_waitcnt lgkmcnt(0)
	v_mfma_f32_16x16x32_bf16 v[96:99], v[132:135], v[174:177], v[96:99]
	v_mfma_f32_16x16x32_bf16 v[92:95], v[140:143], v[174:177], v[92:95]
	v_mfma_f32_16x16x32_bf16 v[88:91], v[132:135], v[182:185], v[88:91]
	v_mfma_f32_16x16x32_bf16 v[84:87], v[140:143], v[182:185], v[84:87]
	v_mfma_f32_16x16x32_bf16 v[80:83], v[132:135], v[204:207], v[80:83]
	v_mfma_f32_16x16x32_bf16 v[76:79], v[140:143], v[204:207], v[76:79]
	v_mfma_f32_16x16x32_bf16 v[72:75], v[132:135], v[212:215], v[72:75]
	v_mfma_f32_16x16x32_bf16 v[68:71], v[140:143], v[212:215], v[68:71]
	v_mfma_f32_16x16x32_bf16 v[96:99], v[136:139], v[178:181], v[96:99]
	v_mfma_f32_16x16x32_bf16 v[92:95], v[144:147], v[178:181], v[92:95]
	v_mfma_f32_16x16x32_bf16 v[88:91], v[136:139], v[186:189], v[88:91]
	v_mfma_f32_16x16x32_bf16 v[84:87], v[144:147], v[186:189], v[84:87]
	v_mfma_f32_16x16x32_bf16 v[80:83], v[136:139], v[208:211], v[80:83]
	v_mfma_f32_16x16x32_bf16 v[76:79], v[144:147], v[208:211], v[76:79]
	v_mfma_f32_16x16x32_bf16 v[72:75], v[136:139], v[238:241], v[72:75]
	v_mfma_f32_16x16x32_bf16 v[68:71], v[144:147], v[238:241], v[68:71]
	s_setprio 0
	s_setprio 1
	v_mfma_f32_16x16x32_bf16 v[32:35], v[148:151], v[174:177], v[32:35]
	v_mfma_f32_16x16x32_bf16 v[28:31], v[166:169], v[174:177], v[28:31]
	v_mfma_f32_16x16x32_bf16 v[24:27], v[148:151], v[182:185], v[24:27]
	v_mfma_f32_16x16x32_bf16 v[12:15], v[166:169], v[182:185], v[12:15]
	v_mfma_f32_16x16x32_bf16 v[20:23], v[148:151], v[204:207], v[20:23]
	v_mfma_f32_16x16x32_bf16 v[8:11], v[166:169], v[204:207], v[8:11]
	v_mfma_f32_16x16x32_bf16 v[16:19], v[148:151], v[212:215], v[16:19]
	v_mfma_f32_16x16x32_bf16 v[4:7], v[166:169], v[212:215], v[4:7]
	v_mfma_f32_16x16x32_bf16 v[32:35], v[162:165], v[178:181], v[32:35]
	v_mfma_f32_16x16x32_bf16 v[28:31], v[170:173], v[178:181], v[28:31]
	v_mfma_f32_16x16x32_bf16 v[24:27], v[162:165], v[186:189], v[24:27]
	v_mfma_f32_16x16x32_bf16 v[12:15], v[170:173], v[186:189], v[12:15]
	v_mfma_f32_16x16x32_bf16 v[20:23], v[162:165], v[208:211], v[20:23]
	v_mfma_f32_16x16x32_bf16 v[8:11], v[170:173], v[208:211], v[8:11]
	v_mfma_f32_16x16x32_bf16 v[16:19], v[162:165], v[238:241], v[16:19]
	v_mfma_f32_16x16x32_bf16 v[4:7], v[170:173], v[238:241], v[4:7]
	s_setprio 0
	s_barrier
	s_add_i32 s43, 0, 0x18000
	s_add_i32 s78, 0, 0x1c000
	v_add_u32_e32 v144, s43, v219
	v_add_u32_e32 v170, s78, v219
	ds_read_b128 v[132:135], v144
	ds_read_b128 v[136:139], v144 offset:1024
	ds_read_b128 v[140:143], v144 offset:2048
	ds_read_b128 v[144:147], v144 offset:3072
	ds_read_b128 v[148:151], v170
	ds_read_b128 v[162:165], v170 offset:1024
	ds_read_b128 v[166:169], v170 offset:2048
	ds_read_b128 v[170:173], v170 offset:3072
	s_add_u32 s40, s40, s10
	s_addc_u32 s41, s41, s11
	s_mov_b32 m0, s55
	v_lshl_add_u64 v[244:245], s[40:41], 0, v[0:1]
	ds_read_b128 v[174:177], v221 offset:32768
	ds_read_b128 v[178:181], v221 offset:33792
	ds_read_b128 v[182:185], v221 offset:34816
	ds_read_b128 v[186:189], v221 offset:35840
	ds_read_b128 v[204:207], v221 offset:36864
	ds_read_b128 v[208:211], v221 offset:37888
	ds_read_b128 v[212:215], v221 offset:38912
	ds_read_b128 v[238:241], v221 offset:39936
	global_load_lds_dwordx4 v[244:245], off
	v_lshl_add_u64 v[244:245], s[40:41], 0, v[154:155]
	s_mov_b32 m0, s58
	s_nop 0
	global_load_lds_dwordx4 v[244:245], off
	s_add_i32 m0, s52, 0x14000
	s_nop 0
	global_load_lds_dwordx4 v[222:223], off
	s_add_i32 m0, s52, 0x16000
	s_nop 0
	global_load_lds_dwordx4 v[230:231], off
	s_waitcnt vmcnt(8)
	s_waitcnt lgkmcnt(0)
	s_barrier
	s_setprio 1
	s_waitcnt lgkmcnt(0)
	v_mfma_f32_16x16x32_bf16 v[128:131], v[132:135], v[174:177], v[128:131]
	v_mfma_f32_16x16x32_bf16 v[124:127], v[140:143], v[174:177], v[124:127]
	v_mfma_f32_16x16x32_bf16 v[120:123], v[132:135], v[182:185], v[120:123]
	v_mfma_f32_16x16x32_bf16 v[116:119], v[140:143], v[182:185], v[116:119]
	v_mfma_f32_16x16x32_bf16 v[112:115], v[132:135], v[204:207], v[112:115]
	v_mfma_f32_16x16x32_bf16 v[108:111], v[140:143], v[204:207], v[108:111]
	v_mfma_f32_16x16x32_bf16 v[104:107], v[132:135], v[212:215], v[104:107]
	v_mfma_f32_16x16x32_bf16 v[100:103], v[140:143], v[212:215], v[100:103]
	v_mfma_f32_16x16x32_bf16 v[128:131], v[136:139], v[178:181], v[128:131]
	v_mfma_f32_16x16x32_bf16 v[124:127], v[144:147], v[178:181], v[124:127]
	v_mfma_f32_16x16x32_bf16 v[120:123], v[136:139], v[186:189], v[120:123]
	v_mfma_f32_16x16x32_bf16 v[116:119], v[144:147], v[186:189], v[116:119]
	v_mfma_f32_16x16x32_bf16 v[112:115], v[136:139], v[208:211], v[112:115]
	v_mfma_f32_16x16x32_bf16 v[108:111], v[144:147], v[208:211], v[108:111]
	v_mfma_f32_16x16x32_bf16 v[104:107], v[136:139], v[238:241], v[104:107]
	v_mfma_f32_16x16x32_bf16 v[100:103], v[144:147], v[238:241], v[100:103]
	s_setprio 0
	s_setprio 1
	v_mfma_f32_16x16x32_bf16 v[64:67], v[148:151], v[174:177], v[64:67]
	v_mfma_f32_16x16x32_bf16 v[56:59], v[166:169], v[174:177], v[56:59]
	v_mfma_f32_16x16x32_bf16 v[60:63], v[148:151], v[182:185], v[60:63]
	v_mfma_f32_16x16x32_bf16 v[52:55], v[166:169], v[182:185], v[52:55]
	v_mfma_f32_16x16x32_bf16 v[48:51], v[148:151], v[204:207], v[48:51]
	v_mfma_f32_16x16x32_bf16 v[40:43], v[166:169], v[204:207], v[40:43]
	v_mfma_f32_16x16x32_bf16 v[44:47], v[148:151], v[212:215], v[44:47]
	v_mfma_f32_16x16x32_bf16 v[36:39], v[166:169], v[212:215], v[36:39]
	v_mfma_f32_16x16x32_bf16 v[64:67], v[162:165], v[178:181], v[64:67]
	v_mfma_f32_16x16x32_bf16 v[56:59], v[170:173], v[178:181], v[56:59]
	v_mfma_f32_16x16x32_bf16 v[60:63], v[162:165], v[186:189], v[60:63]
	v_mfma_f32_16x16x32_bf16 v[52:55], v[170:173], v[186:189], v[52:55]
	v_mfma_f32_16x16x32_bf16 v[48:51], v[162:165], v[208:211], v[48:51]
	v_mfma_f32_16x16x32_bf16 v[40:43], v[170:173], v[208:211], v[40:43]
	v_mfma_f32_16x16x32_bf16 v[44:47], v[162:165], v[238:241], v[44:47]
	v_mfma_f32_16x16x32_bf16 v[36:39], v[170:173], v[238:241], v[36:39]
	s_setprio 0
	s_barrier
; #define PG8_STAGE(bufoff, gbase, voff) do { _Pragma("unroll") for (int _i = 0; _i < 2; ++_i) \
;         __builtin_amdgcn_global_load_lds((const unsigned*)((const char*)(gbase) + (voff)[_i]), (PG8_LAS unsigned*)(lds + (bufoff) + ldsw + _i * 8192), 16, 0, 0); } while (0)
; #define PG8_LDA(dst, b, h) do { _Pragma("unroll") for (int m = 0; m < 4; ++m) _Pragma("unroll") for (int k = 0; k < 2; ++k) dst[m][k] = *(const PG8_LAS bf16x8*)(lds + PG8_SA(b, h) + aoff + m * 2048 + k * 1024); } while (0)
; #define PG8_MMA(ai, bj, At, Bt) do { __builtin_amdgcn_s_setprio(1); _Pragma("unroll") for (int m = 0; m < 4; ++m) _Pragma("unroll") for (int n = 0; n < 2; ++n) _Pragma("unroll") for (int k = 0; k < 2; ++k) \
;         acc[ai][bj][m][n] = __builtin_amdgcn_mfma_f32_16x16x32_bf16(Bt[n][k], At[m][k], acc[ai][bj][m][n], 0, 0, 0); __builtin_amdgcn_s_setprio(0); } while (0)
; #define PG8_WAIT_V(n) asm volatile("s_waitcnt vmcnt(" #n ")" ::: "memory")
; #define PG8_WAIT_L(n) asm volatile("s_waitcnt lgkmcnt(" #n ")" ::: "memory")
; #define PG8_BAR __builtin_amdgcn_s_barrier()
; #define PG8_SCHED __builtin_amdgcn_sched_barrier(0)
; template <class Epi, class Sched, bool ALIGN_EPI = false, bool SP2 = false>
; __device__ __forceinline__ void gemm_phase(PG8_LAS unsigned char* lds, const Gemm g, const Sched& S, const Epi& E, int tid_in) {
;     ...
;         for (int t = 0; t < nt; t += 2) {
;     ...
;             PG8_LDA(At, 1, 1); PG8_STAGE(PG8_SB(1, 0), b3, voffB); PG8_STAGE(PG8_SB(1, 1), b3 + hsB, voffB); PG8_STAGE(PG8_SA(1, 0), a3, voffA);
;             PG8_WAIT_V(8); PG8_WAIT_L(0); PG8_BAR; PG8_MMA(1, 0, At, B0); PG8_MMA(1, 1, At, B1); PG8_BAR; PG8_SCHED;
	s_add_i32 s40, s43, s52
	v_lshl_add_u64 v[190:191], v[190:191], 0, s[80:81]
	s_mov_b32 m0, s40
	ds_read_b128 v[174:177], v221 offset:49152
	ds_read_b128 v[178:181], v221 offset:50176
	ds_read_b128 v[182:185], v221 offset:51200
	ds_read_b128 v[186:189], v221 offset:52224
	ds_read_b128 v[204:207], v221 offset:53248
	ds_read_b128 v[208:211], v221 offset:54272
	ds_read_b128 v[212:215], v221 offset:55296
	ds_read_b128 v[238:241], v221 offset:56320
	global_load_lds_dwordx4 v[190:191], off
	v_lshl_add_u64 v[190:191], v[216:217], 0, s[80:81]
	s_add_i32 m0, s40, 0x2000
	s_add_i32 s40, s78, s52
	global_load_lds_dwordx4 v[190:191], off
	v_lshl_add_u64 v[190:191], v[222:223], 0, s[80:81]
	s_mov_b32 m0, s40
	s_nop 0
	global_load_lds_dwordx4 v[190:191], off
	v_lshl_add_u64 v[190:191], v[230:231], 0, s[80:81]
	s_add_i32 m0, s40, 0x2000
	s_nop 0
	global_load_lds_dwordx4 v[190:191], off
	v_lshl_add_u64 v[190:191], v[232:233], 0, s[80:81]
	s_mov_b32 m0, s61
	s_nop 0
	global_load_lds_dwordx4 v[190:191], off
	v_lshl_add_u64 v[190:191], v[242:243], 0, s[80:81]
	s_mov_b32 m0, s62
	s_nop 0
	global_load_lds_dwordx4 v[190:191], off
	s_waitcnt vmcnt(6)
	s_waitcnt lgkmcnt(0)
	s_barrier
	s_setprio 1
	s_waitcnt lgkmcnt(0)
	v_mfma_f32_16x16x32_bf16 v[96:99], v[132:135], v[174:177], v[96:99]
	v_mfma_f32_16x16x32_bf16 v[92:95], v[140:143], v[174:177], v[92:95]
	v_mfma_f32_16x16x32_bf16 v[88:91], v[132:135], v[182:185], v[88:91]
	v_mfma_f32_16x16x32_bf16 v[84:87], v[140:143], v[182:185], v[84:87]
	v_mfma_f32_16x16x32_bf16 v[80:83], v[132:135], v[204:207], v[80:83]
	v_mfma_f32_16x16x32_bf16 v[76:79], v[140:143], v[204:207], v[76:79]
	v_mfma_f32_16x16x32_bf16 v[72:75], v[132:135], v[212:215], v[72:75]
	v_mfma_f32_16x16x32_bf16 v[68:71], v[140:143], v[212:215], v[68:71]
	v_mfma_f32_16x16x32_bf16 v[96:99], v[136:139], v[178:181], v[96:99]
	v_mfma_f32_16x16x32_bf16 v[92:95], v[144:147], v[178:181], v[92:95]
	v_mfma_f32_16x16x32_bf16 v[88:91], v[136:139], v[186:189], v[88:91]
	v_mfma_f32_16x16x32_bf16 v[84:87], v[144:147], v[186:189], v[84:87]
	v_mfma_f32_16x16x32_bf16 v[80:83], v[136:139], v[208:211], v[80:83]
	v_mfma_f32_16x16x32_bf16 v[76:79], v[144:147], v[208:211], v[76:79]
	v_mfma_f32_16x16x32_bf16 v[72:75], v[136:139], v[238:241], v[72:75]
	v_mfma_f32_16x16x32_bf16 v[68:71], v[144:147], v[238:241], v[68:71]
	s_setprio 0
	s_setprio 1
	v_mfma_f32_16x16x32_bf16 v[32:35], v[148:151], v[174:177], v[32:35]
	v_mfma_f32_16x16x32_bf16 v[28:31], v[166:169], v[174:177], v[28:31]
	v_mfma_f32_16x16x32_bf16 v[24:27], v[148:151], v[182:185], v[24:27]
	v_mfma_f32_16x16x32_bf16 v[12:15], v[166:169], v[182:185], v[12:15]
	v_mfma_f32_16x16x32_bf16 v[20:23], v[148:151], v[204:207], v[20:23]
	v_mfma_f32_16x16x32_bf16 v[8:11], v[166:169], v[204:207], v[8:11]
	v_mfma_f32_16x16x32_bf16 v[16:19], v[148:151], v[212:215], v[16:19]
	v_mfma_f32_16x16x32_bf16 v[4:7], v[166:169], v[212:215], v[4:7]
	v_mfma_f32_16x16x32_bf16 v[32:35], v[162:165], v[178:181], v[32:35]
	v_mfma_f32_16x16x32_bf16 v[28:31], v[170:173], v[178:181], v[28:31]
	v_mfma_f32_16x16x32_bf16 v[24:27], v[162:165], v[186:189], v[24:27]
	v_mfma_f32_16x16x32_bf16 v[12:15], v[170:173], v[186:189], v[12:15]
	v_mfma_f32_16x16x32_bf16 v[20:23], v[162:165], v[208:211], v[20:23]
	v_mfma_f32_16x16x32_bf16 v[8:11], v[170:173], v[208:211], v[8:11]
	v_mfma_f32_16x16x32_bf16 v[16:19], v[162:165], v[238:241], v[16:19]
	v_mfma_f32_16x16x32_bf16 v[4:7], v[170:173], v[238:241], v[4:7]
	s_setprio 0
	s_barrier
	s_add_i32 s40, s42, 2
	s_add_u32 s76, s76, 0x100
	s_addc_u32 s77, s77, 0
	s_add_u32 s4, s4, 0x100
	s_addc_u32 s5, s5, 0
	s_cmp_ge_i32 s42, s64
	s_mov_b32 s42, s40
	s_cbranch_scc0 .LBB0_321
	s_movk_i32 s83, 0x3000

; #define PG8_STAGE(bufoff, gbase, voff) do { _Pragma("unroll") for (int _i = 0; _i < 2; ++_i) \
;         __builtin_amdgcn_global_load_lds((const unsigned*)((const char*)(gbase) + (voff)[_i]), (PG8_LAS unsigned*)(lds + (bufoff) + ldsw + _i * 8192), 16, 0, 0); } while (0)
; #define PG8_LDA(dst, b, h) do { _Pragma("unroll") for (int m = 0; m < 4; ++m) _Pragma("unroll") for (int k = 0; k < 2; ++k) dst[m][k] = *(const PG8_LAS bf16x8*)(lds + PG8_SA(b, h) + aoff + m * 2048 + k * 1024); } while (0)
; #define PG8_LDB(dst, b, h) do { _Pragma("unroll") for (int n = 0; n < 2; ++n) _Pragma("unroll") for (int k = 0; k < 2; ++k) dst[n][k] = *(const PG8_LAS bf16x8*)(lds + PG8_SB(b, h) + boff + n * 2048 + k * 1024); } while (0)
; #define PG8_MMA(ai, bj, At, Bt) do { __builtin_amdgcn_s_setprio(1); _Pragma("unroll") for (int m = 0; m < 4; ++m) _Pragma("unroll") for (int n = 0; n < 2; ++n) _Pragma("unroll") for (int k = 0; k < 2; ++k) \
;         acc[ai][bj][m][n] = __builtin_amdgcn_mfma_f32_16x16x32_bf16(Bt[n][k], At[m][k], acc[ai][bj][m][n], 0, 0, 0); __builtin_amdgcn_s_setprio(0); } while (0)
; template <class Epi, class Sched, bool ALIGN_EPI = false, bool SP2 = false>
; __device__ __forceinline__ void gemm_phase(PG8_LAS unsigned char* lds, const Gemm g, const Sched& S, const Epi& E, int tid_in) {
;     ...
;             const bool last = (t == nt - 2);
;             if constexpr (mid_hook<Epi>::value) { if (t == Epi::H1 || t == Epi::H2) E.mid(acc, cur, wr, wc, fr, fq, t == Epi::H2); }
;             const char* a1 = cA + (size_t)(t + 1) * kstep + (t >= jt ? jb : 0);
;             const char* a2 = last ? nA : cA + (size_t)(t + 2) * kstep + (t + 2 >= jt ? jb : 0); const char* b2 = last ? nB : cB + (size_t)(t + 2) * kstep;
;             const char* a3 = a2 + kstep; const char* b3 = b2 + kstep;
;             if (last && has_next) S.a_ready(nxt);
;             if constexpr (SP2) {
;             PG8_LDB(B0, 0, 0); PG8_LDB(B1, 0, 1); PG8_SCHED; PG8_LDA(At, 0, 0); PG8_STAGE(PG8_SA(1, 1), a1 + hsA, voffA);
;             PG8_WAIT_V(8); PG8_WAIT_L(0); PG8_BAR; PG8_MMA(0, 0, At, B0); PG8_MMA(0, 1, At, B1); PG8_BAR; PG8_SCHED;
;             PG8_LDA(At, 0, 1); PG8_STAGE(PG8_SB(0, 0), b2, voffB); PG8_STAGE(PG8_SB(0, 1), b2 + hsB, voffB); PG8_STAGE(PG8_SA(0, 0), a2, voffA);
;             PG8_WAIT_V(8); PG8_WAIT_L(0); PG8_BAR; PG8_MMA(1, 0, At, B0); PG8_MMA(1, 1, At, B1); PG8_BAR; PG8_SCHED;
.LBB0_352:
	s_add_i32 s24, s55, -2
	s_cmp_ge_i32 s24, s26
	s_cselect_b32 s58, s27, 0
	s_cselect_b32 s59, s42, 0
	s_cmp_ge_i32 s55, s26
	s_cselect_b32 s25, s27, 0
	s_cselect_b32 s24, s42, 0
	s_add_u32 s25, s22, s25
	s_addc_u32 s24, s23, s24
	s_add_u32 s60, s25, 0x80
	s_addc_u32 s24, s24, 0
	s_add_i32 s62, 0, 0x10000
	s_cmp_eq_u32 s41, s55
	s_cselect_b32 s25, s5, s24
	s_cselect_b32 s24, s4, s60
	s_cselect_b32 s61, s21, s54
	s_cselect_b32 s60, s20, s53
	s_add_i32 s63, 0, 0x14000
	v_add_u32_e32 v160, s62, v3
	v_add_u32_e32 v176, s63, v3
	ds_read_b128 v[148:151], v160
	ds_read_b128 v[152:155], v160 offset:1024
	ds_read_b128 v[156:159], v160 offset:2048
	ds_read_b128 v[160:163], v160 offset:3072
	ds_read_b128 v[164:167], v176
	ds_read_b128 v[168:171], v176 offset:1024
	ds_read_b128 v[172:175], v176 offset:2048
	ds_read_b128 v[176:179], v176 offset:3072
	v_lshl_add_u64 v[230:231], s[22:23], 0, v[140:141]
	v_lshl_add_u64 v[230:231], v[230:231], 0, s[58:59]
	s_add_i32 m0, s31, 0xc000
	ds_read_b128 v[180:183], v147
	ds_read_b128 v[184:187], v147 offset:1024
	ds_read_b128 v[188:191], v147 offset:2048
	ds_read_b128 v[204:207], v147 offset:3072
	ds_read_b128 v[208:211], v147 offset:4096
	ds_read_b128 v[212:215], v147 offset:5120
	ds_read_b128 v[216:219], v147 offset:6144
	ds_read_b128 v[220:223], v147 offset:7168
	global_load_lds_dwordx4 v[230:231], off
	v_lshl_add_u64 v[230:231], s[22:23], 0, v[138:139]
	v_lshl_add_u64 v[230:231], v[230:231], 0, s[58:59]
	s_add_i32 m0, s31, 0xe000
	s_nop 0
	global_load_lds_dwordx4 v[230:231], off
	s_waitcnt vmcnt(8)
	s_waitcnt lgkmcnt(0)
	s_barrier
	s_setprio 1
	s_waitcnt lgkmcnt(0)
	v_mfma_f32_16x16x32_bf16 v[124:127], v[148:151], v[180:183], v[124:127]
	v_mfma_f32_16x16x32_bf16 v[128:131], v[156:159], v[180:183], v[128:131]
	v_mfma_f32_16x16x32_bf16 v[112:115], v[148:151], v[188:191], v[112:115]
	v_mfma_f32_16x16x32_bf16 v[108:111], v[156:159], v[188:191], v[108:111]
	v_mfma_f32_16x16x32_bf16 v[96:99], v[148:151], v[208:211], v[96:99]
	v_mfma_f32_16x16x32_bf16 v[92:95], v[156:159], v[208:211], v[92:95]
	v_mfma_f32_16x16x32_bf16 v[80:83], v[148:151], v[216:219], v[80:83]
	v_mfma_f32_16x16x32_bf16 v[76:79], v[156:159], v[216:219], v[76:79]
	v_mfma_f32_16x16x32_bf16 v[124:127], v[152:155], v[184:187], v[124:127]
	v_mfma_f32_16x16x32_bf16 v[128:131], v[160:163], v[184:187], v[128:131]
	v_mfma_f32_16x16x32_bf16 v[112:115], v[152:155], v[204:207], v[112:115]
	v_mfma_f32_16x16x32_bf16 v[108:111], v[160:163], v[204:207], v[108:111]
	v_mfma_f32_16x16x32_bf16 v[96:99], v[152:155], v[212:215], v[96:99]
	v_mfma_f32_16x16x32_bf16 v[92:95], v[160:163], v[212:215], v[92:95]
	v_mfma_f32_16x16x32_bf16 v[80:83], v[152:155], v[220:223], v[80:83]
	v_mfma_f32_16x16x32_bf16 v[76:79], v[160:163], v[220:223], v[76:79]
	s_setprio 0
	s_setprio 1
	v_mfma_f32_16x16x32_bf16 v[120:123], v[164:167], v[180:183], v[120:123]
	v_mfma_f32_16x16x32_bf16 v[116:119], v[172:175], v[180:183], v[116:119]
	v_mfma_f32_16x16x32_bf16 v[104:107], v[164:167], v[188:191], v[104:107]
	v_mfma_f32_16x16x32_bf16 v[100:103], v[172:175], v[188:191], v[100:103]
	v_mfma_f32_16x16x32_bf16 v[88:91], v[164:167], v[208:211], v[88:91]
	v_mfma_f32_16x16x32_bf16 v[84:87], v[172:175], v[208:211], v[84:87]
	v_mfma_f32_16x16x32_bf16 v[72:75], v[164:167], v[216:219], v[72:75]
	v_mfma_f32_16x16x32_bf16 v[68:71], v[172:175], v[216:219], v[68:71]
	v_mfma_f32_16x16x32_bf16 v[120:123], v[168:171], v[184:187], v[120:123]
	v_mfma_f32_16x16x32_bf16 v[116:119], v[176:179], v[184:187], v[116:119]
	v_mfma_f32_16x16x32_bf16 v[104:107], v[168:171], v[204:207], v[104:107]
	v_mfma_f32_16x16x32_bf16 v[100:103], v[176:179], v[204:207], v[100:103]
	v_mfma_f32_16x16x32_bf16 v[88:91], v[168:171], v[212:215], v[88:91]
	v_mfma_f32_16x16x32_bf16 v[84:87], v[176:179], v[212:215], v[84:87]
	v_mfma_f32_16x16x32_bf16 v[72:75], v[168:171], v[220:223], v[72:75]
	v_mfma_f32_16x16x32_bf16 v[68:71], v[176:179], v[220:223], v[68:71]
	s_setprio 0
	s_barrier
	s_add_i32 s58, s62, s30
	v_lshl_add_u64 v[230:231], s[60:61], 0, v[134:135]
	s_mov_b32 m0, s58
	ds_read_b128 v[180:183], v147 offset:16384
	ds_read_b128 v[184:187], v147 offset:17408
	ds_read_b128 v[188:191], v147 offset:18432
	ds_read_b128 v[204:207], v147 offset:19456
	ds_read_b128 v[208:211], v147 offset:20480
	ds_read_b128 v[212:215], v147 offset:21504
	ds_read_b128 v[216:219], v147 offset:22528
	ds_read_b128 v[220:223], v147 offset:23552
	global_load_lds_dwordx4 v[230:231], off
	s_add_i32 m0, s58, 0x2000
	s_add_u32 s58, s60, s8
	v_lshl_add_u64 v[232:233], s[60:61], 0, v[0:1]
	s_addc_u32 s59, s61, s9
	s_add_i32 s60, s63, s30
	global_load_lds_dwordx4 v[232:233], off
	v_lshl_add_u64 v[238:239], s[58:59], 0, v[134:135]
	v_lshl_add_u64 v[240:241], s[58:59], 0, v[0:1]
	v_lshl_add_u64 v[242:243], s[24:25], 0, v[136:137]
	s_mov_b32 m0, s31
	v_lshl_add_u64 v[244:245], s[24:25], 0, v[132:133]
	global_load_lds_dwordx4 v[242:243], off
	s_mov_b32 m0, s33
	s_nop 0
	global_load_lds_dwordx4 v[244:245], off
	s_waitcnt vmcnt(6)
	s_waitcnt lgkmcnt(0)
	s_barrier
; #define PG8_STAGE(bufoff, gbase, voff) do { _Pragma("unroll") for (int _i = 0; _i < 2; ++_i) \
;         __builtin_amdgcn_global_load_lds((const unsigned*)((const char*)(gbase) + (voff)[_i]), (PG8_LAS unsigned*)(lds + (bufoff) + ldsw + _i * 8192), 16, 0, 0); } while (0)
; #define PG8_LDA(dst, b, h) do { _Pragma("unroll") for (int m = 0; m < 4; ++m) _Pragma("unroll") for (int k = 0; k < 2; ++k) dst[m][k] = *(const PG8_LAS bf16x8*)(lds + PG8_SA(b, h) + aoff + m * 2048 + k * 1024); } while (0)
; #define PG8_LDB(dst, b, h) do { _Pragma("unroll") for (int n = 0; n < 2; ++n) _Pragma("unroll") for (int k = 0; k < 2; ++k) dst[n][k] = *(const PG8_LAS bf16x8*)(lds + PG8_SB(b, h) + boff + n * 2048 + k * 1024); } while (0)
; #define PG8_MMA(ai, bj, At, Bt) do { __builtin_amdgcn_s_setprio(1); _Pragma("unroll") for (int m = 0; m < 4; ++m) _Pragma("unroll") for (int n = 0; n < 2; ++n) _Pragma("unroll") for (int k = 0; k < 2; ++k) \
;         acc[ai][bj][m][n] = __builtin_amdgcn_mfma_f32_16x16x32_bf16(Bt[n][k], At[m][k], acc[ai][bj][m][n], 0, 0, 0); __builtin_amdgcn_s_setprio(0); } while (0)
; #define PG8_WAIT_V(n) asm volatile("s_waitcnt vmcnt(" #n ")" ::: "memory")
; #define PG8_WAIT_L(n) asm volatile("s_waitcnt lgkmcnt(" #n ")" ::: "memory")
; #define PG8_BAR __builtin_amdgcn_s_barrier()
; #define PG8_SCHED __builtin_amdgcn_sched_barrier(0)
; template <class Epi, class Sched, bool ALIGN_EPI = false, bool SP2 = false>
; __device__ __forceinline__ void gemm_phase(PG8_LAS unsigned char* lds, const Gemm g, const Sched& S, const Epi& E, int tid_in) {
;     ...
;             PG8_WAIT_V(8); PG8_WAIT_L(0); PG8_BAR; PG8_MMA(1, 0, At, B0); PG8_MMA(1, 1, At, B1); PG8_BAR; PG8_SCHED;
;             PG8_LDB(B0, 1, 0); PG8_LDB(B1, 1, 1); PG8_SCHED; PG8_LDA(At, 1, 0); PG8_STAGE(PG8_SA(0, 1), a2 + hsA, voffA);
;             PG8_WAIT_V(8); PG8_WAIT_L(0); PG8_BAR; PG8_MMA(0, 0, At, B0); PG8_MMA(0, 1, At, B1); PG8_BAR; PG8_SCHED;
	s_setprio 1
	s_waitcnt lgkmcnt(0)
	v_mfma_f32_16x16x32_bf16 v[64:67], v[148:151], v[180:183], v[64:67]
	v_mfma_f32_16x16x32_bf16 v[60:63], v[156:159], v[180:183], v[60:63]
	v_mfma_f32_16x16x32_bf16 v[48:51], v[148:151], v[188:191], v[48:51]
	v_mfma_f32_16x16x32_bf16 v[44:47], v[156:159], v[188:191], v[44:47]
	v_mfma_f32_16x16x32_bf16 v[32:35], v[148:151], v[208:211], v[32:35]
	v_mfma_f32_16x16x32_bf16 v[28:31], v[156:159], v[208:211], v[28:31]
	v_mfma_f32_16x16x32_bf16 v[16:19], v[148:151], v[216:219], v[16:19]
	v_mfma_f32_16x16x32_bf16 v[12:15], v[156:159], v[216:219], v[12:15]
	v_mfma_f32_16x16x32_bf16 v[64:67], v[152:155], v[184:187], v[64:67]
	v_mfma_f32_16x16x32_bf16 v[60:63], v[160:163], v[184:187], v[60:63]
	v_mfma_f32_16x16x32_bf16 v[48:51], v[152:155], v[204:207], v[48:51]
	v_mfma_f32_16x16x32_bf16 v[44:47], v[160:163], v[204:207], v[44:47]
	v_mfma_f32_16x16x32_bf16 v[32:35], v[152:155], v[212:215], v[32:35]
	v_mfma_f32_16x16x32_bf16 v[28:31], v[160:163], v[212:215], v[28:31]
	v_mfma_f32_16x16x32_bf16 v[16:19], v[152:155], v[220:223], v[16:19]
	v_mfma_f32_16x16x32_bf16 v[12:15], v[160:163], v[220:223], v[12:15]
	s_setprio 0
	s_setprio 1
	v_mfma_f32_16x16x32_bf16 v[56:59], v[164:167], v[180:183], v[56:59]
	v_mfma_f32_16x16x32_bf16 v[52:55], v[172:175], v[180:183], v[52:55]
	v_mfma_f32_16x16x32_bf16 v[40:43], v[164:167], v[188:191], v[40:43]
	v_mfma_f32_16x16x32_bf16 v[36:39], v[172:175], v[188:191], v[36:39]
	v_mfma_f32_16x16x32_bf16 v[24:27], v[164:167], v[208:211], v[24:27]
	v_mfma_f32_16x16x32_bf16 v[20:23], v[172:175], v[208:211], v[20:23]
	v_mfma_f32_16x16x32_bf16 v[8:11], v[164:167], v[216:219], v[8:11]
	v_mfma_f32_16x16x32_bf16 v[4:7], v[172:175], v[216:219], v[4:7]
	v_mfma_f32_16x16x32_bf16 v[56:59], v[168:171], v[184:187], v[56:59]
	v_mfma_f32_16x16x32_bf16 v[52:55], v[176:179], v[184:187], v[52:55]
	v_mfma_f32_16x16x32_bf16 v[40:43], v[168:171], v[204:207], v[40:43]
	v_mfma_f32_16x16x32_bf16 v[36:39], v[176:179], v[204:207], v[36:39]
	v_mfma_f32_16x16x32_bf16 v[24:27], v[168:171], v[212:215], v[24:27]
	v_mfma_f32_16x16x32_bf16 v[20:23], v[176:179], v[212:215], v[20:23]
	v_mfma_f32_16x16x32_bf16 v[8:11], v[168:171], v[220:223], v[8:11]
	v_mfma_f32_16x16x32_bf16 v[4:7], v[176:179], v[220:223], v[4:7]
	s_setprio 0
	s_barrier
	s_add_i32 s58, 0, 0x18000
	s_add_i32 s59, 0, 0x1c000
	v_add_u32_e32 v160, s58, v3
	v_add_u32_e32 v176, s59, v3
	ds_read_b128 v[148:151], v160
	ds_read_b128 v[152:155], v160 offset:1024
	ds_read_b128 v[156:159], v160 offset:2048
	ds_read_b128 v[160:163], v160 offset:3072
	ds_read_b128 v[164:167], v176
	ds_read_b128 v[168:171], v176 offset:1024
	ds_read_b128 v[172:175], v176 offset:2048
	ds_read_b128 v[176:179], v176 offset:3072
	s_add_u32 s24, s24, s6
	s_addc_u32 s25, s25, s7
	s_mov_b32 m0, s34
	v_lshl_add_u64 v[246:247], s[24:25], 0, v[136:137]
	ds_read_b128 v[180:183], v147 offset:32768
	ds_read_b128 v[184:187], v147 offset:33792
	ds_read_b128 v[188:191], v147 offset:34816
	ds_read_b128 v[204:207], v147 offset:35840
	ds_read_b128 v[208:211], v147 offset:36864
	ds_read_b128 v[212:215], v147 offset:37888
	ds_read_b128 v[216:219], v147 offset:38912
	ds_read_b128 v[220:223], v147 offset:39936
	global_load_lds_dwordx4 v[246:247], off
	v_lshl_add_u64 v[246:247], s[24:25], 0, v[132:133]
	s_mov_b32 m0, s35
	s_nop 0
	global_load_lds_dwordx4 v[246:247], off
	s_add_i32 m0, s30, 0x14000
	s_nop 0
	global_load_lds_dwordx4 v[238:239], off
	s_add_i32 m0, s30, 0x16000
	s_nop 0
	global_load_lds_dwordx4 v[240:241], off
	s_waitcnt vmcnt(8)
	s_waitcnt lgkmcnt(0)
	s_barrier
	s_setprio 1
	s_waitcnt lgkmcnt(0)
	v_mfma_f32_16x16x32_bf16 v[124:127], v[148:151], v[180:183], v[124:127]
	v_mfma_f32_16x16x32_bf16 v[128:131], v[156:159], v[180:183], v[128:131]
	v_mfma_f32_16x16x32_bf16 v[112:115], v[148:151], v[188:191], v[112:115]
	v_mfma_f32_16x16x32_bf16 v[108:111], v[156:159], v[188:191], v[108:111]
	v_mfma_f32_16x16x32_bf16 v[96:99], v[148:151], v[208:211], v[96:99]
	v_mfma_f32_16x16x32_bf16 v[92:95], v[156:159], v[208:211], v[92:95]
	v_mfma_f32_16x16x32_bf16 v[80:83], v[148:151], v[216:219], v[80:83]
	v_mfma_f32_16x16x32_bf16 v[76:79], v[156:159], v[216:219], v[76:79]
	v_mfma_f32_16x16x32_bf16 v[124:127], v[152:155], v[184:187], v[124:127]
	v_mfma_f32_16x16x32_bf16 v[128:131], v[160:163], v[184:187], v[128:131]
	v_mfma_f32_16x16x32_bf16 v[112:115], v[152:155], v[204:207], v[112:115]
	v_mfma_f32_16x16x32_bf16 v[108:111], v[160:163], v[204:207], v[108:111]
	v_mfma_f32_16x16x32_bf16 v[96:99], v[152:155], v[212:215], v[96:99]
	v_mfma_f32_16x16x32_bf16 v[92:95], v[160:163], v[212:215], v[92:95]
	v_mfma_f32_16x16x32_bf16 v[80:83], v[152:155], v[220:223], v[80:83]
	v_mfma_f32_16x16x32_bf16 v[76:79], v[160:163], v[220:223], v[76:79]
	s_setprio 0
	s_setprio 1
	v_mfma_f32_16x16x32_bf16 v[120:123], v[164:167], v[180:183], v[120:123]
	v_mfma_f32_16x16x32_bf16 v[116:119], v[172:175], v[180:183], v[116:119]
	v_mfma_f32_16x16x32_bf16 v[104:107], v[164:167], v[188:191], v[104:107]
	v_mfma_f32_16x16x32_bf16 v[100:103], v[172:175], v[188:191], v[100:103]
	v_mfma_f32_16x16x32_bf16 v[88:91], v[164:167], v[208:211], v[88:91]
	v_mfma_f32_16x16x32_bf16 v[84:87], v[172:175], v[208:211], v[84:87]
	v_mfma_f32_16x16x32_bf16 v[72:75], v[164:167], v[216:219], v[72:75]
	v_mfma_f32_16x16x32_bf16 v[68:71], v[172:175], v[216:219], v[68:71]
	v_mfma_f32_16x16x32_bf16 v[120:123], v[168:171], v[184:187], v[120:123]
	v_mfma_f32_16x16x32_bf16 v[116:119], v[176:179], v[184:187], v[116:119]
	v_mfma_f32_16x16x32_bf16 v[104:107], v[168:171], v[204:207], v[104:107]
	v_mfma_f32_16x16x32_bf16 v[100:103], v[176:179], v[204:207], v[100:103]
	v_mfma_f32_16x16x32_bf16 v[88:91], v[168:171], v[212:215], v[88:91]
	v_mfma_f32_16x16x32_bf16 v[84:87], v[176:179], v[212:215], v[84:87]
	v_mfma_f32_16x16x32_bf16 v[72:75], v[168:171], v[220:223], v[72:75]
	v_mfma_f32_16x16x32_bf16 v[68:71], v[176:179], v[220:223], v[68:71]
	s_setprio 0
	s_barrier
; #define PG8_STAGE(bufoff, gbase, voff) do { _Pragma("unroll") for (int _i = 0; _i < 2; ++_i) \
;         __builtin_amdgcn_global_load_lds((const unsigned*)((const char*)(gbase) + (voff)[_i]), (PG8_LAS unsigned*)(lds + (bufoff) + ldsw + _i * 8192), 16, 0, 0); } while (0)
; #define PG8_LDA(dst, b, h) do { _Pragma("unroll") for (int m = 0; m < 4; ++m) _Pragma("unroll") for (int k = 0; k < 2; ++k) dst[m][k] = *(const PG8_LAS bf16x8*)(lds + PG8_SA(b, h) + aoff + m * 2048 + k * 1024); } while (0)
; #define PG8_MMA(ai, bj, At, Bt) do { __builtin_amdgcn_s_setprio(1); _Pragma("unroll") for (int m = 0; m < 4; ++m) _Pragma("unroll") for (int n = 0; n < 2; ++n) _Pragma("unroll") for (int k = 0; k < 2; ++k) \
;         acc[ai][bj][m][n] = __builtin_amdgcn_mfma_f32_16x16x32_bf16(Bt[n][k], At[m][k], acc[ai][bj][m][n], 0, 0, 0); __builtin_amdgcn_s_setprio(0); } while (0)
; #define PG8_WAIT_V(n) asm volatile("s_waitcnt vmcnt(" #n ")" ::: "memory")
; #define PG8_WAIT_L(n) asm volatile("s_waitcnt lgkmcnt(" #n ")" ::: "memory")
; #define PG8_BAR __builtin_amdgcn_s_barrier()
; #define PG8_SCHED __builtin_amdgcn_sched_barrier(0)
; template <class Epi, class Sched, bool ALIGN_EPI = false, bool SP2 = false>
; __device__ __forceinline__ void gemm_phase(PG8_LAS unsigned char* lds, const Gemm g, const Sched& S, const Epi& E, int tid_in) {
;     ...
;         for (int t = 0; t < nt; t += 2) {
;     ...
;             PG8_LDA(At, 1, 1); PG8_STAGE(PG8_SB(1, 0), b3, voffB); PG8_STAGE(PG8_SB(1, 1), b3 + hsB, voffB); PG8_STAGE(PG8_SA(1, 0), a3, voffA);
;             PG8_WAIT_V(8); PG8_WAIT_L(0); PG8_BAR; PG8_MMA(1, 0, At, B0); PG8_MMA(1, 1, At, B1); PG8_BAR; PG8_SCHED;
	s_add_i32 s24, s58, s30
	v_lshl_add_u64 v[230:231], v[230:231], 0, s[80:81]
	s_mov_b32 m0, s24
	ds_read_b128 v[180:183], v147 offset:49152
	ds_read_b128 v[184:187], v147 offset:50176
	ds_read_b128 v[188:191], v147 offset:51200
	ds_read_b128 v[204:207], v147 offset:52224
	ds_read_b128 v[208:211], v147 offset:53248
	ds_read_b128 v[212:215], v147 offset:54272
	ds_read_b128 v[216:219], v147 offset:55296
	ds_read_b128 v[220:223], v147 offset:56320
	global_load_lds_dwordx4 v[230:231], off
	v_lshl_add_u64 v[230:231], v[232:233], 0, s[80:81]
	s_add_i32 m0, s24, 0x2000
	s_add_i32 s24, s59, s30
	global_load_lds_dwordx4 v[230:231], off
	v_lshl_add_u64 v[230:231], v[238:239], 0, s[80:81]
	s_mov_b32 m0, s24
	s_nop 0
	global_load_lds_dwordx4 v[230:231], off
	v_lshl_add_u64 v[230:231], v[240:241], 0, s[80:81]
	s_add_i32 m0, s24, 0x2000
	s_nop 0
	global_load_lds_dwordx4 v[230:231], off
	v_lshl_add_u64 v[230:231], v[242:243], 0, s[80:81]
	s_mov_b32 m0, s38
	s_nop 0
	global_load_lds_dwordx4 v[230:231], off
	v_lshl_add_u64 v[230:231], v[244:245], 0, s[80:81]
	s_mov_b32 m0, s39
	s_nop 0
	global_load_lds_dwordx4 v[230:231], off
	s_waitcnt vmcnt(6)
	s_waitcnt lgkmcnt(0)
	s_barrier
	s_setprio 1
	s_waitcnt lgkmcnt(0)
	v_mfma_f32_16x16x32_bf16 v[64:67], v[148:151], v[180:183], v[64:67]
	v_mfma_f32_16x16x32_bf16 v[60:63], v[156:159], v[180:183], v[60:63]
	v_mfma_f32_16x16x32_bf16 v[48:51], v[148:151], v[188:191], v[48:51]
	v_mfma_f32_16x16x32_bf16 v[44:47], v[156:159], v[188:191], v[44:47]
	v_mfma_f32_16x16x32_bf16 v[32:35], v[148:151], v[208:211], v[32:35]
	v_mfma_f32_16x16x32_bf16 v[28:31], v[156:159], v[208:211], v[28:31]
	v_mfma_f32_16x16x32_bf16 v[16:19], v[148:151], v[216:219], v[16:19]
	v_mfma_f32_16x16x32_bf16 v[12:15], v[156:159], v[216:219], v[12:15]
	v_mfma_f32_16x16x32_bf16 v[64:67], v[152:155], v[184:187], v[64:67]
	v_mfma_f32_16x16x32_bf16 v[60:63], v[160:163], v[184:187], v[60:63]
	v_mfma_f32_16x16x32_bf16 v[48:51], v[152:155], v[204:207], v[48:51]
	v_mfma_f32_16x16x32_bf16 v[44:47], v[160:163], v[204:207], v[44:47]
	v_mfma_f32_16x16x32_bf16 v[32:35], v[152:155], v[212:215], v[32:35]
	v_mfma_f32_16x16x32_bf16 v[28:31], v[160:163], v[212:215], v[28:31]
	v_mfma_f32_16x16x32_bf16 v[16:19], v[152:155], v[220:223], v[16:19]
	v_mfma_f32_16x16x32_bf16 v[12:15], v[160:163], v[220:223], v[12:15]
	s_setprio 0
	s_setprio 1
	v_mfma_f32_16x16x32_bf16 v[56:59], v[164:167], v[180:183], v[56:59]
	v_mfma_f32_16x16x32_bf16 v[52:55], v[172:175], v[180:183], v[52:55]
	v_mfma_f32_16x16x32_bf16 v[40:43], v[164:167], v[188:191], v[40:43]
	v_mfma_f32_16x16x32_bf16 v[36:39], v[172:175], v[188:191], v[36:39]
	v_mfma_f32_16x16x32_bf16 v[24:27], v[164:167], v[208:211], v[24:27]
	v_mfma_f32_16x16x32_bf16 v[20:23], v[172:175], v[208:211], v[20:23]
	v_mfma_f32_16x16x32_bf16 v[8:11], v[164:167], v[216:219], v[8:11]
	v_mfma_f32_16x16x32_bf16 v[4:7], v[172:175], v[216:219], v[4:7]
	v_mfma_f32_16x16x32_bf16 v[56:59], v[168:171], v[184:187], v[56:59]
	v_mfma_f32_16x16x32_bf16 v[52:55], v[176:179], v[184:187], v[52:55]
	v_mfma_f32_16x16x32_bf16 v[40:43], v[168:171], v[204:207], v[40:43]
	v_mfma_f32_16x16x32_bf16 v[36:39], v[176:179], v[204:207], v[36:39]
	v_mfma_f32_16x16x32_bf16 v[24:27], v[168:171], v[212:215], v[24:27]
	v_mfma_f32_16x16x32_bf16 v[20:23], v[176:179], v[212:215], v[20:23]
	v_mfma_f32_16x16x32_bf16 v[8:11], v[168:171], v[220:223], v[8:11]
	v_mfma_f32_16x16x32_bf16 v[4:7], v[176:179], v[220:223], v[4:7]
	s_setprio 0
	s_barrier
	s_add_i32 s24, s55, 2
	s_add_u32 s53, s53, 0x100
	s_addc_u32 s54, s54, 0
	s_add_u32 s22, s22, 0x100
	s_addc_u32 s23, s23, 0
	s_cmp_ge_i32 s55, s41
	s_mov_b32 s55, s24
	s_cbranch_scc0 .LBB0_352

; #define PG8_STAGE(bufoff, gbase, voff) do { _Pragma("unroll") for (int _i = 0; _i < 2; ++_i) \
;         __builtin_amdgcn_global_load_lds((const unsigned*)((const char*)(gbase) + (voff)[_i]), (PG8_LAS unsigned*)(lds + (bufoff) + ldsw + _i * 8192), 16, 0, 0); } while (0)
; #define PG8_LDA(dst, b, h) do { _Pragma("unroll") for (int m = 0; m < 4; ++m) _Pragma("unroll") for (int k = 0; k < 2; ++k) dst[m][k] = *(const PG8_LAS bf16x8*)(lds + PG8_SA(b, h) + aoff + m * 2048 + k * 1024); } while (0)
; #define PG8_LDB(dst, b, h) do { _Pragma("unroll") for (int n = 0; n < 2; ++n) _Pragma("unroll") for (int k = 0; k < 2; ++k) dst[n][k] = *(const PG8_LAS bf16x8*)(lds + PG8_SB(b, h) + boff + n * 2048 + k * 1024); } while (0)
; #define PG8_MMA(ai, bj, At, Bt) do { __builtin_amdgcn_s_setprio(1); _Pragma("unroll") for (int m = 0; m < 4; ++m) _Pragma("unroll") for (int n = 0; n < 2; ++n) _Pragma("unroll") for (int k = 0; k < 2; ++k) \
;         acc[ai][bj][m][n] = __builtin_amdgcn_mfma_f32_16x16x32_bf16(Bt[n][k], At[m][k], acc[ai][bj][m][n], 0, 0, 0); __builtin_amdgcn_s_setprio(0); } while (0)
; template <class Epi, class Sched, bool ALIGN_EPI = false, bool SP2 = false>
; __device__ __forceinline__ void gemm_phase(PG8_LAS unsigned char* lds, const Gemm g, const Sched& S, const Epi& E, int tid_in) {
;     ...
;             const bool last = (t == nt - 2);
;             if constexpr (mid_hook<Epi>::value) { if (t == Epi::H1 || t == Epi::H2) E.mid(acc, cur, wr, wc, fr, fq, t == Epi::H2); }
;             const char* a1 = cA + (size_t)(t + 1) * kstep + (t >= jt ? jb : 0);
;             const char* a2 = last ? nA : cA + (size_t)(t + 2) * kstep + (t + 2 >= jt ? jb : 0); const char* b2 = last ? nB : cB + (size_t)(t + 2) * kstep;
;             const char* a3 = a2 + kstep; const char* b3 = b2 + kstep;
;             if (last && has_next) S.a_ready(nxt);
;             if constexpr (SP2) {
;             PG8_LDB(B0, 0, 0); PG8_LDB(B1, 0, 1); PG8_SCHED; PG8_LDA(At, 0, 0); PG8_STAGE(PG8_SA(1, 1), a1 + hsA, voffA);
;             PG8_WAIT_V(8); PG8_WAIT_L(0); PG8_BAR; PG8_MMA(0, 0, At, B0); PG8_MMA(0, 1, At, B1); PG8_BAR; PG8_SCHED;
;             PG8_LDA(At, 0, 1); PG8_STAGE(PG8_SB(0, 0), b2, voffB); PG8_STAGE(PG8_SB(0, 1), b2 + hsB, voffB); PG8_STAGE(PG8_SA(0, 0), a2, voffA);
;             PG8_WAIT_V(8); PG8_WAIT_L(0); PG8_BAR; PG8_MMA(1, 0, At, B0); PG8_MMA(1, 1, At, B1); PG8_BAR; PG8_SCHED;
.LBB0_485:
	s_add_i32 s24, s53, -2
	s_cmp_ge_i32 s24, s28
	s_cselect_b32 s54, s29, 0
	s_cselect_b32 s55, s45, 0
	s_cmp_ge_i32 s53, s28
	s_cselect_b32 s25, s29, 0
	s_cselect_b32 s24, s45, 0
	s_add_u32 s25, s22, s25
	s_addc_u32 s24, s23, s24
	s_add_u32 s58, s25, 0x80
	s_addc_u32 s24, s24, 0
	s_add_i32 s60, 0, 0x10000
	s_cmp_eq_u32 s44, s53
	s_cselect_b32 s25, s5, s24
	s_cselect_b32 s24, s4, s58
	v_add_u32_e32 v145, s60, v142
	s_cselect_b32 s59, s21, s52
	s_cselect_b32 s58, s20, s51
	s_add_i32 s61, 0, 0x14000
	ds_read_b128 v[146:149], v145
	ds_read_b128 v[150:153], v145 offset:1024
	ds_read_b128 v[154:157], v145 offset:2048
	ds_read_b128 v[158:161], v145 offset:3072
	v_add_u32_e32 v145, s61, v142
	ds_read_b128 v[162:165], v145
	ds_read_b128 v[166:169], v145 offset:1024
	ds_read_b128 v[170:173], v145 offset:2048
	ds_read_b128 v[174:177], v145 offset:3072
	v_lshl_add_u64 v[190:191], s[22:23], 0, v[140:141]
	v_lshl_add_u64 v[190:191], v[190:191], 0, s[54:55]
	s_add_i32 m0, s37, 0xc000
	ds_read_b128 v[178:181], v144
	ds_read_b128 v[182:185], v144 offset:1024
	ds_read_b128 v[186:189], v144 offset:2048
	ds_read_b128 v[204:207], v144 offset:3072
	ds_read_b128 v[208:211], v144 offset:4096
	ds_read_b128 v[212:215], v144 offset:5120
	ds_read_b128 v[216:219], v144 offset:6144
	ds_read_b128 v[220:223], v144 offset:7168
	global_load_lds_dwordx4 v[190:191], off
	v_lshl_add_u64 v[190:191], s[22:23], 0, v[138:139]
	v_lshl_add_u64 v[190:191], v[190:191], 0, s[54:55]
	s_add_i32 m0, s37, 0xe000
	s_nop 0
	global_load_lds_dwordx4 v[190:191], off
	s_waitcnt vmcnt(8)
	s_waitcnt lgkmcnt(0)
	s_barrier
	s_setprio 1
	s_waitcnt lgkmcnt(0)
	v_mfma_f32_16x16x32_bf16 v[124:127], v[146:149], v[178:181], v[124:127]
	v_mfma_f32_16x16x32_bf16 v[128:131], v[154:157], v[178:181], v[128:131]
	v_mfma_f32_16x16x32_bf16 v[112:115], v[146:149], v[186:189], v[112:115]
	v_mfma_f32_16x16x32_bf16 v[108:111], v[154:157], v[186:189], v[108:111]
	v_mfma_f32_16x16x32_bf16 v[96:99], v[146:149], v[208:211], v[96:99]
	v_mfma_f32_16x16x32_bf16 v[92:95], v[154:157], v[208:211], v[92:95]
	v_mfma_f32_16x16x32_bf16 v[80:83], v[146:149], v[216:219], v[80:83]
	v_mfma_f32_16x16x32_bf16 v[76:79], v[154:157], v[216:219], v[76:79]
	v_mfma_f32_16x16x32_bf16 v[124:127], v[150:153], v[182:185], v[124:127]
	v_mfma_f32_16x16x32_bf16 v[128:131], v[158:161], v[182:185], v[128:131]
	v_mfma_f32_16x16x32_bf16 v[112:115], v[150:153], v[204:207], v[112:115]
	v_mfma_f32_16x16x32_bf16 v[108:111], v[158:161], v[204:207], v[108:111]
	v_mfma_f32_16x16x32_bf16 v[96:99], v[150:153], v[212:215], v[96:99]
	v_mfma_f32_16x16x32_bf16 v[92:95], v[158:161], v[212:215], v[92:95]
	v_mfma_f32_16x16x32_bf16 v[80:83], v[150:153], v[220:223], v[80:83]
	v_mfma_f32_16x16x32_bf16 v[76:79], v[158:161], v[220:223], v[76:79]
	s_setprio 0
	s_setprio 1
	v_mfma_f32_16x16x32_bf16 v[120:123], v[162:165], v[178:181], v[120:123]
	v_mfma_f32_16x16x32_bf16 v[116:119], v[170:173], v[178:181], v[116:119]
	v_mfma_f32_16x16x32_bf16 v[104:107], v[162:165], v[186:189], v[104:107]
	v_mfma_f32_16x16x32_bf16 v[100:103], v[170:173], v[186:189], v[100:103]
	v_mfma_f32_16x16x32_bf16 v[88:91], v[162:165], v[208:211], v[88:91]
	v_mfma_f32_16x16x32_bf16 v[84:87], v[170:173], v[208:211], v[84:87]
	v_mfma_f32_16x16x32_bf16 v[72:75], v[162:165], v[216:219], v[72:75]
	v_mfma_f32_16x16x32_bf16 v[68:71], v[170:173], v[216:219], v[68:71]
	v_mfma_f32_16x16x32_bf16 v[120:123], v[166:169], v[182:185], v[120:123]
	v_mfma_f32_16x16x32_bf16 v[116:119], v[174:177], v[182:185], v[116:119]
	v_mfma_f32_16x16x32_bf16 v[104:107], v[166:169], v[204:207], v[104:107]
	v_mfma_f32_16x16x32_bf16 v[100:103], v[174:177], v[204:207], v[100:103]
	v_mfma_f32_16x16x32_bf16 v[88:91], v[166:169], v[212:215], v[88:91]
	v_mfma_f32_16x16x32_bf16 v[84:87], v[174:177], v[212:215], v[84:87]
	v_mfma_f32_16x16x32_bf16 v[72:75], v[166:169], v[220:223], v[72:75]
	v_mfma_f32_16x16x32_bf16 v[68:71], v[174:177], v[220:223], v[68:71]
	s_setprio 0
	s_barrier
	s_add_i32 s54, s60, s35
	v_lshl_add_u64 v[190:191], s[58:59], 0, v[134:135]
	s_mov_b32 m0, s54
	ds_read_b128 v[178:181], v144 offset:16384
	ds_read_b128 v[182:185], v144 offset:17408
	ds_read_b128 v[186:189], v144 offset:18432
	ds_read_b128 v[204:207], v144 offset:19456
	ds_read_b128 v[208:211], v144 offset:20480
	ds_read_b128 v[212:215], v144 offset:21504
	ds_read_b128 v[216:219], v144 offset:22528
	ds_read_b128 v[220:223], v144 offset:23552
	global_load_lds_dwordx4 v[190:191], off
	s_add_i32 m0, s54, 0x2000
	s_add_u32 s54, s58, s8
	v_lshl_add_u64 v[230:231], s[58:59], 0, v[0:1]
	s_addc_u32 s55, s59, s9
	s_add_i32 s58, s61, s35
	global_load_lds_dwordx4 v[230:231], off
	v_lshl_add_u64 v[232:233], s[54:55], 0, v[134:135]
	v_lshl_add_u64 v[238:239], s[54:55], 0, v[0:1]
	v_lshl_add_u64 v[240:241], s[24:25], 0, v[136:137]
	s_mov_b32 m0, s37
	v_lshl_add_u64 v[242:243], s[24:25], 0, v[132:133]
	global_load_lds_dwordx4 v[240:241], off
	s_mov_b32 m0, s38
	s_nop 0
	global_load_lds_dwordx4 v[242:243], off
	s_waitcnt vmcnt(6)
	s_waitcnt lgkmcnt(0)
	s_barrier
; #define PG8_STAGE(bufoff, gbase, voff) do { _Pragma("unroll") for (int _i = 0; _i < 2; ++_i) \
;         __builtin_amdgcn_global_load_lds((const unsigned*)((const char*)(gbase) + (voff)[_i]), (PG8_LAS unsigned*)(lds + (bufoff) + ldsw + _i * 8192), 16, 0, 0); } while (0)
; #define PG8_LDA(dst, b, h) do { _Pragma("unroll") for (int m = 0; m < 4; ++m) _Pragma("unroll") for (int k = 0; k < 2; ++k) dst[m][k] = *(const PG8_LAS bf16x8*)(lds + PG8_SA(b, h) + aoff + m * 2048 + k * 1024); } while (0)
; #define PG8_LDB(dst, b, h) do { _Pragma("unroll") for (int n = 0; n < 2; ++n) _Pragma("unroll") for (int k = 0; k < 2; ++k) dst[n][k] = *(const PG8_LAS bf16x8*)(lds + PG8_SB(b, h) + boff + n * 2048 + k * 1024); } while (0)
; #define PG8_MMA(ai, bj, At, Bt) do { __builtin_amdgcn_s_setprio(1); _Pragma("unroll") for (int m = 0; m < 4; ++m) _Pragma("unroll") for (int n = 0; n < 2; ++n) _Pragma("unroll") for (int k = 0; k < 2; ++k) \
;         acc[ai][bj][m][n] = __builtin_amdgcn_mfma_f32_16x16x32_bf16(Bt[n][k], At[m][k], acc[ai][bj][m][n], 0, 0, 0); __builtin_amdgcn_s_setprio(0); } while (0)
; #define PG8_WAIT_V(n) asm volatile("s_waitcnt vmcnt(" #n ")" ::: "memory")
; #define PG8_WAIT_L(n) asm volatile("s_waitcnt lgkmcnt(" #n ")" ::: "memory")
; #define PG8_BAR __builtin_amdgcn_s_barrier()
; #define PG8_SCHED __builtin_amdgcn_sched_barrier(0)
; template <class Epi, class Sched, bool ALIGN_EPI = false, bool SP2 = false>
; __device__ __forceinline__ void gemm_phase(PG8_LAS unsigned char* lds, const Gemm g, const Sched& S, const Epi& E, int tid_in) {
;     ...
;             PG8_WAIT_V(8); PG8_WAIT_L(0); PG8_BAR; PG8_MMA(1, 0, At, B0); PG8_MMA(1, 1, At, B1); PG8_BAR; PG8_SCHED;
;             PG8_LDB(B0, 1, 0); PG8_LDB(B1, 1, 1); PG8_SCHED; PG8_LDA(At, 1, 0); PG8_STAGE(PG8_SA(0, 1), a2 + hsA, voffA);
;             PG8_WAIT_V(8); PG8_WAIT_L(0); PG8_BAR; PG8_MMA(0, 0, At, B0); PG8_MMA(0, 1, At, B1); PG8_BAR; PG8_SCHED;
	s_setprio 1
	s_waitcnt lgkmcnt(0)
	v_mfma_f32_16x16x32_bf16 v[64:67], v[146:149], v[178:181], v[64:67]
	v_mfma_f32_16x16x32_bf16 v[60:63], v[154:157], v[178:181], v[60:63]
	v_mfma_f32_16x16x32_bf16 v[48:51], v[146:149], v[186:189], v[48:51]
	v_mfma_f32_16x16x32_bf16 v[44:47], v[154:157], v[186:189], v[44:47]
	v_mfma_f32_16x16x32_bf16 v[32:35], v[146:149], v[208:211], v[32:35]
	v_mfma_f32_16x16x32_bf16 v[28:31], v[154:157], v[208:211], v[28:31]
	v_mfma_f32_16x16x32_bf16 v[16:19], v[146:149], v[216:219], v[16:19]
	v_mfma_f32_16x16x32_bf16 v[12:15], v[154:157], v[216:219], v[12:15]
	v_mfma_f32_16x16x32_bf16 v[64:67], v[150:153], v[182:185], v[64:67]
	v_mfma_f32_16x16x32_bf16 v[60:63], v[158:161], v[182:185], v[60:63]
	v_mfma_f32_16x16x32_bf16 v[48:51], v[150:153], v[204:207], v[48:51]
	v_mfma_f32_16x16x32_bf16 v[44:47], v[158:161], v[204:207], v[44:47]
	v_mfma_f32_16x16x32_bf16 v[32:35], v[150:153], v[212:215], v[32:35]
	v_mfma_f32_16x16x32_bf16 v[28:31], v[158:161], v[212:215], v[28:31]
	v_mfma_f32_16x16x32_bf16 v[16:19], v[150:153], v[220:223], v[16:19]
	v_mfma_f32_16x16x32_bf16 v[12:15], v[158:161], v[220:223], v[12:15]
	s_setprio 0
	s_setprio 1
	v_mfma_f32_16x16x32_bf16 v[56:59], v[162:165], v[178:181], v[56:59]
	v_mfma_f32_16x16x32_bf16 v[52:55], v[170:173], v[178:181], v[52:55]
	v_mfma_f32_16x16x32_bf16 v[40:43], v[162:165], v[186:189], v[40:43]
	v_mfma_f32_16x16x32_bf16 v[36:39], v[170:173], v[186:189], v[36:39]
	v_mfma_f32_16x16x32_bf16 v[24:27], v[162:165], v[208:211], v[24:27]
	v_mfma_f32_16x16x32_bf16 v[20:23], v[170:173], v[208:211], v[20:23]
	v_mfma_f32_16x16x32_bf16 v[8:11], v[162:165], v[216:219], v[8:11]
	v_mfma_f32_16x16x32_bf16 v[4:7], v[170:173], v[216:219], v[4:7]
	v_mfma_f32_16x16x32_bf16 v[56:59], v[166:169], v[182:185], v[56:59]
	v_mfma_f32_16x16x32_bf16 v[52:55], v[174:177], v[182:185], v[52:55]
	v_mfma_f32_16x16x32_bf16 v[40:43], v[166:169], v[204:207], v[40:43]
	v_mfma_f32_16x16x32_bf16 v[36:39], v[174:177], v[204:207], v[36:39]
	v_mfma_f32_16x16x32_bf16 v[24:27], v[166:169], v[212:215], v[24:27]
	v_mfma_f32_16x16x32_bf16 v[20:23], v[174:177], v[212:215], v[20:23]
	v_mfma_f32_16x16x32_bf16 v[8:11], v[166:169], v[220:223], v[8:11]
	v_mfma_f32_16x16x32_bf16 v[4:7], v[174:177], v[220:223], v[4:7]
	s_setprio 0
	s_barrier
	s_add_i32 s54, 0, 0x18000
	v_add_u32_e32 v145, s54, v142
	s_add_i32 s55, 0, 0x1c000
	ds_read_b128 v[146:149], v145
	ds_read_b128 v[150:153], v145 offset:1024
	ds_read_b128 v[154:157], v145 offset:2048
	ds_read_b128 v[158:161], v145 offset:3072
	v_add_u32_e32 v145, s55, v142
	ds_read_b128 v[162:165], v145
	ds_read_b128 v[166:169], v145 offset:1024
	ds_read_b128 v[170:173], v145 offset:2048
	ds_read_b128 v[174:177], v145 offset:3072
	s_add_u32 s24, s24, s6
	s_addc_u32 s25, s25, s7
	s_mov_b32 m0, s39
	v_lshl_add_u64 v[244:245], s[24:25], 0, v[136:137]
	ds_read_b128 v[178:181], v144 offset:32768
	ds_read_b128 v[182:185], v144 offset:33792
	ds_read_b128 v[186:189], v144 offset:34816
	ds_read_b128 v[204:207], v144 offset:35840
	ds_read_b128 v[208:211], v144 offset:36864
	ds_read_b128 v[212:215], v144 offset:37888
	ds_read_b128 v[216:219], v144 offset:38912
	ds_read_b128 v[220:223], v144 offset:39936
	global_load_lds_dwordx4 v[244:245], off
	v_lshl_add_u64 v[244:245], s[24:25], 0, v[132:133]
	s_mov_b32 m0, s40
	s_nop 0
	global_load_lds_dwordx4 v[244:245], off
	s_add_i32 m0, s35, 0x14000
	s_nop 0
	global_load_lds_dwordx4 v[232:233], off
	s_add_i32 m0, s35, 0x16000
	s_nop 0
	global_load_lds_dwordx4 v[238:239], off
	s_waitcnt vmcnt(8)
	s_waitcnt lgkmcnt(0)
	s_barrier
	s_setprio 1
	s_waitcnt lgkmcnt(0)
	v_mfma_f32_16x16x32_bf16 v[124:127], v[146:149], v[178:181], v[124:127]
	v_mfma_f32_16x16x32_bf16 v[128:131], v[154:157], v[178:181], v[128:131]
	v_mfma_f32_16x16x32_bf16 v[112:115], v[146:149], v[186:189], v[112:115]
	v_mfma_f32_16x16x32_bf16 v[108:111], v[154:157], v[186:189], v[108:111]
	v_mfma_f32_16x16x32_bf16 v[96:99], v[146:149], v[208:211], v[96:99]
	v_mfma_f32_16x16x32_bf16 v[92:95], v[154:157], v[208:211], v[92:95]
	v_mfma_f32_16x16x32_bf16 v[80:83], v[146:149], v[216:219], v[80:83]
	v_mfma_f32_16x16x32_bf16 v[76:79], v[154:157], v[216:219], v[76:79]
	v_mfma_f32_16x16x32_bf16 v[124:127], v[150:153], v[182:185], v[124:127]
	v_mfma_f32_16x16x32_bf16 v[128:131], v[158:161], v[182:185], v[128:131]
	v_mfma_f32_16x16x32_bf16 v[112:115], v[150:153], v[204:207], v[112:115]
	v_mfma_f32_16x16x32_bf16 v[108:111], v[158:161], v[204:207], v[108:111]
	v_mfma_f32_16x16x32_bf16 v[96:99], v[150:153], v[212:215], v[96:99]
	v_mfma_f32_16x16x32_bf16 v[92:95], v[158:161], v[212:215], v[92:95]
	v_mfma_f32_16x16x32_bf16 v[80:83], v[150:153], v[220:223], v[80:83]
	v_mfma_f32_16x16x32_bf16 v[76:79], v[158:161], v[220:223], v[76:79]
	s_setprio 0
	s_setprio 1
	v_mfma_f32_16x16x32_bf16 v[120:123], v[162:165], v[178:181], v[120:123]
	v_mfma_f32_16x16x32_bf16 v[116:119], v[170:173], v[178:181], v[116:119]
	v_mfma_f32_16x16x32_bf16 v[104:107], v[162:165], v[186:189], v[104:107]
	v_mfma_f32_16x16x32_bf16 v[100:103], v[170:173], v[186:189], v[100:103]
	v_mfma_f32_16x16x32_bf16 v[88:91], v[162:165], v[208:211], v[88:91]
	v_mfma_f32_16x16x32_bf16 v[84:87], v[170:173], v[208:211], v[84:87]
	v_mfma_f32_16x16x32_bf16 v[72:75], v[162:165], v[216:219], v[72:75]
	v_mfma_f32_16x16x32_bf16 v[68:71], v[170:173], v[216:219], v[68:71]
	v_mfma_f32_16x16x32_bf16 v[120:123], v[166:169], v[182:185], v[120:123]
	v_mfma_f32_16x16x32_bf16 v[116:119], v[174:177], v[182:185], v[116:119]
	v_mfma_f32_16x16x32_bf16 v[104:107], v[166:169], v[204:207], v[104:107]
	v_mfma_f32_16x16x32_bf16 v[100:103], v[174:177], v[204:207], v[100:103]
	v_mfma_f32_16x16x32_bf16 v[88:91], v[166:169], v[212:215], v[88:91]
	v_mfma_f32_16x16x32_bf16 v[84:87], v[174:177], v[212:215], v[84:87]
	v_mfma_f32_16x16x32_bf16 v[72:75], v[166:169], v[220:223], v[72:75]
	v_mfma_f32_16x16x32_bf16 v[68:71], v[174:177], v[220:223], v[68:71]
	s_setprio 0
	s_barrier
; #define PG8_STAGE(bufoff, gbase, voff) do { _Pragma("unroll") for (int _i = 0; _i < 2; ++_i) \
;         __builtin_amdgcn_global_load_lds((const unsigned*)((const char*)(gbase) + (voff)[_i]), (PG8_LAS unsigned*)(lds + (bufoff) + ldsw + _i * 8192), 16, 0, 0); } while (0)
; #define PG8_LDA(dst, b, h) do { _Pragma("unroll") for (int m = 0; m < 4; ++m) _Pragma("unroll") for (int k = 0; k < 2; ++k) dst[m][k] = *(const PG8_LAS bf16x8*)(lds + PG8_SA(b, h) + aoff + m * 2048 + k * 1024); } while (0)
; #define PG8_MMA(ai, bj, At, Bt) do { __builtin_amdgcn_s_setprio(1); _Pragma("unroll") for (int m = 0; m < 4; ++m) _Pragma("unroll") for (int n = 0; n < 2; ++n) _Pragma("unroll") for (int k = 0; k < 2; ++k) \
;         acc[ai][bj][m][n] = __builtin_amdgcn_mfma_f32_16x16x32_bf16(Bt[n][k], At[m][k], acc[ai][bj][m][n], 0, 0, 0); __builtin_amdgcn_s_setprio(0); } while (0)
; #define PG8_WAIT_V(n) asm volatile("s_waitcnt vmcnt(" #n ")" ::: "memory")
; #define PG8_WAIT_L(n) asm volatile("s_waitcnt lgkmcnt(" #n ")" ::: "memory")
; #define PG8_BAR __builtin_amdgcn_s_barrier()
; #define PG8_SCHED __builtin_amdgcn_sched_barrier(0)
; template <class Epi, class Sched, bool ALIGN_EPI = false, bool SP2 = false>
; __device__ __forceinline__ void gemm_phase(PG8_LAS unsigned char* lds, const Gemm g, const Sched& S, const Epi& E, int tid_in) {
;     ...
;         for (int t = 0; t < nt; t += 2) {
;     ...
;             PG8_LDA(At, 1, 1); PG8_STAGE(PG8_SB(1, 0), b3, voffB); PG8_STAGE(PG8_SB(1, 1), b3 + hsB, voffB); PG8_STAGE(PG8_SA(1, 0), a3, voffA);
;             PG8_WAIT_V(8); PG8_WAIT_L(0); PG8_BAR; PG8_MMA(1, 0, At, B0); PG8_MMA(1, 1, At, B1); PG8_BAR; PG8_SCHED;
	s_add_i32 s24, s54, s35
	v_lshl_add_u64 v[190:191], v[190:191], 0, s[80:81]
	s_mov_b32 m0, s24
	ds_read_b128 v[178:181], v144 offset:49152
	ds_read_b128 v[182:185], v144 offset:50176
	ds_read_b128 v[186:189], v144 offset:51200
	ds_read_b128 v[204:207], v144 offset:52224
	ds_read_b128 v[208:211], v144 offset:53248
	ds_read_b128 v[212:215], v144 offset:54272
	ds_read_b128 v[216:219], v144 offset:55296
	ds_read_b128 v[220:223], v144 offset:56320
	global_load_lds_dwordx4 v[190:191], off
	v_lshl_add_u64 v[190:191], v[230:231], 0, s[80:81]
	s_add_i32 m0, s24, 0x2000
	s_add_i32 s24, s55, s35
	global_load_lds_dwordx4 v[190:191], off
	v_lshl_add_u64 v[190:191], v[232:233], 0, s[80:81]
	s_mov_b32 m0, s24
	s_nop 0
	global_load_lds_dwordx4 v[190:191], off
	v_lshl_add_u64 v[190:191], v[238:239], 0, s[80:81]
	s_add_i32 m0, s24, 0x2000
	s_nop 0
	global_load_lds_dwordx4 v[190:191], off
	v_lshl_add_u64 v[190:191], v[240:241], 0, s[80:81]
	s_mov_b32 m0, s41
	s_nop 0
	global_load_lds_dwordx4 v[190:191], off
	v_lshl_add_u64 v[190:191], v[242:243], 0, s[80:81]
	s_mov_b32 m0, s42
	s_nop 0
	global_load_lds_dwordx4 v[190:191], off
	s_waitcnt vmcnt(6)
	s_waitcnt lgkmcnt(0)
	s_barrier
	s_setprio 1
	s_waitcnt lgkmcnt(0)
	v_mfma_f32_16x16x32_bf16 v[64:67], v[146:149], v[178:181], v[64:67]
	v_mfma_f32_16x16x32_bf16 v[60:63], v[154:157], v[178:181], v[60:63]
	v_mfma_f32_16x16x32_bf16 v[48:51], v[146:149], v[186:189], v[48:51]
	v_mfma_f32_16x16x32_bf16 v[44:47], v[154:157], v[186:189], v[44:47]
	v_mfma_f32_16x16x32_bf16 v[32:35], v[146:149], v[208:211], v[32:35]
	v_mfma_f32_16x16x32_bf16 v[28:31], v[154:157], v[208:211], v[28:31]
	v_mfma_f32_16x16x32_bf16 v[16:19], v[146:149], v[216:219], v[16:19]
	v_mfma_f32_16x16x32_bf16 v[12:15], v[154:157], v[216:219], v[12:15]
	v_mfma_f32_16x16x32_bf16 v[64:67], v[150:153], v[182:185], v[64:67]
	v_mfma_f32_16x16x32_bf16 v[60:63], v[158:161], v[182:185], v[60:63]
	v_mfma_f32_16x16x32_bf16 v[48:51], v[150:153], v[204:207], v[48:51]
	v_mfma_f32_16x16x32_bf16 v[44:47], v[158:161], v[204:207], v[44:47]
	v_mfma_f32_16x16x32_bf16 v[32:35], v[150:153], v[212:215], v[32:35]
	v_mfma_f32_16x16x32_bf16 v[28:31], v[158:161], v[212:215], v[28:31]
	v_mfma_f32_16x16x32_bf16 v[16:19], v[150:153], v[220:223], v[16:19]
	v_mfma_f32_16x16x32_bf16 v[12:15], v[158:161], v[220:223], v[12:15]
	s_setprio 0
	s_setprio 1
	v_mfma_f32_16x16x32_bf16 v[56:59], v[162:165], v[178:181], v[56:59]
	v_mfma_f32_16x16x32_bf16 v[52:55], v[170:173], v[178:181], v[52:55]
	v_mfma_f32_16x16x32_bf16 v[40:43], v[162:165], v[186:189], v[40:43]
	v_mfma_f32_16x16x32_bf16 v[36:39], v[170:173], v[186:189], v[36:39]
	v_mfma_f32_16x16x32_bf16 v[24:27], v[162:165], v[208:211], v[24:27]
	v_mfma_f32_16x16x32_bf16 v[20:23], v[170:173], v[208:211], v[20:23]
	v_mfma_f32_16x16x32_bf16 v[8:11], v[162:165], v[216:219], v[8:11]
	v_mfma_f32_16x16x32_bf16 v[4:7], v[170:173], v[216:219], v[4:7]
	v_mfma_f32_16x16x32_bf16 v[56:59], v[166:169], v[182:185], v[56:59]
	v_mfma_f32_16x16x32_bf16 v[52:55], v[174:177], v[182:185], v[52:55]
	v_mfma_f32_16x16x32_bf16 v[40:43], v[166:169], v[204:207], v[40:43]
	v_mfma_f32_16x16x32_bf16 v[36:39], v[174:177], v[204:207], v[36:39]
	v_mfma_f32_16x16x32_bf16 v[24:27], v[166:169], v[212:215], v[24:27]
	v_mfma_f32_16x16x32_bf16 v[20:23], v[174:177], v[212:215], v[20:23]
	v_mfma_f32_16x16x32_bf16 v[8:11], v[166:169], v[220:223], v[8:11]
	v_mfma_f32_16x16x32_bf16 v[4:7], v[174:177], v[220:223], v[4:7]
	s_setprio 0
	s_barrier
	s_add_i32 s24, s53, 2
	s_add_u32 s51, s51, 0x100
	s_addc_u32 s52, s52, 0
	s_add_u32 s22, s22, 0x100
	s_addc_u32 s23, s23, 0
	s_cmp_ge_i32 s53, s44
	s_mov_b32 s53, s24
	s_cbranch_scc0 .LBB0_485

; #define PG8_STAGE(bufoff, gbase, voff) do { _Pragma("unroll") for (int _i = 0; _i < 2; ++_i) \
;         __builtin_amdgcn_global_load_lds((const unsigned*)((const char*)(gbase) + (voff)[_i]), (PG8_LAS unsigned*)(lds + (bufoff) + ldsw + _i * 8192), 16, 0, 0); } while (0)
; #define PG8_LDA(dst, b, h) do { _Pragma("unroll") for (int m = 0; m < 4; ++m) _Pragma("unroll") for (int k = 0; k < 2; ++k) dst[m][k] = *(const PG8_LAS bf16x8*)(lds + PG8_SA(b, h) + aoff + m * 2048 + k * 1024); } while (0)
; #define PG8_LDB(dst, b, h) do { _Pragma("unroll") for (int n = 0; n < 2; ++n) _Pragma("unroll") for (int k = 0; k < 2; ++k) dst[n][k] = *(const PG8_LAS bf16x8*)(lds + PG8_SB(b, h) + boff + n * 2048 + k * 1024); } while (0)
; #define PG8_MMA(ai, bj, At, Bt) do { __builtin_amdgcn_s_setprio(1); _Pragma("unroll") for (int m = 0; m < 4; ++m) _Pragma("unroll") for (int n = 0; n < 2; ++n) _Pragma("unroll") for (int k = 0; k < 2; ++k) \
;         acc[ai][bj][m][n] = __builtin_amdgcn_mfma_f32_16x16x32_bf16(Bt[n][k], At[m][k], acc[ai][bj][m][n], 0, 0, 0); __builtin_amdgcn_s_setprio(0); } while (0)
; template <class Epi, class Sched, bool ALIGN_EPI = false, bool SP2 = false>
; __device__ __forceinline__ void gemm_phase(PG8_LAS unsigned char* lds, const Gemm g, const Sched& S, const Epi& E, int tid_in) {
;     ...
;             const bool last = (t == nt - 2);
;             if constexpr (mid_hook<Epi>::value) { if (t == Epi::H1 || t == Epi::H2) E.mid(acc, cur, wr, wc, fr, fq, t == Epi::H2); }
;             const char* a1 = cA + (size_t)(t + 1) * kstep + (t >= jt ? jb : 0);
;             const char* a2 = last ? nA : cA + (size_t)(t + 2) * kstep + (t + 2 >= jt ? jb : 0); const char* b2 = last ? nB : cB + (size_t)(t + 2) * kstep;
;             const char* a3 = a2 + kstep; const char* b3 = b2 + kstep;
;             if (last && has_next) S.a_ready(nxt);
;             if constexpr (SP2) {
;             PG8_LDB(B0, 0, 0); PG8_LDB(B1, 0, 1); PG8_SCHED; PG8_LDA(At, 0, 0); PG8_STAGE(PG8_SA(1, 1), a1 + hsA, voffA);
;             PG8_WAIT_V(8); PG8_WAIT_L(0); PG8_BAR; PG8_MMA(0, 0, At, B0); PG8_MMA(0, 1, At, B1); PG8_BAR; PG8_SCHED;
;             PG8_LDA(At, 0, 1); PG8_STAGE(PG8_SB(0, 0), b2, voffB); PG8_STAGE(PG8_SB(0, 1), b2 + hsB, voffB); PG8_STAGE(PG8_SA(0, 0), a2, voffA);
;             PG8_WAIT_V(8); PG8_WAIT_L(0); PG8_BAR; PG8_MMA(1, 0, At, B0); PG8_MMA(1, 1, At, B1); PG8_BAR; PG8_SCHED;
.LBB0_667:
	s_add_i32 s24, s55, -2
	s_cmp_ge_i32 s24, s28
	s_cselect_b32 s58, s29, 0
	s_cselect_b32 s59, s47, 0
	s_cmp_ge_i32 s55, s28
	s_cselect_b32 s25, s29, 0
	s_cselect_b32 s24, s47, 0
	s_add_u32 s25, s22, s25
	s_addc_u32 s24, s23, s24
	s_add_u32 s60, s25, 0x80
	s_addc_u32 s24, s24, 0
	s_add_i32 s62, 0, 0x10000
	s_cmp_eq_u32 s46, s55
	s_cselect_b32 s25, s1, s24
	s_cselect_b32 s24, s0, s60
	s_cselect_b32 s61, s5, s54
	s_cselect_b32 s60, s4, s53
	s_add_i32 s63, 0, 0x14000
	v_add_u32_e32 v48, s62, v162
	v_add_u32_e32 v165, s63, v162
	ds_read_b128 v[28:31], v48
	ds_read_b128 v[32:35], v48 offset:1024
	ds_read_b128 v[44:47], v48 offset:2048
	ds_read_b128 v[48:51], v48 offset:3072
	ds_read_b128 v[158:161], v165
	ds_read_b128 v[166:169], v165 offset:1024
	ds_read_b128 v[170:173], v165 offset:2048
	ds_read_b128 v[174:177], v165 offset:3072
	v_lshl_add_u64 v[190:191], s[22:23], 0, v[156:157]
	v_lshl_add_u64 v[190:191], v[190:191], 0, s[58:59]
	s_add_i32 m0, s38, 0xc000
	ds_read_b128 v[178:181], v164
	ds_read_b128 v[182:185], v164 offset:1024
	ds_read_b128 v[186:189], v164 offset:2048
	ds_read_b128 v[204:207], v164 offset:3072
	ds_read_b128 v[208:211], v164 offset:4096
	ds_read_b128 v[212:215], v164 offset:5120
	ds_read_b128 v[216:219], v164 offset:6144
	ds_read_b128 v[220:223], v164 offset:7168
	global_load_lds_dwordx4 v[190:191], off
	v_lshl_add_u64 v[190:191], s[22:23], 0, v[154:155]
	v_lshl_add_u64 v[190:191], v[190:191], 0, s[58:59]
	s_add_i32 m0, s38, 0xe000
	s_nop 0
	global_load_lds_dwordx4 v[190:191], off
	s_waitcnt vmcnt(8)
	s_waitcnt lgkmcnt(0)
	s_barrier
	s_setprio 1
	s_waitcnt lgkmcnt(0)
	v_mfma_f32_16x16x32_bf16 v[140:143], v[28:31], v[178:181], v[140:143]
	v_mfma_f32_16x16x32_bf16 v[144:147], v[44:47], v[178:181], v[144:147]
	v_mfma_f32_16x16x32_bf16 v[128:131], v[28:31], v[186:189], v[128:131]
	v_mfma_f32_16x16x32_bf16 v[124:127], v[44:47], v[186:189], v[124:127]
	v_mfma_f32_16x16x32_bf16 v[112:115], v[28:31], v[208:211], v[112:115]
	v_mfma_f32_16x16x32_bf16 v[108:111], v[44:47], v[208:211], v[108:111]
	v_mfma_f32_16x16x32_bf16 v[96:99], v[28:31], v[216:219], v[96:99]
	v_mfma_f32_16x16x32_bf16 v[92:95], v[44:47], v[216:219], v[92:95]
	v_mfma_f32_16x16x32_bf16 v[140:143], v[32:35], v[182:185], v[140:143]
	v_mfma_f32_16x16x32_bf16 v[144:147], v[48:51], v[182:185], v[144:147]
	v_mfma_f32_16x16x32_bf16 v[128:131], v[32:35], v[204:207], v[128:131]
	v_mfma_f32_16x16x32_bf16 v[124:127], v[48:51], v[204:207], v[124:127]
	v_mfma_f32_16x16x32_bf16 v[112:115], v[32:35], v[212:215], v[112:115]
	v_mfma_f32_16x16x32_bf16 v[108:111], v[48:51], v[212:215], v[108:111]
	v_mfma_f32_16x16x32_bf16 v[96:99], v[32:35], v[220:223], v[96:99]
	v_mfma_f32_16x16x32_bf16 v[92:95], v[48:51], v[220:223], v[92:95]
	s_setprio 0
	s_setprio 1
	v_mfma_f32_16x16x32_bf16 v[136:139], v[158:161], v[178:181], v[136:139]
	v_mfma_f32_16x16x32_bf16 v[132:135], v[170:173], v[178:181], v[132:135]
	v_mfma_f32_16x16x32_bf16 v[120:123], v[158:161], v[186:189], v[120:123]
	v_mfma_f32_16x16x32_bf16 v[116:119], v[170:173], v[186:189], v[116:119]
	v_mfma_f32_16x16x32_bf16 v[104:107], v[158:161], v[208:211], v[104:107]
	v_mfma_f32_16x16x32_bf16 v[100:103], v[170:173], v[208:211], v[100:103]
	v_mfma_f32_16x16x32_bf16 v[88:91], v[158:161], v[216:219], v[88:91]
	v_mfma_f32_16x16x32_bf16 v[84:87], v[170:173], v[216:219], v[84:87]
	v_mfma_f32_16x16x32_bf16 v[136:139], v[166:169], v[182:185], v[136:139]
	v_mfma_f32_16x16x32_bf16 v[132:135], v[174:177], v[182:185], v[132:135]
	v_mfma_f32_16x16x32_bf16 v[120:123], v[166:169], v[204:207], v[120:123]
	v_mfma_f32_16x16x32_bf16 v[116:119], v[174:177], v[204:207], v[116:119]
	v_mfma_f32_16x16x32_bf16 v[104:107], v[166:169], v[212:215], v[104:107]
	v_mfma_f32_16x16x32_bf16 v[100:103], v[174:177], v[212:215], v[100:103]
	v_mfma_f32_16x16x32_bf16 v[88:91], v[166:169], v[220:223], v[88:91]
	v_mfma_f32_16x16x32_bf16 v[84:87], v[174:177], v[220:223], v[84:87]
	s_setprio 0
	s_barrier
	s_add_i32 s58, s62, s36
	v_lshl_add_u64 v[190:191], s[60:61], 0, v[150:151]
	s_mov_b32 m0, s58
	ds_read_b128 v[178:181], v164 offset:16384
	ds_read_b128 v[182:185], v164 offset:17408
	ds_read_b128 v[186:189], v164 offset:18432
	ds_read_b128 v[204:207], v164 offset:19456
	ds_read_b128 v[208:211], v164 offset:20480
	ds_read_b128 v[212:215], v164 offset:21504
	ds_read_b128 v[216:219], v164 offset:22528
	ds_read_b128 v[220:223], v164 offset:23552
	global_load_lds_dwordx4 v[190:191], off
	s_add_i32 m0, s58, 0x2000
	s_add_u32 s58, s60, s8
	v_lshl_add_u64 v[230:231], s[60:61], 0, v[0:1]
	s_addc_u32 s59, s61, s9
	s_add_i32 s60, s63, s36
	global_load_lds_dwordx4 v[230:231], off
	v_lshl_add_u64 v[232:233], s[58:59], 0, v[150:151]
	v_lshl_add_u64 v[238:239], s[58:59], 0, v[0:1]
	v_lshl_add_u64 v[240:241], s[24:25], 0, v[152:153]
	s_mov_b32 m0, s38
	v_lshl_add_u64 v[242:243], s[24:25], 0, v[148:149]
	global_load_lds_dwordx4 v[240:241], off
	s_mov_b32 m0, s39
	s_nop 0
	global_load_lds_dwordx4 v[242:243], off
	s_waitcnt vmcnt(6)
	s_waitcnt lgkmcnt(0)
	s_barrier
; #define PG8_STAGE(bufoff, gbase, voff) do { _Pragma("unroll") for (int _i = 0; _i < 2; ++_i) \
;         __builtin_amdgcn_global_load_lds((const unsigned*)((const char*)(gbase) + (voff)[_i]), (PG8_LAS unsigned*)(lds + (bufoff) + ldsw + _i * 8192), 16, 0, 0); } while (0)
; #define PG8_LDA(dst, b, h) do { _Pragma("unroll") for (int m = 0; m < 4; ++m) _Pragma("unroll") for (int k = 0; k < 2; ++k) dst[m][k] = *(const PG8_LAS bf16x8*)(lds + PG8_SA(b, h) + aoff + m * 2048 + k * 1024); } while (0)
; #define PG8_LDB(dst, b, h) do { _Pragma("unroll") for (int n = 0; n < 2; ++n) _Pragma("unroll") for (int k = 0; k < 2; ++k) dst[n][k] = *(const PG8_LAS bf16x8*)(lds + PG8_SB(b, h) + boff + n * 2048 + k * 1024); } while (0)
; #define PG8_MMA(ai, bj, At, Bt) do { __builtin_amdgcn_s_setprio(1); _Pragma("unroll") for (int m = 0; m < 4; ++m) _Pragma("unroll") for (int n = 0; n < 2; ++n) _Pragma("unroll") for (int k = 0; k < 2; ++k) \
;         acc[ai][bj][m][n] = __builtin_amdgcn_mfma_f32_16x16x32_bf16(Bt[n][k], At[m][k], acc[ai][bj][m][n], 0, 0, 0); __builtin_amdgcn_s_setprio(0); } while (0)
; #define PG8_WAIT_V(n) asm volatile("s_waitcnt vmcnt(" #n ")" ::: "memory")
; #define PG8_WAIT_L(n) asm volatile("s_waitcnt lgkmcnt(" #n ")" ::: "memory")
; #define PG8_BAR __builtin_amdgcn_s_barrier()
; #define PG8_SCHED __builtin_amdgcn_sched_barrier(0)
; template <class Epi, class Sched, bool ALIGN_EPI = false, bool SP2 = false>
; __device__ __forceinline__ void gemm_phase(PG8_LAS unsigned char* lds, const Gemm g, const Sched& S, const Epi& E, int tid_in) {
;     ...
;             PG8_WAIT_V(8); PG8_WAIT_L(0); PG8_BAR; PG8_MMA(1, 0, At, B0); PG8_MMA(1, 1, At, B1); PG8_BAR; PG8_SCHED;
;             PG8_LDB(B0, 1, 0); PG8_LDB(B1, 1, 1); PG8_SCHED; PG8_LDA(At, 1, 0); PG8_STAGE(PG8_SA(0, 1), a2 + hsA, voffA);
;             PG8_WAIT_V(8); PG8_WAIT_L(0); PG8_BAR; PG8_MMA(0, 0, At, B0); PG8_MMA(0, 1, At, B1); PG8_BAR; PG8_SCHED;
	s_setprio 1
	s_waitcnt lgkmcnt(0)
	v_mfma_f32_16x16x32_bf16 v[80:83], v[28:31], v[178:181], v[80:83]
	v_mfma_f32_16x16x32_bf16 v[76:79], v[44:47], v[178:181], v[76:79]
	v_mfma_f32_16x16x32_bf16 v[64:67], v[28:31], v[186:189], v[64:67]
	v_mfma_f32_16x16x32_bf16 v[60:63], v[44:47], v[186:189], v[60:63]
	v_mfma_f32_16x16x32_bf16 v[40:43], v[28:31], v[208:211], v[40:43]
	v_mfma_f32_16x16x32_bf16 v[36:39], v[44:47], v[208:211], v[36:39]
	v_mfma_f32_16x16x32_bf16 v[16:19], v[28:31], v[216:219], v[16:19]
	v_mfma_f32_16x16x32_bf16 v[12:15], v[44:47], v[216:219], v[12:15]
	v_mfma_f32_16x16x32_bf16 v[80:83], v[32:35], v[182:185], v[80:83]
	v_mfma_f32_16x16x32_bf16 v[76:79], v[48:51], v[182:185], v[76:79]
	v_mfma_f32_16x16x32_bf16 v[64:67], v[32:35], v[204:207], v[64:67]
	v_mfma_f32_16x16x32_bf16 v[60:63], v[48:51], v[204:207], v[60:63]
	v_mfma_f32_16x16x32_bf16 v[40:43], v[32:35], v[212:215], v[40:43]
	v_mfma_f32_16x16x32_bf16 v[36:39], v[48:51], v[212:215], v[36:39]
	v_mfma_f32_16x16x32_bf16 v[16:19], v[32:35], v[220:223], v[16:19]
	v_mfma_f32_16x16x32_bf16 v[12:15], v[48:51], v[220:223], v[12:15]
	s_setprio 0
	s_setprio 1
	v_mfma_f32_16x16x32_bf16 v[24:27], v[158:161], v[208:211], v[24:27]
	v_mfma_f32_16x16x32_bf16 v[20:23], v[170:173], v[208:211], v[20:23]
	v_mfma_f32_16x16x32_bf16 v[8:11], v[158:161], v[216:219], v[8:11]
	v_mfma_f32_16x16x32_bf16 v[4:7], v[170:173], v[216:219], v[4:7]
	v_mfma_f32_16x16x32_bf16 v[28:31], v[158:161], v[178:181], v[72:75]
	v_mfma_f32_16x16x32_bf16 v[32:35], v[170:173], v[178:181], v[68:71]
	v_mfma_f32_16x16x32_bf16 v[44:47], v[158:161], v[186:189], v[56:59]
	v_mfma_f32_16x16x32_bf16 v[48:51], v[170:173], v[186:189], v[52:55]
	v_mfma_f32_16x16x32_bf16 v[24:27], v[166:169], v[212:215], v[24:27]
	v_mfma_f32_16x16x32_bf16 v[20:23], v[174:177], v[212:215], v[20:23]
	v_mfma_f32_16x16x32_bf16 v[8:11], v[166:169], v[220:223], v[8:11]
	v_mfma_f32_16x16x32_bf16 v[4:7], v[174:177], v[220:223], v[4:7]
	v_mfma_f32_16x16x32_bf16 v[28:31], v[166:169], v[182:185], v[28:31]
	v_mfma_f32_16x16x32_bf16 v[32:35], v[174:177], v[182:185], v[32:35]
	v_mfma_f32_16x16x32_bf16 v[44:47], v[166:169], v[204:207], v[44:47]
	v_mfma_f32_16x16x32_bf16 v[48:51], v[174:177], v[204:207], v[48:51]
	s_setprio 0
	s_barrier
	s_add_i32 s58, 0, 0x18000
	s_add_i32 s59, 0, 0x1c000
	v_add_u32_e32 v72, s58, v162
	v_add_u32_e32 v165, s59, v162
	ds_read_b128 v[52:55], v72
	ds_read_b128 v[56:59], v72 offset:1024
	ds_read_b128 v[68:71], v72 offset:2048
	ds_read_b128 v[72:75], v72 offset:3072
	ds_read_b128 v[158:161], v165
	ds_read_b128 v[166:169], v165 offset:1024
	ds_read_b128 v[170:173], v165 offset:2048
	ds_read_b128 v[174:177], v165 offset:3072
	s_add_u32 s24, s24, s6
	s_addc_u32 s25, s25, s7
	s_mov_b32 m0, s40
	v_lshl_add_u64 v[244:245], s[24:25], 0, v[152:153]
	ds_read_b128 v[178:181], v164 offset:32768
	ds_read_b128 v[182:185], v164 offset:33792
	ds_read_b128 v[186:189], v164 offset:34816
	ds_read_b128 v[204:207], v164 offset:35840
	ds_read_b128 v[208:211], v164 offset:36864
	ds_read_b128 v[212:215], v164 offset:37888
	ds_read_b128 v[216:219], v164 offset:38912
	ds_read_b128 v[220:223], v164 offset:39936
	global_load_lds_dwordx4 v[244:245], off
	v_lshl_add_u64 v[244:245], s[24:25], 0, v[148:149]
	s_mov_b32 m0, s41
	s_nop 0
	global_load_lds_dwordx4 v[244:245], off
	s_add_i32 m0, s36, 0x14000
	s_nop 0
	global_load_lds_dwordx4 v[232:233], off
	s_add_i32 m0, s36, 0x16000
	s_nop 0
	global_load_lds_dwordx4 v[238:239], off
	s_waitcnt vmcnt(8)
	s_waitcnt lgkmcnt(0)
	s_barrier
	s_setprio 1
	s_waitcnt lgkmcnt(0)
	v_mfma_f32_16x16x32_bf16 v[140:143], v[52:55], v[178:181], v[140:143]
	v_mfma_f32_16x16x32_bf16 v[144:147], v[68:71], v[178:181], v[144:147]
	v_mfma_f32_16x16x32_bf16 v[128:131], v[52:55], v[186:189], v[128:131]
	v_mfma_f32_16x16x32_bf16 v[124:127], v[68:71], v[186:189], v[124:127]
	v_mfma_f32_16x16x32_bf16 v[112:115], v[52:55], v[208:211], v[112:115]
	v_mfma_f32_16x16x32_bf16 v[108:111], v[68:71], v[208:211], v[108:111]
	v_mfma_f32_16x16x32_bf16 v[96:99], v[52:55], v[216:219], v[96:99]
	v_mfma_f32_16x16x32_bf16 v[92:95], v[68:71], v[216:219], v[92:95]
	v_mfma_f32_16x16x32_bf16 v[140:143], v[56:59], v[182:185], v[140:143]
	v_mfma_f32_16x16x32_bf16 v[144:147], v[72:75], v[182:185], v[144:147]
	v_mfma_f32_16x16x32_bf16 v[128:131], v[56:59], v[204:207], v[128:131]
	v_mfma_f32_16x16x32_bf16 v[124:127], v[72:75], v[204:207], v[124:127]
	v_mfma_f32_16x16x32_bf16 v[112:115], v[56:59], v[212:215], v[112:115]
	v_mfma_f32_16x16x32_bf16 v[108:111], v[72:75], v[212:215], v[108:111]
	v_mfma_f32_16x16x32_bf16 v[96:99], v[56:59], v[220:223], v[96:99]
	v_mfma_f32_16x16x32_bf16 v[92:95], v[72:75], v[220:223], v[92:95]
	s_setprio 0
	s_setprio 1
	v_mfma_f32_16x16x32_bf16 v[136:139], v[158:161], v[178:181], v[136:139]
	v_mfma_f32_16x16x32_bf16 v[132:135], v[170:173], v[178:181], v[132:135]
	v_mfma_f32_16x16x32_bf16 v[120:123], v[158:161], v[186:189], v[120:123]
	v_mfma_f32_16x16x32_bf16 v[116:119], v[170:173], v[186:189], v[116:119]
	v_mfma_f32_16x16x32_bf16 v[104:107], v[158:161], v[208:211], v[104:107]
	v_mfma_f32_16x16x32_bf16 v[100:103], v[170:173], v[208:211], v[100:103]
	v_mfma_f32_16x16x32_bf16 v[88:91], v[158:161], v[216:219], v[88:91]
	v_mfma_f32_16x16x32_bf16 v[84:87], v[170:173], v[216:219], v[84:87]
	v_mfma_f32_16x16x32_bf16 v[136:139], v[166:169], v[182:185], v[136:139]
	v_mfma_f32_16x16x32_bf16 v[132:135], v[174:177], v[182:185], v[132:135]
	v_mfma_f32_16x16x32_bf16 v[120:123], v[166:169], v[204:207], v[120:123]
	v_mfma_f32_16x16x32_bf16 v[116:119], v[174:177], v[204:207], v[116:119]
	v_mfma_f32_16x16x32_bf16 v[104:107], v[166:169], v[212:215], v[104:107]
	v_mfma_f32_16x16x32_bf16 v[100:103], v[174:177], v[212:215], v[100:103]
	v_mfma_f32_16x16x32_bf16 v[88:91], v[166:169], v[220:223], v[88:91]
	v_mfma_f32_16x16x32_bf16 v[84:87], v[174:177], v[220:223], v[84:87]
	s_setprio 0
	s_barrier
; #define PG8_STAGE(bufoff, gbase, voff) do { _Pragma("unroll") for (int _i = 0; _i < 2; ++_i) \
;         __builtin_amdgcn_global_load_lds((const unsigned*)((const char*)(gbase) + (voff)[_i]), (PG8_LAS unsigned*)(lds + (bufoff) + ldsw + _i * 8192), 16, 0, 0); } while (0)
; #define PG8_LDA(dst, b, h) do { _Pragma("unroll") for (int m = 0; m < 4; ++m) _Pragma("unroll") for (int k = 0; k < 2; ++k) dst[m][k] = *(const PG8_LAS bf16x8*)(lds + PG8_SA(b, h) + aoff + m * 2048 + k * 1024); } while (0)
; #define PG8_MMA(ai, bj, At, Bt) do { __builtin_amdgcn_s_setprio(1); _Pragma("unroll") for (int m = 0; m < 4; ++m) _Pragma("unroll") for (int n = 0; n < 2; ++n) _Pragma("unroll") for (int k = 0; k < 2; ++k) \
;         acc[ai][bj][m][n] = __builtin_amdgcn_mfma_f32_16x16x32_bf16(Bt[n][k], At[m][k], acc[ai][bj][m][n], 0, 0, 0); __builtin_amdgcn_s_setprio(0); } while (0)
; #define PG8_WAIT_V(n) asm volatile("s_waitcnt vmcnt(" #n ")" ::: "memory")
; #define PG8_WAIT_L(n) asm volatile("s_waitcnt lgkmcnt(" #n ")" ::: "memory")
; #define PG8_BAR __builtin_amdgcn_s_barrier()
; #define PG8_SCHED __builtin_amdgcn_sched_barrier(0)
; template <class Epi, class Sched, bool ALIGN_EPI = false, bool SP2 = false>
; __device__ __forceinline__ void gemm_phase(PG8_LAS unsigned char* lds, const Gemm g, const Sched& S, const Epi& E, int tid_in) {
;     ...
;         for (int t = 0; t < nt; t += 2) {
;     ...
;             PG8_LDA(At, 1, 1); PG8_STAGE(PG8_SB(1, 0), b3, voffB); PG8_STAGE(PG8_SB(1, 1), b3 + hsB, voffB); PG8_STAGE(PG8_SA(1, 0), a3, voffA);
;             PG8_WAIT_V(8); PG8_WAIT_L(0); PG8_BAR; PG8_MMA(1, 0, At, B0); PG8_MMA(1, 1, At, B1); PG8_BAR; PG8_SCHED;
	s_add_i32 s24, s58, s36
	v_lshl_add_u64 v[190:191], v[190:191], 0, s[80:81]
	s_mov_b32 m0, s24
	ds_read_b128 v[178:181], v164 offset:49152
	ds_read_b128 v[182:185], v164 offset:50176
	ds_read_b128 v[186:189], v164 offset:51200
	ds_read_b128 v[204:207], v164 offset:52224
	ds_read_b128 v[208:211], v164 offset:53248
	ds_read_b128 v[212:215], v164 offset:54272
	ds_read_b128 v[216:219], v164 offset:55296
	ds_read_b128 v[220:223], v164 offset:56320
	global_load_lds_dwordx4 v[190:191], off
	v_lshl_add_u64 v[190:191], v[230:231], 0, s[80:81]
	s_add_i32 m0, s24, 0x2000
	s_add_i32 s24, s59, s36
	global_load_lds_dwordx4 v[190:191], off
	v_lshl_add_u64 v[190:191], v[232:233], 0, s[80:81]
	s_mov_b32 m0, s24
	s_nop 0
	global_load_lds_dwordx4 v[190:191], off
	v_lshl_add_u64 v[190:191], v[238:239], 0, s[80:81]
	s_add_i32 m0, s24, 0x2000
	s_nop 0
	global_load_lds_dwordx4 v[190:191], off
	v_lshl_add_u64 v[190:191], v[240:241], 0, s[80:81]
	s_mov_b32 m0, s44
	s_nop 0
	global_load_lds_dwordx4 v[190:191], off
	v_lshl_add_u64 v[190:191], v[242:243], 0, s[80:81]
	s_mov_b32 m0, s45
	s_nop 0
	global_load_lds_dwordx4 v[190:191], off
	s_waitcnt vmcnt(6)
	s_waitcnt lgkmcnt(0)
	s_barrier
	s_setprio 1
	s_waitcnt lgkmcnt(0)
	v_mfma_f32_16x16x32_bf16 v[80:83], v[52:55], v[178:181], v[80:83]
	v_mfma_f32_16x16x32_bf16 v[76:79], v[68:71], v[178:181], v[76:79]
	v_mfma_f32_16x16x32_bf16 v[64:67], v[52:55], v[186:189], v[64:67]
	v_mfma_f32_16x16x32_bf16 v[60:63], v[68:71], v[186:189], v[60:63]
	v_mfma_f32_16x16x32_bf16 v[40:43], v[52:55], v[208:211], v[40:43]
	v_mfma_f32_16x16x32_bf16 v[36:39], v[68:71], v[208:211], v[36:39]
	v_mfma_f32_16x16x32_bf16 v[16:19], v[52:55], v[216:219], v[16:19]
	v_mfma_f32_16x16x32_bf16 v[12:15], v[68:71], v[216:219], v[12:15]
	v_mfma_f32_16x16x32_bf16 v[80:83], v[56:59], v[182:185], v[80:83]
	v_mfma_f32_16x16x32_bf16 v[76:79], v[72:75], v[182:185], v[76:79]
	v_mfma_f32_16x16x32_bf16 v[64:67], v[56:59], v[204:207], v[64:67]
	v_mfma_f32_16x16x32_bf16 v[60:63], v[72:75], v[204:207], v[60:63]
	v_mfma_f32_16x16x32_bf16 v[40:43], v[56:59], v[212:215], v[40:43]
	v_mfma_f32_16x16x32_bf16 v[36:39], v[72:75], v[212:215], v[36:39]
	v_mfma_f32_16x16x32_bf16 v[16:19], v[56:59], v[220:223], v[16:19]
	v_mfma_f32_16x16x32_bf16 v[12:15], v[72:75], v[220:223], v[12:15]
	s_setprio 0
	s_setprio 1
	v_mfma_f32_16x16x32_bf16 v[28:31], v[158:161], v[178:181], v[28:31]
	v_mfma_f32_16x16x32_bf16 v[72:75], v[166:169], v[182:185], v[28:31]
	v_mfma_f32_16x16x32_bf16 v[28:31], v[170:173], v[178:181], v[32:35]
	v_mfma_f32_16x16x32_bf16 v[68:71], v[174:177], v[182:185], v[28:31]
	v_mfma_f32_16x16x32_bf16 v[28:31], v[158:161], v[186:189], v[44:47]
	v_mfma_f32_16x16x32_bf16 v[56:59], v[166:169], v[204:207], v[28:31]
	v_mfma_f32_16x16x32_bf16 v[28:31], v[170:173], v[186:189], v[48:51]
	v_mfma_f32_16x16x32_bf16 v[24:27], v[158:161], v[208:211], v[24:27]
	v_mfma_f32_16x16x32_bf16 v[20:23], v[170:173], v[208:211], v[20:23]
	v_mfma_f32_16x16x32_bf16 v[8:11], v[158:161], v[216:219], v[8:11]
	v_mfma_f32_16x16x32_bf16 v[4:7], v[170:173], v[216:219], v[4:7]
	v_mfma_f32_16x16x32_bf16 v[52:55], v[174:177], v[204:207], v[28:31]
	v_mfma_f32_16x16x32_bf16 v[24:27], v[166:169], v[212:215], v[24:27]
	v_mfma_f32_16x16x32_bf16 v[20:23], v[174:177], v[212:215], v[20:23]
	v_mfma_f32_16x16x32_bf16 v[8:11], v[166:169], v[220:223], v[8:11]
	v_mfma_f32_16x16x32_bf16 v[4:7], v[174:177], v[220:223], v[4:7]
	s_setprio 0
	s_barrier
	s_add_i32 s24, s55, 2
	s_add_u32 s53, s53, 0x100
	s_addc_u32 s54, s54, 0
	s_add_u32 s22, s22, 0x100
	s_addc_u32 s23, s23, 0
	s_cmp_ge_i32 s55, s46
	s_mov_b32 s55, s24
	s_cbranch_scc0 .LBB0_667

; #define PG8_STAGE(bufoff, gbase, voff) do { _Pragma("unroll") for (int _i = 0; _i < 2; ++_i) \
;         __builtin_amdgcn_global_load_lds((const unsigned*)((const char*)(gbase) + (voff)[_i]), (PG8_LAS unsigned*)(lds + (bufoff) + ldsw + _i * 8192), 16, 0, 0); } while (0)
; #define PG8_LDA(dst, b, h) do { _Pragma("unroll") for (int m = 0; m < 4; ++m) _Pragma("unroll") for (int k = 0; k < 2; ++k) dst[m][k] = *(const PG8_LAS bf16x8*)(lds + PG8_SA(b, h) + aoff + m * 2048 + k * 1024); } while (0)
; #define PG8_LDB(dst, b, h) do { _Pragma("unroll") for (int n = 0; n < 2; ++n) _Pragma("unroll") for (int k = 0; k < 2; ++k) dst[n][k] = *(const PG8_LAS bf16x8*)(lds + PG8_SB(b, h) + boff + n * 2048 + k * 1024); } while (0)
; #define PG8_MMA(ai, bj, At, Bt) do { __builtin_amdgcn_s_setprio(1); _Pragma("unroll") for (int m = 0; m < 4; ++m) _Pragma("unroll") for (int n = 0; n < 2; ++n) _Pragma("unroll") for (int k = 0; k < 2; ++k) \
;         acc[ai][bj][m][n] = __builtin_amdgcn_mfma_f32_16x16x32_bf16(Bt[n][k], At[m][k], acc[ai][bj][m][n], 0, 0, 0); __builtin_amdgcn_s_setprio(0); } while (0)
; template <class Epi, class Sched, bool ALIGN_EPI = false, bool SP2 = false>
; __device__ __forceinline__ void gemm_phase(PG8_LAS unsigned char* lds, const Gemm g, const Sched& S, const Epi& E, int tid_in) {
;     ...
;             const bool last = (t == nt - 2);
;             if constexpr (mid_hook<Epi>::value) { if (t == Epi::H1 || t == Epi::H2) E.mid(acc, cur, wr, wc, fr, fq, t == Epi::H2); }
;             const char* a1 = cA + (size_t)(t + 1) * kstep + (t >= jt ? jb : 0);
;             const char* a2 = last ? nA : cA + (size_t)(t + 2) * kstep + (t + 2 >= jt ? jb : 0); const char* b2 = last ? nB : cB + (size_t)(t + 2) * kstep;
;             const char* a3 = a2 + kstep; const char* b3 = b2 + kstep;
;             if (last && has_next) S.a_ready(nxt);
;             if constexpr (SP2) {
;             PG8_LDB(B0, 0, 0); PG8_LDB(B1, 0, 1); PG8_SCHED; PG8_LDA(At, 0, 0); PG8_STAGE(PG8_SA(1, 1), a1 + hsA, voffA);
;             PG8_WAIT_V(8); PG8_WAIT_L(0); PG8_BAR; PG8_MMA(0, 0, At, B0); PG8_MMA(0, 1, At, B1); PG8_BAR; PG8_SCHED;
;             PG8_LDA(At, 0, 1); PG8_STAGE(PG8_SB(0, 0), b2, voffB); PG8_STAGE(PG8_SB(0, 1), b2 + hsB, voffB); PG8_STAGE(PG8_SA(0, 0), a2, voffA);
;             PG8_WAIT_V(8); PG8_WAIT_L(0); PG8_BAR; PG8_MMA(1, 0, At, B0); PG8_MMA(1, 1, At, B1); PG8_BAR; PG8_SCHED;
.LBB0_688:
	s_add_i32 s24, s55, -2
	s_cmp_ge_i32 s24, s28
	s_cselect_b32 s58, s29, 0
	s_cselect_b32 s59, s46, 0
	s_cmp_ge_i32 s55, s28
	s_cselect_b32 s25, s29, 0
	s_cselect_b32 s24, s46, 0
	s_add_u32 s25, s22, s25
	s_addc_u32 s24, s23, s24
	s_add_u32 s60, s25, 0x80
	s_addc_u32 s24, s24, 0
	s_add_i32 s62, 0, 0x10000
	s_cmp_eq_u32 s45, s55
	s_cselect_b32 s25, s5, s24
	s_cselect_b32 s24, s4, s60
	s_cselect_b32 s61, s21, s54
	s_cselect_b32 s60, s20, s53
	s_add_i32 s63, 0, 0x14000
	v_add_u32_e32 v88, s62, v160
	v_add_u32_e32 v158, s63, v160
	ds_read_b128 v[68:71], v88
	ds_read_b128 v[72:75], v88 offset:1024
	ds_read_b128 v[84:87], v88 offset:2048
	ds_read_b128 v[88:91], v88 offset:3072
	ds_read_b128 v[164:167], v158
	ds_read_b128 v[168:171], v158 offset:1024
	ds_read_b128 v[172:175], v158 offset:2048
	ds_read_b128 v[176:179], v158 offset:3072
	v_lshl_add_u64 v[158:159], s[22:23], 0, v[156:157]
	v_lshl_add_u64 v[158:159], v[158:159], 0, s[58:59]
	s_add_i32 m0, s37, 0xc000
	ds_read_b128 v[180:183], v162
	ds_read_b128 v[184:187], v162 offset:1024
	ds_read_b128 v[188:191], v162 offset:2048
	ds_read_b128 v[204:207], v162 offset:3072
	ds_read_b128 v[208:211], v162 offset:4096
	ds_read_b128 v[212:215], v162 offset:5120
	ds_read_b128 v[216:219], v162 offset:6144
	ds_read_b128 v[220:223], v162 offset:7168
	global_load_lds_dwordx4 v[158:159], off
	v_lshl_add_u64 v[158:159], s[22:23], 0, v[154:155]
	v_lshl_add_u64 v[158:159], v[158:159], 0, s[58:59]
	s_add_i32 m0, s37, 0xe000
	s_nop 0
	global_load_lds_dwordx4 v[158:159], off
	s_waitcnt vmcnt(8)
	s_waitcnt lgkmcnt(0)
	s_barrier
	s_setprio 1
	s_waitcnt lgkmcnt(0)
	v_mfma_f32_16x16x32_bf16 v[140:143], v[68:71], v[180:183], v[140:143]
	v_mfma_f32_16x16x32_bf16 v[144:147], v[84:87], v[180:183], v[144:147]
	v_mfma_f32_16x16x32_bf16 v[128:131], v[68:71], v[188:191], v[128:131]
	v_mfma_f32_16x16x32_bf16 v[124:127], v[84:87], v[188:191], v[124:127]
	v_mfma_f32_16x16x32_bf16 v[112:115], v[68:71], v[208:211], v[112:115]
	v_mfma_f32_16x16x32_bf16 v[108:111], v[84:87], v[208:211], v[108:111]
	v_mfma_f32_16x16x32_bf16 v[96:99], v[68:71], v[216:219], v[96:99]
	v_mfma_f32_16x16x32_bf16 v[92:95], v[84:87], v[216:219], v[92:95]
	v_mfma_f32_16x16x32_bf16 v[140:143], v[72:75], v[184:187], v[140:143]
	v_mfma_f32_16x16x32_bf16 v[144:147], v[88:91], v[184:187], v[144:147]
	v_mfma_f32_16x16x32_bf16 v[128:131], v[72:75], v[204:207], v[128:131]
	v_mfma_f32_16x16x32_bf16 v[124:127], v[88:91], v[204:207], v[124:127]
	v_mfma_f32_16x16x32_bf16 v[112:115], v[72:75], v[212:215], v[112:115]
	v_mfma_f32_16x16x32_bf16 v[108:111], v[88:91], v[212:215], v[108:111]
	v_mfma_f32_16x16x32_bf16 v[96:99], v[72:75], v[220:223], v[96:99]
	v_mfma_f32_16x16x32_bf16 v[92:95], v[88:91], v[220:223], v[92:95]
	s_setprio 0
	s_setprio 1
	v_mfma_f32_16x16x32_bf16 v[136:139], v[164:167], v[180:183], v[136:139]
	v_mfma_f32_16x16x32_bf16 v[132:135], v[172:175], v[180:183], v[132:135]
	v_mfma_f32_16x16x32_bf16 v[120:123], v[164:167], v[188:191], v[120:123]
	v_mfma_f32_16x16x32_bf16 v[116:119], v[172:175], v[188:191], v[116:119]
	v_mfma_f32_16x16x32_bf16 v[104:107], v[164:167], v[208:211], v[104:107]
	v_mfma_f32_16x16x32_bf16 v[100:103], v[172:175], v[208:211], v[100:103]
	v_mfma_f32_16x16x32_bf16 v[80:83], v[164:167], v[216:219], v[80:83]
	v_mfma_f32_16x16x32_bf16 v[76:79], v[172:175], v[216:219], v[76:79]
	v_mfma_f32_16x16x32_bf16 v[136:139], v[168:171], v[184:187], v[136:139]
	v_mfma_f32_16x16x32_bf16 v[132:135], v[176:179], v[184:187], v[132:135]
	v_mfma_f32_16x16x32_bf16 v[120:123], v[168:171], v[204:207], v[120:123]
	v_mfma_f32_16x16x32_bf16 v[116:119], v[176:179], v[204:207], v[116:119]
	v_mfma_f32_16x16x32_bf16 v[104:107], v[168:171], v[212:215], v[104:107]
	v_mfma_f32_16x16x32_bf16 v[100:103], v[176:179], v[212:215], v[100:103]
	v_mfma_f32_16x16x32_bf16 v[80:83], v[168:171], v[220:223], v[80:83]
	v_mfma_f32_16x16x32_bf16 v[76:79], v[176:179], v[220:223], v[76:79]
	s_setprio 0
	s_barrier
	s_add_i32 s58, s62, s35
	v_lshl_add_u64 v[158:159], s[60:61], 0, v[150:151]
	s_mov_b32 m0, s58
	ds_read_b128 v[180:183], v162 offset:16384
	ds_read_b128 v[184:187], v162 offset:17408
	ds_read_b128 v[188:191], v162 offset:18432
	ds_read_b128 v[204:207], v162 offset:19456
	ds_read_b128 v[208:211], v162 offset:20480
	ds_read_b128 v[212:215], v162 offset:21504
	ds_read_b128 v[216:219], v162 offset:22528
	ds_read_b128 v[220:223], v162 offset:23552
	global_load_lds_dwordx4 v[158:159], off
	s_add_i32 m0, s58, 0x2000
	s_add_u32 s58, s60, s6
	v_lshl_add_u64 v[230:231], s[60:61], 0, v[0:1]
	s_addc_u32 s59, s61, s7
	s_add_i32 s60, s63, s35
	global_load_lds_dwordx4 v[230:231], off
	v_lshl_add_u64 v[232:233], s[58:59], 0, v[150:151]
	v_lshl_add_u64 v[238:239], s[58:59], 0, v[0:1]
	v_lshl_add_u64 v[240:241], s[24:25], 0, v[152:153]
	s_mov_b32 m0, s37
	v_lshl_add_u64 v[242:243], s[24:25], 0, v[148:149]
	global_load_lds_dwordx4 v[240:241], off
	s_mov_b32 m0, s38
	s_nop 0
	global_load_lds_dwordx4 v[242:243], off
	s_waitcnt vmcnt(6)
	s_waitcnt lgkmcnt(0)
	s_barrier
; #define PG8_STAGE(bufoff, gbase, voff) do { _Pragma("unroll") for (int _i = 0; _i < 2; ++_i) \
;         __builtin_amdgcn_global_load_lds((const unsigned*)((const char*)(gbase) + (voff)[_i]), (PG8_LAS unsigned*)(lds + (bufoff) + ldsw + _i * 8192), 16, 0, 0); } while (0)
; #define PG8_LDA(dst, b, h) do { _Pragma("unroll") for (int m = 0; m < 4; ++m) _Pragma("unroll") for (int k = 0; k < 2; ++k) dst[m][k] = *(const PG8_LAS bf16x8*)(lds + PG8_SA(b, h) + aoff + m * 2048 + k * 1024); } while (0)
; #define PG8_LDB(dst, b, h) do { _Pragma("unroll") for (int n = 0; n < 2; ++n) _Pragma("unroll") for (int k = 0; k < 2; ++k) dst[n][k] = *(const PG8_LAS bf16x8*)(lds + PG8_SB(b, h) + boff + n * 2048 + k * 1024); } while (0)
; #define PG8_MMA(ai, bj, At, Bt) do { __builtin_amdgcn_s_setprio(1); _Pragma("unroll") for (int m = 0; m < 4; ++m) _Pragma("unroll") for (int n = 0; n < 2; ++n) _Pragma("unroll") for (int k = 0; k < 2; ++k) \
;         acc[ai][bj][m][n] = __builtin_amdgcn_mfma_f32_16x16x32_bf16(Bt[n][k], At[m][k], acc[ai][bj][m][n], 0, 0, 0); __builtin_amdgcn_s_setprio(0); } while (0)
; #define PG8_WAIT_V(n) asm volatile("s_waitcnt vmcnt(" #n ")" ::: "memory")
; #define PG8_WAIT_L(n) asm volatile("s_waitcnt lgkmcnt(" #n ")" ::: "memory")
; #define PG8_BAR __builtin_amdgcn_s_barrier()
; #define PG8_SCHED __builtin_amdgcn_sched_barrier(0)
; template <class Epi, class Sched, bool ALIGN_EPI = false, bool SP2 = false>
; __device__ __forceinline__ void gemm_phase(PG8_LAS unsigned char* lds, const Gemm g, const Sched& S, const Epi& E, int tid_in) {
;     ...
;             PG8_WAIT_V(8); PG8_WAIT_L(0); PG8_BAR; PG8_MMA(1, 0, At, B0); PG8_MMA(1, 1, At, B1); PG8_BAR; PG8_SCHED;
;             PG8_LDB(B0, 1, 0); PG8_LDB(B1, 1, 1); PG8_SCHED; PG8_LDA(At, 1, 0); PG8_STAGE(PG8_SA(0, 1), a2 + hsA, voffA);
;             PG8_WAIT_V(8); PG8_WAIT_L(0); PG8_BAR; PG8_MMA(0, 0, At, B0); PG8_MMA(0, 1, At, B1); PG8_BAR; PG8_SCHED;
	s_setprio 1
	s_waitcnt lgkmcnt(0)
	v_mfma_f32_16x16x32_bf16 v[64:67], v[68:71], v[180:183], v[64:67]
	v_mfma_f32_16x16x32_bf16 v[60:63], v[84:87], v[180:183], v[60:63]
	v_mfma_f32_16x16x32_bf16 v[48:51], v[68:71], v[188:191], v[48:51]
	v_mfma_f32_16x16x32_bf16 v[44:47], v[84:87], v[188:191], v[44:47]
	v_mfma_f32_16x16x32_bf16 v[32:35], v[68:71], v[208:211], v[32:35]
	v_mfma_f32_16x16x32_bf16 v[28:31], v[84:87], v[208:211], v[28:31]
	v_mfma_f32_16x16x32_bf16 v[16:19], v[68:71], v[216:219], v[16:19]
	v_mfma_f32_16x16x32_bf16 v[12:15], v[84:87], v[216:219], v[12:15]
	v_mfma_f32_16x16x32_bf16 v[64:67], v[72:75], v[184:187], v[64:67]
	v_mfma_f32_16x16x32_bf16 v[60:63], v[88:91], v[184:187], v[60:63]
	v_mfma_f32_16x16x32_bf16 v[48:51], v[72:75], v[204:207], v[48:51]
	v_mfma_f32_16x16x32_bf16 v[44:47], v[88:91], v[204:207], v[44:47]
	v_mfma_f32_16x16x32_bf16 v[32:35], v[72:75], v[212:215], v[32:35]
	v_mfma_f32_16x16x32_bf16 v[28:31], v[88:91], v[212:215], v[28:31]
	v_mfma_f32_16x16x32_bf16 v[16:19], v[72:75], v[220:223], v[16:19]
	v_mfma_f32_16x16x32_bf16 v[12:15], v[88:91], v[220:223], v[12:15]
	s_setprio 0
	s_setprio 1
	v_mfma_f32_16x16x32_bf16 v[56:59], v[164:167], v[180:183], v[56:59]
	v_mfma_f32_16x16x32_bf16 v[52:55], v[172:175], v[180:183], v[52:55]
	v_mfma_f32_16x16x32_bf16 v[40:43], v[164:167], v[188:191], v[40:43]
	v_mfma_f32_16x16x32_bf16 v[36:39], v[172:175], v[188:191], v[36:39]
	v_mfma_f32_16x16x32_bf16 v[24:27], v[164:167], v[208:211], v[24:27]
	v_mfma_f32_16x16x32_bf16 v[20:23], v[172:175], v[208:211], v[20:23]
	v_mfma_f32_16x16x32_bf16 v[8:11], v[164:167], v[216:219], v[8:11]
	v_mfma_f32_16x16x32_bf16 v[4:7], v[172:175], v[216:219], v[4:7]
	v_mfma_f32_16x16x32_bf16 v[56:59], v[168:171], v[184:187], v[56:59]
	v_mfma_f32_16x16x32_bf16 v[52:55], v[176:179], v[184:187], v[52:55]
	v_mfma_f32_16x16x32_bf16 v[40:43], v[168:171], v[204:207], v[40:43]
	v_mfma_f32_16x16x32_bf16 v[36:39], v[176:179], v[204:207], v[36:39]
	v_mfma_f32_16x16x32_bf16 v[24:27], v[168:171], v[212:215], v[24:27]
	v_mfma_f32_16x16x32_bf16 v[20:23], v[176:179], v[212:215], v[20:23]
	v_mfma_f32_16x16x32_bf16 v[8:11], v[168:171], v[220:223], v[8:11]
	v_mfma_f32_16x16x32_bf16 v[4:7], v[176:179], v[220:223], v[4:7]
	s_setprio 0
	s_barrier
	s_add_i32 s58, 0, 0x18000
	s_add_i32 s59, 0, 0x1c000
	v_add_u32_e32 v88, s58, v160
	v_add_u32_e32 v163, s59, v160
	ds_read_b128 v[68:71], v88
	ds_read_b128 v[72:75], v88 offset:1024
	ds_read_b128 v[84:87], v88 offset:2048
	ds_read_b128 v[88:91], v88 offset:3072
	ds_read_b128 v[164:167], v163
	ds_read_b128 v[168:171], v163 offset:1024
	ds_read_b128 v[172:175], v163 offset:2048
	ds_read_b128 v[176:179], v163 offset:3072
	s_add_u32 s24, s24, s0
	s_addc_u32 s25, s25, s1
	s_mov_b32 m0, s39
	v_lshl_add_u64 v[244:245], s[24:25], 0, v[152:153]
	ds_read_b128 v[180:183], v162 offset:32768
	ds_read_b128 v[184:187], v162 offset:33792
	ds_read_b128 v[188:191], v162 offset:34816
	ds_read_b128 v[204:207], v162 offset:35840
	ds_read_b128 v[208:211], v162 offset:36864
	ds_read_b128 v[212:215], v162 offset:37888
	ds_read_b128 v[216:219], v162 offset:38912
	ds_read_b128 v[220:223], v162 offset:39936
	global_load_lds_dwordx4 v[244:245], off
	v_lshl_add_u64 v[244:245], s[24:25], 0, v[148:149]
	s_mov_b32 m0, s40
	s_nop 0
	global_load_lds_dwordx4 v[244:245], off
	s_add_i32 m0, s35, 0x14000
	s_nop 0
	global_load_lds_dwordx4 v[232:233], off
	s_add_i32 m0, s35, 0x16000
	s_nop 0
	global_load_lds_dwordx4 v[238:239], off
	s_waitcnt vmcnt(8)
	s_waitcnt lgkmcnt(0)
	s_barrier
	s_setprio 1
	s_waitcnt lgkmcnt(0)
	v_mfma_f32_16x16x32_bf16 v[140:143], v[68:71], v[180:183], v[140:143]
	v_mfma_f32_16x16x32_bf16 v[144:147], v[84:87], v[180:183], v[144:147]
	v_mfma_f32_16x16x32_bf16 v[128:131], v[68:71], v[188:191], v[128:131]
	v_mfma_f32_16x16x32_bf16 v[124:127], v[84:87], v[188:191], v[124:127]
	v_mfma_f32_16x16x32_bf16 v[112:115], v[68:71], v[208:211], v[112:115]
	v_mfma_f32_16x16x32_bf16 v[108:111], v[84:87], v[208:211], v[108:111]
	v_mfma_f32_16x16x32_bf16 v[96:99], v[68:71], v[216:219], v[96:99]
	v_mfma_f32_16x16x32_bf16 v[92:95], v[84:87], v[216:219], v[92:95]
	v_mfma_f32_16x16x32_bf16 v[140:143], v[72:75], v[184:187], v[140:143]
	v_mfma_f32_16x16x32_bf16 v[144:147], v[88:91], v[184:187], v[144:147]
	v_mfma_f32_16x16x32_bf16 v[128:131], v[72:75], v[204:207], v[128:131]
	v_mfma_f32_16x16x32_bf16 v[124:127], v[88:91], v[204:207], v[124:127]
	v_mfma_f32_16x16x32_bf16 v[112:115], v[72:75], v[212:215], v[112:115]
	v_mfma_f32_16x16x32_bf16 v[108:111], v[88:91], v[212:215], v[108:111]
	v_mfma_f32_16x16x32_bf16 v[96:99], v[72:75], v[220:223], v[96:99]
	v_mfma_f32_16x16x32_bf16 v[92:95], v[88:91], v[220:223], v[92:95]
	s_setprio 0
	s_setprio 1
	v_mfma_f32_16x16x32_bf16 v[136:139], v[164:167], v[180:183], v[136:139]
	v_mfma_f32_16x16x32_bf16 v[132:135], v[172:175], v[180:183], v[132:135]
	v_mfma_f32_16x16x32_bf16 v[120:123], v[164:167], v[188:191], v[120:123]
	v_mfma_f32_16x16x32_bf16 v[116:119], v[172:175], v[188:191], v[116:119]
	v_mfma_f32_16x16x32_bf16 v[104:107], v[164:167], v[208:211], v[104:107]
	v_mfma_f32_16x16x32_bf16 v[100:103], v[172:175], v[208:211], v[100:103]
	v_mfma_f32_16x16x32_bf16 v[80:83], v[164:167], v[216:219], v[80:83]
	v_mfma_f32_16x16x32_bf16 v[76:79], v[172:175], v[216:219], v[76:79]
	v_mfma_f32_16x16x32_bf16 v[136:139], v[168:171], v[184:187], v[136:139]
	v_mfma_f32_16x16x32_bf16 v[132:135], v[176:179], v[184:187], v[132:135]
	v_mfma_f32_16x16x32_bf16 v[120:123], v[168:171], v[204:207], v[120:123]
	v_mfma_f32_16x16x32_bf16 v[116:119], v[176:179], v[204:207], v[116:119]
	v_mfma_f32_16x16x32_bf16 v[104:107], v[168:171], v[212:215], v[104:107]
	v_mfma_f32_16x16x32_bf16 v[100:103], v[176:179], v[212:215], v[100:103]
	v_mfma_f32_16x16x32_bf16 v[80:83], v[168:171], v[220:223], v[80:83]
	v_mfma_f32_16x16x32_bf16 v[76:79], v[176:179], v[220:223], v[76:79]
	s_setprio 0
	s_barrier
; #define PG8_STAGE(bufoff, gbase, voff) do { _Pragma("unroll") for (int _i = 0; _i < 2; ++_i) \
;         __builtin_amdgcn_global_load_lds((const unsigned*)((const char*)(gbase) + (voff)[_i]), (PG8_LAS unsigned*)(lds + (bufoff) + ldsw + _i * 8192), 16, 0, 0); } while (0)
; #define PG8_LDA(dst, b, h) do { _Pragma("unroll") for (int m = 0; m < 4; ++m) _Pragma("unroll") for (int k = 0; k < 2; ++k) dst[m][k] = *(const PG8_LAS bf16x8*)(lds + PG8_SA(b, h) + aoff + m * 2048 + k * 1024); } while (0)
; #define PG8_MMA(ai, bj, At, Bt) do { __builtin_amdgcn_s_setprio(1); _Pragma("unroll") for (int m = 0; m < 4; ++m) _Pragma("unroll") for (int n = 0; n < 2; ++n) _Pragma("unroll") for (int k = 0; k < 2; ++k) \
;         acc[ai][bj][m][n] = __builtin_amdgcn_mfma_f32_16x16x32_bf16(Bt[n][k], At[m][k], acc[ai][bj][m][n], 0, 0, 0); __builtin_amdgcn_s_setprio(0); } while (0)
; #define PG8_WAIT_V(n) asm volatile("s_waitcnt vmcnt(" #n ")" ::: "memory")
; #define PG8_WAIT_L(n) asm volatile("s_waitcnt lgkmcnt(" #n ")" ::: "memory")
; #define PG8_BAR __builtin_amdgcn_s_barrier()
; #define PG8_SCHED __builtin_amdgcn_sched_barrier(0)
; template <class Epi, class Sched, bool ALIGN_EPI = false, bool SP2 = false>
; __device__ __forceinline__ void gemm_phase(PG8_LAS unsigned char* lds, const Gemm g, const Sched& S, const Epi& E, int tid_in) {
;     ...
;         for (int t = 0; t < nt; t += 2) {
;     ...
;             PG8_LDA(At, 1, 1); PG8_STAGE(PG8_SB(1, 0), b3, voffB); PG8_STAGE(PG8_SB(1, 1), b3 + hsB, voffB); PG8_STAGE(PG8_SA(1, 0), a3, voffA);
;             PG8_WAIT_V(8); PG8_WAIT_L(0); PG8_BAR; PG8_MMA(1, 0, At, B0); PG8_MMA(1, 1, At, B1); PG8_BAR; PG8_SCHED;
	s_add_i32 s24, s58, s35
	v_lshl_add_u64 v[158:159], v[158:159], 0, s[80:81]
	s_mov_b32 m0, s24
	ds_read_b128 v[180:183], v162 offset:49152
	ds_read_b128 v[184:187], v162 offset:50176
	ds_read_b128 v[188:191], v162 offset:51200
	ds_read_b128 v[204:207], v162 offset:52224
	ds_read_b128 v[208:211], v162 offset:53248
	ds_read_b128 v[212:215], v162 offset:54272
	ds_read_b128 v[216:219], v162 offset:55296
	ds_read_b128 v[220:223], v162 offset:56320
	global_load_lds_dwordx4 v[158:159], off
	v_lshl_add_u64 v[158:159], v[230:231], 0, s[80:81]
	s_add_i32 m0, s24, 0x2000
	s_add_i32 s24, s59, s35
	global_load_lds_dwordx4 v[158:159], off
	v_lshl_add_u64 v[158:159], v[232:233], 0, s[80:81]
	s_mov_b32 m0, s24
	s_nop 0
	global_load_lds_dwordx4 v[158:159], off
	v_lshl_add_u64 v[158:159], v[238:239], 0, s[80:81]
	s_add_i32 m0, s24, 0x2000
	s_nop 0
	global_load_lds_dwordx4 v[158:159], off
	v_lshl_add_u64 v[158:159], v[240:241], 0, s[80:81]
	s_mov_b32 m0, s43
	s_nop 0
	global_load_lds_dwordx4 v[158:159], off
	v_lshl_add_u64 v[158:159], v[242:243], 0, s[80:81]
	s_mov_b32 m0, s44
	s_nop 0
	global_load_lds_dwordx4 v[158:159], off
	s_waitcnt vmcnt(6)
	s_waitcnt lgkmcnt(0)
	s_barrier
	s_setprio 1
	s_waitcnt lgkmcnt(0)
	v_mfma_f32_16x16x32_bf16 v[64:67], v[68:71], v[180:183], v[64:67]
	v_mfma_f32_16x16x32_bf16 v[60:63], v[84:87], v[180:183], v[60:63]
	v_mfma_f32_16x16x32_bf16 v[48:51], v[68:71], v[188:191], v[48:51]
	v_mfma_f32_16x16x32_bf16 v[44:47], v[84:87], v[188:191], v[44:47]
	v_mfma_f32_16x16x32_bf16 v[32:35], v[68:71], v[208:211], v[32:35]
	v_mfma_f32_16x16x32_bf16 v[28:31], v[84:87], v[208:211], v[28:31]
	v_mfma_f32_16x16x32_bf16 v[16:19], v[68:71], v[216:219], v[16:19]
	v_mfma_f32_16x16x32_bf16 v[12:15], v[84:87], v[216:219], v[12:15]
	v_mfma_f32_16x16x32_bf16 v[64:67], v[72:75], v[184:187], v[64:67]
	v_mfma_f32_16x16x32_bf16 v[60:63], v[88:91], v[184:187], v[60:63]
	v_mfma_f32_16x16x32_bf16 v[48:51], v[72:75], v[204:207], v[48:51]
	v_mfma_f32_16x16x32_bf16 v[44:47], v[88:91], v[204:207], v[44:47]
	v_mfma_f32_16x16x32_bf16 v[32:35], v[72:75], v[212:215], v[32:35]
	v_mfma_f32_16x16x32_bf16 v[28:31], v[88:91], v[212:215], v[28:31]
	v_mfma_f32_16x16x32_bf16 v[16:19], v[72:75], v[220:223], v[16:19]
	v_mfma_f32_16x16x32_bf16 v[12:15], v[88:91], v[220:223], v[12:15]
	s_setprio 0
	s_setprio 1
	v_mfma_f32_16x16x32_bf16 v[56:59], v[164:167], v[180:183], v[56:59]
	v_mfma_f32_16x16x32_bf16 v[52:55], v[172:175], v[180:183], v[52:55]
	v_mfma_f32_16x16x32_bf16 v[40:43], v[164:167], v[188:191], v[40:43]
	v_mfma_f32_16x16x32_bf16 v[36:39], v[172:175], v[188:191], v[36:39]
	v_mfma_f32_16x16x32_bf16 v[24:27], v[164:167], v[208:211], v[24:27]
	v_mfma_f32_16x16x32_bf16 v[20:23], v[172:175], v[208:211], v[20:23]
	v_mfma_f32_16x16x32_bf16 v[8:11], v[164:167], v[216:219], v[8:11]
	v_mfma_f32_16x16x32_bf16 v[4:7], v[172:175], v[216:219], v[4:7]
	v_mfma_f32_16x16x32_bf16 v[56:59], v[168:171], v[184:187], v[56:59]
	v_mfma_f32_16x16x32_bf16 v[52:55], v[176:179], v[184:187], v[52:55]
	v_mfma_f32_16x16x32_bf16 v[40:43], v[168:171], v[204:207], v[40:43]
	v_mfma_f32_16x16x32_bf16 v[36:39], v[176:179], v[204:207], v[36:39]
	v_mfma_f32_16x16x32_bf16 v[24:27], v[168:171], v[212:215], v[24:27]
	v_mfma_f32_16x16x32_bf16 v[20:23], v[176:179], v[212:215], v[20:23]
	v_mfma_f32_16x16x32_bf16 v[8:11], v[168:171], v[220:223], v[8:11]
	v_mfma_f32_16x16x32_bf16 v[4:7], v[176:179], v[220:223], v[4:7]
	s_setprio 0
	s_barrier
	s_add_i32 s24, s55, 2
	s_add_u32 s53, s53, 0x100
	s_addc_u32 s54, s54, 0
	s_add_u32 s22, s22, 0x100
	s_addc_u32 s23, s23, 0
	s_cmp_ge_i32 s55, s45
	s_mov_b32 s55, s24
	s_cbranch_scc0 .LBB0_688

; #define PG8_STAGE(bufoff, gbase, voff) do { _Pragma("unroll") for (int _i = 0; _i < 2; ++_i) \
;         __builtin_amdgcn_global_load_lds((const unsigned*)((const char*)(gbase) + (voff)[_i]), (PG8_LAS unsigned*)(lds + (bufoff) + ldsw + _i * 8192), 16, 0, 0); } while (0)
; #define PG8_LDA(dst, b, h) do { _Pragma("unroll") for (int m = 0; m < 4; ++m) _Pragma("unroll") for (int k = 0; k < 2; ++k) dst[m][k] = *(const PG8_LAS bf16x8*)(lds + PG8_SA(b, h) + aoff + m * 2048 + k * 1024); } while (0)
; #define PG8_LDB(dst, b, h) do { _Pragma("unroll") for (int n = 0; n < 2; ++n) _Pragma("unroll") for (int k = 0; k < 2; ++k) dst[n][k] = *(const PG8_LAS bf16x8*)(lds + PG8_SB(b, h) + boff + n * 2048 + k * 1024); } while (0)
; #define PG8_MMA(ai, bj, At, Bt) do { __builtin_amdgcn_s_setprio(1); _Pragma("unroll") for (int m = 0; m < 4; ++m) _Pragma("unroll") for (int n = 0; n < 2; ++n) _Pragma("unroll") for (int k = 0; k < 2; ++k) \
;         acc[ai][bj][m][n] = __builtin_amdgcn_mfma_f32_16x16x32_bf16(Bt[n][k], At[m][k], acc[ai][bj][m][n], 0, 0, 0); __builtin_amdgcn_s_setprio(0); } while (0)
; template <class Epi, class Sched, bool ALIGN_EPI = false, bool SP2 = false>
; __device__ __forceinline__ void gemm_phase(PG8_LAS unsigned char* lds, const Gemm g, const Sched& S, const Epi& E, int tid_in) {
;     ...
;             const bool last = (t == nt - 2);
;             if constexpr (mid_hook<Epi>::value) { if (t == Epi::H1 || t == Epi::H2) E.mid(acc, cur, wr, wc, fr, fq, t == Epi::H2); }
;             const char* a1 = cA + (size_t)(t + 1) * kstep + (t >= jt ? jb : 0);
;             const char* a2 = last ? nA : cA + (size_t)(t + 2) * kstep + (t + 2 >= jt ? jb : 0); const char* b2 = last ? nB : cB + (size_t)(t + 2) * kstep;
;             const char* a3 = a2 + kstep; const char* b3 = b2 + kstep;
;             if (last && has_next) S.a_ready(nxt);
;             if constexpr (SP2) {
;             PG8_LDB(B0, 0, 0); PG8_LDB(B1, 0, 1); PG8_SCHED; PG8_LDA(At, 0, 0); PG8_STAGE(PG8_SA(1, 1), a1 + hsA, voffA);
;             PG8_WAIT_V(8); PG8_WAIT_L(0); PG8_BAR; PG8_MMA(0, 0, At, B0); PG8_MMA(0, 1, At, B1); PG8_BAR; PG8_SCHED;
;             PG8_LDA(At, 0, 1); PG8_STAGE(PG8_SB(0, 0), b2, voffB); PG8_STAGE(PG8_SB(0, 1), b2 + hsB, voffB); PG8_STAGE(PG8_SA(0, 0), a2, voffA);
;             PG8_WAIT_V(8); PG8_WAIT_L(0); PG8_BAR; PG8_MMA(1, 0, At, B0); PG8_MMA(1, 1, At, B1); PG8_BAR; PG8_SCHED;
.LBB0_709:
	s_add_i32 s24, s53, -2
	s_cmp_ge_i32 s24, s28
	s_cselect_b32 s54, s29, 0
	s_cselect_b32 s55, s44, 0
	s_cmp_ge_i32 s53, s28
	s_cselect_b32 s25, s29, 0
	s_cselect_b32 s24, s44, 0
	s_add_u32 s25, s22, s25
	s_addc_u32 s24, s23, s24
	s_add_u32 s58, s25, 0x80
	s_addc_u32 s24, s24, 0
	s_add_i32 s60, 0, 0x10000
	s_cmp_eq_u32 s43, s53
	s_cselect_b32 s25, s5, s24
	s_cselect_b32 s24, s4, s58
	v_add_u32_e32 v145, s60, v142
	s_cselect_b32 s59, s21, s52
	s_cselect_b32 s58, s20, s51
	s_add_i32 s61, 0, 0x14000
	ds_read_b128 v[146:149], v145
	ds_read_b128 v[150:153], v145 offset:1024
	ds_read_b128 v[154:157], v145 offset:2048
	ds_read_b128 v[158:161], v145 offset:3072
	v_add_u32_e32 v145, s61, v142
	ds_read_b128 v[162:165], v145
	ds_read_b128 v[166:169], v145 offset:1024
	ds_read_b128 v[170:173], v145 offset:2048
	ds_read_b128 v[174:177], v145 offset:3072
	v_lshl_add_u64 v[190:191], s[22:23], 0, v[140:141]
	v_lshl_add_u64 v[190:191], v[190:191], 0, s[54:55]
	s_add_i32 m0, s37, 0xc000
	ds_read_b128 v[178:181], v144
	ds_read_b128 v[182:185], v144 offset:1024
	ds_read_b128 v[186:189], v144 offset:2048
	ds_read_b128 v[204:207], v144 offset:3072
	ds_read_b128 v[208:211], v144 offset:4096
	ds_read_b128 v[212:215], v144 offset:5120
	ds_read_b128 v[216:219], v144 offset:6144
	ds_read_b128 v[220:223], v144 offset:7168
	global_load_lds_dwordx4 v[190:191], off
	v_lshl_add_u64 v[190:191], s[22:23], 0, v[138:139]
	v_lshl_add_u64 v[190:191], v[190:191], 0, s[54:55]
	s_add_i32 m0, s37, 0xe000
	s_nop 0
	global_load_lds_dwordx4 v[190:191], off
	s_waitcnt vmcnt(8)
	s_waitcnt lgkmcnt(0)
	s_barrier
	s_setprio 1
	s_waitcnt lgkmcnt(0)
	v_mfma_f32_16x16x32_bf16 v[124:127], v[146:149], v[178:181], v[124:127]
	v_mfma_f32_16x16x32_bf16 v[128:131], v[154:157], v[178:181], v[128:131]
	v_mfma_f32_16x16x32_bf16 v[112:115], v[146:149], v[186:189], v[112:115]
	v_mfma_f32_16x16x32_bf16 v[108:111], v[154:157], v[186:189], v[108:111]
	v_mfma_f32_16x16x32_bf16 v[96:99], v[146:149], v[208:211], v[96:99]
	v_mfma_f32_16x16x32_bf16 v[92:95], v[154:157], v[208:211], v[92:95]
	v_mfma_f32_16x16x32_bf16 v[80:83], v[146:149], v[216:219], v[80:83]
	v_mfma_f32_16x16x32_bf16 v[76:79], v[154:157], v[216:219], v[76:79]
	v_mfma_f32_16x16x32_bf16 v[124:127], v[150:153], v[182:185], v[124:127]
	v_mfma_f32_16x16x32_bf16 v[128:131], v[158:161], v[182:185], v[128:131]
	v_mfma_f32_16x16x32_bf16 v[112:115], v[150:153], v[204:207], v[112:115]
	v_mfma_f32_16x16x32_bf16 v[108:111], v[158:161], v[204:207], v[108:111]
	v_mfma_f32_16x16x32_bf16 v[96:99], v[150:153], v[212:215], v[96:99]
	v_mfma_f32_16x16x32_bf16 v[92:95], v[158:161], v[212:215], v[92:95]
	v_mfma_f32_16x16x32_bf16 v[80:83], v[150:153], v[220:223], v[80:83]
	v_mfma_f32_16x16x32_bf16 v[76:79], v[158:161], v[220:223], v[76:79]
	s_setprio 0
	s_setprio 1
	v_mfma_f32_16x16x32_bf16 v[120:123], v[162:165], v[178:181], v[120:123]
	v_mfma_f32_16x16x32_bf16 v[116:119], v[170:173], v[178:181], v[116:119]
	v_mfma_f32_16x16x32_bf16 v[104:107], v[162:165], v[186:189], v[104:107]
	v_mfma_f32_16x16x32_bf16 v[100:103], v[170:173], v[186:189], v[100:103]
	v_mfma_f32_16x16x32_bf16 v[88:91], v[162:165], v[208:211], v[88:91]
	v_mfma_f32_16x16x32_bf16 v[84:87], v[170:173], v[208:211], v[84:87]
	v_mfma_f32_16x16x32_bf16 v[72:75], v[162:165], v[216:219], v[72:75]
	v_mfma_f32_16x16x32_bf16 v[68:71], v[170:173], v[216:219], v[68:71]
	v_mfma_f32_16x16x32_bf16 v[120:123], v[166:169], v[182:185], v[120:123]
	v_mfma_f32_16x16x32_bf16 v[116:119], v[174:177], v[182:185], v[116:119]
	v_mfma_f32_16x16x32_bf16 v[104:107], v[166:169], v[204:207], v[104:107]
	v_mfma_f32_16x16x32_bf16 v[100:103], v[174:177], v[204:207], v[100:103]
	v_mfma_f32_16x16x32_bf16 v[88:91], v[166:169], v[212:215], v[88:91]
	v_mfma_f32_16x16x32_bf16 v[84:87], v[174:177], v[212:215], v[84:87]
	v_mfma_f32_16x16x32_bf16 v[72:75], v[166:169], v[220:223], v[72:75]
	v_mfma_f32_16x16x32_bf16 v[68:71], v[174:177], v[220:223], v[68:71]
	s_setprio 0
	s_barrier
	s_add_i32 s54, s60, s35
	v_lshl_add_u64 v[190:191], s[58:59], 0, v[134:135]
	s_mov_b32 m0, s54
	ds_read_b128 v[178:181], v144 offset:16384
	ds_read_b128 v[182:185], v144 offset:17408
	ds_read_b128 v[186:189], v144 offset:18432
	ds_read_b128 v[204:207], v144 offset:19456
	ds_read_b128 v[208:211], v144 offset:20480
	ds_read_b128 v[212:215], v144 offset:21504
	ds_read_b128 v[216:219], v144 offset:22528
	ds_read_b128 v[220:223], v144 offset:23552
	global_load_lds_dwordx4 v[190:191], off
	s_add_i32 m0, s54, 0x2000
	s_add_u32 s54, s58, s6
	v_lshl_add_u64 v[230:231], s[58:59], 0, v[0:1]
	s_addc_u32 s55, s59, s7
	s_add_i32 s58, s61, s35
	global_load_lds_dwordx4 v[230:231], off
	v_lshl_add_u64 v[232:233], s[54:55], 0, v[134:135]
	v_lshl_add_u64 v[238:239], s[54:55], 0, v[0:1]
	v_lshl_add_u64 v[240:241], s[24:25], 0, v[136:137]
	s_mov_b32 m0, s37
	v_lshl_add_u64 v[242:243], s[24:25], 0, v[132:133]
	global_load_lds_dwordx4 v[240:241], off
	s_mov_b32 m0, s38
	s_nop 0
	global_load_lds_dwordx4 v[242:243], off
	s_waitcnt vmcnt(6)
	s_waitcnt lgkmcnt(0)
	s_barrier
; #define PG8_STAGE(bufoff, gbase, voff) do { _Pragma("unroll") for (int _i = 0; _i < 2; ++_i) \
;         __builtin_amdgcn_global_load_lds((const unsigned*)((const char*)(gbase) + (voff)[_i]), (PG8_LAS unsigned*)(lds + (bufoff) + ldsw + _i * 8192), 16, 0, 0); } while (0)
; #define PG8_LDA(dst, b, h) do { _Pragma("unroll") for (int m = 0; m < 4; ++m) _Pragma("unroll") for (int k = 0; k < 2; ++k) dst[m][k] = *(const PG8_LAS bf16x8*)(lds + PG8_SA(b, h) + aoff + m * 2048 + k * 1024); } while (0)
; #define PG8_LDB(dst, b, h) do { _Pragma("unroll") for (int n = 0; n < 2; ++n) _Pragma("unroll") for (int k = 0; k < 2; ++k) dst[n][k] = *(const PG8_LAS bf16x8*)(lds + PG8_SB(b, h) + boff + n * 2048 + k * 1024); } while (0)
; #define PG8_MMA(ai, bj, At, Bt) do { __builtin_amdgcn_s_setprio(1); _Pragma("unroll") for (int m = 0; m < 4; ++m) _Pragma("unroll") for (int n = 0; n < 2; ++n) _Pragma("unroll") for (int k = 0; k < 2; ++k) \
;         acc[ai][bj][m][n] = __builtin_amdgcn_mfma_f32_16x16x32_bf16(Bt[n][k], At[m][k], acc[ai][bj][m][n], 0, 0, 0); __builtin_amdgcn_s_setprio(0); } while (0)
; #define PG8_WAIT_V(n) asm volatile("s_waitcnt vmcnt(" #n ")" ::: "memory")
; #define PG8_WAIT_L(n) asm volatile("s_waitcnt lgkmcnt(" #n ")" ::: "memory")
; #define PG8_BAR __builtin_amdgcn_s_barrier()
; #define PG8_SCHED __builtin_amdgcn_sched_barrier(0)
; template <class Epi, class Sched, bool ALIGN_EPI = false, bool SP2 = false>
; __device__ __forceinline__ void gemm_phase(PG8_LAS unsigned char* lds, const Gemm g, const Sched& S, const Epi& E, int tid_in) {
;     ...
;             PG8_WAIT_V(8); PG8_WAIT_L(0); PG8_BAR; PG8_MMA(1, 0, At, B0); PG8_MMA(1, 1, At, B1); PG8_BAR; PG8_SCHED;
;             PG8_LDB(B0, 1, 0); PG8_LDB(B1, 1, 1); PG8_SCHED; PG8_LDA(At, 1, 0); PG8_STAGE(PG8_SA(0, 1), a2 + hsA, voffA);
;             PG8_WAIT_V(8); PG8_WAIT_L(0); PG8_BAR; PG8_MMA(0, 0, At, B0); PG8_MMA(0, 1, At, B1); PG8_BAR; PG8_SCHED;
	s_setprio 1
	s_waitcnt lgkmcnt(0)
	v_mfma_f32_16x16x32_bf16 v[64:67], v[146:149], v[178:181], v[64:67]
	v_mfma_f32_16x16x32_bf16 v[60:63], v[154:157], v[178:181], v[60:63]
	v_mfma_f32_16x16x32_bf16 v[48:51], v[146:149], v[186:189], v[48:51]
	v_mfma_f32_16x16x32_bf16 v[44:47], v[154:157], v[186:189], v[44:47]
	v_mfma_f32_16x16x32_bf16 v[32:35], v[146:149], v[208:211], v[32:35]
	v_mfma_f32_16x16x32_bf16 v[28:31], v[154:157], v[208:211], v[28:31]
	v_mfma_f32_16x16x32_bf16 v[16:19], v[146:149], v[216:219], v[16:19]
	v_mfma_f32_16x16x32_bf16 v[12:15], v[154:157], v[216:219], v[12:15]
	v_mfma_f32_16x16x32_bf16 v[64:67], v[150:153], v[182:185], v[64:67]
	v_mfma_f32_16x16x32_bf16 v[60:63], v[158:161], v[182:185], v[60:63]
	v_mfma_f32_16x16x32_bf16 v[48:51], v[150:153], v[204:207], v[48:51]
	v_mfma_f32_16x16x32_bf16 v[44:47], v[158:161], v[204:207], v[44:47]
	v_mfma_f32_16x16x32_bf16 v[32:35], v[150:153], v[212:215], v[32:35]
	v_mfma_f32_16x16x32_bf16 v[28:31], v[158:161], v[212:215], v[28:31]
	v_mfma_f32_16x16x32_bf16 v[16:19], v[150:153], v[220:223], v[16:19]
	v_mfma_f32_16x16x32_bf16 v[12:15], v[158:161], v[220:223], v[12:15]
	s_setprio 0
	s_setprio 1
	v_mfma_f32_16x16x32_bf16 v[56:59], v[162:165], v[178:181], v[56:59]
	v_mfma_f32_16x16x32_bf16 v[52:55], v[170:173], v[178:181], v[52:55]
	v_mfma_f32_16x16x32_bf16 v[40:43], v[162:165], v[186:189], v[40:43]
	v_mfma_f32_16x16x32_bf16 v[36:39], v[170:173], v[186:189], v[36:39]
	v_mfma_f32_16x16x32_bf16 v[24:27], v[162:165], v[208:211], v[24:27]
	v_mfma_f32_16x16x32_bf16 v[20:23], v[170:173], v[208:211], v[20:23]
	v_mfma_f32_16x16x32_bf16 v[8:11], v[162:165], v[216:219], v[8:11]
	v_mfma_f32_16x16x32_bf16 v[4:7], v[170:173], v[216:219], v[4:7]
	v_mfma_f32_16x16x32_bf16 v[56:59], v[166:169], v[182:185], v[56:59]
	v_mfma_f32_16x16x32_bf16 v[52:55], v[174:177], v[182:185], v[52:55]
	v_mfma_f32_16x16x32_bf16 v[40:43], v[166:169], v[204:207], v[40:43]
	v_mfma_f32_16x16x32_bf16 v[36:39], v[174:177], v[204:207], v[36:39]
	v_mfma_f32_16x16x32_bf16 v[24:27], v[166:169], v[212:215], v[24:27]
	v_mfma_f32_16x16x32_bf16 v[20:23], v[174:177], v[212:215], v[20:23]
	v_mfma_f32_16x16x32_bf16 v[8:11], v[166:169], v[220:223], v[8:11]
	v_mfma_f32_16x16x32_bf16 v[4:7], v[174:177], v[220:223], v[4:7]
	s_setprio 0
	s_barrier
	s_add_i32 s54, 0, 0x18000
	v_add_u32_e32 v145, s54, v142
	s_add_i32 s55, 0, 0x1c000
	ds_read_b128 v[146:149], v145
	ds_read_b128 v[150:153], v145 offset:1024
	ds_read_b128 v[154:157], v145 offset:2048
	ds_read_b128 v[158:161], v145 offset:3072
	v_add_u32_e32 v145, s55, v142
	ds_read_b128 v[162:165], v145
	ds_read_b128 v[166:169], v145 offset:1024
	ds_read_b128 v[170:173], v145 offset:2048
	ds_read_b128 v[174:177], v145 offset:3072
	s_add_u32 s24, s24, s0
	s_addc_u32 s25, s25, s1
	s_mov_b32 m0, s39
	v_lshl_add_u64 v[244:245], s[24:25], 0, v[136:137]
	ds_read_b128 v[178:181], v144 offset:32768
	ds_read_b128 v[182:185], v144 offset:33792
	ds_read_b128 v[186:189], v144 offset:34816
	ds_read_b128 v[204:207], v144 offset:35840
	ds_read_b128 v[208:211], v144 offset:36864
	ds_read_b128 v[212:215], v144 offset:37888
	ds_read_b128 v[216:219], v144 offset:38912
	ds_read_b128 v[220:223], v144 offset:39936
	global_load_lds_dwordx4 v[244:245], off
	v_lshl_add_u64 v[244:245], s[24:25], 0, v[132:133]
	s_mov_b32 m0, s40
	s_nop 0
	global_load_lds_dwordx4 v[244:245], off
	s_add_i32 m0, s35, 0x14000
	s_nop 0
	global_load_lds_dwordx4 v[232:233], off
	s_add_i32 m0, s35, 0x16000
	s_nop 0
	global_load_lds_dwordx4 v[238:239], off
	s_waitcnt vmcnt(8)
	s_waitcnt lgkmcnt(0)
	s_barrier
	s_setprio 1
	s_waitcnt lgkmcnt(0)
	v_mfma_f32_16x16x32_bf16 v[124:127], v[146:149], v[178:181], v[124:127]
	v_mfma_f32_16x16x32_bf16 v[128:131], v[154:157], v[178:181], v[128:131]
	v_mfma_f32_16x16x32_bf16 v[112:115], v[146:149], v[186:189], v[112:115]
	v_mfma_f32_16x16x32_bf16 v[108:111], v[154:157], v[186:189], v[108:111]
	v_mfma_f32_16x16x32_bf16 v[96:99], v[146:149], v[208:211], v[96:99]
	v_mfma_f32_16x16x32_bf16 v[92:95], v[154:157], v[208:211], v[92:95]
	v_mfma_f32_16x16x32_bf16 v[80:83], v[146:149], v[216:219], v[80:83]
	v_mfma_f32_16x16x32_bf16 v[76:79], v[154:157], v[216:219], v[76:79]
	v_mfma_f32_16x16x32_bf16 v[124:127], v[150:153], v[182:185], v[124:127]
	v_mfma_f32_16x16x32_bf16 v[128:131], v[158:161], v[182:185], v[128:131]
	v_mfma_f32_16x16x32_bf16 v[112:115], v[150:153], v[204:207], v[112:115]
	v_mfma_f32_16x16x32_bf16 v[108:111], v[158:161], v[204:207], v[108:111]
	v_mfma_f32_16x16x32_bf16 v[96:99], v[150:153], v[212:215], v[96:99]
	v_mfma_f32_16x16x32_bf16 v[92:95], v[158:161], v[212:215], v[92:95]
	v_mfma_f32_16x16x32_bf16 v[80:83], v[150:153], v[220:223], v[80:83]
	v_mfma_f32_16x16x32_bf16 v[76:79], v[158:161], v[220:223], v[76:79]
	s_setprio 0
	s_setprio 1
	v_mfma_f32_16x16x32_bf16 v[120:123], v[162:165], v[178:181], v[120:123]
	v_mfma_f32_16x16x32_bf16 v[116:119], v[170:173], v[178:181], v[116:119]
	v_mfma_f32_16x16x32_bf16 v[104:107], v[162:165], v[186:189], v[104:107]
	v_mfma_f32_16x16x32_bf16 v[100:103], v[170:173], v[186:189], v[100:103]
	v_mfma_f32_16x16x32_bf16 v[88:91], v[162:165], v[208:211], v[88:91]
	v_mfma_f32_16x16x32_bf16 v[84:87], v[170:173], v[208:211], v[84:87]
	v_mfma_f32_16x16x32_bf16 v[72:75], v[162:165], v[216:219], v[72:75]
	v_mfma_f32_16x16x32_bf16 v[68:71], v[170:173], v[216:219], v[68:71]
	v_mfma_f32_16x16x32_bf16 v[120:123], v[166:169], v[182:185], v[120:123]
	v_mfma_f32_16x16x32_bf16 v[116:119], v[174:177], v[182:185], v[116:119]
	v_mfma_f32_16x16x32_bf16 v[104:107], v[166:169], v[204:207], v[104:107]
	v_mfma_f32_16x16x32_bf16 v[100:103], v[174:177], v[204:207], v[100:103]
	v_mfma_f32_16x16x32_bf16 v[88:91], v[166:169], v[212:215], v[88:91]
	v_mfma_f32_16x16x32_bf16 v[84:87], v[174:177], v[212:215], v[84:87]
	v_mfma_f32_16x16x32_bf16 v[72:75], v[166:169], v[220:223], v[72:75]
	v_mfma_f32_16x16x32_bf16 v[68:71], v[174:177], v[220:223], v[68:71]
	s_setprio 0
	s_barrier
; #define PG8_STAGE(bufoff, gbase, voff) do { _Pragma("unroll") for (int _i = 0; _i < 2; ++_i) \
;         __builtin_amdgcn_global_load_lds((const unsigned*)((const char*)(gbase) + (voff)[_i]), (PG8_LAS unsigned*)(lds + (bufoff) + ldsw + _i * 8192), 16, 0, 0); } while (0)
; #define PG8_LDA(dst, b, h) do { _Pragma("unroll") for (int m = 0; m < 4; ++m) _Pragma("unroll") for (int k = 0; k < 2; ++k) dst[m][k] = *(const PG8_LAS bf16x8*)(lds + PG8_SA(b, h) + aoff + m * 2048 + k * 1024); } while (0)
; #define PG8_MMA(ai, bj, At, Bt) do { __builtin_amdgcn_s_setprio(1); _Pragma("unroll") for (int m = 0; m < 4; ++m) _Pragma("unroll") for (int n = 0; n < 2; ++n) _Pragma("unroll") for (int k = 0; k < 2; ++k) \
;         acc[ai][bj][m][n] = __builtin_amdgcn_mfma_f32_16x16x32_bf16(Bt[n][k], At[m][k], acc[ai][bj][m][n], 0, 0, 0); __builtin_amdgcn_s_setprio(0); } while (0)
; #define PG8_WAIT_V(n) asm volatile("s_waitcnt vmcnt(" #n ")" ::: "memory")
; #define PG8_WAIT_L(n) asm volatile("s_waitcnt lgkmcnt(" #n ")" ::: "memory")
; #define PG8_BAR __builtin_amdgcn_s_barrier()
; #define PG8_SCHED __builtin_amdgcn_sched_barrier(0)
; template <class Epi, class Sched, bool ALIGN_EPI = false, bool SP2 = false>
; __device__ __forceinline__ void gemm_phase(PG8_LAS unsigned char* lds, const Gemm g, const Sched& S, const Epi& E, int tid_in) {
;     ...
;         for (int t = 0; t < nt; t += 2) {
;     ...
;             PG8_LDA(At, 1, 1); PG8_STAGE(PG8_SB(1, 0), b3, voffB); PG8_STAGE(PG8_SB(1, 1), b3 + hsB, voffB); PG8_STAGE(PG8_SA(1, 0), a3, voffA);
;             PG8_WAIT_V(8); PG8_WAIT_L(0); PG8_BAR; PG8_MMA(1, 0, At, B0); PG8_MMA(1, 1, At, B1); PG8_BAR; PG8_SCHED;
	s_add_i32 s24, s54, s35
	v_lshl_add_u64 v[190:191], v[190:191], 0, s[80:81]
	s_mov_b32 m0, s24
	ds_read_b128 v[178:181], v144 offset:49152
	ds_read_b128 v[182:185], v144 offset:50176
	ds_read_b128 v[186:189], v144 offset:51200
	ds_read_b128 v[204:207], v144 offset:52224
	ds_read_b128 v[208:211], v144 offset:53248
	ds_read_b128 v[212:215], v144 offset:54272
	ds_read_b128 v[216:219], v144 offset:55296
	ds_read_b128 v[220:223], v144 offset:56320
	global_load_lds_dwordx4 v[190:191], off
	v_lshl_add_u64 v[190:191], v[230:231], 0, s[80:81]
	s_add_i32 m0, s24, 0x2000
	s_add_i32 s24, s55, s35
	global_load_lds_dwordx4 v[190:191], off
	v_lshl_add_u64 v[190:191], v[232:233], 0, s[80:81]
	s_mov_b32 m0, s24
	s_nop 0
	global_load_lds_dwordx4 v[190:191], off
	v_lshl_add_u64 v[190:191], v[238:239], 0, s[80:81]
	s_add_i32 m0, s24, 0x2000
	s_nop 0
	global_load_lds_dwordx4 v[190:191], off
	v_lshl_add_u64 v[190:191], v[240:241], 0, s[80:81]
	s_mov_b32 m0, s41
	s_nop 0
	global_load_lds_dwordx4 v[190:191], off
	v_lshl_add_u64 v[190:191], v[242:243], 0, s[80:81]
	s_mov_b32 m0, s42
	s_nop 0
	global_load_lds_dwordx4 v[190:191], off
	s_waitcnt vmcnt(6)
	s_waitcnt lgkmcnt(0)
	s_barrier
	s_setprio 1
	s_waitcnt lgkmcnt(0)
	v_mfma_f32_16x16x32_bf16 v[64:67], v[146:149], v[178:181], v[64:67]
	v_mfma_f32_16x16x32_bf16 v[60:63], v[154:157], v[178:181], v[60:63]
	v_mfma_f32_16x16x32_bf16 v[48:51], v[146:149], v[186:189], v[48:51]
	v_mfma_f32_16x16x32_bf16 v[44:47], v[154:157], v[186:189], v[44:47]
	v_mfma_f32_16x16x32_bf16 v[32:35], v[146:149], v[208:211], v[32:35]
	v_mfma_f32_16x16x32_bf16 v[28:31], v[154:157], v[208:211], v[28:31]
	v_mfma_f32_16x16x32_bf16 v[16:19], v[146:149], v[216:219], v[16:19]
	v_mfma_f32_16x16x32_bf16 v[12:15], v[154:157], v[216:219], v[12:15]
	v_mfma_f32_16x16x32_bf16 v[64:67], v[150:153], v[182:185], v[64:67]
	v_mfma_f32_16x16x32_bf16 v[60:63], v[158:161], v[182:185], v[60:63]
	v_mfma_f32_16x16x32_bf16 v[48:51], v[150:153], v[204:207], v[48:51]
	v_mfma_f32_16x16x32_bf16 v[44:47], v[158:161], v[204:207], v[44:47]
	v_mfma_f32_16x16x32_bf16 v[32:35], v[150:153], v[212:215], v[32:35]
	v_mfma_f32_16x16x32_bf16 v[28:31], v[158:161], v[212:215], v[28:31]
	v_mfma_f32_16x16x32_bf16 v[16:19], v[150:153], v[220:223], v[16:19]
	v_mfma_f32_16x16x32_bf16 v[12:15], v[158:161], v[220:223], v[12:15]
	s_setprio 0
	s_setprio 1
	v_mfma_f32_16x16x32_bf16 v[56:59], v[162:165], v[178:181], v[56:59]
	v_mfma_f32_16x16x32_bf16 v[52:55], v[170:173], v[178:181], v[52:55]
	v_mfma_f32_16x16x32_bf16 v[40:43], v[162:165], v[186:189], v[40:43]
	v_mfma_f32_16x16x32_bf16 v[36:39], v[170:173], v[186:189], v[36:39]
	v_mfma_f32_16x16x32_bf16 v[24:27], v[162:165], v[208:211], v[24:27]
	v_mfma_f32_16x16x32_bf16 v[20:23], v[170:173], v[208:211], v[20:23]
	v_mfma_f32_16x16x32_bf16 v[8:11], v[162:165], v[216:219], v[8:11]
	v_mfma_f32_16x16x32_bf16 v[4:7], v[170:173], v[216:219], v[4:7]
	v_mfma_f32_16x16x32_bf16 v[56:59], v[166:169], v[182:185], v[56:59]
	v_mfma_f32_16x16x32_bf16 v[52:55], v[174:177], v[182:185], v[52:55]
	v_mfma_f32_16x16x32_bf16 v[40:43], v[166:169], v[204:207], v[40:43]
	v_mfma_f32_16x16x32_bf16 v[36:39], v[174:177], v[204:207], v[36:39]
	v_mfma_f32_16x16x32_bf16 v[24:27], v[166:169], v[212:215], v[24:27]
	v_mfma_f32_16x16x32_bf16 v[20:23], v[174:177], v[212:215], v[20:23]
	v_mfma_f32_16x16x32_bf16 v[8:11], v[166:169], v[220:223], v[8:11]
	v_mfma_f32_16x16x32_bf16 v[4:7], v[174:177], v[220:223], v[4:7]
	s_setprio 0
	s_barrier
	s_add_i32 s24, s53, 2
	s_add_u32 s51, s51, 0x100
	s_addc_u32 s52, s52, 0
	s_add_u32 s22, s22, 0x100
	s_addc_u32 s23, s23, 0
	s_cmp_ge_i32 s53, s43
	s_mov_b32 s53, s24
	s_cbranch_scc0 .LBB0_709

; #define PG8_STAGE(bufoff, gbase, voff) do { _Pragma("unroll") for (int _i = 0; _i < 2; ++_i) \
;         __builtin_amdgcn_global_load_lds((const unsigned*)((const char*)(gbase) + (voff)[_i]), (PG8_LAS unsigned*)(lds + (bufoff) + ldsw + _i * 8192), 16, 0, 0); } while (0)
; #define PG8_LDA(dst, b, h) do { _Pragma("unroll") for (int m = 0; m < 4; ++m) _Pragma("unroll") for (int k = 0; k < 2; ++k) dst[m][k] = *(const PG8_LAS bf16x8*)(lds + PG8_SA(b, h) + aoff + m * 2048 + k * 1024); } while (0)
; #define PG8_LDB(dst, b, h) do { _Pragma("unroll") for (int n = 0; n < 2; ++n) _Pragma("unroll") for (int k = 0; k < 2; ++k) dst[n][k] = *(const PG8_LAS bf16x8*)(lds + PG8_SB(b, h) + boff + n * 2048 + k * 1024); } while (0)
; #define PG8_MMA(ai, bj, At, Bt) do { __builtin_amdgcn_s_setprio(1); _Pragma("unroll") for (int m = 0; m < 4; ++m) _Pragma("unroll") for (int n = 0; n < 2; ++n) _Pragma("unroll") for (int k = 0; k < 2; ++k) \
;         acc[ai][bj][m][n] = __builtin_amdgcn_mfma_f32_16x16x32_bf16(Bt[n][k], At[m][k], acc[ai][bj][m][n], 0, 0, 0); __builtin_amdgcn_s_setprio(0); } while (0)
; template <class Epi, class Sched, bool ALIGN_EPI = false, bool SP2 = false>
; __device__ __forceinline__ void gemm_phase(PG8_LAS unsigned char* lds, const Gemm g, const Sched& S, const Epi& E, int tid_in) {
;     ...
;             const bool last = (t == nt - 2);
;             if constexpr (mid_hook<Epi>::value) { if (t == Epi::H1 || t == Epi::H2) E.mid(acc, cur, wr, wc, fr, fq, t == Epi::H2); }
;             const char* a1 = cA + (size_t)(t + 1) * kstep + (t >= jt ? jb : 0);
;             const char* a2 = last ? nA : cA + (size_t)(t + 2) * kstep + (t + 2 >= jt ? jb : 0); const char* b2 = last ? nB : cB + (size_t)(t + 2) * kstep;
;             const char* a3 = a2 + kstep; const char* b3 = b2 + kstep;
;             if (last && has_next) S.a_ready(nxt);
;             if constexpr (SP2) {
;             PG8_LDB(B0, 0, 0); PG8_LDB(B1, 0, 1); PG8_SCHED; PG8_LDA(At, 0, 0); PG8_STAGE(PG8_SA(1, 1), a1 + hsA, voffA);
;             PG8_WAIT_V(8); PG8_WAIT_L(0); PG8_BAR; PG8_MMA(0, 0, At, B0); PG8_MMA(0, 1, At, B1); PG8_BAR; PG8_SCHED;
;             PG8_LDA(At, 0, 1); PG8_STAGE(PG8_SB(0, 0), b2, voffB); PG8_STAGE(PG8_SB(0, 1), b2 + hsB, voffB); PG8_STAGE(PG8_SA(0, 0), a2, voffA);
;             PG8_WAIT_V(8); PG8_WAIT_L(0); PG8_BAR; PG8_MMA(1, 0, At, B0); PG8_MMA(1, 1, At, B1); PG8_BAR; PG8_SCHED;
.LBB0_924:
	s_add_i32 s24, s58, -2
	s_cmp_ge_i32 s24, s29
	s_cselect_b32 s60, s30, 0
	s_cselect_b32 s61, s47, 0
	s_cmp_ge_i32 s58, s29
	s_cselect_b32 s25, s30, 0
	s_cselect_b32 s24, s47, 0
	s_add_u32 s25, s22, s25
	s_addc_u32 s24, s23, s24
	s_add_u32 s59, s25, 0x80
	s_addc_u32 s24, s24, 0
	s_add_i32 s64, 0, 0x10000
	s_cmp_eq_u32 s46, s58
	s_cselect_b32 s25, s5, s24
	s_cselect_b32 s24, s4, s59
	v_add_u32_e32 v142, s64, v144
	s_cselect_b32 s63, s21, s55
	s_cselect_b32 s62, s20, s54
	s_add_i32 s59, 0, 0x14000
	ds_read_b128 v[148:151], v142
	ds_read_b128 v[152:155], v142 offset:1024
	ds_read_b128 v[156:159], v142 offset:2048
	ds_read_b128 v[160:163], v142 offset:3072
	v_add_u32_e32 v142, s59, v144
	ds_read_b128 v[164:167], v142
	ds_read_b128 v[168:171], v142 offset:1024
	ds_read_b128 v[172:175], v142 offset:2048
	ds_read_b128 v[176:179], v142 offset:3072
	v_lshl_add_u64 v[142:143], s[22:23], 0, v[140:141]
	v_lshl_add_u64 v[142:143], v[142:143], 0, s[60:61]
	s_add_i32 m0, s40, 0xc000
	ds_read_b128 v[180:183], v146
	ds_read_b128 v[184:187], v146 offset:1024
	ds_read_b128 v[188:191], v146 offset:2048
	ds_read_b128 v[204:207], v146 offset:3072
	ds_read_b128 v[208:211], v146 offset:4096
	ds_read_b128 v[212:215], v146 offset:5120
	ds_read_b128 v[216:219], v146 offset:6144
	ds_read_b128 v[220:223], v146 offset:7168
	global_load_lds_dwordx4 v[142:143], off
	v_lshl_add_u64 v[142:143], s[22:23], 0, v[138:139]
	v_lshl_add_u64 v[142:143], v[142:143], 0, s[60:61]
	s_add_i32 m0, s40, 0xe000
	s_nop 0
	global_load_lds_dwordx4 v[142:143], off
	s_waitcnt vmcnt(8)
	s_waitcnt lgkmcnt(0)
	s_barrier
	s_setprio 1
	s_waitcnt lgkmcnt(0)
	v_mfma_f32_16x16x32_bf16 v[128:131], v[148:151], v[180:183], v[128:131]
	v_mfma_f32_16x16x32_bf16 v[124:127], v[156:159], v[180:183], v[124:127]
	v_mfma_f32_16x16x32_bf16 v[112:115], v[148:151], v[188:191], v[112:115]
	v_mfma_f32_16x16x32_bf16 v[108:111], v[156:159], v[188:191], v[108:111]
	v_mfma_f32_16x16x32_bf16 v[96:99], v[148:151], v[208:211], v[96:99]
	v_mfma_f32_16x16x32_bf16 v[92:95], v[156:159], v[208:211], v[92:95]
	v_mfma_f32_16x16x32_bf16 v[80:83], v[148:151], v[216:219], v[80:83]
	v_mfma_f32_16x16x32_bf16 v[76:79], v[156:159], v[216:219], v[76:79]
	v_mfma_f32_16x16x32_bf16 v[128:131], v[152:155], v[184:187], v[128:131]
	v_mfma_f32_16x16x32_bf16 v[124:127], v[160:163], v[184:187], v[124:127]
	v_mfma_f32_16x16x32_bf16 v[112:115], v[152:155], v[204:207], v[112:115]
	v_mfma_f32_16x16x32_bf16 v[108:111], v[160:163], v[204:207], v[108:111]
	v_mfma_f32_16x16x32_bf16 v[96:99], v[152:155], v[212:215], v[96:99]
	v_mfma_f32_16x16x32_bf16 v[92:95], v[160:163], v[212:215], v[92:95]
	v_mfma_f32_16x16x32_bf16 v[80:83], v[152:155], v[220:223], v[80:83]
	v_mfma_f32_16x16x32_bf16 v[76:79], v[160:163], v[220:223], v[76:79]
	s_setprio 0
	s_setprio 1
	v_mfma_f32_16x16x32_bf16 v[120:123], v[164:167], v[180:183], v[120:123]
	v_mfma_f32_16x16x32_bf16 v[116:119], v[172:175], v[180:183], v[116:119]
	v_mfma_f32_16x16x32_bf16 v[104:107], v[164:167], v[188:191], v[104:107]
	v_mfma_f32_16x16x32_bf16 v[100:103], v[172:175], v[188:191], v[100:103]
	v_mfma_f32_16x16x32_bf16 v[88:91], v[164:167], v[208:211], v[88:91]
	v_mfma_f32_16x16x32_bf16 v[84:87], v[172:175], v[208:211], v[84:87]
	v_mfma_f32_16x16x32_bf16 v[72:75], v[164:167], v[216:219], v[72:75]
	v_mfma_f32_16x16x32_bf16 v[68:71], v[172:175], v[216:219], v[68:71]
	v_mfma_f32_16x16x32_bf16 v[120:123], v[168:171], v[184:187], v[120:123]
	v_mfma_f32_16x16x32_bf16 v[116:119], v[176:179], v[184:187], v[116:119]
	v_mfma_f32_16x16x32_bf16 v[104:107], v[168:171], v[204:207], v[104:107]
	v_mfma_f32_16x16x32_bf16 v[100:103], v[176:179], v[204:207], v[100:103]
	v_mfma_f32_16x16x32_bf16 v[88:91], v[168:171], v[212:215], v[88:91]
	v_mfma_f32_16x16x32_bf16 v[84:87], v[176:179], v[212:215], v[84:87]
	v_mfma_f32_16x16x32_bf16 v[72:75], v[168:171], v[220:223], v[72:75]
	v_mfma_f32_16x16x32_bf16 v[68:71], v[176:179], v[220:223], v[68:71]
	s_setprio 0
	s_barrier
	s_add_i32 s60, s64, s34
	v_lshl_add_u64 v[142:143], s[62:63], 0, v[134:135]
	s_mov_b32 m0, s60
	ds_read_b128 v[180:183], v146 offset:16384
	ds_read_b128 v[184:187], v146 offset:17408
	ds_read_b128 v[188:191], v146 offset:18432
	ds_read_b128 v[204:207], v146 offset:19456
	ds_read_b128 v[208:211], v146 offset:20480
	ds_read_b128 v[212:215], v146 offset:21504
	ds_read_b128 v[216:219], v146 offset:22528
	ds_read_b128 v[220:223], v146 offset:23552
	global_load_lds_dwordx4 v[142:143], off
	s_add_i32 m0, s60, 0x2000
	s_add_u32 s60, s62, s8
	v_lshl_add_u64 v[196:197], s[62:63], 0, v[0:1]
	s_addc_u32 s61, s63, s9
	s_add_i32 s59, s59, s34
	global_load_lds_dwordx4 v[196:197], off
	v_lshl_add_u64 v[198:199], s[60:61], 0, v[134:135]
	v_lshl_add_u64 v[200:201], s[60:61], 0, v[0:1]
	v_lshl_add_u64 v[228:229], s[24:25], 0, v[136:137]
	s_mov_b32 m0, s40
	v_lshl_add_u64 v[230:231], s[24:25], 0, v[132:133]
	global_load_lds_dwordx4 v[228:229], off
	s_mov_b32 m0, s41
	s_nop 0
	global_load_lds_dwordx4 v[230:231], off
	s_waitcnt vmcnt(6)
	s_waitcnt lgkmcnt(0)
	s_barrier
; #define PG8_STAGE(bufoff, gbase, voff) do { _Pragma("unroll") for (int _i = 0; _i < 2; ++_i) \
;         __builtin_amdgcn_global_load_lds((const unsigned*)((const char*)(gbase) + (voff)[_i]), (PG8_LAS unsigned*)(lds + (bufoff) + ldsw + _i * 8192), 16, 0, 0); } while (0)
; #define PG8_LDA(dst, b, h) do { _Pragma("unroll") for (int m = 0; m < 4; ++m) _Pragma("unroll") for (int k = 0; k < 2; ++k) dst[m][k] = *(const PG8_LAS bf16x8*)(lds + PG8_SA(b, h) + aoff + m * 2048 + k * 1024); } while (0)
; #define PG8_LDB(dst, b, h) do { _Pragma("unroll") for (int n = 0; n < 2; ++n) _Pragma("unroll") for (int k = 0; k < 2; ++k) dst[n][k] = *(const PG8_LAS bf16x8*)(lds + PG8_SB(b, h) + boff + n * 2048 + k * 1024); } while (0)
; #define PG8_MMA(ai, bj, At, Bt) do { __builtin_amdgcn_s_setprio(1); _Pragma("unroll") for (int m = 0; m < 4; ++m) _Pragma("unroll") for (int n = 0; n < 2; ++n) _Pragma("unroll") for (int k = 0; k < 2; ++k) \
;         acc[ai][bj][m][n] = __builtin_amdgcn_mfma_f32_16x16x32_bf16(Bt[n][k], At[m][k], acc[ai][bj][m][n], 0, 0, 0); __builtin_amdgcn_s_setprio(0); } while (0)
; #define PG8_WAIT_V(n) asm volatile("s_waitcnt vmcnt(" #n ")" ::: "memory")
; #define PG8_WAIT_L(n) asm volatile("s_waitcnt lgkmcnt(" #n ")" ::: "memory")
; #define PG8_BAR __builtin_amdgcn_s_barrier()
; #define PG8_SCHED __builtin_amdgcn_sched_barrier(0)
; template <class Epi, class Sched, bool ALIGN_EPI = false, bool SP2 = false>
; __device__ __forceinline__ void gemm_phase(PG8_LAS unsigned char* lds, const Gemm g, const Sched& S, const Epi& E, int tid_in) {
;     ...
;             PG8_WAIT_V(8); PG8_WAIT_L(0); PG8_BAR; PG8_MMA(1, 0, At, B0); PG8_MMA(1, 1, At, B1); PG8_BAR; PG8_SCHED;
;             PG8_LDB(B0, 1, 0); PG8_LDB(B1, 1, 1); PG8_SCHED; PG8_LDA(At, 1, 0); PG8_STAGE(PG8_SA(0, 1), a2 + hsA, voffA);
;             PG8_WAIT_V(8); PG8_WAIT_L(0); PG8_BAR; PG8_MMA(0, 0, At, B0); PG8_MMA(0, 1, At, B1); PG8_BAR; PG8_SCHED;
	s_setprio 1
	s_waitcnt lgkmcnt(0)
	v_mfma_f32_16x16x32_bf16 v[64:67], v[148:151], v[180:183], v[64:67]
	v_mfma_f32_16x16x32_bf16 v[60:63], v[156:159], v[180:183], v[60:63]
	v_mfma_f32_16x16x32_bf16 v[48:51], v[148:151], v[188:191], v[48:51]
	v_mfma_f32_16x16x32_bf16 v[44:47], v[156:159], v[188:191], v[44:47]
	v_mfma_f32_16x16x32_bf16 v[32:35], v[148:151], v[208:211], v[32:35]
	v_mfma_f32_16x16x32_bf16 v[28:31], v[156:159], v[208:211], v[28:31]
	v_mfma_f32_16x16x32_bf16 v[16:19], v[148:151], v[216:219], v[16:19]
	v_mfma_f32_16x16x32_bf16 v[12:15], v[156:159], v[216:219], v[12:15]
	v_mfma_f32_16x16x32_bf16 v[64:67], v[152:155], v[184:187], v[64:67]
	v_mfma_f32_16x16x32_bf16 v[60:63], v[160:163], v[184:187], v[60:63]
	v_mfma_f32_16x16x32_bf16 v[48:51], v[152:155], v[204:207], v[48:51]
	v_mfma_f32_16x16x32_bf16 v[44:47], v[160:163], v[204:207], v[44:47]
	v_mfma_f32_16x16x32_bf16 v[32:35], v[152:155], v[212:215], v[32:35]
	v_mfma_f32_16x16x32_bf16 v[28:31], v[160:163], v[212:215], v[28:31]
	v_mfma_f32_16x16x32_bf16 v[16:19], v[152:155], v[220:223], v[16:19]
	v_mfma_f32_16x16x32_bf16 v[12:15], v[160:163], v[220:223], v[12:15]
	s_setprio 0
	s_setprio 1
	v_mfma_f32_16x16x32_bf16 v[56:59], v[164:167], v[180:183], v[56:59]
	v_mfma_f32_16x16x32_bf16 v[52:55], v[172:175], v[180:183], v[52:55]
	v_mfma_f32_16x16x32_bf16 v[40:43], v[164:167], v[188:191], v[40:43]
	v_mfma_f32_16x16x32_bf16 v[36:39], v[172:175], v[188:191], v[36:39]
	v_mfma_f32_16x16x32_bf16 v[24:27], v[164:167], v[208:211], v[24:27]
	v_mfma_f32_16x16x32_bf16 v[20:23], v[172:175], v[208:211], v[20:23]
	v_mfma_f32_16x16x32_bf16 v[8:11], v[164:167], v[216:219], v[8:11]
	v_mfma_f32_16x16x32_bf16 v[4:7], v[172:175], v[216:219], v[4:7]
	v_mfma_f32_16x16x32_bf16 v[56:59], v[168:171], v[184:187], v[56:59]
	v_mfma_f32_16x16x32_bf16 v[52:55], v[176:179], v[184:187], v[52:55]
	v_mfma_f32_16x16x32_bf16 v[40:43], v[168:171], v[204:207], v[40:43]
	v_mfma_f32_16x16x32_bf16 v[36:39], v[176:179], v[204:207], v[36:39]
	v_mfma_f32_16x16x32_bf16 v[24:27], v[168:171], v[212:215], v[24:27]
	v_mfma_f32_16x16x32_bf16 v[20:23], v[176:179], v[212:215], v[20:23]
	v_mfma_f32_16x16x32_bf16 v[8:11], v[168:171], v[220:223], v[8:11]
	v_mfma_f32_16x16x32_bf16 v[4:7], v[176:179], v[220:223], v[4:7]
	s_setprio 0
	s_barrier
	s_add_i32 s59, 0, 0x18000
	v_add_u32_e32 v147, s59, v144
	s_add_i32 s60, 0, 0x1c000
	ds_read_b128 v[148:151], v147
	ds_read_b128 v[152:155], v147 offset:1024
	ds_read_b128 v[156:159], v147 offset:2048
	ds_read_b128 v[160:163], v147 offset:3072
	v_add_u32_e32 v147, s60, v144
	ds_read_b128 v[164:167], v147
	ds_read_b128 v[168:171], v147 offset:1024
	ds_read_b128 v[172:175], v147 offset:2048
	ds_read_b128 v[176:179], v147 offset:3072
	s_add_u32 s24, s24, s6
	s_addc_u32 s25, s25, s7
	s_mov_b32 m0, s42
	v_lshl_add_u64 v[232:233], s[24:25], 0, v[136:137]
	ds_read_b128 v[180:183], v146 offset:32768
	ds_read_b128 v[184:187], v146 offset:33792
	ds_read_b128 v[188:191], v146 offset:34816
	ds_read_b128 v[204:207], v146 offset:35840
	ds_read_b128 v[208:211], v146 offset:36864
	ds_read_b128 v[212:215], v146 offset:37888
	ds_read_b128 v[216:219], v146 offset:38912
	ds_read_b128 v[220:223], v146 offset:39936
	global_load_lds_dwordx4 v[232:233], off
	v_lshl_add_u64 v[232:233], s[24:25], 0, v[132:133]
	s_mov_b32 m0, s43
	s_nop 0
	global_load_lds_dwordx4 v[232:233], off
	s_add_i32 m0, s34, 0x14000
	s_nop 0
	global_load_lds_dwordx4 v[198:199], off
	s_add_i32 m0, s34, 0x16000
	s_nop 0
	global_load_lds_dwordx4 v[200:201], off
	s_waitcnt vmcnt(8)
	s_waitcnt lgkmcnt(0)
	s_barrier
	s_setprio 1
	s_waitcnt lgkmcnt(0)
	v_mfma_f32_16x16x32_bf16 v[128:131], v[148:151], v[180:183], v[128:131]
	v_mfma_f32_16x16x32_bf16 v[124:127], v[156:159], v[180:183], v[124:127]
	v_mfma_f32_16x16x32_bf16 v[112:115], v[148:151], v[188:191], v[112:115]
	v_mfma_f32_16x16x32_bf16 v[108:111], v[156:159], v[188:191], v[108:111]
	v_mfma_f32_16x16x32_bf16 v[96:99], v[148:151], v[208:211], v[96:99]
	v_mfma_f32_16x16x32_bf16 v[92:95], v[156:159], v[208:211], v[92:95]
	v_mfma_f32_16x16x32_bf16 v[80:83], v[148:151], v[216:219], v[80:83]
	v_mfma_f32_16x16x32_bf16 v[76:79], v[156:159], v[216:219], v[76:79]
	v_mfma_f32_16x16x32_bf16 v[128:131], v[152:155], v[184:187], v[128:131]
	v_mfma_f32_16x16x32_bf16 v[124:127], v[160:163], v[184:187], v[124:127]
	v_mfma_f32_16x16x32_bf16 v[112:115], v[152:155], v[204:207], v[112:115]
	v_mfma_f32_16x16x32_bf16 v[108:111], v[160:163], v[204:207], v[108:111]
	v_mfma_f32_16x16x32_bf16 v[96:99], v[152:155], v[212:215], v[96:99]
	v_mfma_f32_16x16x32_bf16 v[92:95], v[160:163], v[212:215], v[92:95]
	v_mfma_f32_16x16x32_bf16 v[80:83], v[152:155], v[220:223], v[80:83]
	v_mfma_f32_16x16x32_bf16 v[76:79], v[160:163], v[220:223], v[76:79]
	s_setprio 0
	s_setprio 1
	v_mfma_f32_16x16x32_bf16 v[120:123], v[164:167], v[180:183], v[120:123]
	v_mfma_f32_16x16x32_bf16 v[116:119], v[172:175], v[180:183], v[116:119]
	v_mfma_f32_16x16x32_bf16 v[104:107], v[164:167], v[188:191], v[104:107]
	v_mfma_f32_16x16x32_bf16 v[100:103], v[172:175], v[188:191], v[100:103]
	v_mfma_f32_16x16x32_bf16 v[88:91], v[164:167], v[208:211], v[88:91]
	v_mfma_f32_16x16x32_bf16 v[84:87], v[172:175], v[208:211], v[84:87]
	v_mfma_f32_16x16x32_bf16 v[72:75], v[164:167], v[216:219], v[72:75]
	v_mfma_f32_16x16x32_bf16 v[68:71], v[172:175], v[216:219], v[68:71]
	v_mfma_f32_16x16x32_bf16 v[120:123], v[168:171], v[184:187], v[120:123]
	v_mfma_f32_16x16x32_bf16 v[116:119], v[176:179], v[184:187], v[116:119]
	v_mfma_f32_16x16x32_bf16 v[104:107], v[168:171], v[204:207], v[104:107]
	v_mfma_f32_16x16x32_bf16 v[100:103], v[176:179], v[204:207], v[100:103]
	v_mfma_f32_16x16x32_bf16 v[88:91], v[168:171], v[212:215], v[88:91]
	v_mfma_f32_16x16x32_bf16 v[84:87], v[176:179], v[212:215], v[84:87]
	v_mfma_f32_16x16x32_bf16 v[72:75], v[168:171], v[220:223], v[72:75]
	v_mfma_f32_16x16x32_bf16 v[68:71], v[176:179], v[220:223], v[68:71]
	s_setprio 0
	s_barrier
; #define PG8_STAGE(bufoff, gbase, voff) do { _Pragma("unroll") for (int _i = 0; _i < 2; ++_i) \
;         __builtin_amdgcn_global_load_lds((const unsigned*)((const char*)(gbase) + (voff)[_i]), (PG8_LAS unsigned*)(lds + (bufoff) + ldsw + _i * 8192), 16, 0, 0); } while (0)
; #define PG8_LDA(dst, b, h) do { _Pragma("unroll") for (int m = 0; m < 4; ++m) _Pragma("unroll") for (int k = 0; k < 2; ++k) dst[m][k] = *(const PG8_LAS bf16x8*)(lds + PG8_SA(b, h) + aoff + m * 2048 + k * 1024); } while (0)
; #define PG8_MMA(ai, bj, At, Bt) do { __builtin_amdgcn_s_setprio(1); _Pragma("unroll") for (int m = 0; m < 4; ++m) _Pragma("unroll") for (int n = 0; n < 2; ++n) _Pragma("unroll") for (int k = 0; k < 2; ++k) \
;         acc[ai][bj][m][n] = __builtin_amdgcn_mfma_f32_16x16x32_bf16(Bt[n][k], At[m][k], acc[ai][bj][m][n], 0, 0, 0); __builtin_amdgcn_s_setprio(0); } while (0)
; #define PG8_WAIT_V(n) asm volatile("s_waitcnt vmcnt(" #n ")" ::: "memory")
; #define PG8_WAIT_L(n) asm volatile("s_waitcnt lgkmcnt(" #n ")" ::: "memory")
; #define PG8_BAR __builtin_amdgcn_s_barrier()
; #define PG8_SCHED __builtin_amdgcn_sched_barrier(0)
; template <class Epi, class Sched, bool ALIGN_EPI = false, bool SP2 = false>
; __device__ __forceinline__ void gemm_phase(PG8_LAS unsigned char* lds, const Gemm g, const Sched& S, const Epi& E, int tid_in) {
;     ...
;         for (int t = 0; t < nt; t += 2) {
;     ...
;             PG8_LDA(At, 1, 1); PG8_STAGE(PG8_SB(1, 0), b3, voffB); PG8_STAGE(PG8_SB(1, 1), b3 + hsB, voffB); PG8_STAGE(PG8_SA(1, 0), a3, voffA);
;             PG8_WAIT_V(8); PG8_WAIT_L(0); PG8_BAR; PG8_MMA(1, 0, At, B0); PG8_MMA(1, 1, At, B1); PG8_BAR; PG8_SCHED;
	s_add_i32 s24, s59, s34
	v_lshl_add_u64 v[142:143], v[142:143], 0, s[80:81]
	s_mov_b32 m0, s24
	ds_read_b128 v[180:183], v146 offset:49152
	ds_read_b128 v[184:187], v146 offset:50176
	ds_read_b128 v[188:191], v146 offset:51200
	ds_read_b128 v[204:207], v146 offset:52224
	ds_read_b128 v[208:211], v146 offset:53248
	ds_read_b128 v[212:215], v146 offset:54272
	ds_read_b128 v[216:219], v146 offset:55296
	ds_read_b128 v[220:223], v146 offset:56320
	global_load_lds_dwordx4 v[142:143], off
	v_lshl_add_u64 v[142:143], v[196:197], 0, s[80:81]
	s_add_i32 m0, s24, 0x2000
	s_add_i32 s24, s60, s34
	global_load_lds_dwordx4 v[142:143], off
	v_lshl_add_u64 v[142:143], v[198:199], 0, s[80:81]
	s_mov_b32 m0, s24
	s_nop 0
	global_load_lds_dwordx4 v[142:143], off
	v_lshl_add_u64 v[142:143], v[200:201], 0, s[80:81]
	s_add_i32 m0, s24, 0x2000
	s_nop 0
	global_load_lds_dwordx4 v[142:143], off
	v_lshl_add_u64 v[142:143], v[228:229], 0, s[80:81]
	s_mov_b32 m0, s44
	s_nop 0
	global_load_lds_dwordx4 v[142:143], off
	v_lshl_add_u64 v[142:143], v[230:231], 0, s[80:81]
	s_mov_b32 m0, s45
	s_nop 0
	global_load_lds_dwordx4 v[142:143], off
	s_waitcnt vmcnt(6)
	s_waitcnt lgkmcnt(0)
	s_barrier
	s_setprio 1
	s_waitcnt lgkmcnt(0)
	v_mfma_f32_16x16x32_bf16 v[64:67], v[148:151], v[180:183], v[64:67]
	v_mfma_f32_16x16x32_bf16 v[60:63], v[156:159], v[180:183], v[60:63]
	v_mfma_f32_16x16x32_bf16 v[48:51], v[148:151], v[188:191], v[48:51]
	v_mfma_f32_16x16x32_bf16 v[44:47], v[156:159], v[188:191], v[44:47]
	v_mfma_f32_16x16x32_bf16 v[32:35], v[148:151], v[208:211], v[32:35]
	v_mfma_f32_16x16x32_bf16 v[28:31], v[156:159], v[208:211], v[28:31]
	v_mfma_f32_16x16x32_bf16 v[16:19], v[148:151], v[216:219], v[16:19]
	v_mfma_f32_16x16x32_bf16 v[12:15], v[156:159], v[216:219], v[12:15]
	v_mfma_f32_16x16x32_bf16 v[64:67], v[152:155], v[184:187], v[64:67]
	v_mfma_f32_16x16x32_bf16 v[60:63], v[160:163], v[184:187], v[60:63]
	v_mfma_f32_16x16x32_bf16 v[48:51], v[152:155], v[204:207], v[48:51]
	v_mfma_f32_16x16x32_bf16 v[44:47], v[160:163], v[204:207], v[44:47]
	v_mfma_f32_16x16x32_bf16 v[32:35], v[152:155], v[212:215], v[32:35]
	v_mfma_f32_16x16x32_bf16 v[28:31], v[160:163], v[212:215], v[28:31]
	v_mfma_f32_16x16x32_bf16 v[16:19], v[152:155], v[220:223], v[16:19]
	v_mfma_f32_16x16x32_bf16 v[12:15], v[160:163], v[220:223], v[12:15]
	s_setprio 0
	s_setprio 1
	v_mfma_f32_16x16x32_bf16 v[56:59], v[164:167], v[180:183], v[56:59]
	v_mfma_f32_16x16x32_bf16 v[52:55], v[172:175], v[180:183], v[52:55]
	v_mfma_f32_16x16x32_bf16 v[40:43], v[164:167], v[188:191], v[40:43]
	v_mfma_f32_16x16x32_bf16 v[36:39], v[172:175], v[188:191], v[36:39]
	v_mfma_f32_16x16x32_bf16 v[24:27], v[164:167], v[208:211], v[24:27]
	v_mfma_f32_16x16x32_bf16 v[20:23], v[172:175], v[208:211], v[20:23]
	v_mfma_f32_16x16x32_bf16 v[8:11], v[164:167], v[216:219], v[8:11]
	v_mfma_f32_16x16x32_bf16 v[4:7], v[172:175], v[216:219], v[4:7]
	v_mfma_f32_16x16x32_bf16 v[56:59], v[168:171], v[184:187], v[56:59]
	v_mfma_f32_16x16x32_bf16 v[52:55], v[176:179], v[184:187], v[52:55]
	v_mfma_f32_16x16x32_bf16 v[40:43], v[168:171], v[204:207], v[40:43]
	v_mfma_f32_16x16x32_bf16 v[36:39], v[176:179], v[204:207], v[36:39]
	v_mfma_f32_16x16x32_bf16 v[24:27], v[168:171], v[212:215], v[24:27]
	v_mfma_f32_16x16x32_bf16 v[20:23], v[176:179], v[212:215], v[20:23]
	v_mfma_f32_16x16x32_bf16 v[8:11], v[168:171], v[220:223], v[8:11]
	v_mfma_f32_16x16x32_bf16 v[4:7], v[176:179], v[220:223], v[4:7]
	s_setprio 0
	s_barrier
	s_add_i32 s24, s58, 2
	s_add_u32 s54, s54, 0x100
	s_addc_u32 s55, s55, 0
	s_add_u32 s22, s22, 0x100
	s_addc_u32 s23, s23, 0
	s_cmp_ge_i32 s58, s46
	s_mov_b32 s58, s24
	s_cbranch_scc0 .LBB0_924

; #define PG8_STAGE(bufoff, gbase, voff) do { _Pragma("unroll") for (int _i = 0; _i < 2; ++_i) \
;         __builtin_amdgcn_global_load_lds((const unsigned*)((const char*)(gbase) + (voff)[_i]), (PG8_LAS unsigned*)(lds + (bufoff) + ldsw + _i * 8192), 16, 0, 0); } while (0)
; #define PG8_LDA(dst, b, h) do { _Pragma("unroll") for (int m = 0; m < 4; ++m) _Pragma("unroll") for (int k = 0; k < 2; ++k) dst[m][k] = *(const PG8_LAS bf16x8*)(lds + PG8_SA(b, h) + aoff + m * 2048 + k * 1024); } while (0)
; #define PG8_LDB(dst, b, h) do { _Pragma("unroll") for (int n = 0; n < 2; ++n) _Pragma("unroll") for (int k = 0; k < 2; ++k) dst[n][k] = *(const PG8_LAS bf16x8*)(lds + PG8_SB(b, h) + boff + n * 2048 + k * 1024); } while (0)
; #define PG8_MMA(ai, bj, At, Bt) do { __builtin_amdgcn_s_setprio(1); _Pragma("unroll") for (int m = 0; m < 4; ++m) _Pragma("unroll") for (int n = 0; n < 2; ++n) _Pragma("unroll") for (int k = 0; k < 2; ++k) \
;         acc[ai][bj][m][n] = __builtin_amdgcn_mfma_f32_16x16x32_bf16(Bt[n][k], At[m][k], acc[ai][bj][m][n], 0, 0, 0); __builtin_amdgcn_s_setprio(0); } while (0)
; template <class Epi, class Sched, bool ALIGN_EPI = false, bool SP2 = false>
; __device__ __forceinline__ void gemm_phase(PG8_LAS unsigned char* lds, const Gemm g, const Sched& S, const Epi& E, int tid_in) {
;     ...
;             const bool last = (t == nt - 2);
;             if constexpr (mid_hook<Epi>::value) { if (t == Epi::H1 || t == Epi::H2) E.mid(acc, cur, wr, wc, fr, fq, t == Epi::H2); }
;             const char* a1 = cA + (size_t)(t + 1) * kstep + (t >= jt ? jb : 0);
;             const char* a2 = last ? nA : cA + (size_t)(t + 2) * kstep + (t + 2 >= jt ? jb : 0); const char* b2 = last ? nB : cB + (size_t)(t + 2) * kstep;
;             const char* a3 = a2 + kstep; const char* b3 = b2 + kstep;
;             if (last && has_next) S.a_ready(nxt);
;             if constexpr (SP2) {
;             PG8_LDB(B0, 0, 0); PG8_LDB(B1, 0, 1); PG8_SCHED; PG8_LDA(At, 0, 0); PG8_STAGE(PG8_SA(1, 1), a1 + hsA, voffA);
;             PG8_WAIT_V(8); PG8_WAIT_L(0); PG8_BAR; PG8_MMA(0, 0, At, B0); PG8_MMA(0, 1, At, B1); PG8_BAR; PG8_SCHED;
;             PG8_LDA(At, 0, 1); PG8_STAGE(PG8_SB(0, 0), b2, voffB); PG8_STAGE(PG8_SB(0, 1), b2 + hsB, voffB); PG8_STAGE(PG8_SA(0, 0), a2, voffA);
;             PG8_WAIT_V(8); PG8_WAIT_L(0); PG8_BAR; PG8_MMA(1, 0, At, B0); PG8_MMA(1, 1, At, B1); PG8_BAR; PG8_SCHED;
.LBB0_994:
	s_cmp_ge_i32 s62, s37
	s_cselect_b32 s64, s38, 0
	s_cselect_b32 s65, s52, 0
	s_add_i32 s30, s62, 2
	s_cmp_ge_i32 s30, s37
	s_cselect_b32 s29, s38, 0
	s_cselect_b32 s28, s52, 0
	s_add_u32 s29, s26, s29
	s_addc_u32 s28, s27, s28
	s_add_u32 s31, s29, 0x80
	s_addc_u32 s28, s28, 0
	s_add_i32 s66, 0, 0x10000
	s_cmp_eq_u32 s53, s62
	s_cselect_b32 s29, s5, s28
	s_cselect_b32 s28, s4, s31
	v_add_u32_e32 v3, s66, v217
	s_cselect_b32 s63, s25, s61
	s_cselect_b32 s62, s24, s60
	s_add_i32 s31, 0, 0x14000
	ds_read_b128 v[134:137], v3
	ds_read_b128 v[138:141], v3 offset:1024
	ds_read_b128 v[142:145], v3 offset:2048
	ds_read_b128 v[146:149], v3 offset:3072
	v_add_u32_e32 v3, s31, v217
	ds_read_b128 v[150:153], v3
	ds_read_b128 v[154:157], v3 offset:1024
	ds_read_b128 v[158:161], v3 offset:2048
	ds_read_b128 v[162:165], v3 offset:3072
	v_lshl_add_u64 v[4:5], s[26:27], 0, v[182:183]
	v_lshl_add_u64 v[4:5], v[4:5], 0, s[64:65]
	s_add_i32 m0, s33, 0xc000
	ds_read_b128 v[166:169], v219
	ds_read_b128 v[170:173], v219 offset:1024
	ds_read_b128 v[220:223], v219 offset:2048
	ds_read_b128 v[238:241], v219 offset:3072
	ds_read_b128 v[242:245], v219 offset:4096
	ds_read_b128 v[246:249], v219 offset:5120
	ds_read_b128 v[250:253], v219 offset:6144
	ds_read_b128 v[230:233], v219 offset:7168
	global_load_lds_dwordx4 v[4:5], off
	v_lshl_add_u64 v[4:5], s[26:27], 0, v[180:181]
	v_lshl_add_u64 v[4:5], v[4:5], 0, s[64:65]
	s_add_i32 m0, s33, 0xe000
	s_nop 0
	global_load_lds_dwordx4 v[4:5], off
	s_waitcnt vmcnt(8)
	s_waitcnt lgkmcnt(0)
	s_barrier
	s_setprio 1
	s_waitcnt lgkmcnt(0)
	v_mfma_f32_16x16x32_bf16 v[126:129], v[134:137], v[166:169], v[126:129]
	v_mfma_f32_16x16x32_bf16 v[130:133], v[142:145], v[166:169], v[130:133]
	v_mfma_f32_16x16x32_bf16 v[114:117], v[134:137], v[220:223], v[114:117]
	v_mfma_f32_16x16x32_bf16 v[110:113], v[142:145], v[220:223], v[110:113]
	v_mfma_f32_16x16x32_bf16 v[98:101], v[134:137], v[242:245], v[98:101]
	v_mfma_f32_16x16x32_bf16 v[94:97], v[142:145], v[242:245], v[94:97]
	v_mfma_f32_16x16x32_bf16 v[82:85], v[134:137], v[250:253], v[82:85]
	v_mfma_f32_16x16x32_bf16 v[78:81], v[142:145], v[250:253], v[78:81]
	v_mfma_f32_16x16x32_bf16 v[126:129], v[138:141], v[170:173], v[126:129]
	v_mfma_f32_16x16x32_bf16 v[130:133], v[146:149], v[170:173], v[130:133]
	v_mfma_f32_16x16x32_bf16 v[114:117], v[138:141], v[238:241], v[114:117]
	v_mfma_f32_16x16x32_bf16 v[110:113], v[146:149], v[238:241], v[110:113]
	v_mfma_f32_16x16x32_bf16 v[98:101], v[138:141], v[246:249], v[98:101]
	v_mfma_f32_16x16x32_bf16 v[94:97], v[146:149], v[246:249], v[94:97]
	v_mfma_f32_16x16x32_bf16 v[82:85], v[138:141], v[230:233], v[82:85]
	v_mfma_f32_16x16x32_bf16 v[78:81], v[146:149], v[230:233], v[78:81]
	s_setprio 0
	s_setprio 1
	v_mfma_f32_16x16x32_bf16 v[122:125], v[150:153], v[166:169], v[122:125]
	v_mfma_f32_16x16x32_bf16 v[118:121], v[158:161], v[166:169], v[118:121]
	v_mfma_f32_16x16x32_bf16 v[106:109], v[150:153], v[220:223], v[106:109]
	v_mfma_f32_16x16x32_bf16 v[102:105], v[158:161], v[220:223], v[102:105]
	v_mfma_f32_16x16x32_bf16 v[90:93], v[150:153], v[242:245], v[90:93]
	v_mfma_f32_16x16x32_bf16 v[86:89], v[158:161], v[242:245], v[86:89]
	v_mfma_f32_16x16x32_bf16 v[74:77], v[150:153], v[250:253], v[74:77]
	v_mfma_f32_16x16x32_bf16 v[70:73], v[158:161], v[250:253], v[70:73]
	v_mfma_f32_16x16x32_bf16 v[122:125], v[154:157], v[170:173], v[122:125]
	v_mfma_f32_16x16x32_bf16 v[118:121], v[162:165], v[170:173], v[118:121]
	v_mfma_f32_16x16x32_bf16 v[106:109], v[154:157], v[238:241], v[106:109]
	v_mfma_f32_16x16x32_bf16 v[102:105], v[162:165], v[238:241], v[102:105]
	v_mfma_f32_16x16x32_bf16 v[90:93], v[154:157], v[246:249], v[90:93]
	v_mfma_f32_16x16x32_bf16 v[86:89], v[162:165], v[246:249], v[86:89]
	v_mfma_f32_16x16x32_bf16 v[74:77], v[154:157], v[230:233], v[74:77]
	v_mfma_f32_16x16x32_bf16 v[70:73], v[162:165], v[230:233], v[70:73]
	s_setprio 0
	s_barrier
	s_add_i32 s64, s66, s43
	v_lshl_add_u64 v[196:197], s[62:63], 0, v[176:177]
	s_mov_b32 m0, s64
	ds_read_b128 v[166:169], v219 offset:16384
	ds_read_b128 v[170:173], v219 offset:17408
	ds_read_b128 v[220:223], v219 offset:18432
	ds_read_b128 v[230:233], v219 offset:19456
	ds_read_b128 v[238:241], v219 offset:20480
	ds_read_b128 v[242:245], v219 offset:21504
	ds_read_b128 v[246:249], v219 offset:22528
	ds_read_b128 v[250:253], v219 offset:23552
	global_load_lds_dwordx4 v[196:197], off
	s_add_i32 m0, s64, 0x2000
	v_lshl_add_u64 v[198:199], s[62:63], 0, v[0:1]
	s_add_u32 s62, s62, s8
	s_addc_u32 s63, s63, s9
	s_add_i32 s31, s31, s43
	global_load_lds_dwordx4 v[198:199], off
	v_lshl_add_u64 v[200:201], s[62:63], 0, v[176:177]
	v_lshl_add_u64 v[228:229], s[62:63], 0, v[0:1]
	v_lshl_add_u64 v[202:203], s[28:29], 0, v[178:179]
	s_mov_b32 m0, s33
	v_lshl_add_u64 v[192:193], s[28:29], 0, v[174:175]
	global_load_lds_dwordx4 v[202:203], off
	s_mov_b32 m0, s46
	s_nop 0
	global_load_lds_dwordx4 v[192:193], off
	s_waitcnt vmcnt(6)
	s_waitcnt lgkmcnt(0)
	s_barrier
; #define PG8_STAGE(bufoff, gbase, voff) do { _Pragma("unroll") for (int _i = 0; _i < 2; ++_i) \
;         __builtin_amdgcn_global_load_lds((const unsigned*)((const char*)(gbase) + (voff)[_i]), (PG8_LAS unsigned*)(lds + (bufoff) + ldsw + _i * 8192), 16, 0, 0); } while (0)
; #define PG8_LDA(dst, b, h) do { _Pragma("unroll") for (int m = 0; m < 4; ++m) _Pragma("unroll") for (int k = 0; k < 2; ++k) dst[m][k] = *(const PG8_LAS bf16x8*)(lds + PG8_SA(b, h) + aoff + m * 2048 + k * 1024); } while (0)
; #define PG8_LDB(dst, b, h) do { _Pragma("unroll") for (int n = 0; n < 2; ++n) _Pragma("unroll") for (int k = 0; k < 2; ++k) dst[n][k] = *(const PG8_LAS bf16x8*)(lds + PG8_SB(b, h) + boff + n * 2048 + k * 1024); } while (0)
; #define PG8_MMA(ai, bj, At, Bt) do { __builtin_amdgcn_s_setprio(1); _Pragma("unroll") for (int m = 0; m < 4; ++m) _Pragma("unroll") for (int n = 0; n < 2; ++n) _Pragma("unroll") for (int k = 0; k < 2; ++k) \
;         acc[ai][bj][m][n] = __builtin_amdgcn_mfma_f32_16x16x32_bf16(Bt[n][k], At[m][k], acc[ai][bj][m][n], 0, 0, 0); __builtin_amdgcn_s_setprio(0); } while (0)
; #define PG8_WAIT_V(n) asm volatile("s_waitcnt vmcnt(" #n ")" ::: "memory")
; #define PG8_WAIT_L(n) asm volatile("s_waitcnt lgkmcnt(" #n ")" ::: "memory")
; #define PG8_BAR __builtin_amdgcn_s_barrier()
; #define PG8_SCHED __builtin_amdgcn_sched_barrier(0)
; template <class Epi, class Sched, bool ALIGN_EPI = false, bool SP2 = false>
; __device__ __forceinline__ void gemm_phase(PG8_LAS unsigned char* lds, const Gemm g, const Sched& S, const Epi& E, int tid_in) {
;     ...
;             PG8_WAIT_V(8); PG8_WAIT_L(0); PG8_BAR; PG8_MMA(1, 0, At, B0); PG8_MMA(1, 1, At, B1); PG8_BAR; PG8_SCHED;
;             PG8_LDB(B0, 1, 0); PG8_LDB(B1, 1, 1); PG8_SCHED; PG8_LDA(At, 1, 0); PG8_STAGE(PG8_SA(0, 1), a2 + hsA, voffA);
;             PG8_WAIT_V(8); PG8_WAIT_L(0); PG8_BAR; PG8_MMA(0, 0, At, B0); PG8_MMA(0, 1, At, B1); PG8_BAR; PG8_SCHED;
	s_setprio 1
	s_waitcnt lgkmcnt(0)
	v_mfma_f32_16x16x32_bf16 v[66:69], v[134:137], v[166:169], v[66:69]
	v_mfma_f32_16x16x32_bf16 v[62:65], v[142:145], v[166:169], v[62:65]
	v_mfma_f32_16x16x32_bf16 v[50:53], v[134:137], v[220:223], v[50:53]
	v_mfma_f32_16x16x32_bf16 v[46:49], v[142:145], v[220:223], v[46:49]
	v_mfma_f32_16x16x32_bf16 v[34:37], v[134:137], v[238:241], v[34:37]
	v_mfma_f32_16x16x32_bf16 v[30:33], v[142:145], v[238:241], v[30:33]
	v_mfma_f32_16x16x32_bf16 v[18:21], v[134:137], v[246:249], v[18:21]
	v_mfma_f32_16x16x32_bf16 v[14:17], v[142:145], v[246:249], v[14:17]
	v_mfma_f32_16x16x32_bf16 v[66:69], v[138:141], v[170:173], v[66:69]
	v_mfma_f32_16x16x32_bf16 v[62:65], v[146:149], v[170:173], v[62:65]
	v_mfma_f32_16x16x32_bf16 v[50:53], v[138:141], v[230:233], v[50:53]
	v_mfma_f32_16x16x32_bf16 v[46:49], v[146:149], v[230:233], v[46:49]
	v_mfma_f32_16x16x32_bf16 v[34:37], v[138:141], v[242:245], v[34:37]
	v_mfma_f32_16x16x32_bf16 v[30:33], v[146:149], v[242:245], v[30:33]
	v_mfma_f32_16x16x32_bf16 v[18:21], v[138:141], v[250:253], v[18:21]
	v_mfma_f32_16x16x32_bf16 v[14:17], v[146:149], v[250:253], v[14:17]
	s_setprio 0
	s_setprio 1
	v_mfma_f32_16x16x32_bf16 v[58:61], v[150:153], v[166:169], v[58:61]
	v_mfma_f32_16x16x32_bf16 v[54:57], v[158:161], v[166:169], v[54:57]
	v_mfma_f32_16x16x32_bf16 v[42:45], v[150:153], v[220:223], v[42:45]
	v_mfma_f32_16x16x32_bf16 v[38:41], v[158:161], v[220:223], v[38:41]
	v_mfma_f32_16x16x32_bf16 v[26:29], v[150:153], v[238:241], v[26:29]
	v_mfma_f32_16x16x32_bf16 v[22:25], v[158:161], v[238:241], v[22:25]
	v_mfma_f32_16x16x32_bf16 v[10:13], v[150:153], v[246:249], v[10:13]
	v_mfma_f32_16x16x32_bf16 v[4:7], v[158:161], v[246:249], v[6:9]
	v_mfma_f32_16x16x32_bf16 v[58:61], v[154:157], v[170:173], v[58:61]
	v_mfma_f32_16x16x32_bf16 v[54:57], v[162:165], v[170:173], v[54:57]
	v_mfma_f32_16x16x32_bf16 v[42:45], v[154:157], v[230:233], v[42:45]
	v_mfma_f32_16x16x32_bf16 v[38:41], v[162:165], v[230:233], v[38:41]
	v_mfma_f32_16x16x32_bf16 v[26:29], v[154:157], v[242:245], v[26:29]
	v_mfma_f32_16x16x32_bf16 v[22:25], v[162:165], v[242:245], v[22:25]
	v_mfma_f32_16x16x32_bf16 v[10:13], v[154:157], v[250:253], v[10:13]
	v_mfma_f32_16x16x32_bf16 v[4:7], v[162:165], v[250:253], v[4:7]
	s_setprio 0
	s_barrier
	s_add_i32 s31, 0, 0x18000
	v_add_u32_e32 v3, s31, v217
	s_add_i32 s62, 0, 0x1c000
	ds_read_b128 v[134:137], v3
	ds_read_b128 v[138:141], v3 offset:1024
	ds_read_b128 v[142:145], v3 offset:2048
	ds_read_b128 v[146:149], v3 offset:3072
	v_add_u32_e32 v3, s62, v217
	ds_read_b128 v[150:153], v3
	ds_read_b128 v[154:157], v3 offset:1024
	ds_read_b128 v[158:161], v3 offset:2048
	ds_read_b128 v[162:165], v3 offset:3072
	s_add_u32 s28, s28, s6
	s_addc_u32 s29, s29, s7
	s_mov_b32 m0, s47
	v_lshl_add_u64 v[8:9], s[28:29], 0, v[178:179]
	ds_read_b128 v[166:169], v219 offset:32768
	ds_read_b128 v[170:173], v219 offset:33792
	ds_read_b128 v[220:223], v219 offset:34816
	ds_read_b128 v[230:233], v219 offset:35840
	ds_read_b128 v[238:241], v219 offset:36864
	ds_read_b128 v[242:245], v219 offset:37888
	ds_read_b128 v[246:249], v219 offset:38912
	ds_read_b128 v[250:253], v219 offset:39936
	global_load_lds_dwordx4 v[8:9], off
	v_lshl_add_u64 v[8:9], s[28:29], 0, v[174:175]
	s_mov_b32 m0, s48
	s_nop 0
	global_load_lds_dwordx4 v[8:9], off
	s_add_i32 m0, s43, 0x14000
	s_nop 0
	global_load_lds_dwordx4 v[200:201], off
	s_add_i32 m0, s43, 0x16000
	s_nop 0
	global_load_lds_dwordx4 v[228:229], off
	s_waitcnt vmcnt(8)
	s_waitcnt lgkmcnt(0)
	s_barrier
	s_setprio 1
	s_waitcnt lgkmcnt(0)
	v_mfma_f32_16x16x32_bf16 v[126:129], v[134:137], v[166:169], v[126:129]
	v_mfma_f32_16x16x32_bf16 v[130:133], v[142:145], v[166:169], v[130:133]
	v_mfma_f32_16x16x32_bf16 v[114:117], v[134:137], v[220:223], v[114:117]
	v_mfma_f32_16x16x32_bf16 v[110:113], v[142:145], v[220:223], v[110:113]
	v_mfma_f32_16x16x32_bf16 v[98:101], v[134:137], v[238:241], v[98:101]
	v_mfma_f32_16x16x32_bf16 v[94:97], v[142:145], v[238:241], v[94:97]
	v_mfma_f32_16x16x32_bf16 v[82:85], v[134:137], v[246:249], v[82:85]
	v_mfma_f32_16x16x32_bf16 v[78:81], v[142:145], v[246:249], v[78:81]
	v_mfma_f32_16x16x32_bf16 v[126:129], v[138:141], v[170:173], v[126:129]
	v_mfma_f32_16x16x32_bf16 v[130:133], v[146:149], v[170:173], v[130:133]
	v_mfma_f32_16x16x32_bf16 v[114:117], v[138:141], v[230:233], v[114:117]
	v_mfma_f32_16x16x32_bf16 v[110:113], v[146:149], v[230:233], v[110:113]
	v_mfma_f32_16x16x32_bf16 v[98:101], v[138:141], v[242:245], v[98:101]
	v_mfma_f32_16x16x32_bf16 v[94:97], v[146:149], v[242:245], v[94:97]
	v_mfma_f32_16x16x32_bf16 v[82:85], v[138:141], v[250:253], v[82:85]
	v_mfma_f32_16x16x32_bf16 v[78:81], v[146:149], v[250:253], v[78:81]
	s_setprio 0
	s_setprio 1
	v_mfma_f32_16x16x32_bf16 v[122:125], v[150:153], v[166:169], v[122:125]
	v_mfma_f32_16x16x32_bf16 v[118:121], v[158:161], v[166:169], v[118:121]
	v_mfma_f32_16x16x32_bf16 v[106:109], v[150:153], v[220:223], v[106:109]
	v_mfma_f32_16x16x32_bf16 v[102:105], v[158:161], v[220:223], v[102:105]
	v_mfma_f32_16x16x32_bf16 v[90:93], v[150:153], v[238:241], v[90:93]
	v_mfma_f32_16x16x32_bf16 v[86:89], v[158:161], v[238:241], v[86:89]
	v_mfma_f32_16x16x32_bf16 v[74:77], v[150:153], v[246:249], v[74:77]
	v_mfma_f32_16x16x32_bf16 v[70:73], v[158:161], v[246:249], v[70:73]
	v_mfma_f32_16x16x32_bf16 v[122:125], v[154:157], v[170:173], v[122:125]
	v_mfma_f32_16x16x32_bf16 v[118:121], v[162:165], v[170:173], v[118:121]
	v_mfma_f32_16x16x32_bf16 v[106:109], v[154:157], v[230:233], v[106:109]
	v_mfma_f32_16x16x32_bf16 v[102:105], v[162:165], v[230:233], v[102:105]
	v_mfma_f32_16x16x32_bf16 v[90:93], v[154:157], v[242:245], v[90:93]
	v_mfma_f32_16x16x32_bf16 v[86:89], v[162:165], v[242:245], v[86:89]
	v_mfma_f32_16x16x32_bf16 v[74:77], v[154:157], v[250:253], v[74:77]
	v_mfma_f32_16x16x32_bf16 v[70:73], v[162:165], v[250:253], v[70:73]
	s_setprio 0
	s_barrier
; #define PG8_STAGE(bufoff, gbase, voff) do { _Pragma("unroll") for (int _i = 0; _i < 2; ++_i) \
;         __builtin_amdgcn_global_load_lds((const unsigned*)((const char*)(gbase) + (voff)[_i]), (PG8_LAS unsigned*)(lds + (bufoff) + ldsw + _i * 8192), 16, 0, 0); } while (0)
; #define PG8_LDA(dst, b, h) do { _Pragma("unroll") for (int m = 0; m < 4; ++m) _Pragma("unroll") for (int k = 0; k < 2; ++k) dst[m][k] = *(const PG8_LAS bf16x8*)(lds + PG8_SA(b, h) + aoff + m * 2048 + k * 1024); } while (0)
; #define PG8_MMA(ai, bj, At, Bt) do { __builtin_amdgcn_s_setprio(1); _Pragma("unroll") for (int m = 0; m < 4; ++m) _Pragma("unroll") for (int n = 0; n < 2; ++n) _Pragma("unroll") for (int k = 0; k < 2; ++k) \
;         acc[ai][bj][m][n] = __builtin_amdgcn_mfma_f32_16x16x32_bf16(Bt[n][k], At[m][k], acc[ai][bj][m][n], 0, 0, 0); __builtin_amdgcn_s_setprio(0); } while (0)
; #define PG8_WAIT_V(n) asm volatile("s_waitcnt vmcnt(" #n ")" ::: "memory")
; #define PG8_WAIT_L(n) asm volatile("s_waitcnt lgkmcnt(" #n ")" ::: "memory")
; #define PG8_BAR __builtin_amdgcn_s_barrier()
; #define PG8_SCHED __builtin_amdgcn_sched_barrier(0)
; template <class Epi, class Sched, bool ALIGN_EPI = false, bool SP2 = false>
; __device__ __forceinline__ void gemm_phase(PG8_LAS unsigned char* lds, const Gemm g, const Sched& S, const Epi& E, int tid_in) {
;     ...
;         for (int t = 0; t < nt; t += 2) {
;             const bool last = (t == nt - 2);
;             if constexpr (mid_hook<Epi>::value) { if (t == Epi::H1 || t == Epi::H2) E.mid(acc, cur, wr, wc, fr, fq, t == Epi::H2); }
;             const char* a1 = cA + (size_t)(t + 1) * kstep + (t >= jt ? jb : 0);
;             const char* a2 = last ? nA : cA + (size_t)(t + 2) * kstep + (t + 2 >= jt ? jb : 0); const char* b2 = last ? nB : cB + (size_t)(t + 2) * kstep;
;     ...
;             PG8_LDA(At, 1, 1); PG8_STAGE(PG8_SB(1, 0), b3, voffB); PG8_STAGE(PG8_SB(1, 1), b3 + hsB, voffB); PG8_STAGE(PG8_SA(1, 0), a3, voffA);
;             PG8_WAIT_V(8); PG8_WAIT_L(0); PG8_BAR; PG8_MMA(1, 0, At, B0); PG8_MMA(1, 1, At, B1); PG8_BAR; PG8_SCHED;
	s_add_i32 s28, s31, s43
	v_lshl_add_u64 v[8:9], v[196:197], 0, s[80:81]
	s_mov_b32 m0, s28
	ds_read_b128 v[166:169], v219 offset:49152
	ds_read_b128 v[170:173], v219 offset:50176
	ds_read_b128 v[220:223], v219 offset:51200
	ds_read_b128 v[230:233], v219 offset:52224
	ds_read_b128 v[238:241], v219 offset:53248
	ds_read_b128 v[242:245], v219 offset:54272
	ds_read_b128 v[246:249], v219 offset:55296
	ds_read_b128 v[250:253], v219 offset:56320
	global_load_lds_dwordx4 v[8:9], off
	v_lshl_add_u64 v[8:9], v[198:199], 0, s[80:81]
	s_add_i32 m0, s28, 0x2000
	s_add_i32 s28, s62, s43
	global_load_lds_dwordx4 v[8:9], off
	v_lshl_add_u64 v[8:9], v[200:201], 0, s[80:81]
	s_mov_b32 m0, s28
	s_nop 0
	global_load_lds_dwordx4 v[8:9], off
	v_lshl_add_u64 v[8:9], v[228:229], 0, s[80:81]
	s_add_i32 m0, s28, 0x2000
	s_nop 0
	global_load_lds_dwordx4 v[8:9], off
	v_lshl_add_u64 v[8:9], v[202:203], 0, s[80:81]
	s_mov_b32 m0, s49
	s_nop 0
	global_load_lds_dwordx4 v[8:9], off
	v_lshl_add_u64 v[8:9], v[192:193], 0, s[80:81]
	s_mov_b32 m0, s50
	s_nop 0
	global_load_lds_dwordx4 v[8:9], off
	s_waitcnt vmcnt(6)
	s_waitcnt lgkmcnt(0)
	s_barrier
	s_setprio 1
	s_waitcnt lgkmcnt(0)
	v_mfma_f32_16x16x32_bf16 v[66:69], v[134:137], v[166:169], v[66:69]
	v_mfma_f32_16x16x32_bf16 v[62:65], v[142:145], v[166:169], v[62:65]
	v_mfma_f32_16x16x32_bf16 v[50:53], v[134:137], v[220:223], v[50:53]
	v_mfma_f32_16x16x32_bf16 v[46:49], v[142:145], v[220:223], v[46:49]
	v_mfma_f32_16x16x32_bf16 v[34:37], v[134:137], v[238:241], v[34:37]
	v_mfma_f32_16x16x32_bf16 v[30:33], v[142:145], v[238:241], v[30:33]
	v_mfma_f32_16x16x32_bf16 v[18:21], v[134:137], v[246:249], v[18:21]
	v_mfma_f32_16x16x32_bf16 v[14:17], v[142:145], v[246:249], v[14:17]
	v_mfma_f32_16x16x32_bf16 v[66:69], v[138:141], v[170:173], v[66:69]
	v_mfma_f32_16x16x32_bf16 v[62:65], v[146:149], v[170:173], v[62:65]
	v_mfma_f32_16x16x32_bf16 v[50:53], v[138:141], v[230:233], v[50:53]
	v_mfma_f32_16x16x32_bf16 v[46:49], v[146:149], v[230:233], v[46:49]
	v_mfma_f32_16x16x32_bf16 v[34:37], v[138:141], v[242:245], v[34:37]
	v_mfma_f32_16x16x32_bf16 v[30:33], v[146:149], v[242:245], v[30:33]
	v_mfma_f32_16x16x32_bf16 v[18:21], v[138:141], v[250:253], v[18:21]
	v_mfma_f32_16x16x32_bf16 v[14:17], v[146:149], v[250:253], v[14:17]
	s_setprio 0
	s_setprio 1
	v_mfma_f32_16x16x32_bf16 v[58:61], v[150:153], v[166:169], v[58:61]
	v_mfma_f32_16x16x32_bf16 v[54:57], v[158:161], v[166:169], v[54:57]
	v_mfma_f32_16x16x32_bf16 v[42:45], v[150:153], v[220:223], v[42:45]
	v_mfma_f32_16x16x32_bf16 v[38:41], v[158:161], v[220:223], v[38:41]
	v_mfma_f32_16x16x32_bf16 v[26:29], v[150:153], v[238:241], v[26:29]
	v_mfma_f32_16x16x32_bf16 v[22:25], v[158:161], v[238:241], v[22:25]
	v_mfma_f32_16x16x32_bf16 v[8:11], v[150:153], v[246:249], v[10:13]
	v_mfma_f32_16x16x32_bf16 v[4:7], v[158:161], v[246:249], v[4:7]
	v_mfma_f32_16x16x32_bf16 v[58:61], v[154:157], v[170:173], v[58:61]
	v_mfma_f32_16x16x32_bf16 v[54:57], v[162:165], v[170:173], v[54:57]
	v_mfma_f32_16x16x32_bf16 v[42:45], v[154:157], v[230:233], v[42:45]
	v_mfma_f32_16x16x32_bf16 v[38:41], v[162:165], v[230:233], v[38:41]
	v_mfma_f32_16x16x32_bf16 v[26:29], v[154:157], v[242:245], v[26:29]
	v_mfma_f32_16x16x32_bf16 v[22:25], v[162:165], v[242:245], v[22:25]
	v_mfma_f32_16x16x32_bf16 v[10:13], v[154:157], v[250:253], v[8:11]
	v_mfma_f32_16x16x32_bf16 v[6:9], v[162:165], v[250:253], v[4:7]
	s_setprio 0
	s_barrier
	s_add_u32 s60, s60, 0x100
	s_addc_u32 s61, s61, 0
	s_add_u32 s26, s26, 0x100
	s_addc_u32 s27, s27, 0
	s_cmp_ge_i32 s30, s51
	s_cbranch_scc1 .LBB0_996
	s_mov_b32 s62, s30
	s_cmp_lt_i32 s62, 32
	s_cbranch_scc1 .LBB0_990
	s_branch .LBB0_989

; #define PG8_STAGE(bufoff, gbase, voff) do { _Pragma("unroll") for (int _i = 0; _i < 2; ++_i) \
;         __builtin_amdgcn_global_load_lds((const unsigned*)((const char*)(gbase) + (voff)[_i]), (PG8_LAS unsigned*)(lds + (bufoff) + ldsw + _i * 8192), 16, 0, 0); } while (0)
; #define PG8_LDA(dst, b, h) do { _Pragma("unroll") for (int m = 0; m < 4; ++m) _Pragma("unroll") for (int k = 0; k < 2; ++k) dst[m][k] = *(const PG8_LAS bf16x8*)(lds + PG8_SA(b, h) + aoff + m * 2048 + k * 1024); } while (0)
; #define PG8_LDB(dst, b, h) do { _Pragma("unroll") for (int n = 0; n < 2; ++n) _Pragma("unroll") for (int k = 0; k < 2; ++k) dst[n][k] = *(const PG8_LAS bf16x8*)(lds + PG8_SB(b, h) + boff + n * 2048 + k * 1024); } while (0)
; #define PG8_MMA(ai, bj, At, Bt) do { __builtin_amdgcn_s_setprio(1); _Pragma("unroll") for (int m = 0; m < 4; ++m) _Pragma("unroll") for (int n = 0; n < 2; ++n) _Pragma("unroll") for (int k = 0; k < 2; ++k) \
;         acc[ai][bj][m][n] = __builtin_amdgcn_mfma_f32_16x16x32_bf16(Bt[n][k], At[m][k], acc[ai][bj][m][n], 0, 0, 0); __builtin_amdgcn_s_setprio(0); } while (0)
; template <class Epi, class Sched, bool ALIGN_EPI = false, bool SP2 = false>
; __device__ __forceinline__ void gemm_phase(PG8_LAS unsigned char* lds, const Gemm g, const Sched& S, const Epi& E, int tid_in) {
;     ...
;             const bool last = (t == nt - 2);
;             if constexpr (mid_hook<Epi>::value) { if (t == Epi::H1 || t == Epi::H2) E.mid(acc, cur, wr, wc, fr, fq, t == Epi::H2); }
;             const char* a1 = cA + (size_t)(t + 1) * kstep + (t >= jt ? jb : 0);
;             const char* a2 = last ? nA : cA + (size_t)(t + 2) * kstep + (t + 2 >= jt ? jb : 0); const char* b2 = last ? nB : cB + (size_t)(t + 2) * kstep;
;             const char* a3 = a2 + kstep; const char* b3 = b2 + kstep;
;             if (last && has_next) S.a_ready(nxt);
;             if constexpr (SP2) {
;             PG8_LDB(B0, 0, 0); PG8_LDB(B1, 0, 1); PG8_SCHED; PG8_LDA(At, 0, 0); PG8_STAGE(PG8_SA(1, 1), a1 + hsA, voffA);
;             PG8_WAIT_V(8); PG8_WAIT_L(0); PG8_BAR; PG8_MMA(0, 0, At, B0); PG8_MMA(0, 1, At, B1); PG8_BAR; PG8_SCHED;
;             PG8_LDA(At, 0, 1); PG8_STAGE(PG8_SB(0, 0), b2, voffB); PG8_STAGE(PG8_SB(0, 1), b2 + hsB, voffB); PG8_STAGE(PG8_SA(0, 0), a2, voffA);
;             PG8_WAIT_V(8); PG8_WAIT_L(0); PG8_BAR; PG8_MMA(1, 0, At, B0); PG8_MMA(1, 1, At, B1); PG8_BAR; PG8_SCHED;
.LBB0_1070:
	s_add_i32 s38, s40, -2
	s_cmp_ge_i32 s38, s46
	s_cselect_b32 s78, s47, 0
	s_cselect_b32 s79, s62, 0
	s_cmp_ge_i32 s40, s46
	s_cselect_b32 s39, s47, 0
	s_cselect_b32 s38, s62, 0
	s_add_u32 s39, s4, s39
	s_addc_u32 s38, s5, s38
	s_add_u32 s41, s39, 0x80
	s_addc_u32 s38, s38, 0
	s_add_i32 s77, 0, 0x10000
	s_cmp_eq_u32 s61, s40
	s_cselect_b32 s39, s35, s38
	s_cselect_b32 s38, s34, s41
	s_cselect_b32 s83, s37, s76
	s_cselect_b32 s82, s36, s75
	s_add_i32 s41, 0, 0x14000
	v_add_u32_e32 v144, s77, v217
	v_add_u32_e32 v170, s41, v217
	ds_read_b128 v[116:119], v144
	ds_read_b128 v[120:123], v144 offset:1024
	ds_read_b128 v[140:143], v144 offset:2048
	ds_read_b128 v[144:147], v144 offset:3072
	ds_read_b128 v[148:151], v170
	ds_read_b128 v[152:155], v170 offset:1024
	ds_read_b128 v[156:159], v170 offset:2048
	ds_read_b128 v[170:173], v170 offset:3072
	v_lshl_add_u64 v[190:191], s[4:5], 0, v[168:169]
	v_lshl_add_u64 v[190:191], v[190:191], 0, s[78:79]
	s_add_i32 m0, s51, 0xc000
	ds_read_b128 v[174:177], v219
	ds_read_b128 v[178:181], v219 offset:1024
	ds_read_b128 v[182:185], v219 offset:2048
	ds_read_b128 v[186:189], v219 offset:3072
	ds_read_b128 v[204:207], v219 offset:4096
	ds_read_b128 v[208:211], v219 offset:5120
	ds_read_b128 v[212:215], v219 offset:6144
	ds_read_b128 v[220:223], v219 offset:7168
	global_load_lds_dwordx4 v[190:191], off
	v_lshl_add_u64 v[190:191], s[4:5], 0, v[166:167]
	v_lshl_add_u64 v[190:191], v[190:191], 0, s[78:79]
	s_add_i32 m0, s51, 0xe000
	s_nop 0
	global_load_lds_dwordx4 v[190:191], off
	s_waitcnt vmcnt(8)
	s_waitcnt lgkmcnt(0)
	s_barrier
	s_setprio 1
	s_waitcnt lgkmcnt(0)
	v_mfma_f32_16x16x32_bf16 v[136:139], v[116:119], v[174:177], v[136:139]
	v_mfma_f32_16x16x32_bf16 v[132:135], v[140:143], v[174:177], v[132:135]
	v_mfma_f32_16x16x32_bf16 v[128:131], v[116:119], v[182:185], v[128:131]
	v_mfma_f32_16x16x32_bf16 v[124:127], v[140:143], v[182:185], v[124:127]
	v_mfma_f32_16x16x32_bf16 v[112:115], v[116:119], v[204:207], v[112:115]
	v_mfma_f32_16x16x32_bf16 v[108:111], v[140:143], v[204:207], v[108:111]
	v_mfma_f32_16x16x32_bf16 v[104:107], v[116:119], v[212:215], v[104:107]
	v_mfma_f32_16x16x32_bf16 v[100:103], v[140:143], v[212:215], v[100:103]
	v_mfma_f32_16x16x32_bf16 v[136:139], v[120:123], v[178:181], v[136:139]
	v_mfma_f32_16x16x32_bf16 v[132:135], v[144:147], v[178:181], v[132:135]
	v_mfma_f32_16x16x32_bf16 v[128:131], v[120:123], v[186:189], v[128:131]
	v_mfma_f32_16x16x32_bf16 v[124:127], v[144:147], v[186:189], v[124:127]
	v_mfma_f32_16x16x32_bf16 v[112:115], v[120:123], v[208:211], v[112:115]
	v_mfma_f32_16x16x32_bf16 v[108:111], v[144:147], v[208:211], v[108:111]
	v_mfma_f32_16x16x32_bf16 v[104:107], v[120:123], v[220:223], v[104:107]
	v_mfma_f32_16x16x32_bf16 v[100:103], v[144:147], v[220:223], v[100:103]
	s_setprio 0
	s_setprio 1
	v_mfma_f32_16x16x32_bf16 v[64:67], v[148:151], v[174:177], v[64:67]
	v_mfma_f32_16x16x32_bf16 v[56:59], v[156:159], v[174:177], v[56:59]
	v_mfma_f32_16x16x32_bf16 v[60:63], v[148:151], v[182:185], v[60:63]
	v_mfma_f32_16x16x32_bf16 v[52:55], v[156:159], v[182:185], v[52:55]
	v_mfma_f32_16x16x32_bf16 v[48:51], v[148:151], v[204:207], v[48:51]
	v_mfma_f32_16x16x32_bf16 v[40:43], v[156:159], v[204:207], v[40:43]
	v_mfma_f32_16x16x32_bf16 v[44:47], v[148:151], v[212:215], v[44:47]
	v_mfma_f32_16x16x32_bf16 v[36:39], v[156:159], v[212:215], v[36:39]
	v_mfma_f32_16x16x32_bf16 v[64:67], v[152:155], v[178:181], v[64:67]
	v_mfma_f32_16x16x32_bf16 v[56:59], v[170:173], v[178:181], v[56:59]
	v_mfma_f32_16x16x32_bf16 v[60:63], v[152:155], v[186:189], v[60:63]
	v_mfma_f32_16x16x32_bf16 v[52:55], v[170:173], v[186:189], v[52:55]
	v_mfma_f32_16x16x32_bf16 v[48:51], v[152:155], v[208:211], v[48:51]
	v_mfma_f32_16x16x32_bf16 v[40:43], v[170:173], v[208:211], v[40:43]
	v_mfma_f32_16x16x32_bf16 v[44:47], v[152:155], v[220:223], v[44:47]
	v_mfma_f32_16x16x32_bf16 v[36:39], v[170:173], v[220:223], v[36:39]
	s_setprio 0
	s_barrier
	s_add_i32 s77, s77, s50
	v_lshl_add_u64 v[190:191], s[82:83], 0, v[160:161]
	s_mov_b32 m0, s77
	ds_read_b128 v[174:177], v219 offset:16384
	ds_read_b128 v[178:181], v219 offset:17408
	ds_read_b128 v[182:185], v219 offset:18432
	ds_read_b128 v[186:189], v219 offset:19456
	ds_read_b128 v[204:207], v219 offset:20480
	ds_read_b128 v[208:211], v219 offset:21504
	ds_read_b128 v[212:215], v219 offset:22528
	ds_read_b128 v[220:223], v219 offset:23552
	global_load_lds_dwordx4 v[190:191], off
	s_add_i32 m0, s77, 0x2000
	s_add_u32 s78, s82, s12
	v_lshl_add_u64 v[192:193], s[82:83], 0, v[164:165]
	s_addc_u32 s79, s83, s13
	s_add_i32 s41, s41, s50
	global_load_lds_dwordx4 v[192:193], off
	v_lshl_add_u64 v[196:197], s[78:79], 0, v[160:161]
	v_lshl_add_u64 v[198:199], s[78:79], 0, v[164:165]
	v_lshl_add_u64 v[200:201], s[38:39], 0, v[0:1]
	s_mov_b32 m0, s51
	v_lshl_add_u64 v[202:203], s[38:39], 0, v[162:163]
	global_load_lds_dwordx4 v[200:201], off
	s_mov_b32 m0, s52
	s_nop 0
	global_load_lds_dwordx4 v[202:203], off
	s_waitcnt vmcnt(6)
	s_waitcnt lgkmcnt(0)
	s_barrier
; #define PG8_STAGE(bufoff, gbase, voff) do { _Pragma("unroll") for (int _i = 0; _i < 2; ++_i) \
;         __builtin_amdgcn_global_load_lds((const unsigned*)((const char*)(gbase) + (voff)[_i]), (PG8_LAS unsigned*)(lds + (bufoff) + ldsw + _i * 8192), 16, 0, 0); } while (0)
; #define PG8_LDA(dst, b, h) do { _Pragma("unroll") for (int m = 0; m < 4; ++m) _Pragma("unroll") for (int k = 0; k < 2; ++k) dst[m][k] = *(const PG8_LAS bf16x8*)(lds + PG8_SA(b, h) + aoff + m * 2048 + k * 1024); } while (0)
; #define PG8_LDB(dst, b, h) do { _Pragma("unroll") for (int n = 0; n < 2; ++n) _Pragma("unroll") for (int k = 0; k < 2; ++k) dst[n][k] = *(const PG8_LAS bf16x8*)(lds + PG8_SB(b, h) + boff + n * 2048 + k * 1024); } while (0)
; #define PG8_MMA(ai, bj, At, Bt) do { __builtin_amdgcn_s_setprio(1); _Pragma("unroll") for (int m = 0; m < 4; ++m) _Pragma("unroll") for (int n = 0; n < 2; ++n) _Pragma("unroll") for (int k = 0; k < 2; ++k) \
;         acc[ai][bj][m][n] = __builtin_amdgcn_mfma_f32_16x16x32_bf16(Bt[n][k], At[m][k], acc[ai][bj][m][n], 0, 0, 0); __builtin_amdgcn_s_setprio(0); } while (0)
; #define PG8_WAIT_V(n) asm volatile("s_waitcnt vmcnt(" #n ")" ::: "memory")
; #define PG8_WAIT_L(n) asm volatile("s_waitcnt lgkmcnt(" #n ")" ::: "memory")
; #define PG8_BAR __builtin_amdgcn_s_barrier()
; #define PG8_SCHED __builtin_amdgcn_sched_barrier(0)
; template <class Epi, class Sched, bool ALIGN_EPI = false, bool SP2 = false>
; __device__ __forceinline__ void gemm_phase(PG8_LAS unsigned char* lds, const Gemm g, const Sched& S, const Epi& E, int tid_in) {
;     ...
;             PG8_WAIT_V(8); PG8_WAIT_L(0); PG8_BAR; PG8_MMA(1, 0, At, B0); PG8_MMA(1, 1, At, B1); PG8_BAR; PG8_SCHED;
;             PG8_LDB(B0, 1, 0); PG8_LDB(B1, 1, 1); PG8_SCHED; PG8_LDA(At, 1, 0); PG8_STAGE(PG8_SA(0, 1), a2 + hsA, voffA);
;             PG8_WAIT_V(8); PG8_WAIT_L(0); PG8_BAR; PG8_MMA(0, 0, At, B0); PG8_MMA(0, 1, At, B1); PG8_BAR; PG8_SCHED;
	s_setprio 1
	s_waitcnt lgkmcnt(0)
	v_mfma_f32_16x16x32_bf16 v[96:99], v[116:119], v[174:177], v[96:99]
	v_mfma_f32_16x16x32_bf16 v[92:95], v[140:143], v[174:177], v[92:95]
	v_mfma_f32_16x16x32_bf16 v[88:91], v[116:119], v[182:185], v[88:91]
	v_mfma_f32_16x16x32_bf16 v[84:87], v[140:143], v[182:185], v[84:87]
	v_mfma_f32_16x16x32_bf16 v[80:83], v[116:119], v[204:207], v[80:83]
	v_mfma_f32_16x16x32_bf16 v[76:79], v[140:143], v[204:207], v[76:79]
	v_mfma_f32_16x16x32_bf16 v[72:75], v[116:119], v[212:215], v[72:75]
	v_mfma_f32_16x16x32_bf16 v[68:71], v[140:143], v[212:215], v[68:71]
	v_mfma_f32_16x16x32_bf16 v[96:99], v[120:123], v[178:181], v[96:99]
	v_mfma_f32_16x16x32_bf16 v[92:95], v[144:147], v[178:181], v[92:95]
	v_mfma_f32_16x16x32_bf16 v[88:91], v[120:123], v[186:189], v[88:91]
	v_mfma_f32_16x16x32_bf16 v[84:87], v[144:147], v[186:189], v[84:87]
	v_mfma_f32_16x16x32_bf16 v[80:83], v[120:123], v[208:211], v[80:83]
	v_mfma_f32_16x16x32_bf16 v[76:79], v[144:147], v[208:211], v[76:79]
	v_mfma_f32_16x16x32_bf16 v[72:75], v[120:123], v[220:223], v[72:75]
	v_mfma_f32_16x16x32_bf16 v[68:71], v[144:147], v[220:223], v[68:71]
	s_setprio 0
	s_setprio 1
	v_mfma_f32_16x16x32_bf16 v[32:35], v[148:151], v[174:177], v[32:35]
	v_mfma_f32_16x16x32_bf16 v[28:31], v[156:159], v[174:177], v[28:31]
	v_mfma_f32_16x16x32_bf16 v[24:27], v[148:151], v[182:185], v[24:27]
	v_mfma_f32_16x16x32_bf16 v[12:15], v[156:159], v[182:185], v[12:15]
	v_mfma_f32_16x16x32_bf16 v[20:23], v[148:151], v[204:207], v[20:23]
	v_mfma_f32_16x16x32_bf16 v[8:11], v[156:159], v[204:207], v[8:11]
	v_mfma_f32_16x16x32_bf16 v[16:19], v[148:151], v[212:215], v[16:19]
	v_mfma_f32_16x16x32_bf16 v[4:7], v[156:159], v[212:215], v[4:7]
	v_mfma_f32_16x16x32_bf16 v[32:35], v[152:155], v[178:181], v[32:35]
	v_mfma_f32_16x16x32_bf16 v[28:31], v[170:173], v[178:181], v[28:31]
	v_mfma_f32_16x16x32_bf16 v[24:27], v[152:155], v[186:189], v[24:27]
	v_mfma_f32_16x16x32_bf16 v[12:15], v[170:173], v[186:189], v[12:15]
	v_mfma_f32_16x16x32_bf16 v[20:23], v[152:155], v[208:211], v[20:23]
	v_mfma_f32_16x16x32_bf16 v[8:11], v[170:173], v[208:211], v[8:11]
	v_mfma_f32_16x16x32_bf16 v[16:19], v[152:155], v[220:223], v[16:19]
	v_mfma_f32_16x16x32_bf16 v[4:7], v[170:173], v[220:223], v[4:7]
	s_setprio 0
	s_barrier
	s_add_i32 s41, 0, 0x18000
	s_add_i32 s77, 0, 0x1c000
	v_add_u32_e32 v144, s41, v217
	v_add_u32_e32 v170, s77, v217
	ds_read_b128 v[116:119], v144
	ds_read_b128 v[120:123], v144 offset:1024
	ds_read_b128 v[140:143], v144 offset:2048
	ds_read_b128 v[144:147], v144 offset:3072
	ds_read_b128 v[148:151], v170
	ds_read_b128 v[152:155], v170 offset:1024
	ds_read_b128 v[156:159], v170 offset:2048
	ds_read_b128 v[170:173], v170 offset:3072
	s_add_u32 s38, s38, s10
	s_addc_u32 s39, s39, s11
	s_mov_b32 m0, s53
	v_lshl_add_u64 v[228:229], s[38:39], 0, v[0:1]
	ds_read_b128 v[174:177], v219 offset:32768
	ds_read_b128 v[178:181], v219 offset:33792
	ds_read_b128 v[182:185], v219 offset:34816
	ds_read_b128 v[186:189], v219 offset:35840
	ds_read_b128 v[204:207], v219 offset:36864
	ds_read_b128 v[208:211], v219 offset:37888
	ds_read_b128 v[212:215], v219 offset:38912
	ds_read_b128 v[220:223], v219 offset:39936
	global_load_lds_dwordx4 v[228:229], off
	v_lshl_add_u64 v[228:229], s[38:39], 0, v[162:163]
	s_mov_b32 m0, s54
	s_nop 0
	global_load_lds_dwordx4 v[228:229], off
	s_add_i32 m0, s50, 0x14000
	s_nop 0
	global_load_lds_dwordx4 v[196:197], off
	s_add_i32 m0, s50, 0x16000
	s_nop 0
	global_load_lds_dwordx4 v[198:199], off
	s_waitcnt vmcnt(8)
	s_waitcnt lgkmcnt(0)
	s_barrier
	s_setprio 1
	s_waitcnt lgkmcnt(0)
	v_mfma_f32_16x16x32_bf16 v[136:139], v[116:119], v[174:177], v[136:139]
	v_mfma_f32_16x16x32_bf16 v[132:135], v[140:143], v[174:177], v[132:135]
	v_mfma_f32_16x16x32_bf16 v[128:131], v[116:119], v[182:185], v[128:131]
	v_mfma_f32_16x16x32_bf16 v[124:127], v[140:143], v[182:185], v[124:127]
	v_mfma_f32_16x16x32_bf16 v[112:115], v[116:119], v[204:207], v[112:115]
	v_mfma_f32_16x16x32_bf16 v[108:111], v[140:143], v[204:207], v[108:111]
	v_mfma_f32_16x16x32_bf16 v[104:107], v[116:119], v[212:215], v[104:107]
	v_mfma_f32_16x16x32_bf16 v[100:103], v[140:143], v[212:215], v[100:103]
	v_mfma_f32_16x16x32_bf16 v[136:139], v[120:123], v[178:181], v[136:139]
	v_mfma_f32_16x16x32_bf16 v[132:135], v[144:147], v[178:181], v[132:135]
	v_mfma_f32_16x16x32_bf16 v[128:131], v[120:123], v[186:189], v[128:131]
	v_mfma_f32_16x16x32_bf16 v[124:127], v[144:147], v[186:189], v[124:127]
	v_mfma_f32_16x16x32_bf16 v[112:115], v[120:123], v[208:211], v[112:115]
	v_mfma_f32_16x16x32_bf16 v[108:111], v[144:147], v[208:211], v[108:111]
	v_mfma_f32_16x16x32_bf16 v[104:107], v[120:123], v[220:223], v[104:107]
	v_mfma_f32_16x16x32_bf16 v[100:103], v[144:147], v[220:223], v[100:103]
	s_setprio 0
	s_setprio 1
	v_mfma_f32_16x16x32_bf16 v[64:67], v[148:151], v[174:177], v[64:67]
	v_mfma_f32_16x16x32_bf16 v[56:59], v[156:159], v[174:177], v[56:59]
	v_mfma_f32_16x16x32_bf16 v[60:63], v[148:151], v[182:185], v[60:63]
	v_mfma_f32_16x16x32_bf16 v[52:55], v[156:159], v[182:185], v[52:55]
	v_mfma_f32_16x16x32_bf16 v[48:51], v[148:151], v[204:207], v[48:51]
	v_mfma_f32_16x16x32_bf16 v[40:43], v[156:159], v[204:207], v[40:43]
	v_mfma_f32_16x16x32_bf16 v[44:47], v[148:151], v[212:215], v[44:47]
	v_mfma_f32_16x16x32_bf16 v[36:39], v[156:159], v[212:215], v[36:39]
	v_mfma_f32_16x16x32_bf16 v[64:67], v[152:155], v[178:181], v[64:67]
	v_mfma_f32_16x16x32_bf16 v[56:59], v[170:173], v[178:181], v[56:59]
	v_mfma_f32_16x16x32_bf16 v[60:63], v[152:155], v[186:189], v[60:63]
	v_mfma_f32_16x16x32_bf16 v[52:55], v[170:173], v[186:189], v[52:55]
	v_mfma_f32_16x16x32_bf16 v[48:51], v[152:155], v[208:211], v[48:51]
	v_mfma_f32_16x16x32_bf16 v[40:43], v[170:173], v[208:211], v[40:43]
	v_mfma_f32_16x16x32_bf16 v[44:47], v[152:155], v[220:223], v[44:47]
	v_mfma_f32_16x16x32_bf16 v[36:39], v[170:173], v[220:223], v[36:39]
	s_setprio 0
	s_barrier
; #define PG8_STAGE(bufoff, gbase, voff) do { _Pragma("unroll") for (int _i = 0; _i < 2; ++_i) \
;         __builtin_amdgcn_global_load_lds((const unsigned*)((const char*)(gbase) + (voff)[_i]), (PG8_LAS unsigned*)(lds + (bufoff) + ldsw + _i * 8192), 16, 0, 0); } while (0)
; #define PG8_LDA(dst, b, h) do { _Pragma("unroll") for (int m = 0; m < 4; ++m) _Pragma("unroll") for (int k = 0; k < 2; ++k) dst[m][k] = *(const PG8_LAS bf16x8*)(lds + PG8_SA(b, h) + aoff + m * 2048 + k * 1024); } while (0)
; #define PG8_MMA(ai, bj, At, Bt) do { __builtin_amdgcn_s_setprio(1); _Pragma("unroll") for (int m = 0; m < 4; ++m) _Pragma("unroll") for (int n = 0; n < 2; ++n) _Pragma("unroll") for (int k = 0; k < 2; ++k) \
;         acc[ai][bj][m][n] = __builtin_amdgcn_mfma_f32_16x16x32_bf16(Bt[n][k], At[m][k], acc[ai][bj][m][n], 0, 0, 0); __builtin_amdgcn_s_setprio(0); } while (0)
; #define PG8_WAIT_V(n) asm volatile("s_waitcnt vmcnt(" #n ")" ::: "memory")
; #define PG8_WAIT_L(n) asm volatile("s_waitcnt lgkmcnt(" #n ")" ::: "memory")
; #define PG8_BAR __builtin_amdgcn_s_barrier()
; #define PG8_SCHED __builtin_amdgcn_sched_barrier(0)
; template <class Epi, class Sched, bool ALIGN_EPI = false, bool SP2 = false>
; __device__ __forceinline__ void gemm_phase(PG8_LAS unsigned char* lds, const Gemm g, const Sched& S, const Epi& E, int tid_in) {
;     ...
;         for (int t = 0; t < nt; t += 2) {
;     ...
;             PG8_LDA(At, 1, 1); PG8_STAGE(PG8_SB(1, 0), b3, voffB); PG8_STAGE(PG8_SB(1, 1), b3 + hsB, voffB); PG8_STAGE(PG8_SA(1, 0), a3, voffA);
;             PG8_WAIT_V(8); PG8_WAIT_L(0); PG8_BAR; PG8_MMA(1, 0, At, B0); PG8_MMA(1, 1, At, B1); PG8_BAR; PG8_SCHED;
	s_add_i32 s38, s41, s50
	v_lshl_add_u64 v[190:191], v[190:191], 0, s[80:81]
	s_mov_b32 m0, s38
	ds_read_b128 v[174:177], v219 offset:49152
	ds_read_b128 v[178:181], v219 offset:50176
	ds_read_b128 v[182:185], v219 offset:51200
	ds_read_b128 v[186:189], v219 offset:52224
	ds_read_b128 v[204:207], v219 offset:53248
	ds_read_b128 v[208:211], v219 offset:54272
	ds_read_b128 v[212:215], v219 offset:55296
	ds_read_b128 v[220:223], v219 offset:56320
	global_load_lds_dwordx4 v[190:191], off
	v_lshl_add_u64 v[190:191], v[192:193], 0, s[80:81]
	s_add_i32 m0, s38, 0x2000
	s_add_i32 s38, s77, s50
	global_load_lds_dwordx4 v[190:191], off
	v_lshl_add_u64 v[190:191], v[196:197], 0, s[80:81]
	s_mov_b32 m0, s38
	s_nop 0
	global_load_lds_dwordx4 v[190:191], off
	v_lshl_add_u64 v[190:191], v[198:199], 0, s[80:81]
	s_add_i32 m0, s38, 0x2000
	s_nop 0
	global_load_lds_dwordx4 v[190:191], off
	v_lshl_add_u64 v[190:191], v[200:201], 0, s[80:81]
	s_mov_b32 m0, s59
	s_nop 0
	global_load_lds_dwordx4 v[190:191], off
	v_lshl_add_u64 v[190:191], v[202:203], 0, s[80:81]
	s_mov_b32 m0, s60
	s_nop 0
	global_load_lds_dwordx4 v[190:191], off
	s_waitcnt vmcnt(6)
	s_waitcnt lgkmcnt(0)
	s_barrier
	s_setprio 1
	s_waitcnt lgkmcnt(0)
	v_mfma_f32_16x16x32_bf16 v[96:99], v[116:119], v[174:177], v[96:99]
	v_mfma_f32_16x16x32_bf16 v[92:95], v[140:143], v[174:177], v[92:95]
	v_mfma_f32_16x16x32_bf16 v[88:91], v[116:119], v[182:185], v[88:91]
	v_mfma_f32_16x16x32_bf16 v[84:87], v[140:143], v[182:185], v[84:87]
	v_mfma_f32_16x16x32_bf16 v[80:83], v[116:119], v[204:207], v[80:83]
	v_mfma_f32_16x16x32_bf16 v[76:79], v[140:143], v[204:207], v[76:79]
	v_mfma_f32_16x16x32_bf16 v[72:75], v[116:119], v[212:215], v[72:75]
	v_mfma_f32_16x16x32_bf16 v[68:71], v[140:143], v[212:215], v[68:71]
	v_mfma_f32_16x16x32_bf16 v[96:99], v[120:123], v[178:181], v[96:99]
	v_mfma_f32_16x16x32_bf16 v[92:95], v[144:147], v[178:181], v[92:95]
	v_mfma_f32_16x16x32_bf16 v[88:91], v[120:123], v[186:189], v[88:91]
	v_mfma_f32_16x16x32_bf16 v[84:87], v[144:147], v[186:189], v[84:87]
	v_mfma_f32_16x16x32_bf16 v[80:83], v[120:123], v[208:211], v[80:83]
	v_mfma_f32_16x16x32_bf16 v[76:79], v[144:147], v[208:211], v[76:79]
	v_mfma_f32_16x16x32_bf16 v[72:75], v[120:123], v[220:223], v[72:75]
	v_mfma_f32_16x16x32_bf16 v[68:71], v[144:147], v[220:223], v[68:71]
	s_setprio 0
	s_setprio 1
	v_mfma_f32_16x16x32_bf16 v[32:35], v[148:151], v[174:177], v[32:35]
	v_mfma_f32_16x16x32_bf16 v[28:31], v[156:159], v[174:177], v[28:31]
	v_mfma_f32_16x16x32_bf16 v[24:27], v[148:151], v[182:185], v[24:27]
	v_mfma_f32_16x16x32_bf16 v[12:15], v[156:159], v[182:185], v[12:15]
	v_mfma_f32_16x16x32_bf16 v[20:23], v[148:151], v[204:207], v[20:23]
	v_mfma_f32_16x16x32_bf16 v[8:11], v[156:159], v[204:207], v[8:11]
	v_mfma_f32_16x16x32_bf16 v[16:19], v[148:151], v[212:215], v[16:19]
	v_mfma_f32_16x16x32_bf16 v[4:7], v[156:159], v[212:215], v[4:7]
	v_mfma_f32_16x16x32_bf16 v[32:35], v[152:155], v[178:181], v[32:35]
	v_mfma_f32_16x16x32_bf16 v[28:31], v[170:173], v[178:181], v[28:31]
	v_mfma_f32_16x16x32_bf16 v[24:27], v[152:155], v[186:189], v[24:27]
	v_mfma_f32_16x16x32_bf16 v[12:15], v[170:173], v[186:189], v[12:15]
	v_mfma_f32_16x16x32_bf16 v[20:23], v[152:155], v[208:211], v[20:23]
	v_mfma_f32_16x16x32_bf16 v[8:11], v[170:173], v[208:211], v[8:11]
	v_mfma_f32_16x16x32_bf16 v[16:19], v[152:155], v[220:223], v[16:19]
	v_mfma_f32_16x16x32_bf16 v[4:7], v[170:173], v[220:223], v[4:7]
	s_setprio 0
	s_barrier
	s_add_i32 s38, s40, 2
	s_add_u32 s75, s75, 0x100
	s_addc_u32 s76, s76, 0
	s_add_u32 s4, s4, 0x100
	s_addc_u32 s5, s5, 0
	s_cmp_ge_i32 s40, s61
	s_mov_b32 s40, s38
	s_cbranch_scc0 .LBB0_1070
	s_movk_i32 s83, 0x3000

; #define PG8_STAGE(bufoff, gbase, voff) do { _Pragma("unroll") for (int _i = 0; _i < 2; ++_i) \
;         __builtin_amdgcn_global_load_lds((const unsigned*)((const char*)(gbase) + (voff)[_i]), (PG8_LAS unsigned*)(lds + (bufoff) + ldsw + _i * 8192), 16, 0, 0); } while (0)
; #define PG8_LDA(dst, b, h) do { _Pragma("unroll") for (int m = 0; m < 4; ++m) _Pragma("unroll") for (int k = 0; k < 2; ++k) dst[m][k] = *(const PG8_LAS bf16x8*)(lds + PG8_SA(b, h) + aoff + m * 2048 + k * 1024); } while (0)
; #define PG8_LDB(dst, b, h) do { _Pragma("unroll") for (int n = 0; n < 2; ++n) _Pragma("unroll") for (int k = 0; k < 2; ++k) dst[n][k] = *(const PG8_LAS bf16x8*)(lds + PG8_SB(b, h) + boff + n * 2048 + k * 1024); } while (0)
; #define PG8_MMA(ai, bj, At, Bt) do { __builtin_amdgcn_s_setprio(1); _Pragma("unroll") for (int m = 0; m < 4; ++m) _Pragma("unroll") for (int n = 0; n < 2; ++n) _Pragma("unroll") for (int k = 0; k < 2; ++k) \
;         acc[ai][bj][m][n] = __builtin_amdgcn_mfma_f32_16x16x32_bf16(Bt[n][k], At[m][k], acc[ai][bj][m][n], 0, 0, 0); __builtin_amdgcn_s_setprio(0); } while (0)
; template <class Epi, class Sched, bool ALIGN_EPI = false, bool SP2 = false>
; __device__ __forceinline__ void gemm_phase(PG8_LAS unsigned char* lds, const Gemm g, const Sched& S, const Epi& E, int tid_in) {
;     ...
;             const bool last = (t == nt - 2);
;             if constexpr (mid_hook<Epi>::value) { if (t == Epi::H1 || t == Epi::H2) E.mid(acc, cur, wr, wc, fr, fq, t == Epi::H2); }
;             const char* a1 = cA + (size_t)(t + 1) * kstep + (t >= jt ? jb : 0);
;             const char* a2 = last ? nA : cA + (size_t)(t + 2) * kstep + (t + 2 >= jt ? jb : 0); const char* b2 = last ? nB : cB + (size_t)(t + 2) * kstep;
;             const char* a3 = a2 + kstep; const char* b3 = b2 + kstep;
;             if (last && has_next) S.a_ready(nxt);
;             if constexpr (SP2) {
;             PG8_LDB(B0, 0, 0); PG8_LDB(B1, 0, 1); PG8_SCHED; PG8_LDA(At, 0, 0); PG8_STAGE(PG8_SA(1, 1), a1 + hsA, voffA);
;             PG8_WAIT_V(8); PG8_WAIT_L(0); PG8_BAR; PG8_MMA(0, 0, At, B0); PG8_MMA(0, 1, At, B1); PG8_BAR; PG8_SCHED;
;             PG8_LDA(At, 0, 1); PG8_STAGE(PG8_SB(0, 0), b2, voffB); PG8_STAGE(PG8_SB(0, 1), b2 + hsB, voffB); PG8_STAGE(PG8_SA(0, 0), a2, voffA);
;             PG8_WAIT_V(8); PG8_WAIT_L(0); PG8_BAR; PG8_MMA(1, 0, At, B0); PG8_MMA(1, 1, At, B1); PG8_BAR; PG8_SCHED;
.LBB0_1102:
	s_add_i32 s26, s55, -2
	s_cmp_ge_i32 s26, s28
	s_cselect_b32 s58, s29, 0
	s_cselect_b32 s59, s49, 0
	s_cmp_ge_i32 s55, s28
	s_cselect_b32 s27, s29, 0
	s_cselect_b32 s26, s49, 0
	s_add_u32 s27, s24, s27
	s_addc_u32 s26, s25, s26
	s_add_u32 s60, s27, 0x80
	s_addc_u32 s26, s26, 0
	s_add_i32 s62, 0, 0x10000
	s_cmp_eq_u32 s48, s55
	s_cselect_b32 s27, s5, s26
	s_cselect_b32 s26, s4, s60
	s_cselect_b32 s61, s23, s21
	s_cselect_b32 s60, s22, s17
	s_add_i32 s63, 0, 0x14000
	v_add_u32_e32 v160, s62, v3
	v_add_u32_e32 v176, s63, v3
	ds_read_b128 v[148:151], v160
	ds_read_b128 v[152:155], v160 offset:1024
	ds_read_b128 v[156:159], v160 offset:2048
	ds_read_b128 v[160:163], v160 offset:3072
	ds_read_b128 v[164:167], v176
	ds_read_b128 v[168:171], v176 offset:1024
	ds_read_b128 v[172:175], v176 offset:2048
	ds_read_b128 v[176:179], v176 offset:3072
	v_lshl_add_u64 v[192:193], s[24:25], 0, v[140:141]
	v_lshl_add_u64 v[192:193], v[192:193], 0, s[58:59]
	s_add_i32 m0, s35, 0xc000
	ds_read_b128 v[180:183], v147
	ds_read_b128 v[184:187], v147 offset:1024
	ds_read_b128 v[188:191], v147 offset:2048
	ds_read_b128 v[204:207], v147 offset:3072
	ds_read_b128 v[208:211], v147 offset:4096
	ds_read_b128 v[212:215], v147 offset:5120
	ds_read_b128 v[216:219], v147 offset:6144
	ds_read_b128 v[220:223], v147 offset:7168
	global_load_lds_dwordx4 v[192:193], off
	v_lshl_add_u64 v[192:193], s[24:25], 0, v[138:139]
	v_lshl_add_u64 v[192:193], v[192:193], 0, s[58:59]
	s_add_i32 m0, s35, 0xe000
	s_nop 0
	global_load_lds_dwordx4 v[192:193], off
	s_waitcnt vmcnt(8)
	s_waitcnt lgkmcnt(0)
	s_barrier
	s_setprio 1
	s_waitcnt lgkmcnt(0)
	v_mfma_f32_16x16x32_bf16 v[124:127], v[148:151], v[180:183], v[124:127]
	v_mfma_f32_16x16x32_bf16 v[128:131], v[156:159], v[180:183], v[128:131]
	v_mfma_f32_16x16x32_bf16 v[112:115], v[148:151], v[188:191], v[112:115]
	v_mfma_f32_16x16x32_bf16 v[108:111], v[156:159], v[188:191], v[108:111]
	v_mfma_f32_16x16x32_bf16 v[96:99], v[148:151], v[208:211], v[96:99]
	v_mfma_f32_16x16x32_bf16 v[92:95], v[156:159], v[208:211], v[92:95]
	v_mfma_f32_16x16x32_bf16 v[80:83], v[148:151], v[216:219], v[80:83]
	v_mfma_f32_16x16x32_bf16 v[76:79], v[156:159], v[216:219], v[76:79]
	v_mfma_f32_16x16x32_bf16 v[124:127], v[152:155], v[184:187], v[124:127]
	v_mfma_f32_16x16x32_bf16 v[128:131], v[160:163], v[184:187], v[128:131]
	v_mfma_f32_16x16x32_bf16 v[112:115], v[152:155], v[204:207], v[112:115]
	v_mfma_f32_16x16x32_bf16 v[108:111], v[160:163], v[204:207], v[108:111]
	v_mfma_f32_16x16x32_bf16 v[96:99], v[152:155], v[212:215], v[96:99]
	v_mfma_f32_16x16x32_bf16 v[92:95], v[160:163], v[212:215], v[92:95]
	v_mfma_f32_16x16x32_bf16 v[80:83], v[152:155], v[220:223], v[80:83]
	v_mfma_f32_16x16x32_bf16 v[76:79], v[160:163], v[220:223], v[76:79]
	s_setprio 0
	s_setprio 1
	v_mfma_f32_16x16x32_bf16 v[120:123], v[164:167], v[180:183], v[120:123]
	v_mfma_f32_16x16x32_bf16 v[116:119], v[172:175], v[180:183], v[116:119]
	v_mfma_f32_16x16x32_bf16 v[104:107], v[164:167], v[188:191], v[104:107]
	v_mfma_f32_16x16x32_bf16 v[100:103], v[172:175], v[188:191], v[100:103]
	v_mfma_f32_16x16x32_bf16 v[88:91], v[164:167], v[208:211], v[88:91]
	v_mfma_f32_16x16x32_bf16 v[84:87], v[172:175], v[208:211], v[84:87]
	v_mfma_f32_16x16x32_bf16 v[72:75], v[164:167], v[216:219], v[72:75]
	v_mfma_f32_16x16x32_bf16 v[68:71], v[172:175], v[216:219], v[68:71]
	v_mfma_f32_16x16x32_bf16 v[120:123], v[168:171], v[184:187], v[120:123]
	v_mfma_f32_16x16x32_bf16 v[116:119], v[176:179], v[184:187], v[116:119]
	v_mfma_f32_16x16x32_bf16 v[104:107], v[168:171], v[204:207], v[104:107]
	v_mfma_f32_16x16x32_bf16 v[100:103], v[176:179], v[204:207], v[100:103]
	v_mfma_f32_16x16x32_bf16 v[88:91], v[168:171], v[212:215], v[88:91]
	v_mfma_f32_16x16x32_bf16 v[84:87], v[176:179], v[212:215], v[84:87]
	v_mfma_f32_16x16x32_bf16 v[72:75], v[168:171], v[220:223], v[72:75]
	v_mfma_f32_16x16x32_bf16 v[68:71], v[176:179], v[220:223], v[68:71]
	s_setprio 0
	s_barrier
	s_add_i32 s58, s62, s33
	v_lshl_add_u64 v[192:193], s[60:61], 0, v[134:135]
	s_mov_b32 m0, s58
	ds_read_b128 v[180:183], v147 offset:16384
	ds_read_b128 v[184:187], v147 offset:17408
	ds_read_b128 v[188:191], v147 offset:18432
	ds_read_b128 v[204:207], v147 offset:19456
	ds_read_b128 v[208:211], v147 offset:20480
	ds_read_b128 v[212:215], v147 offset:21504
	ds_read_b128 v[216:219], v147 offset:22528
	ds_read_b128 v[220:223], v147 offset:23552
	global_load_lds_dwordx4 v[192:193], off
	s_add_i32 m0, s58, 0x2000
	s_add_u32 s58, s60, s8
	v_lshl_add_u64 v[196:197], s[60:61], 0, v[0:1]
	s_addc_u32 s59, s61, s9
	s_add_i32 s60, s63, s33
	global_load_lds_dwordx4 v[196:197], off
	v_lshl_add_u64 v[198:199], s[58:59], 0, v[134:135]
	v_lshl_add_u64 v[200:201], s[58:59], 0, v[0:1]
	v_lshl_add_u64 v[202:203], s[26:27], 0, v[136:137]
	s_mov_b32 m0, s35
	v_lshl_add_u64 v[228:229], s[26:27], 0, v[132:133]
	global_load_lds_dwordx4 v[202:203], off
	s_mov_b32 m0, s36
	s_nop 0
	global_load_lds_dwordx4 v[228:229], off
	s_waitcnt vmcnt(6)
	s_waitcnt lgkmcnt(0)
	s_barrier
; #define PG8_STAGE(bufoff, gbase, voff) do { _Pragma("unroll") for (int _i = 0; _i < 2; ++_i) \
;         __builtin_amdgcn_global_load_lds((const unsigned*)((const char*)(gbase) + (voff)[_i]), (PG8_LAS unsigned*)(lds + (bufoff) + ldsw + _i * 8192), 16, 0, 0); } while (0)
; #define PG8_LDA(dst, b, h) do { _Pragma("unroll") for (int m = 0; m < 4; ++m) _Pragma("unroll") for (int k = 0; k < 2; ++k) dst[m][k] = *(const PG8_LAS bf16x8*)(lds + PG8_SA(b, h) + aoff + m * 2048 + k * 1024); } while (0)
; #define PG8_LDB(dst, b, h) do { _Pragma("unroll") for (int n = 0; n < 2; ++n) _Pragma("unroll") for (int k = 0; k < 2; ++k) dst[n][k] = *(const PG8_LAS bf16x8*)(lds + PG8_SB(b, h) + boff + n * 2048 + k * 1024); } while (0)
; #define PG8_MMA(ai, bj, At, Bt) do { __builtin_amdgcn_s_setprio(1); _Pragma("unroll") for (int m = 0; m < 4; ++m) _Pragma("unroll") for (int n = 0; n < 2; ++n) _Pragma("unroll") for (int k = 0; k < 2; ++k) \
;         acc[ai][bj][m][n] = __builtin_amdgcn_mfma_f32_16x16x32_bf16(Bt[n][k], At[m][k], acc[ai][bj][m][n], 0, 0, 0); __builtin_amdgcn_s_setprio(0); } while (0)
; #define PG8_WAIT_V(n) asm volatile("s_waitcnt vmcnt(" #n ")" ::: "memory")
; #define PG8_WAIT_L(n) asm volatile("s_waitcnt lgkmcnt(" #n ")" ::: "memory")
; #define PG8_BAR __builtin_amdgcn_s_barrier()
; #define PG8_SCHED __builtin_amdgcn_sched_barrier(0)
; template <class Epi, class Sched, bool ALIGN_EPI = false, bool SP2 = false>
; __device__ __forceinline__ void gemm_phase(PG8_LAS unsigned char* lds, const Gemm g, const Sched& S, const Epi& E, int tid_in) {
;     ...
;             PG8_WAIT_V(8); PG8_WAIT_L(0); PG8_BAR; PG8_MMA(1, 0, At, B0); PG8_MMA(1, 1, At, B1); PG8_BAR; PG8_SCHED;
;             PG8_LDB(B0, 1, 0); PG8_LDB(B1, 1, 1); PG8_SCHED; PG8_LDA(At, 1, 0); PG8_STAGE(PG8_SA(0, 1), a2 + hsA, voffA);
;             PG8_WAIT_V(8); PG8_WAIT_L(0); PG8_BAR; PG8_MMA(0, 0, At, B0); PG8_MMA(0, 1, At, B1); PG8_BAR; PG8_SCHED;
	s_setprio 1
	s_waitcnt lgkmcnt(0)
	v_mfma_f32_16x16x32_bf16 v[64:67], v[148:151], v[180:183], v[64:67]
	v_mfma_f32_16x16x32_bf16 v[60:63], v[156:159], v[180:183], v[60:63]
	v_mfma_f32_16x16x32_bf16 v[48:51], v[148:151], v[188:191], v[48:51]
	v_mfma_f32_16x16x32_bf16 v[44:47], v[156:159], v[188:191], v[44:47]
	v_mfma_f32_16x16x32_bf16 v[32:35], v[148:151], v[208:211], v[32:35]
	v_mfma_f32_16x16x32_bf16 v[28:31], v[156:159], v[208:211], v[28:31]
	v_mfma_f32_16x16x32_bf16 v[16:19], v[148:151], v[216:219], v[16:19]
	v_mfma_f32_16x16x32_bf16 v[12:15], v[156:159], v[216:219], v[12:15]
	v_mfma_f32_16x16x32_bf16 v[64:67], v[152:155], v[184:187], v[64:67]
	v_mfma_f32_16x16x32_bf16 v[60:63], v[160:163], v[184:187], v[60:63]
	v_mfma_f32_16x16x32_bf16 v[48:51], v[152:155], v[204:207], v[48:51]
	v_mfma_f32_16x16x32_bf16 v[44:47], v[160:163], v[204:207], v[44:47]
	v_mfma_f32_16x16x32_bf16 v[32:35], v[152:155], v[212:215], v[32:35]
	v_mfma_f32_16x16x32_bf16 v[28:31], v[160:163], v[212:215], v[28:31]
	v_mfma_f32_16x16x32_bf16 v[16:19], v[152:155], v[220:223], v[16:19]
	v_mfma_f32_16x16x32_bf16 v[12:15], v[160:163], v[220:223], v[12:15]
	s_setprio 0
	s_setprio 1
	v_mfma_f32_16x16x32_bf16 v[56:59], v[164:167], v[180:183], v[56:59]
	v_mfma_f32_16x16x32_bf16 v[52:55], v[172:175], v[180:183], v[52:55]
	v_mfma_f32_16x16x32_bf16 v[40:43], v[164:167], v[188:191], v[40:43]
	v_mfma_f32_16x16x32_bf16 v[36:39], v[172:175], v[188:191], v[36:39]
	v_mfma_f32_16x16x32_bf16 v[24:27], v[164:167], v[208:211], v[24:27]
	v_mfma_f32_16x16x32_bf16 v[20:23], v[172:175], v[208:211], v[20:23]
	v_mfma_f32_16x16x32_bf16 v[8:11], v[164:167], v[216:219], v[8:11]
	v_mfma_f32_16x16x32_bf16 v[4:7], v[172:175], v[216:219], v[4:7]
	v_mfma_f32_16x16x32_bf16 v[56:59], v[168:171], v[184:187], v[56:59]
	v_mfma_f32_16x16x32_bf16 v[52:55], v[176:179], v[184:187], v[52:55]
	v_mfma_f32_16x16x32_bf16 v[40:43], v[168:171], v[204:207], v[40:43]
	v_mfma_f32_16x16x32_bf16 v[36:39], v[176:179], v[204:207], v[36:39]
	v_mfma_f32_16x16x32_bf16 v[24:27], v[168:171], v[212:215], v[24:27]
	v_mfma_f32_16x16x32_bf16 v[20:23], v[176:179], v[212:215], v[20:23]
	v_mfma_f32_16x16x32_bf16 v[8:11], v[168:171], v[220:223], v[8:11]
	v_mfma_f32_16x16x32_bf16 v[4:7], v[176:179], v[220:223], v[4:7]
	s_setprio 0
	s_barrier
	s_add_i32 s58, 0, 0x18000
	s_add_i32 s59, 0, 0x1c000
	v_add_u32_e32 v160, s58, v3
	v_add_u32_e32 v176, s59, v3
	ds_read_b128 v[148:151], v160
	ds_read_b128 v[152:155], v160 offset:1024
	ds_read_b128 v[156:159], v160 offset:2048
	ds_read_b128 v[160:163], v160 offset:3072
	ds_read_b128 v[164:167], v176
	ds_read_b128 v[168:171], v176 offset:1024
	ds_read_b128 v[172:175], v176 offset:2048
	ds_read_b128 v[176:179], v176 offset:3072
	s_add_u32 s26, s26, s6
	s_addc_u32 s27, s27, s7
	s_mov_b32 m0, s37
	v_lshl_add_u64 v[230:231], s[26:27], 0, v[136:137]
	ds_read_b128 v[180:183], v147 offset:32768
	ds_read_b128 v[184:187], v147 offset:33792
	ds_read_b128 v[188:191], v147 offset:34816
	ds_read_b128 v[204:207], v147 offset:35840
	ds_read_b128 v[208:211], v147 offset:36864
	ds_read_b128 v[212:215], v147 offset:37888
	ds_read_b128 v[216:219], v147 offset:38912
	ds_read_b128 v[220:223], v147 offset:39936
	global_load_lds_dwordx4 v[230:231], off
	v_lshl_add_u64 v[230:231], s[26:27], 0, v[132:133]
	s_mov_b32 m0, s38
	s_nop 0
	global_load_lds_dwordx4 v[230:231], off
	s_add_i32 m0, s33, 0x14000
	s_nop 0
	global_load_lds_dwordx4 v[198:199], off
	s_add_i32 m0, s33, 0x16000
	s_nop 0
	global_load_lds_dwordx4 v[200:201], off
	s_waitcnt vmcnt(8)
	s_waitcnt lgkmcnt(0)
	s_barrier
	s_setprio 1
	s_waitcnt lgkmcnt(0)
	v_mfma_f32_16x16x32_bf16 v[124:127], v[148:151], v[180:183], v[124:127]
	v_mfma_f32_16x16x32_bf16 v[128:131], v[156:159], v[180:183], v[128:131]
	v_mfma_f32_16x16x32_bf16 v[112:115], v[148:151], v[188:191], v[112:115]
	v_mfma_f32_16x16x32_bf16 v[108:111], v[156:159], v[188:191], v[108:111]
	v_mfma_f32_16x16x32_bf16 v[96:99], v[148:151], v[208:211], v[96:99]
	v_mfma_f32_16x16x32_bf16 v[92:95], v[156:159], v[208:211], v[92:95]
	v_mfma_f32_16x16x32_bf16 v[80:83], v[148:151], v[216:219], v[80:83]
	v_mfma_f32_16x16x32_bf16 v[76:79], v[156:159], v[216:219], v[76:79]
	v_mfma_f32_16x16x32_bf16 v[124:127], v[152:155], v[184:187], v[124:127]
	v_mfma_f32_16x16x32_bf16 v[128:131], v[160:163], v[184:187], v[128:131]
	v_mfma_f32_16x16x32_bf16 v[112:115], v[152:155], v[204:207], v[112:115]
	v_mfma_f32_16x16x32_bf16 v[108:111], v[160:163], v[204:207], v[108:111]
	v_mfma_f32_16x16x32_bf16 v[96:99], v[152:155], v[212:215], v[96:99]
	v_mfma_f32_16x16x32_bf16 v[92:95], v[160:163], v[212:215], v[92:95]
	v_mfma_f32_16x16x32_bf16 v[80:83], v[152:155], v[220:223], v[80:83]
	v_mfma_f32_16x16x32_bf16 v[76:79], v[160:163], v[220:223], v[76:79]
	s_setprio 0
	s_setprio 1
	v_mfma_f32_16x16x32_bf16 v[120:123], v[164:167], v[180:183], v[120:123]
	v_mfma_f32_16x16x32_bf16 v[116:119], v[172:175], v[180:183], v[116:119]
	v_mfma_f32_16x16x32_bf16 v[104:107], v[164:167], v[188:191], v[104:107]
	v_mfma_f32_16x16x32_bf16 v[100:103], v[172:175], v[188:191], v[100:103]
	v_mfma_f32_16x16x32_bf16 v[88:91], v[164:167], v[208:211], v[88:91]
	v_mfma_f32_16x16x32_bf16 v[84:87], v[172:175], v[208:211], v[84:87]
	v_mfma_f32_16x16x32_bf16 v[72:75], v[164:167], v[216:219], v[72:75]
	v_mfma_f32_16x16x32_bf16 v[68:71], v[172:175], v[216:219], v[68:71]
	v_mfma_f32_16x16x32_bf16 v[120:123], v[168:171], v[184:187], v[120:123]
	v_mfma_f32_16x16x32_bf16 v[116:119], v[176:179], v[184:187], v[116:119]
	v_mfma_f32_16x16x32_bf16 v[104:107], v[168:171], v[204:207], v[104:107]
	v_mfma_f32_16x16x32_bf16 v[100:103], v[176:179], v[204:207], v[100:103]
	v_mfma_f32_16x16x32_bf16 v[88:91], v[168:171], v[212:215], v[88:91]
	v_mfma_f32_16x16x32_bf16 v[84:87], v[176:179], v[212:215], v[84:87]
	v_mfma_f32_16x16x32_bf16 v[72:75], v[168:171], v[220:223], v[72:75]
	v_mfma_f32_16x16x32_bf16 v[68:71], v[176:179], v[220:223], v[68:71]
	s_setprio 0
	s_barrier
; #define PG8_STAGE(bufoff, gbase, voff) do { _Pragma("unroll") for (int _i = 0; _i < 2; ++_i) \
;         __builtin_amdgcn_global_load_lds((const unsigned*)((const char*)(gbase) + (voff)[_i]), (PG8_LAS unsigned*)(lds + (bufoff) + ldsw + _i * 8192), 16, 0, 0); } while (0)
; #define PG8_LDA(dst, b, h) do { _Pragma("unroll") for (int m = 0; m < 4; ++m) _Pragma("unroll") for (int k = 0; k < 2; ++k) dst[m][k] = *(const PG8_LAS bf16x8*)(lds + PG8_SA(b, h) + aoff + m * 2048 + k * 1024); } while (0)
; #define PG8_MMA(ai, bj, At, Bt) do { __builtin_amdgcn_s_setprio(1); _Pragma("unroll") for (int m = 0; m < 4; ++m) _Pragma("unroll") for (int n = 0; n < 2; ++n) _Pragma("unroll") for (int k = 0; k < 2; ++k) \
;         acc[ai][bj][m][n] = __builtin_amdgcn_mfma_f32_16x16x32_bf16(Bt[n][k], At[m][k], acc[ai][bj][m][n], 0, 0, 0); __builtin_amdgcn_s_setprio(0); } while (0)
; #define PG8_WAIT_V(n) asm volatile("s_waitcnt vmcnt(" #n ")" ::: "memory")
; #define PG8_WAIT_L(n) asm volatile("s_waitcnt lgkmcnt(" #n ")" ::: "memory")
; #define PG8_BAR __builtin_amdgcn_s_barrier()
; #define PG8_SCHED __builtin_amdgcn_sched_barrier(0)
; template <class Epi, class Sched, bool ALIGN_EPI = false, bool SP2 = false>
; __device__ __forceinline__ void gemm_phase(PG8_LAS unsigned char* lds, const Gemm g, const Sched& S, const Epi& E, int tid_in) {
;     ...
;         for (int t = 0; t < nt; t += 2) {
;     ...
;             PG8_LDA(At, 1, 1); PG8_STAGE(PG8_SB(1, 0), b3, voffB); PG8_STAGE(PG8_SB(1, 1), b3 + hsB, voffB); PG8_STAGE(PG8_SA(1, 0), a3, voffA);
;             PG8_WAIT_V(8); PG8_WAIT_L(0); PG8_BAR; PG8_MMA(1, 0, At, B0); PG8_MMA(1, 1, At, B1); PG8_BAR; PG8_SCHED;
	s_add_i32 s26, s58, s33
	v_lshl_add_u64 v[192:193], v[192:193], 0, s[80:81]
	s_mov_b32 m0, s26
	ds_read_b128 v[180:183], v147 offset:49152
	ds_read_b128 v[184:187], v147 offset:50176
	ds_read_b128 v[188:191], v147 offset:51200
	ds_read_b128 v[204:207], v147 offset:52224
	ds_read_b128 v[208:211], v147 offset:53248
	ds_read_b128 v[212:215], v147 offset:54272
	ds_read_b128 v[216:219], v147 offset:55296
	ds_read_b128 v[220:223], v147 offset:56320
	global_load_lds_dwordx4 v[192:193], off
	v_lshl_add_u64 v[192:193], v[196:197], 0, s[80:81]
	s_add_i32 m0, s26, 0x2000
	s_add_i32 s26, s59, s33
	global_load_lds_dwordx4 v[192:193], off
	v_lshl_add_u64 v[192:193], v[198:199], 0, s[80:81]
	s_mov_b32 m0, s26
	s_nop 0
	global_load_lds_dwordx4 v[192:193], off
	v_lshl_add_u64 v[192:193], v[200:201], 0, s[80:81]
	s_add_i32 m0, s26, 0x2000
	s_nop 0
	global_load_lds_dwordx4 v[192:193], off
	v_lshl_add_u64 v[192:193], v[202:203], 0, s[80:81]
	s_mov_b32 m0, s41
	s_nop 0
	global_load_lds_dwordx4 v[192:193], off
	v_lshl_add_u64 v[192:193], v[228:229], 0, s[80:81]
	s_mov_b32 m0, s46
	s_nop 0
	global_load_lds_dwordx4 v[192:193], off
	s_waitcnt vmcnt(6)
	s_waitcnt lgkmcnt(0)
	s_barrier
	s_setprio 1
	s_waitcnt lgkmcnt(0)
	v_mfma_f32_16x16x32_bf16 v[64:67], v[148:151], v[180:183], v[64:67]
	v_mfma_f32_16x16x32_bf16 v[60:63], v[156:159], v[180:183], v[60:63]
	v_mfma_f32_16x16x32_bf16 v[48:51], v[148:151], v[188:191], v[48:51]
	v_mfma_f32_16x16x32_bf16 v[44:47], v[156:159], v[188:191], v[44:47]
	v_mfma_f32_16x16x32_bf16 v[32:35], v[148:151], v[208:211], v[32:35]
	v_mfma_f32_16x16x32_bf16 v[28:31], v[156:159], v[208:211], v[28:31]
	v_mfma_f32_16x16x32_bf16 v[16:19], v[148:151], v[216:219], v[16:19]
	v_mfma_f32_16x16x32_bf16 v[12:15], v[156:159], v[216:219], v[12:15]
	v_mfma_f32_16x16x32_bf16 v[64:67], v[152:155], v[184:187], v[64:67]
	v_mfma_f32_16x16x32_bf16 v[60:63], v[160:163], v[184:187], v[60:63]
	v_mfma_f32_16x16x32_bf16 v[48:51], v[152:155], v[204:207], v[48:51]
	v_mfma_f32_16x16x32_bf16 v[44:47], v[160:163], v[204:207], v[44:47]
	v_mfma_f32_16x16x32_bf16 v[32:35], v[152:155], v[212:215], v[32:35]
	v_mfma_f32_16x16x32_bf16 v[28:31], v[160:163], v[212:215], v[28:31]
	v_mfma_f32_16x16x32_bf16 v[16:19], v[152:155], v[220:223], v[16:19]
	v_mfma_f32_16x16x32_bf16 v[12:15], v[160:163], v[220:223], v[12:15]
	s_setprio 0
	s_setprio 1
	v_mfma_f32_16x16x32_bf16 v[56:59], v[164:167], v[180:183], v[56:59]
	v_mfma_f32_16x16x32_bf16 v[52:55], v[172:175], v[180:183], v[52:55]
	v_mfma_f32_16x16x32_bf16 v[40:43], v[164:167], v[188:191], v[40:43]
	v_mfma_f32_16x16x32_bf16 v[36:39], v[172:175], v[188:191], v[36:39]
	v_mfma_f32_16x16x32_bf16 v[24:27], v[164:167], v[208:211], v[24:27]
	v_mfma_f32_16x16x32_bf16 v[20:23], v[172:175], v[208:211], v[20:23]
	v_mfma_f32_16x16x32_bf16 v[8:11], v[164:167], v[216:219], v[8:11]
	v_mfma_f32_16x16x32_bf16 v[4:7], v[172:175], v[216:219], v[4:7]
	v_mfma_f32_16x16x32_bf16 v[56:59], v[168:171], v[184:187], v[56:59]
	v_mfma_f32_16x16x32_bf16 v[52:55], v[176:179], v[184:187], v[52:55]
	v_mfma_f32_16x16x32_bf16 v[40:43], v[168:171], v[204:207], v[40:43]
	v_mfma_f32_16x16x32_bf16 v[36:39], v[176:179], v[204:207], v[36:39]
	v_mfma_f32_16x16x32_bf16 v[24:27], v[168:171], v[212:215], v[24:27]
	v_mfma_f32_16x16x32_bf16 v[20:23], v[176:179], v[212:215], v[20:23]
	v_mfma_f32_16x16x32_bf16 v[8:11], v[168:171], v[220:223], v[8:11]
	v_mfma_f32_16x16x32_bf16 v[4:7], v[176:179], v[220:223], v[4:7]
	s_setprio 0
	s_barrier
	s_add_i32 s26, s55, 2
	s_add_u32 s17, s17, 0x100
	s_addc_u32 s21, s21, 0
	s_add_u32 s24, s24, 0x100
	s_addc_u32 s25, s25, 0
	s_cmp_ge_i32 s55, s48
	s_mov_b32 s55, s26
	s_cbranch_scc0 .LBB0_1102

; #define PG8_STAGE(bufoff, gbase, voff) do { _Pragma("unroll") for (int _i = 0; _i < 2; ++_i) \
;         __builtin_amdgcn_global_load_lds((const unsigned*)((const char*)(gbase) + (voff)[_i]), (PG8_LAS unsigned*)(lds + (bufoff) + ldsw + _i * 8192), 16, 0, 0); } while (0)
; #define PG8_LDA(dst, b, h) do { _Pragma("unroll") for (int m = 0; m < 4; ++m) _Pragma("unroll") for (int k = 0; k < 2; ++k) dst[m][k] = *(const PG8_LAS bf16x8*)(lds + PG8_SA(b, h) + aoff + m * 2048 + k * 1024); } while (0)
; #define PG8_LDB(dst, b, h) do { _Pragma("unroll") for (int n = 0; n < 2; ++n) _Pragma("unroll") for (int k = 0; k < 2; ++k) dst[n][k] = *(const PG8_LAS bf16x8*)(lds + PG8_SB(b, h) + boff + n * 2048 + k * 1024); } while (0)
; #define PG8_MMA(ai, bj, At, Bt) do { __builtin_amdgcn_s_setprio(1); _Pragma("unroll") for (int m = 0; m < 4; ++m) _Pragma("unroll") for (int n = 0; n < 2; ++n) _Pragma("unroll") for (int k = 0; k < 2; ++k) \
;         acc[ai][bj][m][n] = __builtin_amdgcn_mfma_f32_16x16x32_bf16(Bt[n][k], At[m][k], acc[ai][bj][m][n], 0, 0, 0); __builtin_amdgcn_s_setprio(0); } while (0)
; template <class Epi, class Sched, bool ALIGN_EPI = false, bool SP2 = false>
; __device__ __forceinline__ void gemm_phase(PG8_LAS unsigned char* lds, const Gemm g, const Sched& S, const Epi& E, int tid_in) {
;     ...
;             const bool last = (t == nt - 2);
;             if constexpr (mid_hook<Epi>::value) { if (t == Epi::H1 || t == Epi::H2) E.mid(acc, cur, wr, wc, fr, fq, t == Epi::H2); }
;             const char* a1 = cA + (size_t)(t + 1) * kstep + (t >= jt ? jb : 0);
;             const char* a2 = last ? nA : cA + (size_t)(t + 2) * kstep + (t + 2 >= jt ? jb : 0); const char* b2 = last ? nB : cB + (size_t)(t + 2) * kstep;
;             const char* a3 = a2 + kstep; const char* b3 = b2 + kstep;
;             if (last && has_next) S.a_ready(nxt);
;             if constexpr (SP2) {
;             PG8_LDB(B0, 0, 0); PG8_LDB(B1, 0, 1); PG8_SCHED; PG8_LDA(At, 0, 0); PG8_STAGE(PG8_SA(1, 1), a1 + hsA, voffA);
;             PG8_WAIT_V(8); PG8_WAIT_L(0); PG8_BAR; PG8_MMA(0, 0, At, B0); PG8_MMA(0, 1, At, B1); PG8_BAR; PG8_SCHED;
;             PG8_LDA(At, 0, 1); PG8_STAGE(PG8_SB(0, 0), b2, voffB); PG8_STAGE(PG8_SB(0, 1), b2 + hsB, voffB); PG8_STAGE(PG8_SA(0, 0), a2, voffA);
;             PG8_WAIT_V(8); PG8_WAIT_L(0); PG8_BAR; PG8_MMA(1, 0, At, B0); PG8_MMA(1, 1, At, B1); PG8_BAR; PG8_SCHED;
.LBB0_1255:
	s_add_i32 s24, s58, -2
	s_cmp_ge_i32 s24, s29
	s_cselect_b32 s60, s30, 0
	s_cselect_b32 s61, s47, 0
	s_cmp_ge_i32 s58, s29
	s_cselect_b32 s25, s30, 0
	s_cselect_b32 s24, s47, 0
	s_add_u32 s25, s22, s25
	s_addc_u32 s24, s23, s24
	s_add_u32 s59, s25, 0x80
	s_addc_u32 s24, s24, 0
	s_add_i32 s64, 0, 0x10000
	s_cmp_eq_u32 s46, s58
	s_cselect_b32 s25, s5, s24
	s_cselect_b32 s24, s4, s59
	s_cselect_b32 s63, s21, s55
	s_cselect_b32 s62, s20, s54
	s_add_i32 s59, 0, 0x14000
	v_add_u32_e32 v160, s64, v142
	v_add_u32_e32 v176, s59, v142
	ds_read_b128 v[148:151], v160
	ds_read_b128 v[152:155], v160 offset:1024
	ds_read_b128 v[156:159], v160 offset:2048
	ds_read_b128 v[160:163], v160 offset:3072
	ds_read_b128 v[164:167], v176
	ds_read_b128 v[168:171], v176 offset:1024
	ds_read_b128 v[172:175], v176 offset:2048
	ds_read_b128 v[176:179], v176 offset:3072
	v_lshl_add_u64 v[192:193], s[22:23], 0, v[140:141]
	v_lshl_add_u64 v[192:193], v[192:193], 0, s[60:61]
	s_add_i32 m0, s40, 0xc000
	ds_read_b128 v[180:183], v147
	ds_read_b128 v[184:187], v147 offset:1024
	ds_read_b128 v[188:191], v147 offset:2048
	ds_read_b128 v[204:207], v147 offset:3072
	ds_read_b128 v[208:211], v147 offset:4096
	ds_read_b128 v[212:215], v147 offset:5120
	ds_read_b128 v[216:219], v147 offset:6144
	ds_read_b128 v[220:223], v147 offset:7168
	global_load_lds_dwordx4 v[192:193], off
	v_lshl_add_u64 v[192:193], s[22:23], 0, v[138:139]
	v_lshl_add_u64 v[192:193], v[192:193], 0, s[60:61]
	s_add_i32 m0, s40, 0xe000
	s_nop 0
	global_load_lds_dwordx4 v[192:193], off
	s_waitcnt vmcnt(8)
	s_waitcnt lgkmcnt(0)
	s_barrier
	s_setprio 1
	s_waitcnt lgkmcnt(0)
	v_mfma_f32_16x16x32_bf16 v[124:127], v[148:151], v[180:183], v[124:127]
	v_mfma_f32_16x16x32_bf16 v[120:123], v[156:159], v[180:183], v[120:123]
	v_mfma_f32_16x16x32_bf16 v[112:115], v[148:151], v[188:191], v[112:115]
	v_mfma_f32_16x16x32_bf16 v[104:107], v[156:159], v[188:191], v[104:107]
	v_mfma_f32_16x16x32_bf16 v[96:99], v[148:151], v[208:211], v[96:99]
	v_mfma_f32_16x16x32_bf16 v[88:91], v[156:159], v[208:211], v[88:91]
	v_mfma_f32_16x16x32_bf16 v[80:83], v[148:151], v[216:219], v[80:83]
	v_mfma_f32_16x16x32_bf16 v[72:75], v[156:159], v[216:219], v[72:75]
	v_mfma_f32_16x16x32_bf16 v[124:127], v[152:155], v[184:187], v[124:127]
	v_mfma_f32_16x16x32_bf16 v[120:123], v[160:163], v[184:187], v[120:123]
	v_mfma_f32_16x16x32_bf16 v[112:115], v[152:155], v[204:207], v[112:115]
	v_mfma_f32_16x16x32_bf16 v[104:107], v[160:163], v[204:207], v[104:107]
	v_mfma_f32_16x16x32_bf16 v[96:99], v[152:155], v[212:215], v[96:99]
	v_mfma_f32_16x16x32_bf16 v[88:91], v[160:163], v[212:215], v[88:91]
	v_mfma_f32_16x16x32_bf16 v[80:83], v[152:155], v[220:223], v[80:83]
	v_mfma_f32_16x16x32_bf16 v[72:75], v[160:163], v[220:223], v[72:75]
	s_setprio 0
	s_setprio 1
	v_mfma_f32_16x16x32_bf16 v[128:131], v[164:167], v[180:183], v[128:131]
	v_mfma_f32_16x16x32_bf16 v[116:119], v[172:175], v[180:183], v[116:119]
	v_mfma_f32_16x16x32_bf16 v[108:111], v[164:167], v[188:191], v[108:111]
	v_mfma_f32_16x16x32_bf16 v[100:103], v[172:175], v[188:191], v[100:103]
	v_mfma_f32_16x16x32_bf16 v[92:95], v[164:167], v[208:211], v[92:95]
	v_mfma_f32_16x16x32_bf16 v[84:87], v[172:175], v[208:211], v[84:87]
	v_mfma_f32_16x16x32_bf16 v[76:79], v[164:167], v[216:219], v[76:79]
	v_mfma_f32_16x16x32_bf16 v[68:71], v[172:175], v[216:219], v[68:71]
	v_mfma_f32_16x16x32_bf16 v[128:131], v[168:171], v[184:187], v[128:131]
	v_mfma_f32_16x16x32_bf16 v[116:119], v[176:179], v[184:187], v[116:119]
	v_mfma_f32_16x16x32_bf16 v[108:111], v[168:171], v[204:207], v[108:111]
	v_mfma_f32_16x16x32_bf16 v[100:103], v[176:179], v[204:207], v[100:103]
	v_mfma_f32_16x16x32_bf16 v[92:95], v[168:171], v[212:215], v[92:95]
	v_mfma_f32_16x16x32_bf16 v[84:87], v[176:179], v[212:215], v[84:87]
	v_mfma_f32_16x16x32_bf16 v[76:79], v[168:171], v[220:223], v[76:79]
	v_mfma_f32_16x16x32_bf16 v[68:71], v[176:179], v[220:223], v[68:71]
	s_setprio 0
	s_barrier
	s_add_i32 s60, s64, s36
	v_lshl_add_u64 v[192:193], s[62:63], 0, v[134:135]
	s_mov_b32 m0, s60
	ds_read_b128 v[180:183], v147 offset:16384
	ds_read_b128 v[184:187], v147 offset:17408
	ds_read_b128 v[188:191], v147 offset:18432
	ds_read_b128 v[204:207], v147 offset:19456
	ds_read_b128 v[208:211], v147 offset:20480
	ds_read_b128 v[212:215], v147 offset:21504
	ds_read_b128 v[216:219], v147 offset:22528
	ds_read_b128 v[220:223], v147 offset:23552
	global_load_lds_dwordx4 v[192:193], off
	s_add_i32 m0, s60, 0x2000
	s_add_u32 s60, s62, s6
	v_lshl_add_u64 v[196:197], s[62:63], 0, v[0:1]
	s_addc_u32 s61, s63, s7
	s_add_i32 s59, s59, s36
	global_load_lds_dwordx4 v[196:197], off
	v_lshl_add_u64 v[198:199], s[60:61], 0, v[134:135]
	v_lshl_add_u64 v[200:201], s[60:61], 0, v[0:1]
	v_lshl_add_u64 v[202:203], s[24:25], 0, v[136:137]
	s_mov_b32 m0, s40
	v_lshl_add_u64 v[228:229], s[24:25], 0, v[132:133]
	global_load_lds_dwordx4 v[202:203], off
	s_mov_b32 m0, s41
	s_nop 0
	global_load_lds_dwordx4 v[228:229], off
	s_waitcnt vmcnt(6)
	s_waitcnt lgkmcnt(0)
	s_barrier
; #define PG8_STAGE(bufoff, gbase, voff) do { _Pragma("unroll") for (int _i = 0; _i < 2; ++_i) \
;         __builtin_amdgcn_global_load_lds((const unsigned*)((const char*)(gbase) + (voff)[_i]), (PG8_LAS unsigned*)(lds + (bufoff) + ldsw + _i * 8192), 16, 0, 0); } while (0)
; #define PG8_LDA(dst, b, h) do { _Pragma("unroll") for (int m = 0; m < 4; ++m) _Pragma("unroll") for (int k = 0; k < 2; ++k) dst[m][k] = *(const PG8_LAS bf16x8*)(lds + PG8_SA(b, h) + aoff + m * 2048 + k * 1024); } while (0)
; #define PG8_LDB(dst, b, h) do { _Pragma("unroll") for (int n = 0; n < 2; ++n) _Pragma("unroll") for (int k = 0; k < 2; ++k) dst[n][k] = *(const PG8_LAS bf16x8*)(lds + PG8_SB(b, h) + boff + n * 2048 + k * 1024); } while (0)
; #define PG8_MMA(ai, bj, At, Bt) do { __builtin_amdgcn_s_setprio(1); _Pragma("unroll") for (int m = 0; m < 4; ++m) _Pragma("unroll") for (int n = 0; n < 2; ++n) _Pragma("unroll") for (int k = 0; k < 2; ++k) \
;         acc[ai][bj][m][n] = __builtin_amdgcn_mfma_f32_16x16x32_bf16(Bt[n][k], At[m][k], acc[ai][bj][m][n], 0, 0, 0); __builtin_amdgcn_s_setprio(0); } while (0)
; #define PG8_WAIT_V(n) asm volatile("s_waitcnt vmcnt(" #n ")" ::: "memory")
; #define PG8_WAIT_L(n) asm volatile("s_waitcnt lgkmcnt(" #n ")" ::: "memory")
; #define PG8_BAR __builtin_amdgcn_s_barrier()
; #define PG8_SCHED __builtin_amdgcn_sched_barrier(0)
; template <class Epi, class Sched, bool ALIGN_EPI = false, bool SP2 = false>
; __device__ __forceinline__ void gemm_phase(PG8_LAS unsigned char* lds, const Gemm g, const Sched& S, const Epi& E, int tid_in) {
;     ...
;             PG8_WAIT_V(8); PG8_WAIT_L(0); PG8_BAR; PG8_MMA(1, 0, At, B0); PG8_MMA(1, 1, At, B1); PG8_BAR; PG8_SCHED;
;             PG8_LDB(B0, 1, 0); PG8_LDB(B1, 1, 1); PG8_SCHED; PG8_LDA(At, 1, 0); PG8_STAGE(PG8_SA(0, 1), a2 + hsA, voffA);
;             PG8_WAIT_V(8); PG8_WAIT_L(0); PG8_BAR; PG8_MMA(0, 0, At, B0); PG8_MMA(0, 1, At, B1); PG8_BAR; PG8_SCHED;
	s_setprio 1
	s_waitcnt lgkmcnt(0)
	v_mfma_f32_16x16x32_bf16 v[64:67], v[148:151], v[180:183], v[64:67]
	v_mfma_f32_16x16x32_bf16 v[56:59], v[156:159], v[180:183], v[56:59]
	v_mfma_f32_16x16x32_bf16 v[48:51], v[148:151], v[188:191], v[48:51]
	v_mfma_f32_16x16x32_bf16 v[40:43], v[156:159], v[188:191], v[40:43]
	v_mfma_f32_16x16x32_bf16 v[32:35], v[148:151], v[208:211], v[32:35]
	v_mfma_f32_16x16x32_bf16 v[24:27], v[156:159], v[208:211], v[24:27]
	v_mfma_f32_16x16x32_bf16 v[16:19], v[148:151], v[216:219], v[16:19]
	v_mfma_f32_16x16x32_bf16 v[8:11], v[156:159], v[216:219], v[8:11]
	v_mfma_f32_16x16x32_bf16 v[64:67], v[152:155], v[184:187], v[64:67]
	v_mfma_f32_16x16x32_bf16 v[56:59], v[160:163], v[184:187], v[56:59]
	v_mfma_f32_16x16x32_bf16 v[48:51], v[152:155], v[204:207], v[48:51]
	v_mfma_f32_16x16x32_bf16 v[40:43], v[160:163], v[204:207], v[40:43]
	v_mfma_f32_16x16x32_bf16 v[32:35], v[152:155], v[212:215], v[32:35]
	v_mfma_f32_16x16x32_bf16 v[24:27], v[160:163], v[212:215], v[24:27]
	v_mfma_f32_16x16x32_bf16 v[16:19], v[152:155], v[220:223], v[16:19]
	v_mfma_f32_16x16x32_bf16 v[8:11], v[160:163], v[220:223], v[8:11]
	s_setprio 0
	s_setprio 1
	v_mfma_f32_16x16x32_bf16 v[60:63], v[164:167], v[180:183], v[60:63]
	v_mfma_f32_16x16x32_bf16 v[52:55], v[172:175], v[180:183], v[52:55]
	v_mfma_f32_16x16x32_bf16 v[44:47], v[164:167], v[188:191], v[44:47]
	v_mfma_f32_16x16x32_bf16 v[36:39], v[172:175], v[188:191], v[36:39]
	v_mfma_f32_16x16x32_bf16 v[28:31], v[164:167], v[208:211], v[28:31]
	v_mfma_f32_16x16x32_bf16 v[20:23], v[172:175], v[208:211], v[20:23]
	v_mfma_f32_16x16x32_bf16 v[12:15], v[164:167], v[216:219], v[12:15]
	v_mfma_f32_16x16x32_bf16 v[4:7], v[172:175], v[216:219], v[4:7]
	v_mfma_f32_16x16x32_bf16 v[60:63], v[168:171], v[184:187], v[60:63]
	v_mfma_f32_16x16x32_bf16 v[52:55], v[176:179], v[184:187], v[52:55]
	v_mfma_f32_16x16x32_bf16 v[44:47], v[168:171], v[204:207], v[44:47]
	v_mfma_f32_16x16x32_bf16 v[36:39], v[176:179], v[204:207], v[36:39]
	v_mfma_f32_16x16x32_bf16 v[28:31], v[168:171], v[212:215], v[28:31]
	v_mfma_f32_16x16x32_bf16 v[20:23], v[176:179], v[212:215], v[20:23]
	v_mfma_f32_16x16x32_bf16 v[12:15], v[168:171], v[220:223], v[12:15]
	v_mfma_f32_16x16x32_bf16 v[4:7], v[176:179], v[220:223], v[4:7]
	s_setprio 0
	s_barrier
	s_add_i32 s59, 0, 0x18000
	s_add_i32 s60, 0, 0x1c000
	v_add_u32_e32 v160, s59, v142
	v_add_u32_e32 v176, s60, v142
	ds_read_b128 v[148:151], v160
	ds_read_b128 v[152:155], v160 offset:1024
	ds_read_b128 v[156:159], v160 offset:2048
	ds_read_b128 v[160:163], v160 offset:3072
	ds_read_b128 v[164:167], v176
	ds_read_b128 v[168:171], v176 offset:1024
	ds_read_b128 v[172:175], v176 offset:2048
	ds_read_b128 v[176:179], v176 offset:3072
	s_add_u32 s24, s24, s0
	s_addc_u32 s25, s25, s1
	s_mov_b32 m0, s42
	v_lshl_add_u64 v[230:231], s[24:25], 0, v[136:137]
	ds_read_b128 v[180:183], v147 offset:32768
	ds_read_b128 v[184:187], v147 offset:33792
	ds_read_b128 v[188:191], v147 offset:34816
	ds_read_b128 v[204:207], v147 offset:35840
	ds_read_b128 v[208:211], v147 offset:36864
	ds_read_b128 v[212:215], v147 offset:37888
	ds_read_b128 v[216:219], v147 offset:38912
	ds_read_b128 v[220:223], v147 offset:39936
	global_load_lds_dwordx4 v[230:231], off
	v_lshl_add_u64 v[230:231], s[24:25], 0, v[132:133]
	s_mov_b32 m0, s43
	s_nop 0
	global_load_lds_dwordx4 v[230:231], off
	s_add_i32 m0, s36, 0x14000
	s_nop 0
	global_load_lds_dwordx4 v[198:199], off
	s_add_i32 m0, s36, 0x16000
	s_nop 0
	global_load_lds_dwordx4 v[200:201], off
	s_waitcnt vmcnt(8)
	s_waitcnt lgkmcnt(0)
	s_barrier
	s_setprio 1
	s_waitcnt lgkmcnt(0)
	v_mfma_f32_16x16x32_bf16 v[124:127], v[148:151], v[180:183], v[124:127]
	v_mfma_f32_16x16x32_bf16 v[120:123], v[156:159], v[180:183], v[120:123]
	v_mfma_f32_16x16x32_bf16 v[112:115], v[148:151], v[188:191], v[112:115]
	v_mfma_f32_16x16x32_bf16 v[104:107], v[156:159], v[188:191], v[104:107]
	v_mfma_f32_16x16x32_bf16 v[96:99], v[148:151], v[208:211], v[96:99]
	v_mfma_f32_16x16x32_bf16 v[88:91], v[156:159], v[208:211], v[88:91]
	v_mfma_f32_16x16x32_bf16 v[80:83], v[148:151], v[216:219], v[80:83]
	v_mfma_f32_16x16x32_bf16 v[72:75], v[156:159], v[216:219], v[72:75]
	v_mfma_f32_16x16x32_bf16 v[124:127], v[152:155], v[184:187], v[124:127]
	v_mfma_f32_16x16x32_bf16 v[120:123], v[160:163], v[184:187], v[120:123]
	v_mfma_f32_16x16x32_bf16 v[112:115], v[152:155], v[204:207], v[112:115]
	v_mfma_f32_16x16x32_bf16 v[104:107], v[160:163], v[204:207], v[104:107]
	v_mfma_f32_16x16x32_bf16 v[96:99], v[152:155], v[212:215], v[96:99]
	v_mfma_f32_16x16x32_bf16 v[88:91], v[160:163], v[212:215], v[88:91]
	v_mfma_f32_16x16x32_bf16 v[80:83], v[152:155], v[220:223], v[80:83]
	v_mfma_f32_16x16x32_bf16 v[72:75], v[160:163], v[220:223], v[72:75]
	s_setprio 0
	s_setprio 1
	v_mfma_f32_16x16x32_bf16 v[128:131], v[164:167], v[180:183], v[128:131]
	v_mfma_f32_16x16x32_bf16 v[116:119], v[172:175], v[180:183], v[116:119]
	v_mfma_f32_16x16x32_bf16 v[108:111], v[164:167], v[188:191], v[108:111]
	v_mfma_f32_16x16x32_bf16 v[100:103], v[172:175], v[188:191], v[100:103]
	v_mfma_f32_16x16x32_bf16 v[92:95], v[164:167], v[208:211], v[92:95]
	v_mfma_f32_16x16x32_bf16 v[84:87], v[172:175], v[208:211], v[84:87]
	v_mfma_f32_16x16x32_bf16 v[76:79], v[164:167], v[216:219], v[76:79]
	v_mfma_f32_16x16x32_bf16 v[68:71], v[172:175], v[216:219], v[68:71]
	v_mfma_f32_16x16x32_bf16 v[128:131], v[168:171], v[184:187], v[128:131]
	v_mfma_f32_16x16x32_bf16 v[116:119], v[176:179], v[184:187], v[116:119]
	v_mfma_f32_16x16x32_bf16 v[108:111], v[168:171], v[204:207], v[108:111]
	v_mfma_f32_16x16x32_bf16 v[100:103], v[176:179], v[204:207], v[100:103]
	v_mfma_f32_16x16x32_bf16 v[92:95], v[168:171], v[212:215], v[92:95]
	v_mfma_f32_16x16x32_bf16 v[84:87], v[176:179], v[212:215], v[84:87]
	v_mfma_f32_16x16x32_bf16 v[76:79], v[168:171], v[220:223], v[76:79]
	v_mfma_f32_16x16x32_bf16 v[68:71], v[176:179], v[220:223], v[68:71]
	s_setprio 0
	s_barrier
; #define PG8_STAGE(bufoff, gbase, voff) do { _Pragma("unroll") for (int _i = 0; _i < 2; ++_i) \
;         __builtin_amdgcn_global_load_lds((const unsigned*)((const char*)(gbase) + (voff)[_i]), (PG8_LAS unsigned*)(lds + (bufoff) + ldsw + _i * 8192), 16, 0, 0); } while (0)
; #define PG8_LDA(dst, b, h) do { _Pragma("unroll") for (int m = 0; m < 4; ++m) _Pragma("unroll") for (int k = 0; k < 2; ++k) dst[m][k] = *(const PG8_LAS bf16x8*)(lds + PG8_SA(b, h) + aoff + m * 2048 + k * 1024); } while (0)
; #define PG8_MMA(ai, bj, At, Bt) do { __builtin_amdgcn_s_setprio(1); _Pragma("unroll") for (int m = 0; m < 4; ++m) _Pragma("unroll") for (int n = 0; n < 2; ++n) _Pragma("unroll") for (int k = 0; k < 2; ++k) \
;         acc[ai][bj][m][n] = __builtin_amdgcn_mfma_f32_16x16x32_bf16(Bt[n][k], At[m][k], acc[ai][bj][m][n], 0, 0, 0); __builtin_amdgcn_s_setprio(0); } while (0)
; #define PG8_WAIT_V(n) asm volatile("s_waitcnt vmcnt(" #n ")" ::: "memory")
; #define PG8_WAIT_L(n) asm volatile("s_waitcnt lgkmcnt(" #n ")" ::: "memory")
; #define PG8_BAR __builtin_amdgcn_s_barrier()
; #define PG8_SCHED __builtin_amdgcn_sched_barrier(0)
; template <class Epi, class Sched, bool ALIGN_EPI = false, bool SP2 = false>
; __device__ __forceinline__ void gemm_phase(PG8_LAS unsigned char* lds, const Gemm g, const Sched& S, const Epi& E, int tid_in) {
;     ...
;         for (int t = 0; t < nt; t += 2) {
;     ...
;             PG8_LDA(At, 1, 1); PG8_STAGE(PG8_SB(1, 0), b3, voffB); PG8_STAGE(PG8_SB(1, 1), b3 + hsB, voffB); PG8_STAGE(PG8_SA(1, 0), a3, voffA);
;             PG8_WAIT_V(8); PG8_WAIT_L(0); PG8_BAR; PG8_MMA(1, 0, At, B0); PG8_MMA(1, 1, At, B1); PG8_BAR; PG8_SCHED;
	s_add_i32 s24, s59, s36
	v_lshl_add_u64 v[192:193], v[192:193], 0, s[80:81]
	s_mov_b32 m0, s24
	ds_read_b128 v[180:183], v147 offset:49152
	ds_read_b128 v[184:187], v147 offset:50176
	ds_read_b128 v[188:191], v147 offset:51200
	ds_read_b128 v[204:207], v147 offset:52224
	ds_read_b128 v[208:211], v147 offset:53248
	ds_read_b128 v[212:215], v147 offset:54272
	ds_read_b128 v[216:219], v147 offset:55296
	ds_read_b128 v[220:223], v147 offset:56320
	global_load_lds_dwordx4 v[192:193], off
	v_lshl_add_u64 v[192:193], v[196:197], 0, s[80:81]
	s_add_i32 m0, s24, 0x2000
	s_add_i32 s24, s60, s36
	global_load_lds_dwordx4 v[192:193], off
	v_lshl_add_u64 v[192:193], v[198:199], 0, s[80:81]
	s_mov_b32 m0, s24
	s_nop 0
	global_load_lds_dwordx4 v[192:193], off
	v_lshl_add_u64 v[192:193], v[200:201], 0, s[80:81]
	s_add_i32 m0, s24, 0x2000
	s_nop 0
	global_load_lds_dwordx4 v[192:193], off
	v_lshl_add_u64 v[192:193], v[202:203], 0, s[80:81]
	s_mov_b32 m0, s44
	s_nop 0
	global_load_lds_dwordx4 v[192:193], off
	v_lshl_add_u64 v[192:193], v[228:229], 0, s[80:81]
	s_mov_b32 m0, s45
	s_nop 0
	global_load_lds_dwordx4 v[192:193], off
	s_waitcnt vmcnt(6)
	s_waitcnt lgkmcnt(0)
	s_barrier
	s_setprio 1
	s_waitcnt lgkmcnt(0)
	v_mfma_f32_16x16x32_bf16 v[64:67], v[148:151], v[180:183], v[64:67]
	v_mfma_f32_16x16x32_bf16 v[56:59], v[156:159], v[180:183], v[56:59]
	v_mfma_f32_16x16x32_bf16 v[48:51], v[148:151], v[188:191], v[48:51]
	v_mfma_f32_16x16x32_bf16 v[40:43], v[156:159], v[188:191], v[40:43]
	v_mfma_f32_16x16x32_bf16 v[32:35], v[148:151], v[208:211], v[32:35]
	v_mfma_f32_16x16x32_bf16 v[24:27], v[156:159], v[208:211], v[24:27]
	v_mfma_f32_16x16x32_bf16 v[16:19], v[148:151], v[216:219], v[16:19]
	v_mfma_f32_16x16x32_bf16 v[8:11], v[156:159], v[216:219], v[8:11]
	v_mfma_f32_16x16x32_bf16 v[64:67], v[152:155], v[184:187], v[64:67]
	v_mfma_f32_16x16x32_bf16 v[56:59], v[160:163], v[184:187], v[56:59]
	v_mfma_f32_16x16x32_bf16 v[48:51], v[152:155], v[204:207], v[48:51]
	v_mfma_f32_16x16x32_bf16 v[40:43], v[160:163], v[204:207], v[40:43]
	v_mfma_f32_16x16x32_bf16 v[32:35], v[152:155], v[212:215], v[32:35]
	v_mfma_f32_16x16x32_bf16 v[24:27], v[160:163], v[212:215], v[24:27]
	v_mfma_f32_16x16x32_bf16 v[16:19], v[152:155], v[220:223], v[16:19]
	v_mfma_f32_16x16x32_bf16 v[8:11], v[160:163], v[220:223], v[8:11]
	s_setprio 0
	s_setprio 1
	v_mfma_f32_16x16x32_bf16 v[60:63], v[164:167], v[180:183], v[60:63]
	v_mfma_f32_16x16x32_bf16 v[52:55], v[172:175], v[180:183], v[52:55]
	v_mfma_f32_16x16x32_bf16 v[44:47], v[164:167], v[188:191], v[44:47]
	v_mfma_f32_16x16x32_bf16 v[36:39], v[172:175], v[188:191], v[36:39]
	v_mfma_f32_16x16x32_bf16 v[28:31], v[164:167], v[208:211], v[28:31]
	v_mfma_f32_16x16x32_bf16 v[20:23], v[172:175], v[208:211], v[20:23]
	v_mfma_f32_16x16x32_bf16 v[12:15], v[164:167], v[216:219], v[12:15]
	v_mfma_f32_16x16x32_bf16 v[4:7], v[172:175], v[216:219], v[4:7]
	v_mfma_f32_16x16x32_bf16 v[60:63], v[168:171], v[184:187], v[60:63]
	v_mfma_f32_16x16x32_bf16 v[52:55], v[176:179], v[184:187], v[52:55]
	v_mfma_f32_16x16x32_bf16 v[44:47], v[168:171], v[204:207], v[44:47]
	v_mfma_f32_16x16x32_bf16 v[36:39], v[176:179], v[204:207], v[36:39]
	v_mfma_f32_16x16x32_bf16 v[28:31], v[168:171], v[212:215], v[28:31]
	v_mfma_f32_16x16x32_bf16 v[20:23], v[176:179], v[212:215], v[20:23]
	v_mfma_f32_16x16x32_bf16 v[12:15], v[168:171], v[220:223], v[12:15]
	v_mfma_f32_16x16x32_bf16 v[4:7], v[176:179], v[220:223], v[4:7]
	s_setprio 0
	s_barrier
	s_add_i32 s24, s58, 2
	s_add_u32 s54, s54, 0x100
	s_addc_u32 s55, s55, 0
	s_add_u32 s22, s22, 0x100
	s_addc_u32 s23, s23, 0
	s_cmp_ge_i32 s58, s46
	s_mov_b32 s58, s24
	s_cbranch_scc0 .LBB0_1255

; #define PG8_STAGE(bufoff, gbase, voff) do { _Pragma("unroll") for (int _i = 0; _i < 2; ++_i) \
;         __builtin_amdgcn_global_load_lds((const unsigned*)((const char*)(gbase) + (voff)[_i]), (PG8_LAS unsigned*)(lds + (bufoff) + ldsw + _i * 8192), 16, 0, 0); } while (0)
; #define PG8_LDA(dst, b, h) do { _Pragma("unroll") for (int m = 0; m < 4; ++m) _Pragma("unroll") for (int k = 0; k < 2; ++k) dst[m][k] = *(const PG8_LAS bf16x8*)(lds + PG8_SA(b, h) + aoff + m * 2048 + k * 1024); } while (0)
; #define PG8_LDB(dst, b, h) do { _Pragma("unroll") for (int n = 0; n < 2; ++n) _Pragma("unroll") for (int k = 0; k < 2; ++k) dst[n][k] = *(const PG8_LAS bf16x8*)(lds + PG8_SB(b, h) + boff + n * 2048 + k * 1024); } while (0)
; #define PG8_MMA(ai, bj, At, Bt) do { __builtin_amdgcn_s_setprio(1); _Pragma("unroll") for (int m = 0; m < 4; ++m) _Pragma("unroll") for (int n = 0; n < 2; ++n) _Pragma("unroll") for (int k = 0; k < 2; ++k) \
;         acc[ai][bj][m][n] = __builtin_amdgcn_mfma_f32_16x16x32_bf16(Bt[n][k], At[m][k], acc[ai][bj][m][n], 0, 0, 0); __builtin_amdgcn_s_setprio(0); } while (0)
; template <class Epi, class Sched, bool ALIGN_EPI = false, bool SP2 = false>
; __device__ __forceinline__ void gemm_phase(PG8_LAS unsigned char* lds, const Gemm g, const Sched& S, const Epi& E, int tid_in) {
;     ...
;             const bool last = (t == nt - 2);
;             if constexpr (mid_hook<Epi>::value) { if (t == Epi::H1 || t == Epi::H2) E.mid(acc, cur, wr, wc, fr, fq, t == Epi::H2); }
;             const char* a1 = cA + (size_t)(t + 1) * kstep + (t >= jt ? jb : 0);
;             const char* a2 = last ? nA : cA + (size_t)(t + 2) * kstep + (t + 2 >= jt ? jb : 0); const char* b2 = last ? nB : cB + (size_t)(t + 2) * kstep;
;             const char* a3 = a2 + kstep; const char* b3 = b2 + kstep;
;             if (last && has_next) S.a_ready(nxt);
;             if constexpr (SP2) {
;             PG8_LDB(B0, 0, 0); PG8_LDB(B1, 0, 1); PG8_SCHED; PG8_LDA(At, 0, 0); PG8_STAGE(PG8_SA(1, 1), a1 + hsA, voffA);
;             PG8_WAIT_V(8); PG8_WAIT_L(0); PG8_BAR; PG8_MMA(0, 0, At, B0); PG8_MMA(0, 1, At, B1); PG8_BAR; PG8_SCHED;
;             PG8_LDA(At, 0, 1); PG8_STAGE(PG8_SB(0, 0), b2, voffB); PG8_STAGE(PG8_SB(0, 1), b2 + hsB, voffB); PG8_STAGE(PG8_SA(0, 0), a2, voffA);
;             PG8_WAIT_V(8); PG8_WAIT_L(0); PG8_BAR; PG8_MMA(1, 0, At, B0); PG8_MMA(1, 1, At, B1); PG8_BAR; PG8_SCHED;
.LBB0_1331:
	s_add_i32 s38, s40, -2
	s_cmp_ge_i32 s38, s33
	s_cselect_b32 s76, s46, 0
	s_cselect_b32 s77, s61, 0
	s_cmp_ge_i32 s40, s33
	s_cselect_b32 s39, s46, 0
	s_cselect_b32 s38, s61, 0
	s_add_u32 s39, s4, s39
	s_addc_u32 s38, s5, s38
	s_add_u32 s41, s39, 0x80
	s_addc_u32 s38, s38, 0
	s_add_i32 s82, 0, 0x10000
	s_cmp_eq_u32 s60, s40
	s_cselect_b32 s39, s35, s38
	s_cselect_b32 s38, s34, s41
	s_cselect_b32 s79, s37, s75
	s_cselect_b32 s78, s36, s74
	s_add_i32 s41, 0, 0x14000
	v_add_u32_e32 v144, s82, v217
	v_add_u32_e32 v170, s41, v217
	ds_read_b128 v[132:135], v144
	ds_read_b128 v[136:139], v144 offset:1024
	ds_read_b128 v[140:143], v144 offset:2048
	ds_read_b128 v[144:147], v144 offset:3072
	ds_read_b128 v[148:151], v170
	ds_read_b128 v[162:165], v170 offset:1024
	ds_read_b128 v[166:169], v170 offset:2048
	ds_read_b128 v[170:173], v170 offset:3072
	v_lshl_add_u64 v[190:191], s[4:5], 0, v[160:161]
	v_lshl_add_u64 v[190:191], v[190:191], 0, s[76:77]
	s_add_i32 m0, s50, 0xc000
	ds_read_b128 v[174:177], v219
	ds_read_b128 v[178:181], v219 offset:1024
	ds_read_b128 v[182:185], v219 offset:2048
	ds_read_b128 v[186:189], v219 offset:3072
	ds_read_b128 v[204:207], v219 offset:4096
	ds_read_b128 v[208:211], v219 offset:5120
	ds_read_b128 v[212:215], v219 offset:6144
	ds_read_b128 v[220:223], v219 offset:7168
	global_load_lds_dwordx4 v[190:191], off
	v_lshl_add_u64 v[190:191], s[4:5], 0, v[158:159]
	v_lshl_add_u64 v[190:191], v[190:191], 0, s[76:77]
	s_add_i32 m0, s50, 0xe000
	s_nop 0
	global_load_lds_dwordx4 v[190:191], off
	s_waitcnt vmcnt(8)
	s_waitcnt lgkmcnt(0)
	s_barrier
	s_setprio 1
	s_waitcnt lgkmcnt(0)
	v_mfma_f32_16x16x32_bf16 v[128:131], v[132:135], v[174:177], v[128:131]
	v_mfma_f32_16x16x32_bf16 v[124:127], v[140:143], v[174:177], v[124:127]
	v_mfma_f32_16x16x32_bf16 v[120:123], v[132:135], v[182:185], v[120:123]
	v_mfma_f32_16x16x32_bf16 v[116:119], v[140:143], v[182:185], v[116:119]
	v_mfma_f32_16x16x32_bf16 v[112:115], v[132:135], v[204:207], v[112:115]
	v_mfma_f32_16x16x32_bf16 v[108:111], v[140:143], v[204:207], v[108:111]
	v_mfma_f32_16x16x32_bf16 v[104:107], v[132:135], v[212:215], v[104:107]
	v_mfma_f32_16x16x32_bf16 v[100:103], v[140:143], v[212:215], v[100:103]
	v_mfma_f32_16x16x32_bf16 v[128:131], v[136:139], v[178:181], v[128:131]
	v_mfma_f32_16x16x32_bf16 v[124:127], v[144:147], v[178:181], v[124:127]
	v_mfma_f32_16x16x32_bf16 v[120:123], v[136:139], v[186:189], v[120:123]
	v_mfma_f32_16x16x32_bf16 v[116:119], v[144:147], v[186:189], v[116:119]
	v_mfma_f32_16x16x32_bf16 v[112:115], v[136:139], v[208:211], v[112:115]
	v_mfma_f32_16x16x32_bf16 v[108:111], v[144:147], v[208:211], v[108:111]
	v_mfma_f32_16x16x32_bf16 v[104:107], v[136:139], v[220:223], v[104:107]
	v_mfma_f32_16x16x32_bf16 v[100:103], v[144:147], v[220:223], v[100:103]
	s_setprio 0
	s_setprio 1
	v_mfma_f32_16x16x32_bf16 v[64:67], v[148:151], v[174:177], v[64:67]
	v_mfma_f32_16x16x32_bf16 v[56:59], v[166:169], v[174:177], v[56:59]
	v_mfma_f32_16x16x32_bf16 v[60:63], v[148:151], v[182:185], v[60:63]
	v_mfma_f32_16x16x32_bf16 v[52:55], v[166:169], v[182:185], v[52:55]
	v_mfma_f32_16x16x32_bf16 v[48:51], v[148:151], v[204:207], v[48:51]
	v_mfma_f32_16x16x32_bf16 v[40:43], v[166:169], v[204:207], v[40:43]
	v_mfma_f32_16x16x32_bf16 v[44:47], v[148:151], v[212:215], v[44:47]
	v_mfma_f32_16x16x32_bf16 v[36:39], v[166:169], v[212:215], v[36:39]
	v_mfma_f32_16x16x32_bf16 v[64:67], v[162:165], v[178:181], v[64:67]
	v_mfma_f32_16x16x32_bf16 v[56:59], v[170:173], v[178:181], v[56:59]
	v_mfma_f32_16x16x32_bf16 v[60:63], v[162:165], v[186:189], v[60:63]
	v_mfma_f32_16x16x32_bf16 v[52:55], v[170:173], v[186:189], v[52:55]
	v_mfma_f32_16x16x32_bf16 v[48:51], v[162:165], v[208:211], v[48:51]
	v_mfma_f32_16x16x32_bf16 v[40:43], v[170:173], v[208:211], v[40:43]
	v_mfma_f32_16x16x32_bf16 v[44:47], v[162:165], v[220:223], v[44:47]
	v_mfma_f32_16x16x32_bf16 v[36:39], v[170:173], v[220:223], v[36:39]
	s_setprio 0
	s_barrier
	s_add_i32 s76, s82, s49
	v_lshl_add_u64 v[190:191], s[78:79], 0, v[152:153]
	s_mov_b32 m0, s76
	ds_read_b128 v[174:177], v219 offset:16384
	ds_read_b128 v[178:181], v219 offset:17408
	ds_read_b128 v[182:185], v219 offset:18432
	ds_read_b128 v[186:189], v219 offset:19456
	ds_read_b128 v[204:207], v219 offset:20480
	ds_read_b128 v[208:211], v219 offset:21504
	ds_read_b128 v[212:215], v219 offset:22528
	ds_read_b128 v[220:223], v219 offset:23552
	global_load_lds_dwordx4 v[190:191], off
	s_add_i32 m0, s76, 0x2000
	s_add_u32 s76, s78, s12
	v_lshl_add_u64 v[192:193], s[78:79], 0, v[156:157]
	s_addc_u32 s77, s79, s13
	s_add_i32 s41, s41, s49
	global_load_lds_dwordx4 v[192:193], off
	v_lshl_add_u64 v[196:197], s[76:77], 0, v[152:153]
	v_lshl_add_u64 v[198:199], s[76:77], 0, v[156:157]
	v_lshl_add_u64 v[200:201], s[38:39], 0, v[0:1]
	s_mov_b32 m0, s50
	v_lshl_add_u64 v[202:203], s[38:39], 0, v[154:155]
	global_load_lds_dwordx4 v[200:201], off
	s_mov_b32 m0, s51
	s_nop 0
	global_load_lds_dwordx4 v[202:203], off
	s_waitcnt vmcnt(6)
	s_waitcnt lgkmcnt(0)
	s_barrier
; #define PG8_STAGE(bufoff, gbase, voff) do { _Pragma("unroll") for (int _i = 0; _i < 2; ++_i) \
;         __builtin_amdgcn_global_load_lds((const unsigned*)((const char*)(gbase) + (voff)[_i]), (PG8_LAS unsigned*)(lds + (bufoff) + ldsw + _i * 8192), 16, 0, 0); } while (0)
; #define PG8_LDA(dst, b, h) do { _Pragma("unroll") for (int m = 0; m < 4; ++m) _Pragma("unroll") for (int k = 0; k < 2; ++k) dst[m][k] = *(const PG8_LAS bf16x8*)(lds + PG8_SA(b, h) + aoff + m * 2048 + k * 1024); } while (0)
; #define PG8_LDB(dst, b, h) do { _Pragma("unroll") for (int n = 0; n < 2; ++n) _Pragma("unroll") for (int k = 0; k < 2; ++k) dst[n][k] = *(const PG8_LAS bf16x8*)(lds + PG8_SB(b, h) + boff + n * 2048 + k * 1024); } while (0)
; #define PG8_MMA(ai, bj, At, Bt) do { __builtin_amdgcn_s_setprio(1); _Pragma("unroll") for (int m = 0; m < 4; ++m) _Pragma("unroll") for (int n = 0; n < 2; ++n) _Pragma("unroll") for (int k = 0; k < 2; ++k) \
;         acc[ai][bj][m][n] = __builtin_amdgcn_mfma_f32_16x16x32_bf16(Bt[n][k], At[m][k], acc[ai][bj][m][n], 0, 0, 0); __builtin_amdgcn_s_setprio(0); } while (0)
; #define PG8_WAIT_V(n) asm volatile("s_waitcnt vmcnt(" #n ")" ::: "memory")
; #define PG8_WAIT_L(n) asm volatile("s_waitcnt lgkmcnt(" #n ")" ::: "memory")
; #define PG8_BAR __builtin_amdgcn_s_barrier()
; #define PG8_SCHED __builtin_amdgcn_sched_barrier(0)
; template <class Epi, class Sched, bool ALIGN_EPI = false, bool SP2 = false>
; __device__ __forceinline__ void gemm_phase(PG8_LAS unsigned char* lds, const Gemm g, const Sched& S, const Epi& E, int tid_in) {
;     ...
;             PG8_WAIT_V(8); PG8_WAIT_L(0); PG8_BAR; PG8_MMA(1, 0, At, B0); PG8_MMA(1, 1, At, B1); PG8_BAR; PG8_SCHED;
;             PG8_LDB(B0, 1, 0); PG8_LDB(B1, 1, 1); PG8_SCHED; PG8_LDA(At, 1, 0); PG8_STAGE(PG8_SA(0, 1), a2 + hsA, voffA);
;             PG8_WAIT_V(8); PG8_WAIT_L(0); PG8_BAR; PG8_MMA(0, 0, At, B0); PG8_MMA(0, 1, At, B1); PG8_BAR; PG8_SCHED;
	s_setprio 1
	s_waitcnt lgkmcnt(0)
	v_mfma_f32_16x16x32_bf16 v[96:99], v[132:135], v[174:177], v[96:99]
	v_mfma_f32_16x16x32_bf16 v[92:95], v[140:143], v[174:177], v[92:95]
	v_mfma_f32_16x16x32_bf16 v[88:91], v[132:135], v[182:185], v[88:91]
	v_mfma_f32_16x16x32_bf16 v[84:87], v[140:143], v[182:185], v[84:87]
	v_mfma_f32_16x16x32_bf16 v[80:83], v[132:135], v[204:207], v[80:83]
	v_mfma_f32_16x16x32_bf16 v[76:79], v[140:143], v[204:207], v[76:79]
	v_mfma_f32_16x16x32_bf16 v[72:75], v[132:135], v[212:215], v[72:75]
	v_mfma_f32_16x16x32_bf16 v[68:71], v[140:143], v[212:215], v[68:71]
	v_mfma_f32_16x16x32_bf16 v[96:99], v[136:139], v[178:181], v[96:99]
	v_mfma_f32_16x16x32_bf16 v[92:95], v[144:147], v[178:181], v[92:95]
	v_mfma_f32_16x16x32_bf16 v[88:91], v[136:139], v[186:189], v[88:91]
	v_mfma_f32_16x16x32_bf16 v[84:87], v[144:147], v[186:189], v[84:87]
	v_mfma_f32_16x16x32_bf16 v[80:83], v[136:139], v[208:211], v[80:83]
	v_mfma_f32_16x16x32_bf16 v[76:79], v[144:147], v[208:211], v[76:79]
	v_mfma_f32_16x16x32_bf16 v[72:75], v[136:139], v[220:223], v[72:75]
	v_mfma_f32_16x16x32_bf16 v[68:71], v[144:147], v[220:223], v[68:71]
	s_setprio 0
	s_setprio 1
	v_mfma_f32_16x16x32_bf16 v[32:35], v[148:151], v[174:177], v[32:35]
	v_mfma_f32_16x16x32_bf16 v[28:31], v[166:169], v[174:177], v[28:31]
	v_mfma_f32_16x16x32_bf16 v[24:27], v[148:151], v[182:185], v[24:27]
	v_mfma_f32_16x16x32_bf16 v[12:15], v[166:169], v[182:185], v[12:15]
	v_mfma_f32_16x16x32_bf16 v[20:23], v[148:151], v[204:207], v[20:23]
	v_mfma_f32_16x16x32_bf16 v[8:11], v[166:169], v[204:207], v[8:11]
	v_mfma_f32_16x16x32_bf16 v[16:19], v[148:151], v[212:215], v[16:19]
	v_mfma_f32_16x16x32_bf16 v[4:7], v[166:169], v[212:215], v[4:7]
	v_mfma_f32_16x16x32_bf16 v[32:35], v[162:165], v[178:181], v[32:35]
	v_mfma_f32_16x16x32_bf16 v[28:31], v[170:173], v[178:181], v[28:31]
	v_mfma_f32_16x16x32_bf16 v[24:27], v[162:165], v[186:189], v[24:27]
	v_mfma_f32_16x16x32_bf16 v[12:15], v[170:173], v[186:189], v[12:15]
	v_mfma_f32_16x16x32_bf16 v[20:23], v[162:165], v[208:211], v[20:23]
	v_mfma_f32_16x16x32_bf16 v[8:11], v[170:173], v[208:211], v[8:11]
	v_mfma_f32_16x16x32_bf16 v[16:19], v[162:165], v[220:223], v[16:19]
	v_mfma_f32_16x16x32_bf16 v[4:7], v[170:173], v[220:223], v[4:7]
	s_setprio 0
	s_barrier
	s_add_i32 s41, 0, 0x18000
	s_add_i32 s76, 0, 0x1c000
	v_add_u32_e32 v144, s41, v217
	v_add_u32_e32 v170, s76, v217
	ds_read_b128 v[132:135], v144
	ds_read_b128 v[136:139], v144 offset:1024
	ds_read_b128 v[140:143], v144 offset:2048
	ds_read_b128 v[144:147], v144 offset:3072
	ds_read_b128 v[148:151], v170
	ds_read_b128 v[162:165], v170 offset:1024
	ds_read_b128 v[166:169], v170 offset:2048
	ds_read_b128 v[170:173], v170 offset:3072
	s_add_u32 s38, s38, s10
	s_addc_u32 s39, s39, s11
	s_mov_b32 m0, s52
	v_lshl_add_u64 v[228:229], s[38:39], 0, v[0:1]
	ds_read_b128 v[174:177], v219 offset:32768
	ds_read_b128 v[178:181], v219 offset:33792
	ds_read_b128 v[182:185], v219 offset:34816
	ds_read_b128 v[186:189], v219 offset:35840
	ds_read_b128 v[204:207], v219 offset:36864
	ds_read_b128 v[208:211], v219 offset:37888
	ds_read_b128 v[212:215], v219 offset:38912
	ds_read_b128 v[220:223], v219 offset:39936
	global_load_lds_dwordx4 v[228:229], off
	v_lshl_add_u64 v[228:229], s[38:39], 0, v[154:155]
	s_mov_b32 m0, s53
	s_nop 0
	global_load_lds_dwordx4 v[228:229], off
	s_add_i32 m0, s49, 0x14000
	s_nop 0
	global_load_lds_dwordx4 v[196:197], off
	s_add_i32 m0, s49, 0x16000
	s_nop 0
	global_load_lds_dwordx4 v[198:199], off
	s_waitcnt vmcnt(8)
	s_waitcnt lgkmcnt(0)
	s_barrier
	s_setprio 1
	s_waitcnt lgkmcnt(0)
	v_mfma_f32_16x16x32_bf16 v[128:131], v[132:135], v[174:177], v[128:131]
	v_mfma_f32_16x16x32_bf16 v[124:127], v[140:143], v[174:177], v[124:127]
	v_mfma_f32_16x16x32_bf16 v[120:123], v[132:135], v[182:185], v[120:123]
	v_mfma_f32_16x16x32_bf16 v[116:119], v[140:143], v[182:185], v[116:119]
	v_mfma_f32_16x16x32_bf16 v[112:115], v[132:135], v[204:207], v[112:115]
	v_mfma_f32_16x16x32_bf16 v[108:111], v[140:143], v[204:207], v[108:111]
	v_mfma_f32_16x16x32_bf16 v[104:107], v[132:135], v[212:215], v[104:107]
	v_mfma_f32_16x16x32_bf16 v[100:103], v[140:143], v[212:215], v[100:103]
	v_mfma_f32_16x16x32_bf16 v[128:131], v[136:139], v[178:181], v[128:131]
	v_mfma_f32_16x16x32_bf16 v[124:127], v[144:147], v[178:181], v[124:127]
	v_mfma_f32_16x16x32_bf16 v[120:123], v[136:139], v[186:189], v[120:123]
	v_mfma_f32_16x16x32_bf16 v[116:119], v[144:147], v[186:189], v[116:119]
	v_mfma_f32_16x16x32_bf16 v[112:115], v[136:139], v[208:211], v[112:115]
	v_mfma_f32_16x16x32_bf16 v[108:111], v[144:147], v[208:211], v[108:111]
	v_mfma_f32_16x16x32_bf16 v[104:107], v[136:139], v[220:223], v[104:107]
	v_mfma_f32_16x16x32_bf16 v[100:103], v[144:147], v[220:223], v[100:103]
	s_setprio 0
	s_setprio 1
	v_mfma_f32_16x16x32_bf16 v[64:67], v[148:151], v[174:177], v[64:67]
	v_mfma_f32_16x16x32_bf16 v[56:59], v[166:169], v[174:177], v[56:59]
	v_mfma_f32_16x16x32_bf16 v[60:63], v[148:151], v[182:185], v[60:63]
	v_mfma_f32_16x16x32_bf16 v[52:55], v[166:169], v[182:185], v[52:55]
	v_mfma_f32_16x16x32_bf16 v[48:51], v[148:151], v[204:207], v[48:51]
	v_mfma_f32_16x16x32_bf16 v[40:43], v[166:169], v[204:207], v[40:43]
	v_mfma_f32_16x16x32_bf16 v[44:47], v[148:151], v[212:215], v[44:47]
	v_mfma_f32_16x16x32_bf16 v[36:39], v[166:169], v[212:215], v[36:39]
	v_mfma_f32_16x16x32_bf16 v[64:67], v[162:165], v[178:181], v[64:67]
	v_mfma_f32_16x16x32_bf16 v[56:59], v[170:173], v[178:181], v[56:59]
	v_mfma_f32_16x16x32_bf16 v[60:63], v[162:165], v[186:189], v[60:63]
	v_mfma_f32_16x16x32_bf16 v[52:55], v[170:173], v[186:189], v[52:55]
	v_mfma_f32_16x16x32_bf16 v[48:51], v[162:165], v[208:211], v[48:51]
	v_mfma_f32_16x16x32_bf16 v[40:43], v[170:173], v[208:211], v[40:43]
	v_mfma_f32_16x16x32_bf16 v[44:47], v[162:165], v[220:223], v[44:47]
	v_mfma_f32_16x16x32_bf16 v[36:39], v[170:173], v[220:223], v[36:39]
	s_setprio 0
	s_barrier
; #define PG8_STAGE(bufoff, gbase, voff) do { _Pragma("unroll") for (int _i = 0; _i < 2; ++_i) \
;         __builtin_amdgcn_global_load_lds((const unsigned*)((const char*)(gbase) + (voff)[_i]), (PG8_LAS unsigned*)(lds + (bufoff) + ldsw + _i * 8192), 16, 0, 0); } while (0)
; #define PG8_LDA(dst, b, h) do { _Pragma("unroll") for (int m = 0; m < 4; ++m) _Pragma("unroll") for (int k = 0; k < 2; ++k) dst[m][k] = *(const PG8_LAS bf16x8*)(lds + PG8_SA(b, h) + aoff + m * 2048 + k * 1024); } while (0)
; #define PG8_MMA(ai, bj, At, Bt) do { __builtin_amdgcn_s_setprio(1); _Pragma("unroll") for (int m = 0; m < 4; ++m) _Pragma("unroll") for (int n = 0; n < 2; ++n) _Pragma("unroll") for (int k = 0; k < 2; ++k) \
;         acc[ai][bj][m][n] = __builtin_amdgcn_mfma_f32_16x16x32_bf16(Bt[n][k], At[m][k], acc[ai][bj][m][n], 0, 0, 0); __builtin_amdgcn_s_setprio(0); } while (0)
; #define PG8_WAIT_V(n) asm volatile("s_waitcnt vmcnt(" #n ")" ::: "memory")
; #define PG8_WAIT_L(n) asm volatile("s_waitcnt lgkmcnt(" #n ")" ::: "memory")
; #define PG8_BAR __builtin_amdgcn_s_barrier()
; #define PG8_SCHED __builtin_amdgcn_sched_barrier(0)
; template <class Epi, class Sched, bool ALIGN_EPI = false, bool SP2 = false>
; __device__ __forceinline__ void gemm_phase(PG8_LAS unsigned char* lds, const Gemm g, const Sched& S, const Epi& E, int tid_in) {
;     ...
;         for (int t = 0; t < nt; t += 2) {
;     ...
;             PG8_LDA(At, 1, 1); PG8_STAGE(PG8_SB(1, 0), b3, voffB); PG8_STAGE(PG8_SB(1, 1), b3 + hsB, voffB); PG8_STAGE(PG8_SA(1, 0), a3, voffA);
;             PG8_WAIT_V(8); PG8_WAIT_L(0); PG8_BAR; PG8_MMA(1, 0, At, B0); PG8_MMA(1, 1, At, B1); PG8_BAR; PG8_SCHED;
	s_add_i32 s38, s41, s49
	v_lshl_add_u64 v[190:191], v[190:191], 0, s[80:81]
	s_mov_b32 m0, s38
	ds_read_b128 v[174:177], v219 offset:49152
	ds_read_b128 v[178:181], v219 offset:50176
	ds_read_b128 v[182:185], v219 offset:51200
	ds_read_b128 v[186:189], v219 offset:52224
	ds_read_b128 v[204:207], v219 offset:53248
	ds_read_b128 v[208:211], v219 offset:54272
	ds_read_b128 v[212:215], v219 offset:55296
	ds_read_b128 v[220:223], v219 offset:56320
	global_load_lds_dwordx4 v[190:191], off
	v_lshl_add_u64 v[190:191], v[192:193], 0, s[80:81]
	s_add_i32 m0, s38, 0x2000
	s_add_i32 s38, s76, s49
	global_load_lds_dwordx4 v[190:191], off
	v_lshl_add_u64 v[190:191], v[196:197], 0, s[80:81]
	s_mov_b32 m0, s38
	s_nop 0
	global_load_lds_dwordx4 v[190:191], off
	v_lshl_add_u64 v[190:191], v[198:199], 0, s[80:81]
	s_add_i32 m0, s38, 0x2000
	s_nop 0
	global_load_lds_dwordx4 v[190:191], off
	v_lshl_add_u64 v[190:191], v[200:201], 0, s[80:81]
	s_mov_b32 m0, s58
	s_nop 0
	global_load_lds_dwordx4 v[190:191], off
	v_lshl_add_u64 v[190:191], v[202:203], 0, s[80:81]
	s_mov_b32 m0, s59
	s_nop 0
	global_load_lds_dwordx4 v[190:191], off
	s_waitcnt vmcnt(6)
	s_waitcnt lgkmcnt(0)
	s_barrier
	s_setprio 1
	s_waitcnt lgkmcnt(0)
	v_mfma_f32_16x16x32_bf16 v[96:99], v[132:135], v[174:177], v[96:99]
	v_mfma_f32_16x16x32_bf16 v[92:95], v[140:143], v[174:177], v[92:95]
	v_mfma_f32_16x16x32_bf16 v[88:91], v[132:135], v[182:185], v[88:91]
	v_mfma_f32_16x16x32_bf16 v[84:87], v[140:143], v[182:185], v[84:87]
	v_mfma_f32_16x16x32_bf16 v[80:83], v[132:135], v[204:207], v[80:83]
	v_mfma_f32_16x16x32_bf16 v[76:79], v[140:143], v[204:207], v[76:79]
	v_mfma_f32_16x16x32_bf16 v[72:75], v[132:135], v[212:215], v[72:75]
	v_mfma_f32_16x16x32_bf16 v[68:71], v[140:143], v[212:215], v[68:71]
	v_mfma_f32_16x16x32_bf16 v[96:99], v[136:139], v[178:181], v[96:99]
	v_mfma_f32_16x16x32_bf16 v[92:95], v[144:147], v[178:181], v[92:95]
	v_mfma_f32_16x16x32_bf16 v[88:91], v[136:139], v[186:189], v[88:91]
	v_mfma_f32_16x16x32_bf16 v[84:87], v[144:147], v[186:189], v[84:87]
	v_mfma_f32_16x16x32_bf16 v[80:83], v[136:139], v[208:211], v[80:83]
	v_mfma_f32_16x16x32_bf16 v[76:79], v[144:147], v[208:211], v[76:79]
	v_mfma_f32_16x16x32_bf16 v[72:75], v[136:139], v[220:223], v[72:75]
	v_mfma_f32_16x16x32_bf16 v[68:71], v[144:147], v[220:223], v[68:71]
	s_setprio 0
	s_setprio 1
	v_mfma_f32_16x16x32_bf16 v[32:35], v[148:151], v[174:177], v[32:35]
	v_mfma_f32_16x16x32_bf16 v[28:31], v[166:169], v[174:177], v[28:31]
	v_mfma_f32_16x16x32_bf16 v[24:27], v[148:151], v[182:185], v[24:27]
	v_mfma_f32_16x16x32_bf16 v[12:15], v[166:169], v[182:185], v[12:15]
	v_mfma_f32_16x16x32_bf16 v[20:23], v[148:151], v[204:207], v[20:23]
	v_mfma_f32_16x16x32_bf16 v[8:11], v[166:169], v[204:207], v[8:11]
	v_mfma_f32_16x16x32_bf16 v[16:19], v[148:151], v[212:215], v[16:19]
	v_mfma_f32_16x16x32_bf16 v[4:7], v[166:169], v[212:215], v[4:7]
	v_mfma_f32_16x16x32_bf16 v[32:35], v[162:165], v[178:181], v[32:35]
	v_mfma_f32_16x16x32_bf16 v[28:31], v[170:173], v[178:181], v[28:31]
	v_mfma_f32_16x16x32_bf16 v[24:27], v[162:165], v[186:189], v[24:27]
	v_mfma_f32_16x16x32_bf16 v[12:15], v[170:173], v[186:189], v[12:15]
	v_mfma_f32_16x16x32_bf16 v[20:23], v[162:165], v[208:211], v[20:23]
	v_mfma_f32_16x16x32_bf16 v[8:11], v[170:173], v[208:211], v[8:11]
	v_mfma_f32_16x16x32_bf16 v[16:19], v[162:165], v[220:223], v[16:19]
	v_mfma_f32_16x16x32_bf16 v[4:7], v[170:173], v[220:223], v[4:7]
	s_setprio 0
	s_barrier
	s_add_i32 s38, s40, 2
	s_add_u32 s74, s74, 0x100
	s_addc_u32 s75, s75, 0
	s_add_u32 s4, s4, 0x100
	s_addc_u32 s5, s5, 0
	s_cmp_ge_i32 s40, s60
	s_mov_b32 s40, s38
	s_cbranch_scc0 .LBB0_1331
	s_movk_i32 s74, 0x2c00

; #define PG8_STAGE(bufoff, gbase, voff) do { _Pragma("unroll") for (int _i = 0; _i < 2; ++_i) \
;         __builtin_amdgcn_global_load_lds((const unsigned*)((const char*)(gbase) + (voff)[_i]), (PG8_LAS unsigned*)(lds + (bufoff) + ldsw + _i * 8192), 16, 0, 0); } while (0)
; #define PG8_LDA(dst, b, h) do { _Pragma("unroll") for (int m = 0; m < 4; ++m) _Pragma("unroll") for (int k = 0; k < 2; ++k) dst[m][k] = *(const PG8_LAS bf16x8*)(lds + PG8_SA(b, h) + aoff + m * 2048 + k * 1024); } while (0)
; #define PG8_LDB(dst, b, h) do { _Pragma("unroll") for (int n = 0; n < 2; ++n) _Pragma("unroll") for (int k = 0; k < 2; ++k) dst[n][k] = *(const PG8_LAS bf16x8*)(lds + PG8_SB(b, h) + boff + n * 2048 + k * 1024); } while (0)
; #define PG8_MMA(ai, bj, At, Bt) do { __builtin_amdgcn_s_setprio(1); _Pragma("unroll") for (int m = 0; m < 4; ++m) _Pragma("unroll") for (int n = 0; n < 2; ++n) _Pragma("unroll") for (int k = 0; k < 2; ++k) \
;         acc[ai][bj][m][n] = __builtin_amdgcn_mfma_f32_16x16x32_bf16(Bt[n][k], At[m][k], acc[ai][bj][m][n], 0, 0, 0); __builtin_amdgcn_s_setprio(0); } while (0)
; template <class Epi, class Sched, bool ALIGN_EPI = false, bool SP2 = false>
; __device__ __forceinline__ void gemm_phase(PG8_LAS unsigned char* lds, const Gemm g, const Sched& S, const Epi& E, int tid_in) {
;     ...
;             const bool last = (t == nt - 2);
;             if constexpr (mid_hook<Epi>::value) { if (t == Epi::H1 || t == Epi::H2) E.mid(acc, cur, wr, wc, fr, fq, t == Epi::H2); }
;             const char* a1 = cA + (size_t)(t + 1) * kstep + (t >= jt ? jb : 0);
;             const char* a2 = last ? nA : cA + (size_t)(t + 2) * kstep + (t + 2 >= jt ? jb : 0); const char* b2 = last ? nB : cB + (size_t)(t + 2) * kstep;
;             const char* a3 = a2 + kstep; const char* b3 = b2 + kstep;
;             if (last && has_next) S.a_ready(nxt);
;             if constexpr (SP2) {
;             PG8_LDB(B0, 0, 0); PG8_LDB(B1, 0, 1); PG8_SCHED; PG8_LDA(At, 0, 0); PG8_STAGE(PG8_SA(1, 1), a1 + hsA, voffA);
;             PG8_WAIT_V(8); PG8_WAIT_L(0); PG8_BAR; PG8_MMA(0, 0, At, B0); PG8_MMA(0, 1, At, B1); PG8_BAR; PG8_SCHED;
;             PG8_LDA(At, 0, 1); PG8_STAGE(PG8_SB(0, 0), b2, voffB); PG8_STAGE(PG8_SB(0, 1), b2 + hsB, voffB); PG8_STAGE(PG8_SA(0, 0), a2, voffA);
;             PG8_WAIT_V(8); PG8_WAIT_L(0); PG8_BAR; PG8_MMA(1, 0, At, B0); PG8_MMA(1, 1, At, B1); PG8_BAR; PG8_SCHED;
.LBB0_1362:
	s_add_i32 s24, s55, -2
	s_cmp_ge_i32 s24, s26
	s_cselect_b32 s58, s27, 0
	s_cselect_b32 s59, s47, 0
	s_cmp_ge_i32 s55, s26
	s_cselect_b32 s25, s27, 0
	s_cselect_b32 s24, s47, 0
	s_add_u32 s25, s22, s25
	s_addc_u32 s24, s23, s24
	s_add_u32 s60, s25, 0x80
	s_addc_u32 s24, s24, 0
	s_add_i32 s62, 0, 0x10000
	s_cmp_eq_u32 s46, s55
	s_cselect_b32 s25, s5, s24
	s_cselect_b32 s24, s4, s60
	s_cselect_b32 s61, s21, s54
	s_cselect_b32 s60, s20, s53
	s_add_i32 s63, 0, 0x14000
	v_add_u32_e32 v160, s62, v3
	v_add_u32_e32 v176, s63, v3
	ds_read_b128 v[148:151], v160
	ds_read_b128 v[152:155], v160 offset:1024
	ds_read_b128 v[156:159], v160 offset:2048
	ds_read_b128 v[160:163], v160 offset:3072
	ds_read_b128 v[164:167], v176
	ds_read_b128 v[168:171], v176 offset:1024
	ds_read_b128 v[172:175], v176 offset:2048
	ds_read_b128 v[176:179], v176 offset:3072
	v_lshl_add_u64 v[192:193], s[22:23], 0, v[140:141]
	v_lshl_add_u64 v[192:193], v[192:193], 0, s[58:59]
	s_add_i32 m0, s33, 0xc000
	ds_read_b128 v[180:183], v147
	ds_read_b128 v[184:187], v147 offset:1024
	ds_read_b128 v[188:191], v147 offset:2048
	ds_read_b128 v[204:207], v147 offset:3072
	ds_read_b128 v[208:211], v147 offset:4096
	ds_read_b128 v[212:215], v147 offset:5120
	ds_read_b128 v[216:219], v147 offset:6144
	ds_read_b128 v[220:223], v147 offset:7168
	global_load_lds_dwordx4 v[192:193], off
	v_lshl_add_u64 v[192:193], s[22:23], 0, v[138:139]
	v_lshl_add_u64 v[192:193], v[192:193], 0, s[58:59]
	s_add_i32 m0, s33, 0xe000
	s_nop 0
	global_load_lds_dwordx4 v[192:193], off
	s_waitcnt vmcnt(8)
	s_waitcnt lgkmcnt(0)
	s_barrier
	s_setprio 1
	s_waitcnt lgkmcnt(0)
	v_mfma_f32_16x16x32_bf16 v[124:127], v[148:151], v[180:183], v[124:127]
	v_mfma_f32_16x16x32_bf16 v[128:131], v[156:159], v[180:183], v[128:131]
	v_mfma_f32_16x16x32_bf16 v[112:115], v[148:151], v[188:191], v[112:115]
	v_mfma_f32_16x16x32_bf16 v[108:111], v[156:159], v[188:191], v[108:111]
	v_mfma_f32_16x16x32_bf16 v[96:99], v[148:151], v[208:211], v[96:99]
	v_mfma_f32_16x16x32_bf16 v[92:95], v[156:159], v[208:211], v[92:95]
	v_mfma_f32_16x16x32_bf16 v[80:83], v[148:151], v[216:219], v[80:83]
	v_mfma_f32_16x16x32_bf16 v[76:79], v[156:159], v[216:219], v[76:79]
	v_mfma_f32_16x16x32_bf16 v[124:127], v[152:155], v[184:187], v[124:127]
	v_mfma_f32_16x16x32_bf16 v[128:131], v[160:163], v[184:187], v[128:131]
	v_mfma_f32_16x16x32_bf16 v[112:115], v[152:155], v[204:207], v[112:115]
	v_mfma_f32_16x16x32_bf16 v[108:111], v[160:163], v[204:207], v[108:111]
	v_mfma_f32_16x16x32_bf16 v[96:99], v[152:155], v[212:215], v[96:99]
	v_mfma_f32_16x16x32_bf16 v[92:95], v[160:163], v[212:215], v[92:95]
	v_mfma_f32_16x16x32_bf16 v[80:83], v[152:155], v[220:223], v[80:83]
	v_mfma_f32_16x16x32_bf16 v[76:79], v[160:163], v[220:223], v[76:79]
	s_setprio 0
	s_setprio 1
	v_mfma_f32_16x16x32_bf16 v[120:123], v[164:167], v[180:183], v[120:123]
	v_mfma_f32_16x16x32_bf16 v[116:119], v[172:175], v[180:183], v[116:119]
	v_mfma_f32_16x16x32_bf16 v[104:107], v[164:167], v[188:191], v[104:107]
	v_mfma_f32_16x16x32_bf16 v[100:103], v[172:175], v[188:191], v[100:103]
	v_mfma_f32_16x16x32_bf16 v[88:91], v[164:167], v[208:211], v[88:91]
	v_mfma_f32_16x16x32_bf16 v[84:87], v[172:175], v[208:211], v[84:87]
	v_mfma_f32_16x16x32_bf16 v[72:75], v[164:167], v[216:219], v[72:75]
	v_mfma_f32_16x16x32_bf16 v[68:71], v[172:175], v[216:219], v[68:71]
	v_mfma_f32_16x16x32_bf16 v[120:123], v[168:171], v[184:187], v[120:123]
	v_mfma_f32_16x16x32_bf16 v[116:119], v[176:179], v[184:187], v[116:119]
	v_mfma_f32_16x16x32_bf16 v[104:107], v[168:171], v[204:207], v[104:107]
	v_mfma_f32_16x16x32_bf16 v[100:103], v[176:179], v[204:207], v[100:103]
	v_mfma_f32_16x16x32_bf16 v[88:91], v[168:171], v[212:215], v[88:91]
	v_mfma_f32_16x16x32_bf16 v[84:87], v[176:179], v[212:215], v[84:87]
	v_mfma_f32_16x16x32_bf16 v[72:75], v[168:171], v[220:223], v[72:75]
	v_mfma_f32_16x16x32_bf16 v[68:71], v[176:179], v[220:223], v[68:71]
	s_setprio 0
	s_barrier
	s_add_i32 s58, s62, s30
	v_lshl_add_u64 v[192:193], s[60:61], 0, v[134:135]
	s_mov_b32 m0, s58
	ds_read_b128 v[180:183], v147 offset:16384
	ds_read_b128 v[184:187], v147 offset:17408
	ds_read_b128 v[188:191], v147 offset:18432
	ds_read_b128 v[204:207], v147 offset:19456
	ds_read_b128 v[208:211], v147 offset:20480
	ds_read_b128 v[212:215], v147 offset:21504
	ds_read_b128 v[216:219], v147 offset:22528
	ds_read_b128 v[220:223], v147 offset:23552
	global_load_lds_dwordx4 v[192:193], off
	s_add_i32 m0, s58, 0x2000
	s_add_u32 s58, s60, s8
	v_lshl_add_u64 v[196:197], s[60:61], 0, v[0:1]
	s_addc_u32 s59, s61, s9
	s_add_i32 s60, s63, s30
	global_load_lds_dwordx4 v[196:197], off
	v_lshl_add_u64 v[198:199], s[58:59], 0, v[134:135]
	v_lshl_add_u64 v[200:201], s[58:59], 0, v[0:1]
	v_lshl_add_u64 v[202:203], s[24:25], 0, v[136:137]
	s_mov_b32 m0, s33
	v_lshl_add_u64 v[228:229], s[24:25], 0, v[132:133]
	global_load_lds_dwordx4 v[202:203], off
	s_mov_b32 m0, s34
	s_nop 0
	global_load_lds_dwordx4 v[228:229], off
	s_waitcnt vmcnt(6)
	s_waitcnt lgkmcnt(0)
	s_barrier
; #define PG8_STAGE(bufoff, gbase, voff) do { _Pragma("unroll") for (int _i = 0; _i < 2; ++_i) \
;         __builtin_amdgcn_global_load_lds((const unsigned*)((const char*)(gbase) + (voff)[_i]), (PG8_LAS unsigned*)(lds + (bufoff) + ldsw + _i * 8192), 16, 0, 0); } while (0)
; #define PG8_LDA(dst, b, h) do { _Pragma("unroll") for (int m = 0; m < 4; ++m) _Pragma("unroll") for (int k = 0; k < 2; ++k) dst[m][k] = *(const PG8_LAS bf16x8*)(lds + PG8_SA(b, h) + aoff + m * 2048 + k * 1024); } while (0)
; #define PG8_LDB(dst, b, h) do { _Pragma("unroll") for (int n = 0; n < 2; ++n) _Pragma("unroll") for (int k = 0; k < 2; ++k) dst[n][k] = *(const PG8_LAS bf16x8*)(lds + PG8_SB(b, h) + boff + n * 2048 + k * 1024); } while (0)
; #define PG8_MMA(ai, bj, At, Bt) do { __builtin_amdgcn_s_setprio(1); _Pragma("unroll") for (int m = 0; m < 4; ++m) _Pragma("unroll") for (int n = 0; n < 2; ++n) _Pragma("unroll") for (int k = 0; k < 2; ++k) \
;         acc[ai][bj][m][n] = __builtin_amdgcn_mfma_f32_16x16x32_bf16(Bt[n][k], At[m][k], acc[ai][bj][m][n], 0, 0, 0); __builtin_amdgcn_s_setprio(0); } while (0)
; #define PG8_WAIT_V(n) asm volatile("s_waitcnt vmcnt(" #n ")" ::: "memory")
; #define PG8_WAIT_L(n) asm volatile("s_waitcnt lgkmcnt(" #n ")" ::: "memory")
; #define PG8_BAR __builtin_amdgcn_s_barrier()
; #define PG8_SCHED __builtin_amdgcn_sched_barrier(0)
; template <class Epi, class Sched, bool ALIGN_EPI = false, bool SP2 = false>
; __device__ __forceinline__ void gemm_phase(PG8_LAS unsigned char* lds, const Gemm g, const Sched& S, const Epi& E, int tid_in) {
;     ...
;             PG8_WAIT_V(8); PG8_WAIT_L(0); PG8_BAR; PG8_MMA(1, 0, At, B0); PG8_MMA(1, 1, At, B1); PG8_BAR; PG8_SCHED;
;             PG8_LDB(B0, 1, 0); PG8_LDB(B1, 1, 1); PG8_SCHED; PG8_LDA(At, 1, 0); PG8_STAGE(PG8_SA(0, 1), a2 + hsA, voffA);
;             PG8_WAIT_V(8); PG8_WAIT_L(0); PG8_BAR; PG8_MMA(0, 0, At, B0); PG8_MMA(0, 1, At, B1); PG8_BAR; PG8_SCHED;
	s_setprio 1
	s_waitcnt lgkmcnt(0)
	v_mfma_f32_16x16x32_bf16 v[64:67], v[148:151], v[180:183], v[64:67]
	v_mfma_f32_16x16x32_bf16 v[60:63], v[156:159], v[180:183], v[60:63]
	v_mfma_f32_16x16x32_bf16 v[48:51], v[148:151], v[188:191], v[48:51]
	v_mfma_f32_16x16x32_bf16 v[44:47], v[156:159], v[188:191], v[44:47]
	v_mfma_f32_16x16x32_bf16 v[32:35], v[148:151], v[208:211], v[32:35]
	v_mfma_f32_16x16x32_bf16 v[28:31], v[156:159], v[208:211], v[28:31]
	v_mfma_f32_16x16x32_bf16 v[16:19], v[148:151], v[216:219], v[16:19]
	v_mfma_f32_16x16x32_bf16 v[12:15], v[156:159], v[216:219], v[12:15]
	v_mfma_f32_16x16x32_bf16 v[64:67], v[152:155], v[184:187], v[64:67]
	v_mfma_f32_16x16x32_bf16 v[60:63], v[160:163], v[184:187], v[60:63]
	v_mfma_f32_16x16x32_bf16 v[48:51], v[152:155], v[204:207], v[48:51]
	v_mfma_f32_16x16x32_bf16 v[44:47], v[160:163], v[204:207], v[44:47]
	v_mfma_f32_16x16x32_bf16 v[32:35], v[152:155], v[212:215], v[32:35]
	v_mfma_f32_16x16x32_bf16 v[28:31], v[160:163], v[212:215], v[28:31]
	v_mfma_f32_16x16x32_bf16 v[16:19], v[152:155], v[220:223], v[16:19]
	v_mfma_f32_16x16x32_bf16 v[12:15], v[160:163], v[220:223], v[12:15]
	s_setprio 0
	s_setprio 1
	v_mfma_f32_16x16x32_bf16 v[56:59], v[164:167], v[180:183], v[56:59]
	v_mfma_f32_16x16x32_bf16 v[52:55], v[172:175], v[180:183], v[52:55]
	v_mfma_f32_16x16x32_bf16 v[40:43], v[164:167], v[188:191], v[40:43]
	v_mfma_f32_16x16x32_bf16 v[36:39], v[172:175], v[188:191], v[36:39]
	v_mfma_f32_16x16x32_bf16 v[24:27], v[164:167], v[208:211], v[24:27]
	v_mfma_f32_16x16x32_bf16 v[20:23], v[172:175], v[208:211], v[20:23]
	v_mfma_f32_16x16x32_bf16 v[8:11], v[164:167], v[216:219], v[8:11]
	v_mfma_f32_16x16x32_bf16 v[4:7], v[172:175], v[216:219], v[4:7]
	v_mfma_f32_16x16x32_bf16 v[56:59], v[168:171], v[184:187], v[56:59]
	v_mfma_f32_16x16x32_bf16 v[52:55], v[176:179], v[184:187], v[52:55]
	v_mfma_f32_16x16x32_bf16 v[40:43], v[168:171], v[204:207], v[40:43]
	v_mfma_f32_16x16x32_bf16 v[36:39], v[176:179], v[204:207], v[36:39]
	v_mfma_f32_16x16x32_bf16 v[24:27], v[168:171], v[212:215], v[24:27]
	v_mfma_f32_16x16x32_bf16 v[20:23], v[176:179], v[212:215], v[20:23]
	v_mfma_f32_16x16x32_bf16 v[8:11], v[168:171], v[220:223], v[8:11]
	v_mfma_f32_16x16x32_bf16 v[4:7], v[176:179], v[220:223], v[4:7]
	s_setprio 0
	s_barrier
	s_add_i32 s58, 0, 0x18000
	s_add_i32 s59, 0, 0x1c000
	v_add_u32_e32 v160, s58, v3
	v_add_u32_e32 v176, s59, v3
	ds_read_b128 v[148:151], v160
	ds_read_b128 v[152:155], v160 offset:1024
	ds_read_b128 v[156:159], v160 offset:2048
	ds_read_b128 v[160:163], v160 offset:3072
	ds_read_b128 v[164:167], v176
	ds_read_b128 v[168:171], v176 offset:1024
	ds_read_b128 v[172:175], v176 offset:2048
	ds_read_b128 v[176:179], v176 offset:3072
	s_add_u32 s24, s24, s6
	s_addc_u32 s25, s25, s7
	s_mov_b32 m0, s35
	v_lshl_add_u64 v[230:231], s[24:25], 0, v[136:137]
	ds_read_b128 v[180:183], v147 offset:32768
	ds_read_b128 v[184:187], v147 offset:33792
	ds_read_b128 v[188:191], v147 offset:34816
	ds_read_b128 v[204:207], v147 offset:35840
	ds_read_b128 v[208:211], v147 offset:36864
	ds_read_b128 v[212:215], v147 offset:37888
	ds_read_b128 v[216:219], v147 offset:38912
	ds_read_b128 v[220:223], v147 offset:39936
	global_load_lds_dwordx4 v[230:231], off
	v_lshl_add_u64 v[230:231], s[24:25], 0, v[132:133]
	s_mov_b32 m0, s36
	s_nop 0
	global_load_lds_dwordx4 v[230:231], off
	s_add_i32 m0, s30, 0x14000
	s_nop 0
	global_load_lds_dwordx4 v[198:199], off
	s_add_i32 m0, s30, 0x16000
	s_nop 0
	global_load_lds_dwordx4 v[200:201], off
	s_waitcnt vmcnt(8)
	s_waitcnt lgkmcnt(0)
	s_barrier
	s_setprio 1
	s_waitcnt lgkmcnt(0)
	v_mfma_f32_16x16x32_bf16 v[124:127], v[148:151], v[180:183], v[124:127]
	v_mfma_f32_16x16x32_bf16 v[128:131], v[156:159], v[180:183], v[128:131]
	v_mfma_f32_16x16x32_bf16 v[112:115], v[148:151], v[188:191], v[112:115]
	v_mfma_f32_16x16x32_bf16 v[108:111], v[156:159], v[188:191], v[108:111]
	v_mfma_f32_16x16x32_bf16 v[96:99], v[148:151], v[208:211], v[96:99]
	v_mfma_f32_16x16x32_bf16 v[92:95], v[156:159], v[208:211], v[92:95]
	v_mfma_f32_16x16x32_bf16 v[80:83], v[148:151], v[216:219], v[80:83]
	v_mfma_f32_16x16x32_bf16 v[76:79], v[156:159], v[216:219], v[76:79]
	v_mfma_f32_16x16x32_bf16 v[124:127], v[152:155], v[184:187], v[124:127]
	v_mfma_f32_16x16x32_bf16 v[128:131], v[160:163], v[184:187], v[128:131]
	v_mfma_f32_16x16x32_bf16 v[112:115], v[152:155], v[204:207], v[112:115]
	v_mfma_f32_16x16x32_bf16 v[108:111], v[160:163], v[204:207], v[108:111]
	v_mfma_f32_16x16x32_bf16 v[96:99], v[152:155], v[212:215], v[96:99]
	v_mfma_f32_16x16x32_bf16 v[92:95], v[160:163], v[212:215], v[92:95]
	v_mfma_f32_16x16x32_bf16 v[80:83], v[152:155], v[220:223], v[80:83]
	v_mfma_f32_16x16x32_bf16 v[76:79], v[160:163], v[220:223], v[76:79]
	s_setprio 0
	s_setprio 1
	v_mfma_f32_16x16x32_bf16 v[120:123], v[164:167], v[180:183], v[120:123]
	v_mfma_f32_16x16x32_bf16 v[116:119], v[172:175], v[180:183], v[116:119]
	v_mfma_f32_16x16x32_bf16 v[104:107], v[164:167], v[188:191], v[104:107]
	v_mfma_f32_16x16x32_bf16 v[100:103], v[172:175], v[188:191], v[100:103]
	v_mfma_f32_16x16x32_bf16 v[88:91], v[164:167], v[208:211], v[88:91]
	v_mfma_f32_16x16x32_bf16 v[84:87], v[172:175], v[208:211], v[84:87]
	v_mfma_f32_16x16x32_bf16 v[72:75], v[164:167], v[216:219], v[72:75]
	v_mfma_f32_16x16x32_bf16 v[68:71], v[172:175], v[216:219], v[68:71]
	v_mfma_f32_16x16x32_bf16 v[120:123], v[168:171], v[184:187], v[120:123]
	v_mfma_f32_16x16x32_bf16 v[116:119], v[176:179], v[184:187], v[116:119]
	v_mfma_f32_16x16x32_bf16 v[104:107], v[168:171], v[204:207], v[104:107]
	v_mfma_f32_16x16x32_bf16 v[100:103], v[176:179], v[204:207], v[100:103]
	v_mfma_f32_16x16x32_bf16 v[88:91], v[168:171], v[212:215], v[88:91]
	v_mfma_f32_16x16x32_bf16 v[84:87], v[176:179], v[212:215], v[84:87]
	v_mfma_f32_16x16x32_bf16 v[72:75], v[168:171], v[220:223], v[72:75]
	v_mfma_f32_16x16x32_bf16 v[68:71], v[176:179], v[220:223], v[68:71]
	s_setprio 0
	s_barrier
; #define PG8_STAGE(bufoff, gbase, voff) do { _Pragma("unroll") for (int _i = 0; _i < 2; ++_i) \
;         __builtin_amdgcn_global_load_lds((const unsigned*)((const char*)(gbase) + (voff)[_i]), (PG8_LAS unsigned*)(lds + (bufoff) + ldsw + _i * 8192), 16, 0, 0); } while (0)
; #define PG8_LDA(dst, b, h) do { _Pragma("unroll") for (int m = 0; m < 4; ++m) _Pragma("unroll") for (int k = 0; k < 2; ++k) dst[m][k] = *(const PG8_LAS bf16x8*)(lds + PG8_SA(b, h) + aoff + m * 2048 + k * 1024); } while (0)
; #define PG8_MMA(ai, bj, At, Bt) do { __builtin_amdgcn_s_setprio(1); _Pragma("unroll") for (int m = 0; m < 4; ++m) _Pragma("unroll") for (int n = 0; n < 2; ++n) _Pragma("unroll") for (int k = 0; k < 2; ++k) \
;         acc[ai][bj][m][n] = __builtin_amdgcn_mfma_f32_16x16x32_bf16(Bt[n][k], At[m][k], acc[ai][bj][m][n], 0, 0, 0); __builtin_amdgcn_s_setprio(0); } while (0)
; #define PG8_WAIT_V(n) asm volatile("s_waitcnt vmcnt(" #n ")" ::: "memory")
; #define PG8_WAIT_L(n) asm volatile("s_waitcnt lgkmcnt(" #n ")" ::: "memory")
; #define PG8_BAR __builtin_amdgcn_s_barrier()
; #define PG8_SCHED __builtin_amdgcn_sched_barrier(0)
; template <class Epi, class Sched, bool ALIGN_EPI = false, bool SP2 = false>
; __device__ __forceinline__ void gemm_phase(PG8_LAS unsigned char* lds, const Gemm g, const Sched& S, const Epi& E, int tid_in) {
;     ...
;         for (int t = 0; t < nt; t += 2) {
;     ...
;             PG8_LDA(At, 1, 1); PG8_STAGE(PG8_SB(1, 0), b3, voffB); PG8_STAGE(PG8_SB(1, 1), b3 + hsB, voffB); PG8_STAGE(PG8_SA(1, 0), a3, voffA);
;             PG8_WAIT_V(8); PG8_WAIT_L(0); PG8_BAR; PG8_MMA(1, 0, At, B0); PG8_MMA(1, 1, At, B1); PG8_BAR; PG8_SCHED;
	s_add_i32 s24, s58, s30
	v_lshl_add_u64 v[192:193], v[192:193], 0, s[80:81]
	s_mov_b32 m0, s24
	ds_read_b128 v[180:183], v147 offset:49152
	ds_read_b128 v[184:187], v147 offset:50176
	ds_read_b128 v[188:191], v147 offset:51200
	ds_read_b128 v[204:207], v147 offset:52224
	ds_read_b128 v[208:211], v147 offset:53248
	ds_read_b128 v[212:215], v147 offset:54272
	ds_read_b128 v[216:219], v147 offset:55296
	ds_read_b128 v[220:223], v147 offset:56320
	global_load_lds_dwordx4 v[192:193], off
	v_lshl_add_u64 v[192:193], v[196:197], 0, s[80:81]
	s_add_i32 m0, s24, 0x2000
	s_add_i32 s24, s59, s30
	global_load_lds_dwordx4 v[192:193], off
	v_lshl_add_u64 v[192:193], v[198:199], 0, s[80:81]
	s_mov_b32 m0, s24
	s_nop 0
	global_load_lds_dwordx4 v[192:193], off
	v_lshl_add_u64 v[192:193], v[200:201], 0, s[80:81]
	s_add_i32 m0, s24, 0x2000
	s_nop 0
	global_load_lds_dwordx4 v[192:193], off
	v_lshl_add_u64 v[192:193], v[202:203], 0, s[80:81]
	s_mov_b32 m0, s39
	s_nop 0
	global_load_lds_dwordx4 v[192:193], off
	v_lshl_add_u64 v[192:193], v[228:229], 0, s[80:81]
	s_mov_b32 m0, s40
	s_nop 0
	global_load_lds_dwordx4 v[192:193], off
	s_waitcnt vmcnt(6)
	s_waitcnt lgkmcnt(0)
	s_barrier
	s_setprio 1
	s_waitcnt lgkmcnt(0)
	v_mfma_f32_16x16x32_bf16 v[64:67], v[148:151], v[180:183], v[64:67]
	v_mfma_f32_16x16x32_bf16 v[60:63], v[156:159], v[180:183], v[60:63]
	v_mfma_f32_16x16x32_bf16 v[48:51], v[148:151], v[188:191], v[48:51]
	v_mfma_f32_16x16x32_bf16 v[44:47], v[156:159], v[188:191], v[44:47]
	v_mfma_f32_16x16x32_bf16 v[32:35], v[148:151], v[208:211], v[32:35]
	v_mfma_f32_16x16x32_bf16 v[28:31], v[156:159], v[208:211], v[28:31]
	v_mfma_f32_16x16x32_bf16 v[16:19], v[148:151], v[216:219], v[16:19]
	v_mfma_f32_16x16x32_bf16 v[12:15], v[156:159], v[216:219], v[12:15]
	v_mfma_f32_16x16x32_bf16 v[64:67], v[152:155], v[184:187], v[64:67]
	v_mfma_f32_16x16x32_bf16 v[60:63], v[160:163], v[184:187], v[60:63]
	v_mfma_f32_16x16x32_bf16 v[48:51], v[152:155], v[204:207], v[48:51]
	v_mfma_f32_16x16x32_bf16 v[44:47], v[160:163], v[204:207], v[44:47]
	v_mfma_f32_16x16x32_bf16 v[32:35], v[152:155], v[212:215], v[32:35]
	v_mfma_f32_16x16x32_bf16 v[28:31], v[160:163], v[212:215], v[28:31]
	v_mfma_f32_16x16x32_bf16 v[16:19], v[152:155], v[220:223], v[16:19]
	v_mfma_f32_16x16x32_bf16 v[12:15], v[160:163], v[220:223], v[12:15]
	s_setprio 0
	s_setprio 1
	v_mfma_f32_16x16x32_bf16 v[56:59], v[164:167], v[180:183], v[56:59]
	v_mfma_f32_16x16x32_bf16 v[52:55], v[172:175], v[180:183], v[52:55]
	v_mfma_f32_16x16x32_bf16 v[40:43], v[164:167], v[188:191], v[40:43]
	v_mfma_f32_16x16x32_bf16 v[36:39], v[172:175], v[188:191], v[36:39]
	v_mfma_f32_16x16x32_bf16 v[24:27], v[164:167], v[208:211], v[24:27]
	v_mfma_f32_16x16x32_bf16 v[20:23], v[172:175], v[208:211], v[20:23]
	v_mfma_f32_16x16x32_bf16 v[8:11], v[164:167], v[216:219], v[8:11]
	v_mfma_f32_16x16x32_bf16 v[4:7], v[172:175], v[216:219], v[4:7]
	v_mfma_f32_16x16x32_bf16 v[56:59], v[168:171], v[184:187], v[56:59]
	v_mfma_f32_16x16x32_bf16 v[52:55], v[176:179], v[184:187], v[52:55]
	v_mfma_f32_16x16x32_bf16 v[40:43], v[168:171], v[204:207], v[40:43]
	v_mfma_f32_16x16x32_bf16 v[36:39], v[176:179], v[204:207], v[36:39]
	v_mfma_f32_16x16x32_bf16 v[24:27], v[168:171], v[212:215], v[24:27]
	v_mfma_f32_16x16x32_bf16 v[20:23], v[176:179], v[212:215], v[20:23]
	v_mfma_f32_16x16x32_bf16 v[8:11], v[168:171], v[220:223], v[8:11]
	v_mfma_f32_16x16x32_bf16 v[4:7], v[176:179], v[220:223], v[4:7]
	s_setprio 0
	s_barrier
	s_add_i32 s24, s55, 2
	s_add_u32 s53, s53, 0x100
	s_addc_u32 s54, s54, 0
	s_add_u32 s22, s22, 0x100
	s_addc_u32 s23, s23, 0
	s_cmp_ge_i32 s55, s46
	s_mov_b32 s55, s24
	s_cbranch_scc0 .LBB0_1362
